# peeled first K-iteration (C=0, no accumulator zeroing, store-aware vmcnt) for G2/G3/G4 units after the first; EpiIn flat_store -> global_store
# speedup vs baseline: 1.0034x; 1.0034x over previous
; __device__ __forceinline__ unsigned cvt_pk_bf16(float lo, float hi) { unsigned r; asm volatile("v_cvt_pk_bf16_f32 %0, %1, %2" : "=v"(r) : "v"(lo), "v"(hi)); return r; }
;     __device__ __forceinline__ void operator()(const pg8::f32x4 (&acc)[2][2][4][2], const pg8::Unit& u, int wr, int wc, int fr, int fq) const {
;     ...
;         const int pm = u.pm, pn = u.pn; const bool isctx = pm >= 256;
;         if (isctx && last && pn != 2) return;
;         const int b = isctx ? pm - 256 : pm >> 5;
;         const int sbase = (isctx ? 0 : (pm & 31) * 256) + wr * 64 + fr;
;         const size_t grow0 = (size_t)pm * 256 + wr * 64 + fr;
;         const int c8 = wc * 32 + 8 * fq;
;     ...
;             if (!isctx) {
;                 bf16_t* base = GT + ((size_t)b * 256 * 16 + fr) * 512 + 16 * (pm & 31) + 4 * wr;
; #pragma unroll
;                 for (int bj = 0; bj < 2; ++bj)
; #pragma unroll
;                     for (int n = 0; n < 2; ++n)
; #pragma unroll
;                         for (int j = 0; j < 4; ++j) { const int ch = bj * HALF + c8 + 4 * n + j;
; #pragma unroll
;                             for (int ai = 0; ai < 2; ++ai) { u32x2 w; w.x = cvt_pk_bf16(acc[ai][bj][0][n][j], acc[ai][bj][1][n][j]); w.y = cvt_pk_bf16(acc[ai][bj][2][n][j], acc[ai][bj][3][n][j]);
;                                 *(u32x2*)(base + (size_t)ch * 8192 + 8 * ai) = w; } asm volatile("" ::: "memory"); }
.LBB0_171:
	s_cmpk_gt_i32 s70, 0xff
	s_cselect_b64 s[64:65], -1, 0
	s_cmpk_lt_i32 s70, 0x100
	s_cselect_b64 s[8:9], -1, 0
	s_cmp_lg_u32 s91, 2
	s_cselect_b64 s[6:7], -1, 0
	s_and_b64 s[18:19], s[92:93], s[64:65]
	s_and_b64 s[6:7], s[18:19], s[6:7]
	v_mov_b32_e32 v148, v196
	v_mov_b32_e32 v199, v180
	s_mov_b64 s[0:1], s[60:61]
	s_and_b64 vcc, exec, s[6:7]
	s_cbranch_vccnz .LBB0_235
	s_lshl_b32 s6, s70, 8
	s_add_i32 s46, s70, 0xffffff00
	s_ashr_i32 s68, s70, 5
	s_and_b32 s18, s6, 0x1f00
	s_and_b64 s[6:7], s[64:65], exec
	s_cselect_b32 s6, 0, s18
	s_add_i32 s6, s6, s77
	s_ashr_i32 s71, s70, 31
	v_add_u32_e32 v144, s6, v148
	s_lshl_b64 s[6:7], s[70:71], 8
	s_add_u32 s6, s6, s77
	v_ashrrev_i32_e32 v149, 31, v148
	s_addc_u32 s7, s7, s80
	v_lshlrev_b32_e32 v200, 3, v199
	v_lshl_add_u64 v[146:147], s[6:7], 0, v[148:149]
	v_add_u32_e32 v142, s78, v200
	s_cmp_gt_i32 s91, 2
	s_mov_b64 s[6:7], -1
	s_cbranch_scc0 .LBB0_190
	s_cmp_lt_i32 s91, 4
	s_cbranch_scc1 .LBB0_187
	s_cmp_lg_u32 s91, 4
	s_cbranch_scc0 .LBB0_180
	s_andn2_b64 vcc, exec, s[8:9]
	s_cbranch_vccnz .LBB0_177
	s_ashr_i32 s69, s68, 31
	s_lshl_b64 s[6:7], s[68:69], 22
	s_add_u32 s6, s0, s6
	s_addc_u32 s7, s1, s7
	v_lshlrev_b64 v[150:151], 10, v[148:149]
	v_lshl_add_u64 v[150:151], s[6:7], 0, v[150:151]
	s_lshl_b32 s6, s70, 5
	s_and_b32 s6, s6, 0x3e0
	s_mov_b32 s7, s47
	v_lshl_add_u64 v[150:151], v[150:151], 0, s[6:7]
	v_lshl_add_u64 v[150:151], s[38:39], 1, v[150:151]
	s_mov_b64 s[6:7], 0x26200000
	v_ashrrev_i32_e32 v143, 31, v142
	v_lshl_add_u64 v[152:153], v[150:151], 0, s[6:7]
	v_lshlrev_b64 v[150:151], 14, v[142:143]
	v_lshl_add_u64 v[150:151], v[152:153], 0, v[150:151]
	v_cvt_pk_bf16_f32 v154, v120, v112
	v_cvt_pk_bf16_f32 v155, v104, v96
	global_store_dwordx2 v[150:151], v[154:155], off
	v_cvt_pk_bf16_f32 v154, v88, v80
	v_cvt_pk_bf16_f32 v155, v72, v64
	global_store_dwordx2 v[150:151], v[154:155], off offset:16
	v_or_b32_e32 v154, 1, v142
	v_ashrrev_i32_e32 v155, 31, v154
	v_lshlrev_b64 v[154:155], 14, v[154:155]
	v_lshl_add_u64 v[154:155], v[152:153], 0, v[154:155]
	v_cvt_pk_bf16_f32 v156, v121, v113
	v_cvt_pk_bf16_f32 v157, v105, v97
	global_store_dwordx2 v[154:155], v[156:157], off
	v_cvt_pk_bf16_f32 v156, v89, v81
	v_cvt_pk_bf16_f32 v157, v73, v65
	global_store_dwordx2 v[154:155], v[156:157], off offset:16
	v_or_b32_e32 v154, 2, v142
	v_ashrrev_i32_e32 v155, 31, v154
	v_lshlrev_b64 v[154:155], 14, v[154:155]
	v_lshl_add_u64 v[154:155], v[152:153], 0, v[154:155]
	v_cvt_pk_bf16_f32 v156, v122, v114
	v_cvt_pk_bf16_f32 v157, v106, v98
	global_store_dwordx2 v[154:155], v[156:157], off
	v_cvt_pk_bf16_f32 v156, v90, v82
	v_cvt_pk_bf16_f32 v157, v74, v66
	global_store_dwordx2 v[154:155], v[156:157], off offset:16
	v_or_b32_e32 v154, 3, v142
	v_ashrrev_i32_e32 v155, 31, v154
	v_lshlrev_b64 v[154:155], 14, v[154:155]
	v_lshl_add_u64 v[154:155], v[152:153], 0, v[154:155]
	v_cvt_pk_bf16_f32 v156, v123, v115
	v_cvt_pk_bf16_f32 v157, v107, v99
	global_store_dwordx2 v[154:155], v[156:157], off
	v_cvt_pk_bf16_f32 v156, v91, v83
	v_cvt_pk_bf16_f32 v157, v75, v67
	global_store_dwordx2 v[154:155], v[156:157], off offset:16
	v_or_b32_e32 v154, 4, v142
	v_ashrrev_i32_e32 v155, 31, v154
	v_lshlrev_b64 v[154:155], 14, v[154:155]
	v_lshl_add_u64 v[154:155], v[152:153], 0, v[154:155]
	v_cvt_pk_bf16_f32 v156, v124, v116
	v_cvt_pk_bf16_f32 v157, v108, v100
	global_store_dwordx2 v[154:155], v[156:157], off
	v_cvt_pk_bf16_f32 v156, v92, v84
	v_cvt_pk_bf16_f32 v157, v76, v68
	global_store_dwordx2 v[154:155], v[156:157], off offset:16
	v_or_b32_e32 v154, 5, v142
	v_ashrrev_i32_e32 v155, 31, v154
	v_lshlrev_b64 v[154:155], 14, v[154:155]
	v_lshl_add_u64 v[154:155], v[152:153], 0, v[154:155]
	v_cvt_pk_bf16_f32 v156, v125, v117
	v_cvt_pk_bf16_f32 v157, v109, v101
	global_store_dwordx2 v[154:155], v[156:157], off
	v_cvt_pk_bf16_f32 v156, v93, v85
	v_cvt_pk_bf16_f32 v157, v77, v69
	global_store_dwordx2 v[154:155], v[156:157], off offset:16
	v_or_b32_e32 v154, 6, v142
	v_ashrrev_i32_e32 v155, 31, v154
	v_lshlrev_b64 v[154:155], 14, v[154:155]
	v_lshl_add_u64 v[154:155], v[152:153], 0, v[154:155]
	v_cvt_pk_bf16_f32 v156, v126, v118
	v_cvt_pk_bf16_f32 v157, v110, v102
	global_store_dwordx2 v[154:155], v[156:157], off
	v_cvt_pk_bf16_f32 v156, v94, v86
	v_cvt_pk_bf16_f32 v157, v78, v70
	global_store_dwordx2 v[154:155], v[156:157], off offset:16
	v_or_b32_e32 v154, 7, v142
	v_ashrrev_i32_e32 v155, 31, v154
	v_lshlrev_b64 v[154:155], 14, v[154:155]
	v_lshl_add_u64 v[152:153], v[152:153], 0, v[154:155]
	v_cvt_pk_bf16_f32 v154, v127, v119
	v_cvt_pk_bf16_f32 v155, v111, v103
	s_mov_b64 s[6:7], 0x200000
	global_store_dwordx2 v[152:153], v[154:155], off
	v_cvt_pk_bf16_f32 v154, v95, v87
	v_cvt_pk_bf16_f32 v155, v79, v71
	global_store_dwordx2 v[152:153], v[154:155], off offset:16
	v_lshl_add_u64 v[152:153], v[150:151], 0, s[6:7]
	s_mov_b32 s6, 0x200000
	v_add_co_u32_e32 v156, vcc, s6, v150
	v_cvt_pk_bf16_f32 v154, v60, v52
	v_cvt_pk_bf16_f32 v155, v44, v36
	s_mov_b64 s[6:7], 0x204000
	s_nop 0
	v_addc_co_u32_e32 v157, vcc, 0, v151, vcc
	global_store_dwordx2 v[156:157], v[154:155], off
	v_cvt_pk_bf16_f32 v154, v28, v20
	v_cvt_pk_bf16_f32 v155, v12, v4
	global_store_dwordx2 v[152:153], v[154:155], off offset:16
	v_lshl_add_u64 v[152:153], v[150:151], 0, s[6:7]
	s_mov_b32 s6, 0x204000
	v_add_co_u32_e32 v156, vcc, s6, v150
	v_cvt_pk_bf16_f32 v154, v61, v53
	v_cvt_pk_bf16_f32 v155, v45, v37
	s_mov_b64 s[6:7], 0x208000
	s_nop 0
	v_addc_co_u32_e32 v157, vcc, 0, v151, vcc
	global_store_dwordx2 v[156:157], v[154:155], off
	v_cvt_pk_bf16_f32 v154, v29, v21
	v_cvt_pk_bf16_f32 v155, v13, v5
	global_store_dwordx2 v[152:153], v[154:155], off offset:16
; __device__ __forceinline__ unsigned cvt_pk_bf16(float lo, float hi) { unsigned r; asm volatile("v_cvt_pk_bf16_f32 %0, %1, %2" : "=v"(r) : "v"(lo), "v"(hi)); return r; }
; __device__ __forceinline__ unsigned short f2bf1(float f) { return (unsigned short)(cvt_pk_bf16(f, 0.f) & 0xffffu); }
;     __device__ __forceinline__ void operator()(const pg8::f32x4 (&acc)[2][2][4][2], const pg8::Unit& u, int wr, int wc, int fr, int fq) const {
;     ...
;                         for (int j = 0; j < 4; ++j) { const int ch = bj * HALF + c8 + 4 * n + j;
; #pragma unroll
;                             for (int ai = 0; ai < 2; ++ai) { u32x2 w; w.x = cvt_pk_bf16(acc[ai][bj][0][n][j], acc[ai][bj][1][n][j]); w.y = cvt_pk_bf16(acc[ai][bj][2][n][j], acc[ai][bj][3][n][j]);
;                                 *(u32x2*)(base + (size_t)ch * 8192 + 8 * ai) = w; } asm volatile("" ::: "memory"); }
;             } else {
;                 bf16_t* base = GTc + (size_t)b * 256 * 512;
; #pragma unroll
;                 for (int ai = 0; ai < 2; ++ai)
; #pragma unroll
;                     for (int m = 0; m < 4; ++m) { const int s = sbase + ai * HALF + m * 16;
; #pragma unroll
;                         for (int bj = 0; bj < 2; ++bj)
; #pragma unroll
;                             for (int n = 0; n < 2; ++n)
; #pragma unroll
;                                 for (int j = 0; j < 4; ++j) { const int ch = bj * HALF + c8 + 4 * n + j; const bool ity = (ch & 1) && ((ch & 63) != 1);
;                                     base[(size_t)ch * 512 + (ity ? 256 : 0) + s] = f2bf1(acc[ai][bj][m][n][j]); base[(size_t)ch * 512 + (ity ? 0 : 256) + s] = 0; } asm volatile("" ::: "memory"); }
	v_lshl_add_u64 v[152:153], v[150:151], 0, s[6:7]
	s_mov_b32 s6, 0x208000
	v_add_co_u32_e32 v156, vcc, s6, v150
	v_cvt_pk_bf16_f32 v154, v62, v54
	v_cvt_pk_bf16_f32 v155, v46, v38
	s_mov_b64 s[6:7], 0x20c000
	s_nop 0
	v_addc_co_u32_e32 v157, vcc, 0, v151, vcc
	global_store_dwordx2 v[156:157], v[154:155], off
	v_cvt_pk_bf16_f32 v154, v30, v22
	v_cvt_pk_bf16_f32 v155, v14, v6
	global_store_dwordx2 v[152:153], v[154:155], off offset:16
	v_lshl_add_u64 v[152:153], v[150:151], 0, s[6:7]
	s_mov_b32 s6, 0x20c000
	v_add_co_u32_e32 v156, vcc, s6, v150
	v_cvt_pk_bf16_f32 v154, v63, v55
	v_cvt_pk_bf16_f32 v155, v47, v39
	s_mov_b64 s[6:7], 0x210000
	s_nop 0
	v_addc_co_u32_e32 v157, vcc, 0, v151, vcc
	global_store_dwordx2 v[156:157], v[154:155], off
	v_cvt_pk_bf16_f32 v154, v31, v23
	v_cvt_pk_bf16_f32 v155, v15, v7
	global_store_dwordx2 v[152:153], v[154:155], off offset:16
	v_lshl_add_u64 v[152:153], v[150:151], 0, s[6:7]
	s_mov_b32 s6, 0x210000
	v_add_co_u32_e32 v156, vcc, s6, v150
	v_cvt_pk_bf16_f32 v154, v56, v48
	v_cvt_pk_bf16_f32 v155, v40, v32
	s_mov_b64 s[6:7], 0x214000
	s_nop 0
	v_addc_co_u32_e32 v157, vcc, 0, v151, vcc
	global_store_dwordx2 v[156:157], v[154:155], off
	v_cvt_pk_bf16_f32 v154, v24, v16
	v_cvt_pk_bf16_f32 v155, v8, v0
	global_store_dwordx2 v[152:153], v[154:155], off offset:16
	v_lshl_add_u64 v[152:153], v[150:151], 0, s[6:7]
	s_mov_b32 s6, 0x214000
	v_add_co_u32_e32 v156, vcc, s6, v150
	v_cvt_pk_bf16_f32 v154, v57, v49
	v_cvt_pk_bf16_f32 v155, v41, v33
	s_mov_b64 s[6:7], 0x218000
	s_nop 0
	v_addc_co_u32_e32 v157, vcc, 0, v151, vcc
	global_store_dwordx2 v[156:157], v[154:155], off
	v_cvt_pk_bf16_f32 v154, v25, v17
	v_cvt_pk_bf16_f32 v155, v9, v1
	global_store_dwordx2 v[152:153], v[154:155], off offset:16
	v_lshl_add_u64 v[152:153], v[150:151], 0, s[6:7]
	s_mov_b32 s6, 0x218000
	v_add_co_u32_e32 v156, vcc, s6, v150
	v_cvt_pk_bf16_f32 v154, v58, v50
	v_cvt_pk_bf16_f32 v155, v42, v34
	s_mov_b64 s[6:7], 0x21c000
	s_nop 0
	v_addc_co_u32_e32 v157, vcc, 0, v151, vcc
	global_store_dwordx2 v[156:157], v[154:155], off
	v_cvt_pk_bf16_f32 v154, v26, v18
	v_cvt_pk_bf16_f32 v155, v10, v2
	global_store_dwordx2 v[152:153], v[154:155], off offset:16
	v_lshl_add_u64 v[152:153], v[150:151], 0, s[6:7]
	v_add_co_u32_e32 v150, vcc, 0x21c000, v150
	v_cvt_pk_bf16_f32 v154, v59, v51
	v_cvt_pk_bf16_f32 v155, v43, v35
	s_mov_b64 s[6:7], 0
	s_nop 0
	v_addc_co_u32_e32 v151, vcc, 0, v151, vcc
	global_store_dwordx2 v[150:151], v[154:155], off
	v_cvt_pk_bf16_f32 v150, v27, v19
	v_cvt_pk_bf16_f32 v151, v11, v3
	global_store_dwordx2 v[152:153], v[150:151], off offset:16
.LBB0_177:
	s_andn2_b64 vcc, exec, s[6:7]
	s_cbranch_vccnz .LBB0_179
	s_lshl_b64 s[6:7], s[46:47], 18
	s_add_u32 s6, s0, s6
	s_addc_u32 s7, s1, s7
	s_add_u32 s6, s6, 0x2a200000
	v_ashrrev_i32_e32 v143, 31, v142
	s_addc_u32 s7, s7, 0
	v_ashrrev_i32_e32 v145, 31, v144
	v_lshlrev_b64 v[150:151], 10, v[142:143]
	v_lshl_add_u64 v[150:151], s[6:7], 0, v[150:151]
	v_lshlrev_b64 v[172:173], 1, v[144:145]
	v_or_b32_e32 v152, 1, v142
	v_cvt_pk_bf16_f32 v149, v120, v177
	v_lshl_add_u64 v[150:151], v[150:151], 0, v[172:173]
	v_bitop3_b32 v143, v142, 57, 1 bitop3:0xc8
	v_ashrrev_i32_e32 v153, 31, v152
	global_store_short v[150:151], v149, off
	global_store_short v[150:151], v177, off offset:512
	v_cmp_eq_u32_e32 vcc, 1, v143
	v_mov_b32_e32 v149, 0x200
	v_lshlrev_b64 v[152:153], 10, v[152:153]
	v_cndmask_b32_e64 v176, v149, 0, vcc
	v_lshl_add_u64 v[154:155], s[6:7], 0, v[152:153]
	v_or_b32_e32 v156, 2, v142
	v_lshl_add_u64 v[152:153], v[154:155], 0, v[176:177]
	v_cndmask_b32_e32 v176, 0, v149, vcc
	v_ashrrev_i32_e32 v157, 31, v156
	v_or_b32_e32 v158, 3, v142
	v_lshl_add_u64 v[154:155], v[154:155], 0, v[176:177]
	v_lshlrev_b64 v[156:157], 10, v[156:157]
	v_ashrrev_i32_e32 v159, 31, v158
	v_or_b32_e32 v160, 4, v142
	v_lshl_add_u64 v[152:153], v[152:153], 0, v[172:173]
	v_lshl_add_u64 v[154:155], v[154:155], 0, v[172:173]
	v_lshl_add_u64 v[156:157], s[6:7], 0, v[156:157]
	v_lshlrev_b64 v[158:159], 10, v[158:159]
	v_ashrrev_i32_e32 v161, 31, v160
	v_or_b32_e32 v162, 5, v142
	v_cvt_pk_bf16_f32 v145, v121, v177
	global_store_short v[152:153], v145, off
	global_store_short v[154:155], v177, off
	v_cvt_pk_bf16_f32 v143, v122, v177
	v_lshl_add_u64 v[156:157], v[156:157], 0, v[172:173]
	v_lshl_add_u64 v[158:159], s[6:7], 0, v[158:159]
	v_lshlrev_b64 v[160:161], 10, v[160:161]
	v_ashrrev_i32_e32 v163, 31, v162
	v_or_b32_e32 v164, 6, v142
	global_store_short v[156:157], v143, off
	global_store_short v[156:157], v177, off offset:512
	v_cvt_pk_bf16_f32 v143, v123, v177
	v_lshl_add_u64 v[158:159], v[158:159], 0, v[172:173]
	v_lshl_add_u64 v[160:161], s[6:7], 0, v[160:161]
	v_lshlrev_b64 v[162:163], 10, v[162:163]
	v_ashrrev_i32_e32 v165, 31, v164
	v_or_b32_e32 v166, 7, v142
	global_store_short v[158:159], v143, off offset:512
	global_store_short v[158:159], v177, off
	v_cvt_pk_bf16_f32 v143, v124, v177
	v_lshl_add_u64 v[160:161], v[160:161], 0, v[172:173]
	v_lshl_add_u64 v[162:163], s[6:7], 0, v[162:163]
	v_lshlrev_b64 v[164:165], 10, v[164:165]
	v_ashrrev_i32_e32 v167, 31, v166
	global_store_short v[160:161], v143, off
	global_store_short v[160:161], v177, off offset:512
	v_cvt_pk_bf16_f32 v143, v125, v177
	v_lshl_add_u64 v[162:163], v[162:163], 0, v[172:173]
	v_lshl_add_u64 v[164:165], s[6:7], 0, v[164:165]
	v_lshlrev_b64 v[166:167], 10, v[166:167]
	global_store_short v[162:163], v143, off offset:512
	global_store_short v[162:163], v177, off
	v_cvt_pk_bf16_f32 v143, v126, v177
	v_lshl_add_u64 v[164:165], v[164:165], 0, v[172:173]
	v_lshl_add_u64 v[166:167], s[6:7], 0, v[166:167]
	global_store_short v[164:165], v143, off
; __device__ __forceinline__ unsigned short f2bf1(float f) { return (unsigned short)(cvt_pk_bf16(f, 0.f) & 0xffffu); }
;     __device__ __forceinline__ void operator()(const pg8::f32x4 (&acc)[2][2][4][2], const pg8::Unit& u, int wr, int wc, int fr, int fq) const {
;     ...
;                 bf16_t* base = GTc + (size_t)b * 256 * 512;
; #pragma unroll
;                 for (int ai = 0; ai < 2; ++ai)
; #pragma unroll
;                     for (int m = 0; m < 4; ++m) { const int s = sbase + ai * HALF + m * 16;
; #pragma unroll
;                         for (int bj = 0; bj < 2; ++bj)
; #pragma unroll
;                             for (int n = 0; n < 2; ++n)
; #pragma unroll
;                                 for (int j = 0; j < 4; ++j) { const int ch = bj * HALF + c8 + 4 * n + j; const bool ity = (ch & 1) && ((ch & 63) != 1);
;                                     base[(size_t)ch * 512 + (ity ? 256 : 0) + s] = f2bf1(acc[ai][bj][m][n][j]); base[(size_t)ch * 512 + (ity ? 0 : 256) + s] = 0; } asm volatile("" ::: "memory"); }
	global_store_short v[164:165], v177, off offset:512
	v_cvt_pk_bf16_f32 v143, v127, v177
	v_lshl_add_u64 v[166:167], v[166:167], 0, v[172:173]
	v_add_co_u32_e32 v182, vcc, s49, v150
	global_store_short v[166:167], v143, off offset:512
	global_store_short v[166:167], v177, off
	v_cvt_pk_bf16_f32 v143, v60, v177
	s_mov_b64 s[18:19], 0x20000
	v_addc_co_u32_e32 v183, vcc, 0, v151, vcc
	v_add_u32_e32 v170, 0x81, v142
	v_lshl_add_u64 v[168:169], v[150:151], 0, s[18:19]
	global_store_short v[182:183], v143, off
	global_store_short v[168:169], v177, off offset:512
	v_and_b32_e32 v143, 57, v170
	v_ashrrev_i32_e32 v171, 31, v170
	v_cmp_eq_u32_e32 vcc, 1, v143
	v_lshlrev_b64 v[170:171], 10, v[170:171]
	v_lshl_add_u64 v[174:175], s[6:7], 0, v[170:171]
	v_cndmask_b32_e64 v176, v149, 0, vcc
	v_lshl_add_u64 v[170:171], v[174:175], 0, v[176:177]
	v_cndmask_b32_e32 v176, 0, v149, vcc
	v_lshl_add_u64 v[174:175], v[174:175], 0, v[176:177]
	s_mov_b64 s[6:7], 0x20800
	v_lshl_add_u64 v[170:171], v[170:171], 0, v[172:173]
	v_lshl_add_u64 v[172:173], v[174:175], 0, v[172:173]
	v_lshl_add_u64 v[174:175], v[150:151], 0, s[6:7]
	s_mov_b64 s[6:7], 0x20c00
	v_cvt_pk_bf16_f32 v145, v61, v177
	global_store_short v[170:171], v145, off
	global_store_short v[172:173], v177, off
	v_cvt_pk_bf16_f32 v143, v62, v177
	v_lshl_add_u64 v[186:187], v[150:151], 0, s[6:7]
	s_mov_b64 s[6:7], 0x21000
	global_store_short v[182:183], v143, off offset:2048
	global_store_short v[174:175], v177, off offset:512
	v_cvt_pk_bf16_f32 v143, v63, v177
	v_lshl_add_u64 v[188:189], v[150:151], 0, s[6:7]
	s_mov_b32 s6, 0x21000
	global_store_short v[186:187], v143, off offset:512
	global_store_short v[182:183], v177, off offset:3072
	v_add_co_u32_e32 v182, vcc, s6, v150
	v_cvt_pk_bf16_f32 v143, v56, v177
	s_mov_b64 s[6:7], 0x21400
	s_nop 0
	v_addc_co_u32_e32 v183, vcc, 0, v151, vcc
	global_store_short v[182:183], v143, off
	global_store_short v[188:189], v177, off offset:512
	v_cvt_pk_bf16_f32 v143, v57, v177
	v_lshl_add_u64 v[190:191], v[150:151], 0, s[6:7]
	s_mov_b64 s[6:7], 0x21800
	global_store_short v[190:191], v143, off offset:512
	global_store_short v[182:183], v177, off offset:1024
	v_cvt_pk_bf16_f32 v143, v58, v177
	v_lshl_add_u64 v[192:193], v[150:151], 0, s[6:7]
	s_mov_b64 s[6:7], 0x21c00
	global_store_short v[182:183], v143, off offset:2048
	global_store_short v[192:193], v177, off offset:512
	v_cvt_pk_bf16_f32 v143, v59, v177
	v_lshl_add_u64 v[194:195], v[150:151], 0, s[6:7]
	global_store_short v[194:195], v143, off offset:512
	global_store_short v[182:183], v177, off offset:3072
	v_cvt_pk_bf16_f32 v143, v112, v177
	global_store_short v[150:151], v143, off offset:32
	global_store_short v[150:151], v177, off offset:544
	v_cvt_pk_bf16_f32 v143, v113, v177
	global_store_short v[152:153], v143, off offset:32
	global_store_short v[154:155], v177, off offset:32
	v_cvt_pk_bf16_f32 v143, v114, v177
	global_store_short v[156:157], v143, off offset:32
	global_store_short v[156:157], v177, off offset:544
	v_cvt_pk_bf16_f32 v143, v115, v177
	global_store_short v[158:159], v143, off offset:544
	global_store_short v[158:159], v177, off offset:32
	v_cvt_pk_bf16_f32 v143, v116, v177
	global_store_short v[160:161], v143, off offset:32
	global_store_short v[160:161], v177, off offset:544
	v_cvt_pk_bf16_f32 v143, v117, v177
	global_store_short v[162:163], v143, off offset:544
	global_store_short v[162:163], v177, off offset:32
	v_cvt_pk_bf16_f32 v143, v118, v177
	global_store_short v[164:165], v143, off offset:32
	global_store_short v[164:165], v177, off offset:544
	v_cvt_pk_bf16_f32 v143, v119, v177
	global_store_short v[166:167], v143, off offset:544
	global_store_short v[166:167], v177, off offset:32
	v_cvt_pk_bf16_f32 v143, v52, v177
	global_store_short v[168:169], v143, off offset:32
	global_store_short v[168:169], v177, off offset:544
	v_cvt_pk_bf16_f32 v143, v53, v177
	global_store_short v[170:171], v143, off offset:32
	global_store_short v[172:173], v177, off offset:32
	v_cvt_pk_bf16_f32 v143, v54, v177
	global_store_short v[174:175], v143, off offset:32
	global_store_short v[174:175], v177, off offset:544
	v_cvt_pk_bf16_f32 v143, v55, v177
	global_store_short v[186:187], v143, off offset:544
	global_store_short v[186:187], v177, off offset:32
	v_cvt_pk_bf16_f32 v143, v48, v177
	global_store_short v[188:189], v143, off offset:32
	global_store_short v[188:189], v177, off offset:544
	v_cvt_pk_bf16_f32 v143, v49, v177
	global_store_short v[190:191], v143, off offset:544
	global_store_short v[190:191], v177, off offset:32
	v_cvt_pk_bf16_f32 v143, v50, v177
	global_store_short v[192:193], v143, off offset:32
	global_store_short v[192:193], v177, off offset:544
	v_cvt_pk_bf16_f32 v143, v51, v177
	global_store_short v[194:195], v143, off offset:544
	global_store_short v[194:195], v177, off offset:32
	v_cvt_pk_bf16_f32 v143, v104, v177
	global_store_short v[150:151], v143, off offset:64
	global_store_short v[150:151], v177, off offset:576
	v_cvt_pk_bf16_f32 v143, v105, v177
	global_store_short v[152:153], v143, off offset:64
	global_store_short v[154:155], v177, off offset:64
	v_cvt_pk_bf16_f32 v143, v106, v177
	global_store_short v[156:157], v143, off offset:64
	global_store_short v[156:157], v177, off offset:576
	v_cvt_pk_bf16_f32 v143, v107, v177
	global_store_short v[158:159], v143, off offset:576
	global_store_short v[158:159], v177, off offset:64
	v_cvt_pk_bf16_f32 v143, v108, v177
	global_store_short v[160:161], v143, off offset:64
	global_store_short v[160:161], v177, off offset:576
	v_cvt_pk_bf16_f32 v143, v109, v177
	global_store_short v[162:163], v143, off offset:576
; __device__ __forceinline__ unsigned short f2bf1(float f) { return (unsigned short)(cvt_pk_bf16(f, 0.f) & 0xffffu); }
;     __device__ __forceinline__ void operator()(const pg8::f32x4 (&acc)[2][2][4][2], const pg8::Unit& u, int wr, int wc, int fr, int fq) const {
;     ...
;                 bf16_t* base = GTc + (size_t)b * 256 * 512;
; #pragma unroll
;                 for (int ai = 0; ai < 2; ++ai)
; #pragma unroll
;                     for (int m = 0; m < 4; ++m) { const int s = sbase + ai * HALF + m * 16;
; #pragma unroll
;                         for (int bj = 0; bj < 2; ++bj)
; #pragma unroll
;                             for (int n = 0; n < 2; ++n)
; #pragma unroll
;                                 for (int j = 0; j < 4; ++j) { const int ch = bj * HALF + c8 + 4 * n + j; const bool ity = (ch & 1) && ((ch & 63) != 1);
;                                     base[(size_t)ch * 512 + (ity ? 256 : 0) + s] = f2bf1(acc[ai][bj][m][n][j]); base[(size_t)ch * 512 + (ity ? 0 : 256) + s] = 0; } asm volatile("" ::: "memory"); }
	global_store_short v[162:163], v177, off offset:64
	v_cvt_pk_bf16_f32 v143, v110, v177
	global_store_short v[164:165], v143, off offset:64
	global_store_short v[164:165], v177, off offset:576
	v_cvt_pk_bf16_f32 v143, v111, v177
	global_store_short v[166:167], v143, off offset:576
	global_store_short v[166:167], v177, off offset:64
	v_cvt_pk_bf16_f32 v143, v44, v177
	global_store_short v[168:169], v143, off offset:64
	global_store_short v[168:169], v177, off offset:576
	v_cvt_pk_bf16_f32 v143, v45, v177
	global_store_short v[170:171], v143, off offset:64
	global_store_short v[172:173], v177, off offset:64
	v_cvt_pk_bf16_f32 v143, v46, v177
	global_store_short v[174:175], v143, off offset:64
	global_store_short v[174:175], v177, off offset:576
	v_cvt_pk_bf16_f32 v143, v47, v177
	global_store_short v[186:187], v143, off offset:576
	global_store_short v[186:187], v177, off offset:64
	v_cvt_pk_bf16_f32 v143, v40, v177
	global_store_short v[188:189], v143, off offset:64
	global_store_short v[188:189], v177, off offset:576
	v_cvt_pk_bf16_f32 v143, v41, v177
	global_store_short v[190:191], v143, off offset:576
	global_store_short v[190:191], v177, off offset:64
	v_cvt_pk_bf16_f32 v143, v42, v177
	global_store_short v[192:193], v143, off offset:64
	global_store_short v[192:193], v177, off offset:576
	v_cvt_pk_bf16_f32 v143, v43, v177
	global_store_short v[194:195], v143, off offset:576
	global_store_short v[194:195], v177, off offset:64
	v_cvt_pk_bf16_f32 v143, v96, v177
	global_store_short v[150:151], v143, off offset:96
	global_store_short v[150:151], v177, off offset:608
	v_cvt_pk_bf16_f32 v143, v97, v177
	global_store_short v[152:153], v143, off offset:96
	global_store_short v[154:155], v177, off offset:96
	v_cvt_pk_bf16_f32 v143, v98, v177
	global_store_short v[156:157], v143, off offset:96
	global_store_short v[156:157], v177, off offset:608
	v_cvt_pk_bf16_f32 v143, v99, v177
	global_store_short v[158:159], v143, off offset:608
	global_store_short v[158:159], v177, off offset:96
	v_cvt_pk_bf16_f32 v143, v100, v177
	global_store_short v[160:161], v143, off offset:96
	global_store_short v[160:161], v177, off offset:608
	v_cvt_pk_bf16_f32 v143, v101, v177
	global_store_short v[162:163], v143, off offset:608
	global_store_short v[162:163], v177, off offset:96
	v_cvt_pk_bf16_f32 v143, v102, v177
	global_store_short v[164:165], v143, off offset:96
	global_store_short v[164:165], v177, off offset:608
	v_cvt_pk_bf16_f32 v143, v103, v177
	global_store_short v[166:167], v143, off offset:608
	global_store_short v[166:167], v177, off offset:96
	v_cvt_pk_bf16_f32 v143, v36, v177
	global_store_short v[168:169], v143, off offset:96
	global_store_short v[168:169], v177, off offset:608
	v_cvt_pk_bf16_f32 v143, v37, v177
	global_store_short v[170:171], v143, off offset:96
	global_store_short v[172:173], v177, off offset:96
	v_cvt_pk_bf16_f32 v143, v38, v177
	global_store_short v[174:175], v143, off offset:96
	global_store_short v[174:175], v177, off offset:608
	v_cvt_pk_bf16_f32 v143, v39, v177
	global_store_short v[186:187], v143, off offset:608
	global_store_short v[186:187], v177, off offset:96
	v_cvt_pk_bf16_f32 v143, v32, v177
	global_store_short v[188:189], v143, off offset:96
	global_store_short v[188:189], v177, off offset:608
	v_cvt_pk_bf16_f32 v143, v33, v177
	global_store_short v[190:191], v143, off offset:608
	global_store_short v[190:191], v177, off offset:96
	v_cvt_pk_bf16_f32 v143, v34, v177
	global_store_short v[192:193], v143, off offset:96
	global_store_short v[192:193], v177, off offset:608
	v_cvt_pk_bf16_f32 v143, v35, v177
	global_store_short v[194:195], v143, off offset:608
	global_store_short v[194:195], v177, off offset:96
	v_cvt_pk_bf16_f32 v143, v88, v177
	global_store_short v[150:151], v143, off offset:256
	global_store_short v[150:151], v177, off offset:768
	v_cvt_pk_bf16_f32 v143, v89, v177
	global_store_short v[152:153], v143, off offset:256
	global_store_short v[154:155], v177, off offset:256
	v_cvt_pk_bf16_f32 v143, v90, v177
	global_store_short v[156:157], v143, off offset:256
	global_store_short v[156:157], v177, off offset:768
	v_cvt_pk_bf16_f32 v143, v91, v177
	global_store_short v[158:159], v143, off offset:768
	global_store_short v[158:159], v177, off offset:256
	v_cvt_pk_bf16_f32 v143, v92, v177
	global_store_short v[160:161], v143, off offset:256
	global_store_short v[160:161], v177, off offset:768
	v_cvt_pk_bf16_f32 v143, v93, v177
	global_store_short v[162:163], v143, off offset:768
	global_store_short v[162:163], v177, off offset:256
	v_cvt_pk_bf16_f32 v143, v94, v177
	global_store_short v[164:165], v143, off offset:256
	global_store_short v[164:165], v177, off offset:768
	v_cvt_pk_bf16_f32 v143, v95, v177
	global_store_short v[166:167], v143, off offset:768
	global_store_short v[166:167], v177, off offset:256
	v_cvt_pk_bf16_f32 v143, v28, v177
	global_store_short v[168:169], v143, off offset:256
	global_store_short v[168:169], v177, off offset:768
	v_cvt_pk_bf16_f32 v143, v29, v177
	global_store_short v[170:171], v143, off offset:256
	global_store_short v[172:173], v177, off offset:256
	v_cvt_pk_bf16_f32 v143, v30, v177
	global_store_short v[174:175], v143, off offset:256
	global_store_short v[174:175], v177, off offset:768
	v_cvt_pk_bf16_f32 v143, v31, v177
	global_store_short v[186:187], v143, off offset:768
	global_store_short v[186:187], v177, off offset:256
	v_cvt_pk_bf16_f32 v143, v24, v177
	global_store_short v[188:189], v143, off offset:256
	global_store_short v[188:189], v177, off offset:768
	v_cvt_pk_bf16_f32 v143, v25, v177
	global_store_short v[190:191], v143, off offset:768
; __device__ __forceinline__ unsigned short f2bf1(float f) { return (unsigned short)(cvt_pk_bf16(f, 0.f) & 0xffffu); }
;     __device__ __forceinline__ void operator()(const pg8::f32x4 (&acc)[2][2][4][2], const pg8::Unit& u, int wr, int wc, int fr, int fq) const {
;     ...
;                 bf16_t* base = GTc + (size_t)b * 256 * 512;
; #pragma unroll
;                 for (int ai = 0; ai < 2; ++ai)
; #pragma unroll
;                     for (int m = 0; m < 4; ++m) { const int s = sbase + ai * HALF + m * 16;
; #pragma unroll
;                         for (int bj = 0; bj < 2; ++bj)
; #pragma unroll
;                             for (int n = 0; n < 2; ++n)
; #pragma unroll
;                                 for (int j = 0; j < 4; ++j) { const int ch = bj * HALF + c8 + 4 * n + j; const bool ity = (ch & 1) && ((ch & 63) != 1);
;                                     base[(size_t)ch * 512 + (ity ? 256 : 0) + s] = f2bf1(acc[ai][bj][m][n][j]); base[(size_t)ch * 512 + (ity ? 0 : 256) + s] = 0; } asm volatile("" ::: "memory"); }
	global_store_short v[190:191], v177, off offset:256
	v_cvt_pk_bf16_f32 v143, v26, v177
	global_store_short v[192:193], v143, off offset:256
	global_store_short v[192:193], v177, off offset:768
	v_cvt_pk_bf16_f32 v143, v27, v177
	global_store_short v[194:195], v143, off offset:768
	global_store_short v[194:195], v177, off offset:256
	v_cvt_pk_bf16_f32 v143, v80, v177
	global_store_short v[150:151], v143, off offset:288
	global_store_short v[150:151], v177, off offset:800
	v_cvt_pk_bf16_f32 v143, v81, v177
	global_store_short v[152:153], v143, off offset:288
	global_store_short v[154:155], v177, off offset:288
	v_cvt_pk_bf16_f32 v143, v82, v177
	global_store_short v[156:157], v143, off offset:288
	global_store_short v[156:157], v177, off offset:800
	v_cvt_pk_bf16_f32 v143, v83, v177
	global_store_short v[158:159], v143, off offset:800
	global_store_short v[158:159], v177, off offset:288
	v_cvt_pk_bf16_f32 v143, v84, v177
	global_store_short v[160:161], v143, off offset:288
	global_store_short v[160:161], v177, off offset:800
	v_cvt_pk_bf16_f32 v143, v85, v177
	global_store_short v[162:163], v143, off offset:800
	global_store_short v[162:163], v177, off offset:288
	v_cvt_pk_bf16_f32 v143, v86, v177
	global_store_short v[164:165], v143, off offset:288
	global_store_short v[164:165], v177, off offset:800
	v_cvt_pk_bf16_f32 v143, v87, v177
	global_store_short v[166:167], v143, off offset:800
	global_store_short v[166:167], v177, off offset:288
	v_cvt_pk_bf16_f32 v143, v20, v177
	global_store_short v[168:169], v143, off offset:288
	global_store_short v[168:169], v177, off offset:800
	v_cvt_pk_bf16_f32 v143, v21, v177
	global_store_short v[170:171], v143, off offset:288
	global_store_short v[172:173], v177, off offset:288
	v_cvt_pk_bf16_f32 v143, v22, v177
	global_store_short v[174:175], v143, off offset:288
	global_store_short v[174:175], v177, off offset:800
	v_cvt_pk_bf16_f32 v143, v23, v177
	global_store_short v[186:187], v143, off offset:800
	global_store_short v[186:187], v177, off offset:288
	v_cvt_pk_bf16_f32 v143, v16, v177
	global_store_short v[188:189], v143, off offset:288
	global_store_short v[188:189], v177, off offset:800
	v_cvt_pk_bf16_f32 v143, v17, v177
	global_store_short v[190:191], v143, off offset:800
	global_store_short v[190:191], v177, off offset:288
	v_cvt_pk_bf16_f32 v143, v18, v177
	global_store_short v[192:193], v143, off offset:288
	global_store_short v[192:193], v177, off offset:800
	v_cvt_pk_bf16_f32 v143, v19, v177
	global_store_short v[194:195], v143, off offset:800
	global_store_short v[194:195], v177, off offset:288
	v_cvt_pk_bf16_f32 v143, v72, v177
	global_store_short v[150:151], v143, off offset:320
	global_store_short v[150:151], v177, off offset:832
	v_cvt_pk_bf16_f32 v143, v73, v177
	global_store_short v[152:153], v143, off offset:320
	global_store_short v[154:155], v177, off offset:320
	v_cvt_pk_bf16_f32 v143, v74, v177
	global_store_short v[156:157], v143, off offset:320
	global_store_short v[156:157], v177, off offset:832
	v_cvt_pk_bf16_f32 v143, v75, v177
	global_store_short v[158:159], v143, off offset:832
	global_store_short v[158:159], v177, off offset:320
	v_cvt_pk_bf16_f32 v143, v76, v177
	global_store_short v[160:161], v143, off offset:320
	global_store_short v[160:161], v177, off offset:832
	v_cvt_pk_bf16_f32 v143, v77, v177
	global_store_short v[162:163], v143, off offset:832
	global_store_short v[162:163], v177, off offset:320
	v_cvt_pk_bf16_f32 v143, v78, v177
	global_store_short v[164:165], v143, off offset:320
; __device__ __forceinline__ unsigned short f2bf1(float f) { return (unsigned short)(cvt_pk_bf16(f, 0.f) & 0xffffu); }
;     __device__ __forceinline__ void operator()(const pg8::f32x4 (&acc)[2][2][4][2], const pg8::Unit& u, int wr, int wc, int fr, int fq) const {
;     ...
;                 bf16_t* base = GTc + (size_t)b * 256 * 512;
; #pragma unroll
;                 for (int ai = 0; ai < 2; ++ai)
; #pragma unroll
;                     for (int m = 0; m < 4; ++m) { const int s = sbase + ai * HALF + m * 16;
; #pragma unroll
;                         for (int bj = 0; bj < 2; ++bj)
; #pragma unroll
;                             for (int n = 0; n < 2; ++n)
; #pragma unroll
;                                 for (int j = 0; j < 4; ++j) { const int ch = bj * HALF + c8 + 4 * n + j; const bool ity = (ch & 1) && ((ch & 63) != 1);
;                                     base[(size_t)ch * 512 + (ity ? 256 : 0) + s] = f2bf1(acc[ai][bj][m][n][j]); base[(size_t)ch * 512 + (ity ? 0 : 256) + s] = 0; } asm volatile("" ::: "memory"); }
	global_store_short v[164:165], v177, off offset:832
	v_cvt_pk_bf16_f32 v143, v79, v177
	global_store_short v[166:167], v143, off offset:832
	global_store_short v[166:167], v177, off offset:320
	v_cvt_pk_bf16_f32 v143, v12, v177
	global_store_short v[168:169], v143, off offset:320
	global_store_short v[168:169], v177, off offset:832
	v_cvt_pk_bf16_f32 v143, v13, v177
	global_store_short v[170:171], v143, off offset:320
	global_store_short v[172:173], v177, off offset:320
	v_cvt_pk_bf16_f32 v143, v14, v177
	global_store_short v[174:175], v143, off offset:320
	global_store_short v[174:175], v177, off offset:832
	v_cvt_pk_bf16_f32 v143, v15, v177
	global_store_short v[186:187], v143, off offset:832
	global_store_short v[186:187], v177, off offset:320
	v_cvt_pk_bf16_f32 v143, v8, v177
	global_store_short v[188:189], v143, off offset:320
	global_store_short v[188:189], v177, off offset:832
	v_cvt_pk_bf16_f32 v143, v9, v177
	global_store_short v[190:191], v143, off offset:832
	global_store_short v[190:191], v177, off offset:320
	v_cvt_pk_bf16_f32 v143, v10, v177
	global_store_short v[192:193], v143, off offset:320
	global_store_short v[192:193], v177, off offset:832
	v_cvt_pk_bf16_f32 v143, v11, v177
	global_store_short v[194:195], v143, off offset:832
	global_store_short v[194:195], v177, off offset:320
	v_cvt_pk_bf16_f32 v143, v64, v177
	global_store_short v[150:151], v143, off offset:352
	global_store_short v[150:151], v177, off offset:864
	v_cvt_pk_bf16_f32 v143, v65, v177
	global_store_short v[152:153], v143, off offset:352
	global_store_short v[154:155], v177, off offset:352
	v_cvt_pk_bf16_f32 v143, v66, v177
	global_store_short v[156:157], v143, off offset:352
	global_store_short v[156:157], v177, off offset:864
	v_cvt_pk_bf16_f32 v143, v67, v177
	global_store_short v[158:159], v143, off offset:864
	global_store_short v[158:159], v177, off offset:352
	v_cvt_pk_bf16_f32 v143, v68, v177
	global_store_short v[160:161], v143, off offset:352
	global_store_short v[160:161], v177, off offset:864
	v_cvt_pk_bf16_f32 v143, v69, v177
	global_store_short v[162:163], v143, off offset:864
	global_store_short v[162:163], v177, off offset:352
	v_cvt_pk_bf16_f32 v143, v70, v177
	global_store_short v[164:165], v143, off offset:352
	global_store_short v[164:165], v177, off offset:864
	v_cvt_pk_bf16_f32 v143, v71, v177
	global_store_short v[166:167], v143, off offset:864
	global_store_short v[166:167], v177, off offset:352
	v_cvt_pk_bf16_f32 v143, v4, v177
	global_store_short v[168:169], v143, off offset:352
	global_store_short v[168:169], v177, off offset:864
	v_cvt_pk_bf16_f32 v143, v5, v177
	global_store_short v[170:171], v143, off offset:352
	global_store_short v[172:173], v177, off offset:352
	v_cvt_pk_bf16_f32 v143, v6, v177
	global_store_short v[174:175], v143, off offset:352
	global_store_short v[174:175], v177, off offset:864
	v_cvt_pk_bf16_f32 v143, v7, v177
	global_store_short v[186:187], v143, off offset:864
	global_store_short v[186:187], v177, off offset:352
	v_cvt_pk_bf16_f32 v143, v0, v177
	global_store_short v[188:189], v143, off offset:352
	global_store_short v[188:189], v177, off offset:864
	v_cvt_pk_bf16_f32 v143, v1, v177
	global_store_short v[190:191], v143, off offset:864
	global_store_short v[190:191], v177, off offset:352
	v_cvt_pk_bf16_f32 v143, v2, v177
	global_store_short v[192:193], v143, off offset:352
	global_store_short v[192:193], v177, off offset:864
	v_cvt_pk_bf16_f32 v143, v3, v177
	global_store_short v[194:195], v143, off offset:864
	global_store_short v[194:195], v177, off offset:352

; __device__ __forceinline__ unsigned short f2bf1(float f) { return (unsigned short)(cvt_pk_bf16(f, 0.f) & 0xffffu); }
; __device__ __forceinline__ float gelu_tanh(float x) {
;     const float u = 0.7978845608f * (x + 0.044715f * x * x * x);
;     return x * __builtin_amdgcn_rcpf(1.0f + __builtin_amdgcn_exp2f(-2.885390082f * u));
; }
;     __device__ __forceinline__ void operator()(const pg8::f32x4 (&acc)[2][2][4][2], const pg8::Unit& u, int wr, int wc, int fr, int fq) const {
;     ...
;         } else if (pn == 4) {
;             bf16_t* base = isctx ? GVTc + (size_t)b * 256 * 256 : GVT + (size_t)b * 256 * 8192; const int ld = isctx ? 256 : 8192;
; #pragma unroll
;             for (int ai = 0; ai < 2; ++ai)
; #pragma unroll
;                 for (int m = 0; m < 4; ++m) { const int s = sbase + ai * HALF + m * 16;
; #pragma unroll
;                     for (int bj = 0; bj < 2; ++bj)
; #pragma unroll
;                         for (int n = 0; n < 2; ++n)
; #pragma unroll
;                             for (int j = 0; j < 4; ++j) base[(size_t)(bj * HALF + c8 + 4 * n + j) * ld + s] = f2bf1(gelu_tanh(acc[ai][bj][m][n][j])); asm volatile("" ::: "memory"); }
.LBB0_185:
	v_mul_f32_e32 v143, 0x3d372713, v120
	v_mul_f32_e32 v143, v120, v143
	v_fma_f32 v143, v120, v143, v120
	v_mul_f32_e32 v149, 0x3d372713, v121
	v_mul_f32_e32 v143, 0x3f4c422a, v143
	v_mul_f32_e32 v149, v121, v149
	v_mul_f32_e32 v143, 0xc038aa3b, v143
	v_fma_f32 v149, v121, v149, v121
	v_exp_f32_e32 v143, v143
	v_mul_f32_e32 v149, 0x3f4c422a, v149
	v_mul_f32_e32 v149, 0xc038aa3b, v149
	v_exp_f32_e32 v149, v149
	v_add_f32_e32 v143, 1.0, v143
	v_ashrrev_i32_e32 v145, 31, v144
	v_rcp_f32_e32 v143, v143
	v_lshl_add_u64 v[190:191], v[144:145], 1, s[18:19]
	v_add_f32_e32 v145, 1.0, v149
	v_rcp_f32_e32 v145, v145
	v_mul_f32_e32 v143, v120, v143
	v_mad_i64_i32 v[150:151], s[18:19], s6, v142, 0
	v_cvt_pk_bf16_f32 v143, v143, v177
	v_lshl_add_u64 v[152:153], v[150:151], 1, v[190:191]
	v_mul_f32_e32 v149, 0x3d372713, v122
	global_store_short v[152:153], v143, off
	v_mul_f32_e32 v143, v121, v145
	v_or_b32_e32 v145, 1, v142
	v_mul_f32_e32 v149, v122, v149
	v_fma_f32 v149, v122, v149, v122
	v_mad_i64_i32 v[150:151], s[18:19], s6, v145, 0
	v_mul_f32_e32 v145, 0x3d372713, v123
	v_mul_f32_e32 v149, 0x3f4c422a, v149
	v_mul_f32_e32 v145, v123, v145
	v_mul_f32_e32 v149, 0xc038aa3b, v149
	v_fma_f32 v145, v123, v145, v123
	v_exp_f32_e32 v149, v149
	v_mul_f32_e32 v145, 0x3f4c422a, v145
	v_mul_f32_e32 v145, 0xc038aa3b, v145
	v_exp_f32_e32 v145, v145
	v_cvt_pk_bf16_f32 v143, v143, v177
	v_lshl_add_u64 v[150:151], v[150:151], 1, v[190:191]
	global_store_short v[150:151], v143, off
	v_add_f32_e32 v143, 1.0, v149
	v_rcp_f32_e32 v143, v143
	v_add_f32_e32 v145, 1.0, v145
	v_rcp_f32_e32 v145, v145
	v_or_b32_e32 v149, 2, v142
	v_mul_f32_e32 v143, v122, v143
	v_mad_i64_i32 v[154:155], s[18:19], s6, v149, 0
	v_cvt_pk_bf16_f32 v143, v143, v177
	v_lshl_add_u64 v[156:157], v[154:155], 1, v[190:191]
	v_mul_f32_e32 v149, 0x3d372713, v124
	global_store_short v[156:157], v143, off
	v_mul_f32_e32 v143, v123, v145
	v_or_b32_e32 v145, 3, v142
	v_mul_f32_e32 v149, v124, v149
	v_fma_f32 v149, v124, v149, v124
	v_mad_i64_i32 v[154:155], s[18:19], s6, v145, 0
	v_mul_f32_e32 v145, 0x3d372713, v125
	v_mul_f32_e32 v149, 0x3f4c422a, v149
	v_mul_f32_e32 v145, v125, v145
	v_mul_f32_e32 v149, 0xc038aa3b, v149
	v_fma_f32 v145, v125, v145, v125
	v_exp_f32_e32 v149, v149
	v_mul_f32_e32 v145, 0x3f4c422a, v145
	v_mul_f32_e32 v145, 0xc038aa3b, v145
	v_exp_f32_e32 v145, v145
	v_cvt_pk_bf16_f32 v143, v143, v177
	v_lshl_add_u64 v[154:155], v[154:155], 1, v[190:191]
	global_store_short v[154:155], v143, off
	v_add_f32_e32 v143, 1.0, v149
	v_rcp_f32_e32 v143, v143
	v_add_f32_e32 v145, 1.0, v145
	v_rcp_f32_e32 v145, v145
	v_or_b32_e32 v149, 4, v142
	v_mul_f32_e32 v143, v124, v143
	v_mad_i64_i32 v[158:159], s[18:19], s6, v149, 0
	v_cvt_pk_bf16_f32 v143, v143, v177
	v_lshl_add_u64 v[160:161], v[158:159], 1, v[190:191]
	v_mul_f32_e32 v149, 0x3d372713, v126
	global_store_short v[160:161], v143, off
	v_mul_f32_e32 v143, v125, v145
	v_or_b32_e32 v145, 5, v142
	v_mul_f32_e32 v149, v126, v149
	v_fma_f32 v149, v126, v149, v126
	v_mad_i64_i32 v[158:159], s[18:19], s6, v145, 0
	v_mul_f32_e32 v145, 0x3d372713, v127
	v_mul_f32_e32 v149, 0x3f4c422a, v149
	v_mul_f32_e32 v145, v127, v145
	v_mul_f32_e32 v149, 0xc038aa3b, v149
	v_fma_f32 v145, v127, v145, v127
	v_exp_f32_e32 v149, v149
	v_mul_f32_e32 v145, 0x3f4c422a, v145
	v_mul_f32_e32 v145, 0xc038aa3b, v145
	v_exp_f32_e32 v145, v145
	v_cvt_pk_bf16_f32 v143, v143, v177
	v_lshl_add_u64 v[158:159], v[158:159], 1, v[190:191]
	global_store_short v[158:159], v143, off
	v_add_f32_e32 v143, 1.0, v149
	v_rcp_f32_e32 v143, v143
	v_add_f32_e32 v145, 1.0, v145
	v_rcp_f32_e32 v145, v145
	v_or_b32_e32 v149, 6, v142
	v_mul_f32_e32 v143, v126, v143
	v_mad_i64_i32 v[162:163], s[18:19], s6, v149, 0
	v_cvt_pk_bf16_f32 v143, v143, v177
	v_lshl_add_u64 v[164:165], v[162:163], 1, v[190:191]
	v_mul_f32_e32 v149, 0x3d372713, v60
	global_store_short v[164:165], v143, off
	v_mul_f32_e32 v143, v127, v145
	v_or_b32_e32 v145, 7, v142
	v_mul_f32_e32 v149, v60, v149
	v_fma_f32 v149, v60, v149, v60
	v_mad_i64_i32 v[162:163], s[18:19], s6, v145, 0
	v_mul_f32_e32 v145, 0x3d372713, v61
	v_mul_f32_e32 v149, 0x3f4c422a, v149
	v_mul_f32_e32 v145, v61, v145
	v_mul_f32_e32 v149, 0xc038aa3b, v149
	v_fma_f32 v145, v61, v145, v61
	v_exp_f32_e32 v149, v149
	v_mul_f32_e32 v145, 0x3f4c422a, v145
	v_mul_f32_e32 v145, 0xc038aa3b, v145
	v_exp_f32_e32 v145, v145
	v_cvt_pk_bf16_f32 v143, v143, v177
	v_lshl_add_u64 v[162:163], v[162:163], 1, v[190:191]
	global_store_short v[162:163], v143, off
	v_add_f32_e32 v143, 1.0, v149
	v_rcp_f32_e32 v143, v143
	v_add_f32_e32 v145, 1.0, v145
	v_rcp_f32_e32 v145, v145
	v_add_u32_e32 v149, 0x80, v142
	v_mul_f32_e32 v143, v60, v143
	v_mad_i64_i32 v[166:167], s[18:19], s6, v149, 0
	v_cvt_pk_bf16_f32 v143, v143, v177
	v_lshl_add_u64 v[168:169], v[166:167], 1, v[190:191]
	v_mul_f32_e32 v149, 0x3d372713, v62
	global_store_short v[168:169], v143, off
	v_mul_f32_e32 v143, v61, v145
	v_add_u32_e32 v145, 0x81, v142
	v_mul_f32_e32 v149, v62, v149
	v_fma_f32 v149, v62, v149, v62
	v_mad_i64_i32 v[166:167], s[18:19], s6, v145, 0
	v_mul_f32_e32 v145, 0x3d372713, v63
	v_mul_f32_e32 v149, 0x3f4c422a, v149
	v_mul_f32_e32 v145, v63, v145
	v_mul_f32_e32 v149, 0xc038aa3b, v149
	v_fma_f32 v145, v63, v145, v63
	v_exp_f32_e32 v149, v149
	v_mul_f32_e32 v145, 0x3f4c422a, v145
	v_mul_f32_e32 v145, 0xc038aa3b, v145
	v_exp_f32_e32 v145, v145
	v_cvt_pk_bf16_f32 v143, v143, v177
	v_lshl_add_u64 v[166:167], v[166:167], 1, v[190:191]
	global_store_short v[166:167], v143, off
	v_add_f32_e32 v143, 1.0, v149
	v_rcp_f32_e32 v143, v143
	v_add_f32_e32 v145, 1.0, v145
	v_rcp_f32_e32 v145, v145
; __device__ __forceinline__ unsigned short f2bf1(float f) { return (unsigned short)(cvt_pk_bf16(f, 0.f) & 0xffffu); }
; __device__ __forceinline__ float gelu_tanh(float x) {
;     const float u = 0.7978845608f * (x + 0.044715f * x * x * x);
;     return x * __builtin_amdgcn_rcpf(1.0f + __builtin_amdgcn_exp2f(-2.885390082f * u));
; }
;     __device__ __forceinline__ void operator()(const pg8::f32x4 (&acc)[2][2][4][2], const pg8::Unit& u, int wr, int wc, int fr, int fq) const {
;     ...
;         } else if (pn == 4) {
;             bf16_t* base = isctx ? GVTc + (size_t)b * 256 * 256 : GVT + (size_t)b * 256 * 8192; const int ld = isctx ? 256 : 8192;
; #pragma unroll
;             for (int ai = 0; ai < 2; ++ai)
; #pragma unroll
;                 for (int m = 0; m < 4; ++m) { const int s = sbase + ai * HALF + m * 16;
; #pragma unroll
;                     for (int bj = 0; bj < 2; ++bj)
; #pragma unroll
;                         for (int n = 0; n < 2; ++n)
; #pragma unroll
;                             for (int j = 0; j < 4; ++j) base[(size_t)(bj * HALF + c8 + 4 * n + j) * ld + s] = f2bf1(gelu_tanh(acc[ai][bj][m][n][j])); asm volatile("" ::: "memory"); }
	v_add_u32_e32 v149, 0x82, v142
	v_mul_f32_e32 v143, v62, v143
	v_mad_i64_i32 v[170:171], s[18:19], s6, v149, 0
	v_cvt_pk_bf16_f32 v143, v143, v177
	v_lshl_add_u64 v[172:173], v[170:171], 1, v[190:191]
	v_mul_f32_e32 v149, 0x3d372713, v56
	global_store_short v[172:173], v143, off
	v_mul_f32_e32 v143, v63, v145
	v_add_u32_e32 v145, 0x83, v142
	v_mul_f32_e32 v149, v56, v149
	v_fma_f32 v149, v56, v149, v56
	v_mad_i64_i32 v[170:171], s[18:19], s6, v145, 0
	v_mul_f32_e32 v145, 0x3d372713, v57
	v_mul_f32_e32 v149, 0x3f4c422a, v149
	v_mul_f32_e32 v145, v57, v145
	v_mul_f32_e32 v149, 0xc038aa3b, v149
	v_fma_f32 v145, v57, v145, v57
	v_exp_f32_e32 v149, v149
	v_mul_f32_e32 v145, 0x3f4c422a, v145
	v_mul_f32_e32 v145, 0xc038aa3b, v145
	v_exp_f32_e32 v145, v145
	v_cvt_pk_bf16_f32 v143, v143, v177
	v_lshl_add_u64 v[170:171], v[170:171], 1, v[190:191]
	global_store_short v[170:171], v143, off
	v_add_f32_e32 v143, 1.0, v149
	v_rcp_f32_e32 v143, v143
	v_add_f32_e32 v145, 1.0, v145
	v_rcp_f32_e32 v145, v145
	v_add_u32_e32 v149, 0x84, v142
	v_mul_f32_e32 v143, v56, v143
	v_mad_i64_i32 v[174:175], s[18:19], s6, v149, 0
	v_cvt_pk_bf16_f32 v143, v143, v177
	v_lshl_add_u64 v[186:187], v[174:175], 1, v[190:191]
	v_mul_f32_e32 v149, 0x3d372713, v58
	global_store_short v[186:187], v143, off
	v_mul_f32_e32 v143, v57, v145
	v_add_u32_e32 v145, 0x85, v142
	v_mul_f32_e32 v149, v58, v149
	v_fma_f32 v149, v58, v149, v58
	v_mad_i64_i32 v[174:175], s[18:19], s6, v145, 0
	v_mul_f32_e32 v145, 0x3d372713, v59
	v_mul_f32_e32 v149, 0x3f4c422a, v149
	v_mul_f32_e32 v145, v59, v145
	v_mul_f32_e32 v149, 0xc038aa3b, v149
	v_fma_f32 v145, v59, v145, v59
	v_exp_f32_e32 v149, v149
	v_mul_f32_e32 v145, 0x3f4c422a, v145
	v_mul_f32_e32 v145, 0xc038aa3b, v145
	v_exp_f32_e32 v145, v145
	v_cvt_pk_bf16_f32 v143, v143, v177
	v_lshl_add_u64 v[174:175], v[174:175], 1, v[190:191]
	global_store_short v[174:175], v143, off
	v_add_f32_e32 v143, 1.0, v149
	v_rcp_f32_e32 v143, v143
	v_add_f32_e32 v145, 1.0, v145
	v_rcp_f32_e32 v145, v145
	v_add_u32_e32 v149, 0x86, v142
	v_mul_f32_e32 v143, v58, v143
	v_mad_i64_i32 v[182:183], s[18:19], s6, v149, 0
	v_cvt_pk_bf16_f32 v143, v143, v177
	v_lshl_add_u64 v[188:189], v[182:183], 1, v[190:191]
	global_store_short v[188:189], v143, off
	v_mul_f32_e32 v143, v59, v145
	v_add_u32_e32 v145, 0x87, v142
	v_mad_i64_i32 v[182:183], s[6:7], s6, v145, 0
	v_cvt_pk_bf16_f32 v143, v143, v177
	v_lshl_add_u64 v[190:191], v[182:183], 1, v[190:191]
	global_store_short v[190:191], v143, off
	v_mul_f32_e32 v143, 0x3d372713, v112
	v_mul_f32_e32 v143, v112, v143
	v_fma_f32 v143, v112, v143, v112
	v_mul_f32_e32 v145, 0x3d372713, v113
	v_mul_f32_e32 v143, 0x3f4c422a, v143
	v_mul_f32_e32 v145, v113, v145
	v_mul_f32_e32 v143, 0xc038aa3b, v143
	v_fma_f32 v145, v113, v145, v113
	v_exp_f32_e32 v143, v143
	v_mul_f32_e32 v145, 0x3f4c422a, v145
	v_mul_f32_e32 v145, 0xc038aa3b, v145
	v_exp_f32_e32 v145, v145
	v_add_f32_e32 v143, 1.0, v143
	v_rcp_f32_e32 v143, v143
	v_add_f32_e32 v145, 1.0, v145
	v_rcp_f32_e32 v145, v145
	v_mul_f32_e32 v143, v112, v143
	v_cvt_pk_bf16_f32 v143, v143, v177
	global_store_short v[152:153], v143, off offset:32
	v_mul_f32_e32 v143, v113, v145
	v_mul_f32_e32 v145, 0x3d372713, v114
	v_mul_f32_e32 v145, v114, v145
	v_fma_f32 v145, v114, v145, v114
	v_mul_f32_e32 v145, 0x3f4c422a, v145
	v_mul_f32_e32 v145, 0xc038aa3b, v145
	v_exp_f32_e32 v145, v145
	v_cvt_pk_bf16_f32 v143, v143, v177
	global_store_short v[150:151], v143, off offset:32
	v_mul_f32_e32 v149, 0x3d372713, v115
	v_add_f32_e32 v145, 1.0, v145
	v_rcp_f32_e32 v145, v145
	v_mul_f32_e32 v149, v115, v149
	v_fma_f32 v149, v115, v149, v115
	v_mul_f32_e32 v149, 0x3f4c422a, v149
	v_mul_f32_e32 v145, v114, v145
	v_cvt_pk_bf16_f32 v145, v145, v177
	global_store_short v[156:157], v145, off offset:32
	v_mul_f32_e32 v145, 0x3d372713, v116
	v_mul_f32_e32 v145, v116, v145
	v_fma_f32 v145, v116, v145, v116
	v_mul_f32_e32 v145, 0x3f4c422a, v145
	v_mul_f32_e32 v149, 0xc038aa3b, v149
	v_mul_f32_e32 v145, 0xc038aa3b, v145
	v_exp_f32_e32 v149, v149
	v_exp_f32_e32 v145, v145
	v_add_f32_e32 v143, 1.0, v149
	v_add_f32_e32 v145, 1.0, v145
	v_rcp_f32_e32 v143, v143
	v_rcp_f32_e32 v145, v145
	v_mul_f32_e32 v149, 0x3d372713, v117
	v_mul_f32_e32 v149, v117, v149
	v_mul_f32_e32 v143, v115, v143
	v_mul_f32_e32 v145, v116, v145
	v_cvt_pk_bf16_f32 v143, v143, v177
	global_store_short v[154:155], v143, off offset:32
	v_cvt_pk_bf16_f32 v145, v145, v177
	global_store_short v[160:161], v145, off offset:32
	v_mul_f32_e32 v145, 0x3d372713, v118
	v_mul_f32_e32 v145, v118, v145
	v_fma_f32 v149, v117, v149, v117
	v_fma_f32 v145, v118, v145, v118
	v_mul_f32_e32 v149, 0x3f4c422a, v149
	v_mul_f32_e32 v145, 0x3f4c422a, v145
	v_mul_f32_e32 v149, 0xc038aa3b, v149
	v_mul_f32_e32 v145, 0xc038aa3b, v145
	v_exp_f32_e32 v149, v149
	v_exp_f32_e32 v145, v145
	v_add_f32_e32 v143, 1.0, v149
	v_add_f32_e32 v145, 1.0, v145
	v_rcp_f32_e32 v143, v143
	v_rcp_f32_e32 v145, v145
	v_mul_f32_e32 v149, 0x3d372713, v119
	v_mul_f32_e32 v149, v119, v149
	v_mul_f32_e32 v143, v117, v143
	v_mul_f32_e32 v145, v118, v145
	v_cvt_pk_bf16_f32 v143, v143, v177
	global_store_short v[158:159], v143, off offset:32
	v_cvt_pk_bf16_f32 v145, v145, v177
	global_store_short v[164:165], v145, off offset:32
	v_mul_f32_e32 v145, 0x3d372713, v52
	v_mul_f32_e32 v145, v52, v145
	v_fma_f32 v149, v119, v149, v119
	v_fma_f32 v145, v52, v145, v52
	v_mul_f32_e32 v149, 0x3f4c422a, v149
	v_mul_f32_e32 v145, 0x3f4c422a, v145
	v_mul_f32_e32 v149, 0xc038aa3b, v149
	v_mul_f32_e32 v145, 0xc038aa3b, v145
	v_exp_f32_e32 v149, v149
	v_exp_f32_e32 v145, v145
	v_add_f32_e32 v143, 1.0, v149
	v_add_f32_e32 v145, 1.0, v145
; __device__ __forceinline__ unsigned short f2bf1(float f) { return (unsigned short)(cvt_pk_bf16(f, 0.f) & 0xffffu); }
; __device__ __forceinline__ float gelu_tanh(float x) {
;     const float u = 0.7978845608f * (x + 0.044715f * x * x * x);
;     return x * __builtin_amdgcn_rcpf(1.0f + __builtin_amdgcn_exp2f(-2.885390082f * u));
; }
;     __device__ __forceinline__ void operator()(const pg8::f32x4 (&acc)[2][2][4][2], const pg8::Unit& u, int wr, int wc, int fr, int fq) const {
;     ...
;         } else if (pn == 4) {
;             bf16_t* base = isctx ? GVTc + (size_t)b * 256 * 256 : GVT + (size_t)b * 256 * 8192; const int ld = isctx ? 256 : 8192;
; #pragma unroll
;             for (int ai = 0; ai < 2; ++ai)
; #pragma unroll
;                 for (int m = 0; m < 4; ++m) { const int s = sbase + ai * HALF + m * 16;
; #pragma unroll
;                     for (int bj = 0; bj < 2; ++bj)
; #pragma unroll
;                         for (int n = 0; n < 2; ++n)
; #pragma unroll
;                             for (int j = 0; j < 4; ++j) base[(size_t)(bj * HALF + c8 + 4 * n + j) * ld + s] = f2bf1(gelu_tanh(acc[ai][bj][m][n][j])); asm volatile("" ::: "memory"); }
	v_rcp_f32_e32 v143, v143
	v_rcp_f32_e32 v145, v145
	v_mul_f32_e32 v149, 0x3d372713, v53
	v_mul_f32_e32 v149, v53, v149
	v_mul_f32_e32 v143, v119, v143
	v_mul_f32_e32 v145, v52, v145
	v_cvt_pk_bf16_f32 v143, v143, v177
	global_store_short v[162:163], v143, off offset:32
	v_cvt_pk_bf16_f32 v145, v145, v177
	global_store_short v[168:169], v145, off offset:32
	v_mul_f32_e32 v145, 0x3d372713, v54
	v_mul_f32_e32 v145, v54, v145
	v_fma_f32 v149, v53, v149, v53
	v_fma_f32 v145, v54, v145, v54
	v_mul_f32_e32 v149, 0x3f4c422a, v149
	v_mul_f32_e32 v145, 0x3f4c422a, v145
	v_mul_f32_e32 v149, 0xc038aa3b, v149
	v_mul_f32_e32 v145, 0xc038aa3b, v145
	v_exp_f32_e32 v149, v149
	v_exp_f32_e32 v145, v145
	v_add_f32_e32 v143, 1.0, v149
	v_add_f32_e32 v145, 1.0, v145
	v_rcp_f32_e32 v143, v143
	v_rcp_f32_e32 v145, v145
	v_mul_f32_e32 v149, 0x3d372713, v55
	v_mul_f32_e32 v149, v55, v149
	v_mul_f32_e32 v143, v53, v143
	v_mul_f32_e32 v145, v54, v145
	v_cvt_pk_bf16_f32 v143, v143, v177
	global_store_short v[166:167], v143, off offset:32
	v_cvt_pk_bf16_f32 v145, v145, v177
	v_fma_f32 v149, v55, v149, v55
	global_store_short v[172:173], v145, off offset:32
	v_mul_f32_e32 v145, 0x3d372713, v48
	v_mul_f32_e32 v149, 0x3f4c422a, v149
	v_mul_f32_e32 v145, v48, v145
	v_mul_f32_e32 v149, 0xc038aa3b, v149
	v_fma_f32 v145, v48, v145, v48
	v_exp_f32_e32 v149, v149
	v_mul_f32_e32 v145, 0x3f4c422a, v145
	v_mul_f32_e32 v145, 0xc038aa3b, v145
	v_exp_f32_e32 v145, v145
	v_add_f32_e32 v143, 1.0, v149
	v_mul_f32_e32 v149, 0x3d372713, v49
	v_mul_f32_e32 v149, v49, v149
	v_fma_f32 v149, v49, v149, v49
	v_add_f32_e32 v145, 1.0, v145
	v_rcp_f32_e32 v143, v143
	v_mul_f32_e32 v149, 0x3f4c422a, v149
	v_rcp_f32_e32 v145, v145
	v_mul_f32_e32 v149, 0xc038aa3b, v149
	v_exp_f32_e32 v149, v149
	v_mul_f32_e32 v143, v55, v143
	v_mul_f32_e32 v145, v48, v145
	v_cvt_pk_bf16_f32 v143, v143, v177
	global_store_short v[170:171], v143, off offset:32
	v_cvt_pk_bf16_f32 v145, v145, v177
	v_add_f32_e32 v143, 1.0, v149
	global_store_short v[186:187], v145, off offset:32
	v_mul_f32_e32 v145, 0x3d372713, v50
	v_mul_f32_e32 v149, 0x3d372713, v51
	v_mul_f32_e32 v145, v50, v145
	v_mul_f32_e32 v149, v51, v149
	v_fma_f32 v145, v50, v145, v50
	v_fma_f32 v149, v51, v149, v51
	v_rcp_f32_e32 v143, v143
	v_mul_f32_e32 v145, 0x3f4c422a, v145
	v_mul_f32_e32 v149, 0x3f4c422a, v149
	v_mul_f32_e32 v145, 0xc038aa3b, v145
	v_mul_f32_e32 v149, 0xc038aa3b, v149
	v_exp_f32_e32 v145, v145
	v_exp_f32_e32 v149, v149
	v_mul_f32_e32 v143, v49, v143
	v_cvt_pk_bf16_f32 v143, v143, v177
	v_add_f32_e32 v145, 1.0, v145
	global_store_short v[174:175], v143, off offset:32
	v_add_f32_e32 v143, 1.0, v149
	v_rcp_f32_e32 v145, v145
	v_rcp_f32_e32 v143, v143
	v_mul_f32_e32 v149, 0x3d372713, v107
	v_mul_f32_e32 v149, v107, v149
	v_mul_f32_e32 v145, v50, v145
	v_mul_f32_e32 v143, v51, v143
	v_cvt_pk_bf16_f32 v145, v145, v177
	global_store_short v[188:189], v145, off offset:32
	v_cvt_pk_bf16_f32 v143, v143, v177
	global_store_short v[190:191], v143, off offset:32
	v_mul_f32_e32 v143, 0x3d372713, v104
	v_mul_f32_e32 v143, v104, v143
	v_fma_f32 v143, v104, v143, v104
	v_mul_f32_e32 v145, 0x3d372713, v105
	v_mul_f32_e32 v143, 0x3f4c422a, v143
	v_mul_f32_e32 v145, v105, v145
	v_mul_f32_e32 v143, 0xc038aa3b, v143
	v_fma_f32 v145, v105, v145, v105
	v_exp_f32_e32 v143, v143
	v_mul_f32_e32 v145, 0x3f4c422a, v145
	v_mul_f32_e32 v145, 0xc038aa3b, v145
	v_exp_f32_e32 v145, v145
	v_add_f32_e32 v143, 1.0, v143
	v_rcp_f32_e32 v143, v143
	v_add_f32_e32 v145, 1.0, v145
	v_rcp_f32_e32 v145, v145
	v_mul_f32_e32 v143, v104, v143
	v_cvt_pk_bf16_f32 v143, v143, v177
	global_store_short v[152:153], v143, off offset:64
	v_mul_f32_e32 v143, v105, v145
	v_mul_f32_e32 v145, 0x3d372713, v106
	v_mul_f32_e32 v145, v106, v145
	v_fma_f32 v145, v106, v145, v106
	v_mul_f32_e32 v145, 0x3f4c422a, v145
	v_mul_f32_e32 v145, 0xc038aa3b, v145
	v_exp_f32_e32 v145, v145
	v_cvt_pk_bf16_f32 v143, v143, v177
	global_store_short v[150:151], v143, off offset:64
	v_fma_f32 v149, v107, v149, v107
	v_add_f32_e32 v145, 1.0, v145
	v_rcp_f32_e32 v145, v145
	v_mul_f32_e32 v149, 0x3f4c422a, v149
	v_mul_f32_e32 v149, 0xc038aa3b, v149
	v_exp_f32_e32 v149, v149
	v_mul_f32_e32 v145, v106, v145
	v_cvt_pk_bf16_f32 v145, v145, v177
	global_store_short v[156:157], v145, off offset:64
	v_mul_f32_e32 v145, 0x3d372713, v108
	v_mul_f32_e32 v145, v108, v145
	v_fma_f32 v145, v108, v145, v108
	v_mul_f32_e32 v145, 0x3f4c422a, v145
	v_mul_f32_e32 v145, 0xc038aa3b, v145
	v_exp_f32_e32 v145, v145
	v_add_f32_e32 v143, 1.0, v149
	v_rcp_f32_e32 v143, v143
	v_mul_f32_e32 v149, 0x3d372713, v109
	v_add_f32_e32 v145, 1.0, v145
	v_rcp_f32_e32 v145, v145
	v_mul_f32_e32 v143, v107, v143
	v_cvt_pk_bf16_f32 v143, v143, v177
	global_store_short v[154:155], v143, off offset:64
	v_mul_f32_e32 v145, v108, v145
	v_cvt_pk_bf16_f32 v145, v145, v177
	global_store_short v[160:161], v145, off offset:64
	v_mul_f32_e32 v145, 0x3d372713, v110
	v_mul_f32_e32 v149, v109, v149
	v_mul_f32_e32 v145, v110, v145
	v_fma_f32 v149, v109, v149, v109
	v_fma_f32 v145, v110, v145, v110
	v_mul_f32_e32 v149, 0x3f4c422a, v149
	v_mul_f32_e32 v145, 0x3f4c422a, v145
	v_mul_f32_e32 v149, 0xc038aa3b, v149
	v_mul_f32_e32 v145, 0xc038aa3b, v145
	v_exp_f32_e32 v149, v149
	v_exp_f32_e32 v145, v145
	v_add_f32_e32 v143, 1.0, v149
	v_add_f32_e32 v145, 1.0, v145
	v_rcp_f32_e32 v143, v143
	v_rcp_f32_e32 v145, v145
	v_mul_f32_e32 v149, 0x3d372713, v111
	v_mul_f32_e32 v149, v111, v149
	v_mul_f32_e32 v143, v109, v143
	v_mul_f32_e32 v145, v110, v145
	v_cvt_pk_bf16_f32 v143, v143, v177
	global_store_short v[158:159], v143, off offset:64
	v_cvt_pk_bf16_f32 v145, v145, v177
; __device__ __forceinline__ unsigned short f2bf1(float f) { return (unsigned short)(cvt_pk_bf16(f, 0.f) & 0xffffu); }
; __device__ __forceinline__ float gelu_tanh(float x) {
;     const float u = 0.7978845608f * (x + 0.044715f * x * x * x);
;     return x * __builtin_amdgcn_rcpf(1.0f + __builtin_amdgcn_exp2f(-2.885390082f * u));
; }
;     __device__ __forceinline__ void operator()(const pg8::f32x4 (&acc)[2][2][4][2], const pg8::Unit& u, int wr, int wc, int fr, int fq) const {
;     ...
;         } else if (pn == 4) {
;             bf16_t* base = isctx ? GVTc + (size_t)b * 256 * 256 : GVT + (size_t)b * 256 * 8192; const int ld = isctx ? 256 : 8192;
; #pragma unroll
;             for (int ai = 0; ai < 2; ++ai)
; #pragma unroll
;                 for (int m = 0; m < 4; ++m) { const int s = sbase + ai * HALF + m * 16;
; #pragma unroll
;                     for (int bj = 0; bj < 2; ++bj)
; #pragma unroll
;                         for (int n = 0; n < 2; ++n)
; #pragma unroll
;                             for (int j = 0; j < 4; ++j) base[(size_t)(bj * HALF + c8 + 4 * n + j) * ld + s] = f2bf1(gelu_tanh(acc[ai][bj][m][n][j])); asm volatile("" ::: "memory"); }
	global_store_short v[164:165], v145, off offset:64
	v_mul_f32_e32 v145, 0x3d372713, v44
	v_mul_f32_e32 v145, v44, v145
	v_fma_f32 v149, v111, v149, v111
	v_fma_f32 v145, v44, v145, v44
	v_mul_f32_e32 v149, 0x3f4c422a, v149
	v_mul_f32_e32 v145, 0x3f4c422a, v145
	v_mul_f32_e32 v149, 0xc038aa3b, v149
	v_mul_f32_e32 v145, 0xc038aa3b, v145
	v_exp_f32_e32 v149, v149
	v_exp_f32_e32 v145, v145
	v_add_f32_e32 v143, 1.0, v149
	v_add_f32_e32 v145, 1.0, v145
	v_rcp_f32_e32 v143, v143
	v_rcp_f32_e32 v145, v145
	v_mul_f32_e32 v149, 0x3d372713, v45
	v_mul_f32_e32 v149, v45, v149
	v_mul_f32_e32 v143, v111, v143
	v_mul_f32_e32 v145, v44, v145
	v_cvt_pk_bf16_f32 v143, v143, v177
	global_store_short v[162:163], v143, off offset:64
	v_cvt_pk_bf16_f32 v145, v145, v177
	global_store_short v[168:169], v145, off offset:64
	v_mul_f32_e32 v145, 0x3d372713, v46
	v_mul_f32_e32 v145, v46, v145
	v_fma_f32 v149, v45, v149, v45
	v_fma_f32 v145, v46, v145, v46
	v_mul_f32_e32 v149, 0x3f4c422a, v149
	v_mul_f32_e32 v145, 0x3f4c422a, v145
	v_mul_f32_e32 v149, 0xc038aa3b, v149
	v_mul_f32_e32 v145, 0xc038aa3b, v145
	v_exp_f32_e32 v149, v149
	v_exp_f32_e32 v145, v145
	v_add_f32_e32 v143, 1.0, v149
	v_add_f32_e32 v145, 1.0, v145
	v_rcp_f32_e32 v143, v143
	v_rcp_f32_e32 v145, v145
	v_mul_f32_e32 v149, 0x3d372713, v47
	v_mul_f32_e32 v149, v47, v149
	v_mul_f32_e32 v143, v45, v143
	v_mul_f32_e32 v145, v46, v145
	v_cvt_pk_bf16_f32 v143, v143, v177
	global_store_short v[166:167], v143, off offset:64
	v_cvt_pk_bf16_f32 v145, v145, v177
	v_fma_f32 v149, v47, v149, v47
	global_store_short v[172:173], v145, off offset:64
	v_mul_f32_e32 v145, 0x3d372713, v40
	v_mul_f32_e32 v149, 0x3f4c422a, v149
	v_mul_f32_e32 v145, v40, v145
	v_mul_f32_e32 v149, 0xc038aa3b, v149
	v_fma_f32 v145, v40, v145, v40
	v_exp_f32_e32 v149, v149
	v_mul_f32_e32 v145, 0x3f4c422a, v145
	v_mul_f32_e32 v145, 0xc038aa3b, v145
	v_exp_f32_e32 v145, v145
	v_add_f32_e32 v143, 1.0, v149
	v_mul_f32_e32 v149, 0x3d372713, v41
	v_mul_f32_e32 v149, v41, v149
	v_fma_f32 v149, v41, v149, v41
	v_add_f32_e32 v145, 1.0, v145
	v_rcp_f32_e32 v143, v143
	v_mul_f32_e32 v149, 0x3f4c422a, v149
	v_rcp_f32_e32 v145, v145
	v_mul_f32_e32 v149, 0xc038aa3b, v149
	v_exp_f32_e32 v149, v149
	v_mul_f32_e32 v143, v47, v143
	v_mul_f32_e32 v145, v40, v145
	v_cvt_pk_bf16_f32 v143, v143, v177
	global_store_short v[170:171], v143, off offset:64
	v_cvt_pk_bf16_f32 v145, v145, v177
	v_add_f32_e32 v143, 1.0, v149
	global_store_short v[186:187], v145, off offset:64
	v_mul_f32_e32 v145, 0x3d372713, v42
	v_mul_f32_e32 v149, 0x3d372713, v43
	v_mul_f32_e32 v145, v42, v145
	v_mul_f32_e32 v149, v43, v149
	v_fma_f32 v145, v42, v145, v42
	v_fma_f32 v149, v43, v149, v43
	v_rcp_f32_e32 v143, v143
	v_mul_f32_e32 v145, 0x3f4c422a, v145
	v_mul_f32_e32 v149, 0x3f4c422a, v149
	v_mul_f32_e32 v145, 0xc038aa3b, v145
	v_mul_f32_e32 v149, 0xc038aa3b, v149
	v_exp_f32_e32 v145, v145
	v_exp_f32_e32 v149, v149
	v_mul_f32_e32 v143, v41, v143
	v_cvt_pk_bf16_f32 v143, v143, v177
	v_add_f32_e32 v145, 1.0, v145
	global_store_short v[174:175], v143, off offset:64
	v_add_f32_e32 v143, 1.0, v149
	v_rcp_f32_e32 v145, v145
	v_rcp_f32_e32 v143, v143
	v_mul_f32_e32 v149, 0x3d372713, v99
	v_mul_f32_e32 v149, v99, v149
	v_mul_f32_e32 v145, v42, v145
	v_mul_f32_e32 v143, v43, v143
	v_cvt_pk_bf16_f32 v145, v145, v177
	global_store_short v[188:189], v145, off offset:64
	v_cvt_pk_bf16_f32 v143, v143, v177
	global_store_short v[190:191], v143, off offset:64
	v_mul_f32_e32 v143, 0x3d372713, v96
	v_mul_f32_e32 v143, v96, v143
	v_fma_f32 v143, v96, v143, v96
	v_mul_f32_e32 v145, 0x3d372713, v97
	v_mul_f32_e32 v143, 0x3f4c422a, v143
	v_mul_f32_e32 v145, v97, v145
	v_mul_f32_e32 v143, 0xc038aa3b, v143
	v_fma_f32 v145, v97, v145, v97
	v_exp_f32_e32 v143, v143
	v_mul_f32_e32 v145, 0x3f4c422a, v145
	v_mul_f32_e32 v145, 0xc038aa3b, v145
	v_exp_f32_e32 v145, v145
	v_add_f32_e32 v143, 1.0, v143
	v_rcp_f32_e32 v143, v143
	v_add_f32_e32 v145, 1.0, v145
	v_rcp_f32_e32 v145, v145
	v_mul_f32_e32 v143, v96, v143
	v_cvt_pk_bf16_f32 v143, v143, v177
	global_store_short v[152:153], v143, off offset:96
	v_mul_f32_e32 v143, v97, v145
	v_mul_f32_e32 v145, 0x3d372713, v98
	v_mul_f32_e32 v145, v98, v145
	v_fma_f32 v145, v98, v145, v98
	v_mul_f32_e32 v145, 0x3f4c422a, v145
	v_mul_f32_e32 v145, 0xc038aa3b, v145
	v_exp_f32_e32 v145, v145
	v_cvt_pk_bf16_f32 v143, v143, v177
	global_store_short v[150:151], v143, off offset:96
	v_fma_f32 v149, v99, v149, v99
	v_add_f32_e32 v145, 1.0, v145
	v_rcp_f32_e32 v145, v145
	v_mul_f32_e32 v149, 0x3f4c422a, v149
	v_mul_f32_e32 v149, 0xc038aa3b, v149
	v_exp_f32_e32 v149, v149
	v_mul_f32_e32 v145, v98, v145
	v_cvt_pk_bf16_f32 v145, v145, v177
	global_store_short v[156:157], v145, off offset:96
	v_mul_f32_e32 v145, 0x3d372713, v100
	v_mul_f32_e32 v145, v100, v145
	v_fma_f32 v145, v100, v145, v100
	v_mul_f32_e32 v145, 0x3f4c422a, v145
	v_mul_f32_e32 v145, 0xc038aa3b, v145
	v_exp_f32_e32 v145, v145
	v_add_f32_e32 v143, 1.0, v149
	v_rcp_f32_e32 v143, v143
	v_mul_f32_e32 v149, 0x3d372713, v101
	v_add_f32_e32 v145, 1.0, v145
	v_rcp_f32_e32 v145, v145
	v_mul_f32_e32 v143, v99, v143
	v_cvt_pk_bf16_f32 v143, v143, v177
	global_store_short v[154:155], v143, off offset:96
	v_mul_f32_e32 v145, v100, v145
	v_cvt_pk_bf16_f32 v145, v145, v177
	global_store_short v[160:161], v145, off offset:96
	v_mul_f32_e32 v145, 0x3d372713, v102
	v_mul_f32_e32 v149, v101, v149
	v_mul_f32_e32 v145, v102, v145
	v_fma_f32 v149, v101, v149, v101
	v_fma_f32 v145, v102, v145, v102
	v_mul_f32_e32 v149, 0x3f4c422a, v149
	v_mul_f32_e32 v145, 0x3f4c422a, v145
	v_mul_f32_e32 v149, 0xc038aa3b, v149
	v_mul_f32_e32 v145, 0xc038aa3b, v145
; __device__ __forceinline__ unsigned short f2bf1(float f) { return (unsigned short)(cvt_pk_bf16(f, 0.f) & 0xffffu); }
; __device__ __forceinline__ float gelu_tanh(float x) {
;     const float u = 0.7978845608f * (x + 0.044715f * x * x * x);
;     return x * __builtin_amdgcn_rcpf(1.0f + __builtin_amdgcn_exp2f(-2.885390082f * u));
; }
;     __device__ __forceinline__ void operator()(const pg8::f32x4 (&acc)[2][2][4][2], const pg8::Unit& u, int wr, int wc, int fr, int fq) const {
;     ...
;         } else if (pn == 4) {
;             bf16_t* base = isctx ? GVTc + (size_t)b * 256 * 256 : GVT + (size_t)b * 256 * 8192; const int ld = isctx ? 256 : 8192;
; #pragma unroll
;             for (int ai = 0; ai < 2; ++ai)
; #pragma unroll
;                 for (int m = 0; m < 4; ++m) { const int s = sbase + ai * HALF + m * 16;
; #pragma unroll
;                     for (int bj = 0; bj < 2; ++bj)
; #pragma unroll
;                         for (int n = 0; n < 2; ++n)
; #pragma unroll
;                             for (int j = 0; j < 4; ++j) base[(size_t)(bj * HALF + c8 + 4 * n + j) * ld + s] = f2bf1(gelu_tanh(acc[ai][bj][m][n][j])); asm volatile("" ::: "memory"); }
	v_exp_f32_e32 v149, v149
	v_exp_f32_e32 v145, v145
	v_add_f32_e32 v143, 1.0, v149
	v_add_f32_e32 v145, 1.0, v145
	v_rcp_f32_e32 v143, v143
	v_rcp_f32_e32 v145, v145
	v_mul_f32_e32 v149, 0x3d372713, v103
	v_mul_f32_e32 v149, v103, v149
	v_mul_f32_e32 v143, v101, v143
	v_mul_f32_e32 v145, v102, v145
	v_cvt_pk_bf16_f32 v143, v143, v177
	global_store_short v[158:159], v143, off offset:96
	v_cvt_pk_bf16_f32 v145, v145, v177
	global_store_short v[164:165], v145, off offset:96
	v_mul_f32_e32 v145, 0x3d372713, v36
	v_mul_f32_e32 v145, v36, v145
	v_fma_f32 v149, v103, v149, v103
	v_fma_f32 v145, v36, v145, v36
	v_mul_f32_e32 v149, 0x3f4c422a, v149
	v_mul_f32_e32 v145, 0x3f4c422a, v145
	v_mul_f32_e32 v149, 0xc038aa3b, v149
	v_mul_f32_e32 v145, 0xc038aa3b, v145
	v_exp_f32_e32 v149, v149
	v_exp_f32_e32 v145, v145
	v_add_f32_e32 v143, 1.0, v149
	v_add_f32_e32 v145, 1.0, v145
	v_rcp_f32_e32 v143, v143
	v_rcp_f32_e32 v145, v145
	v_mul_f32_e32 v149, 0x3d372713, v37
	v_mul_f32_e32 v149, v37, v149
	v_mul_f32_e32 v143, v103, v143
	v_mul_f32_e32 v145, v36, v145
	v_cvt_pk_bf16_f32 v143, v143, v177
	global_store_short v[162:163], v143, off offset:96
	v_cvt_pk_bf16_f32 v145, v145, v177
	global_store_short v[168:169], v145, off offset:96
	v_mul_f32_e32 v145, 0x3d372713, v38
	v_mul_f32_e32 v145, v38, v145
	v_fma_f32 v149, v37, v149, v37
	v_fma_f32 v145, v38, v145, v38
	v_mul_f32_e32 v149, 0x3f4c422a, v149
	v_mul_f32_e32 v145, 0x3f4c422a, v145
	v_mul_f32_e32 v149, 0xc038aa3b, v149
	v_mul_f32_e32 v145, 0xc038aa3b, v145
	v_exp_f32_e32 v149, v149
	v_exp_f32_e32 v145, v145
	v_add_f32_e32 v143, 1.0, v149
	v_add_f32_e32 v145, 1.0, v145
	v_rcp_f32_e32 v143, v143
	v_rcp_f32_e32 v145, v145
	v_mul_f32_e32 v149, 0x3d372713, v39
	v_mul_f32_e32 v149, v39, v149
	v_mul_f32_e32 v143, v37, v143
	v_mul_f32_e32 v145, v38, v145
	v_cvt_pk_bf16_f32 v143, v143, v177
	global_store_short v[166:167], v143, off offset:96
	v_cvt_pk_bf16_f32 v145, v145, v177
	v_fma_f32 v149, v39, v149, v39
	global_store_short v[172:173], v145, off offset:96
	v_mul_f32_e32 v145, 0x3d372713, v32
	v_mul_f32_e32 v149, 0x3f4c422a, v149
	v_mul_f32_e32 v145, v32, v145
	v_mul_f32_e32 v149, 0xc038aa3b, v149
	v_fma_f32 v145, v32, v145, v32
	v_exp_f32_e32 v149, v149
	v_mul_f32_e32 v145, 0x3f4c422a, v145
	v_mul_f32_e32 v145, 0xc038aa3b, v145
	v_exp_f32_e32 v145, v145
	v_add_f32_e32 v143, 1.0, v149
	v_mul_f32_e32 v149, 0x3d372713, v33
	v_mul_f32_e32 v149, v33, v149
	v_fma_f32 v149, v33, v149, v33
	v_add_f32_e32 v145, 1.0, v145
	v_rcp_f32_e32 v143, v143
	v_mul_f32_e32 v149, 0x3f4c422a, v149
	v_rcp_f32_e32 v145, v145
	v_mul_f32_e32 v149, 0xc038aa3b, v149
	v_exp_f32_e32 v149, v149
	v_mul_f32_e32 v143, v39, v143
	v_mul_f32_e32 v145, v32, v145
	v_cvt_pk_bf16_f32 v143, v143, v177
	global_store_short v[170:171], v143, off offset:96
	v_cvt_pk_bf16_f32 v145, v145, v177
	v_add_f32_e32 v143, 1.0, v149
	global_store_short v[186:187], v145, off offset:96
	v_mul_f32_e32 v145, 0x3d372713, v34
	v_mul_f32_e32 v149, 0x3d372713, v35
	v_mul_f32_e32 v145, v34, v145
	v_mul_f32_e32 v149, v35, v149
	v_fma_f32 v145, v34, v145, v34
	v_fma_f32 v149, v35, v149, v35
	v_rcp_f32_e32 v143, v143
	v_mul_f32_e32 v145, 0x3f4c422a, v145
	v_mul_f32_e32 v149, 0x3f4c422a, v149
	v_mul_f32_e32 v145, 0xc038aa3b, v145
	v_mul_f32_e32 v149, 0xc038aa3b, v149
	v_exp_f32_e32 v145, v145
	v_exp_f32_e32 v149, v149
	v_mul_f32_e32 v143, v33, v143
	v_cvt_pk_bf16_f32 v143, v143, v177
	v_add_f32_e32 v145, 1.0, v145
	global_store_short v[174:175], v143, off offset:96
	v_add_f32_e32 v143, 1.0, v149
	v_rcp_f32_e32 v145, v145
	v_rcp_f32_e32 v143, v143
	v_mul_f32_e32 v149, 0x3d372713, v91
	v_mul_f32_e32 v149, v91, v149
	v_mul_f32_e32 v145, v34, v145
	v_mul_f32_e32 v143, v35, v143
	v_cvt_pk_bf16_f32 v145, v145, v177
	global_store_short v[188:189], v145, off offset:96
	v_cvt_pk_bf16_f32 v143, v143, v177
	global_store_short v[190:191], v143, off offset:96
	v_mul_f32_e32 v143, 0x3d372713, v88
	v_mul_f32_e32 v143, v88, v143
	v_fma_f32 v143, v88, v143, v88
	v_mul_f32_e32 v145, 0x3d372713, v89
	v_mul_f32_e32 v143, 0x3f4c422a, v143
	v_mul_f32_e32 v145, v89, v145
	v_mul_f32_e32 v143, 0xc038aa3b, v143
	v_fma_f32 v145, v89, v145, v89
	v_exp_f32_e32 v143, v143
	v_mul_f32_e32 v145, 0x3f4c422a, v145
	v_mul_f32_e32 v145, 0xc038aa3b, v145
	v_exp_f32_e32 v145, v145
	v_add_f32_e32 v143, 1.0, v143
	v_rcp_f32_e32 v143, v143
	v_add_f32_e32 v145, 1.0, v145
	v_rcp_f32_e32 v145, v145
	v_mul_f32_e32 v143, v88, v143
	v_cvt_pk_bf16_f32 v143, v143, v177
	global_store_short v[152:153], v143, off offset:256
	v_mul_f32_e32 v143, v89, v145
	v_mul_f32_e32 v145, 0x3d372713, v90
	v_mul_f32_e32 v145, v90, v145
	v_fma_f32 v145, v90, v145, v90
	v_mul_f32_e32 v145, 0x3f4c422a, v145
	v_mul_f32_e32 v145, 0xc038aa3b, v145
	v_exp_f32_e32 v145, v145
	v_cvt_pk_bf16_f32 v143, v143, v177
	global_store_short v[150:151], v143, off offset:256
	v_fma_f32 v149, v91, v149, v91
	v_add_f32_e32 v145, 1.0, v145
	v_rcp_f32_e32 v145, v145
	v_mul_f32_e32 v149, 0x3f4c422a, v149
	v_mul_f32_e32 v149, 0xc038aa3b, v149
	v_exp_f32_e32 v149, v149
	v_mul_f32_e32 v145, v90, v145
	v_cvt_pk_bf16_f32 v145, v145, v177
	global_store_short v[156:157], v145, off offset:256
	v_mul_f32_e32 v145, 0x3d372713, v92
	v_mul_f32_e32 v145, v92, v145
	v_fma_f32 v145, v92, v145, v92
	v_mul_f32_e32 v145, 0x3f4c422a, v145
	v_mul_f32_e32 v145, 0xc038aa3b, v145
	v_exp_f32_e32 v145, v145
	v_add_f32_e32 v143, 1.0, v149
	v_rcp_f32_e32 v143, v143
	v_mul_f32_e32 v149, 0x3d372713, v93
	v_add_f32_e32 v145, 1.0, v145
	v_rcp_f32_e32 v145, v145
	v_mul_f32_e32 v143, v91, v143
	v_cvt_pk_bf16_f32 v143, v143, v177
	global_store_short v[154:155], v143, off offset:256
; __device__ __forceinline__ unsigned short f2bf1(float f) { return (unsigned short)(cvt_pk_bf16(f, 0.f) & 0xffffu); }
; __device__ __forceinline__ float gelu_tanh(float x) {
;     const float u = 0.7978845608f * (x + 0.044715f * x * x * x);
;     return x * __builtin_amdgcn_rcpf(1.0f + __builtin_amdgcn_exp2f(-2.885390082f * u));
; }
;     __device__ __forceinline__ void operator()(const pg8::f32x4 (&acc)[2][2][4][2], const pg8::Unit& u, int wr, int wc, int fr, int fq) const {
;     ...
;         } else if (pn == 4) {
;             bf16_t* base = isctx ? GVTc + (size_t)b * 256 * 256 : GVT + (size_t)b * 256 * 8192; const int ld = isctx ? 256 : 8192;
; #pragma unroll
;             for (int ai = 0; ai < 2; ++ai)
; #pragma unroll
;                 for (int m = 0; m < 4; ++m) { const int s = sbase + ai * HALF + m * 16;
; #pragma unroll
;                     for (int bj = 0; bj < 2; ++bj)
; #pragma unroll
;                         for (int n = 0; n < 2; ++n)
; #pragma unroll
;                             for (int j = 0; j < 4; ++j) base[(size_t)(bj * HALF + c8 + 4 * n + j) * ld + s] = f2bf1(gelu_tanh(acc[ai][bj][m][n][j])); asm volatile("" ::: "memory"); }
	v_mul_f32_e32 v145, v92, v145
	v_cvt_pk_bf16_f32 v145, v145, v177
	global_store_short v[160:161], v145, off offset:256
	v_mul_f32_e32 v145, 0x3d372713, v94
	v_mul_f32_e32 v149, v93, v149
	v_mul_f32_e32 v145, v94, v145
	v_fma_f32 v149, v93, v149, v93
	v_fma_f32 v145, v94, v145, v94
	v_mul_f32_e32 v149, 0x3f4c422a, v149
	v_mul_f32_e32 v145, 0x3f4c422a, v145
	v_mul_f32_e32 v149, 0xc038aa3b, v149
	v_mul_f32_e32 v145, 0xc038aa3b, v145
	v_exp_f32_e32 v149, v149
	v_exp_f32_e32 v145, v145
	v_add_f32_e32 v143, 1.0, v149
	v_add_f32_e32 v145, 1.0, v145
	v_rcp_f32_e32 v143, v143
	v_rcp_f32_e32 v145, v145
	v_mul_f32_e32 v149, 0x3d372713, v95
	v_mul_f32_e32 v149, v95, v149
	v_mul_f32_e32 v143, v93, v143
	v_mul_f32_e32 v145, v94, v145
	v_cvt_pk_bf16_f32 v143, v143, v177
	global_store_short v[158:159], v143, off offset:256
	v_cvt_pk_bf16_f32 v145, v145, v177
	global_store_short v[164:165], v145, off offset:256
	v_mul_f32_e32 v145, 0x3d372713, v28
	v_mul_f32_e32 v145, v28, v145
	v_fma_f32 v149, v95, v149, v95
	v_fma_f32 v145, v28, v145, v28
	v_mul_f32_e32 v149, 0x3f4c422a, v149
	v_mul_f32_e32 v145, 0x3f4c422a, v145
	v_mul_f32_e32 v149, 0xc038aa3b, v149
	v_mul_f32_e32 v145, 0xc038aa3b, v145
	v_exp_f32_e32 v149, v149
	v_exp_f32_e32 v145, v145
	v_add_f32_e32 v143, 1.0, v149
	v_add_f32_e32 v145, 1.0, v145
	v_rcp_f32_e32 v143, v143
	v_rcp_f32_e32 v145, v145
	v_mul_f32_e32 v149, 0x3d372713, v29
	v_mul_f32_e32 v149, v29, v149
	v_mul_f32_e32 v143, v95, v143
	v_mul_f32_e32 v145, v28, v145
	v_cvt_pk_bf16_f32 v143, v143, v177
	global_store_short v[162:163], v143, off offset:256
	v_cvt_pk_bf16_f32 v145, v145, v177
	global_store_short v[168:169], v145, off offset:256
	v_mul_f32_e32 v145, 0x3d372713, v30
	v_mul_f32_e32 v145, v30, v145
	v_fma_f32 v149, v29, v149, v29
	v_fma_f32 v145, v30, v145, v30
	v_mul_f32_e32 v149, 0x3f4c422a, v149
	v_mul_f32_e32 v145, 0x3f4c422a, v145
	v_mul_f32_e32 v149, 0xc038aa3b, v149
	v_mul_f32_e32 v145, 0xc038aa3b, v145
	v_exp_f32_e32 v149, v149
	v_exp_f32_e32 v145, v145
	v_add_f32_e32 v143, 1.0, v149
	v_add_f32_e32 v145, 1.0, v145
	v_rcp_f32_e32 v143, v143
	v_rcp_f32_e32 v145, v145
	v_mul_f32_e32 v149, 0x3d372713, v31
	v_mul_f32_e32 v149, v31, v149
	v_mul_f32_e32 v143, v29, v143
	v_mul_f32_e32 v145, v30, v145
	v_cvt_pk_bf16_f32 v143, v143, v177
	global_store_short v[166:167], v143, off offset:256
	v_cvt_pk_bf16_f32 v145, v145, v177
	v_fma_f32 v149, v31, v149, v31
	global_store_short v[172:173], v145, off offset:256
	v_mul_f32_e32 v145, 0x3d372713, v24
	v_mul_f32_e32 v149, 0x3f4c422a, v149
	v_mul_f32_e32 v145, v24, v145
	v_mul_f32_e32 v149, 0xc038aa3b, v149
	v_fma_f32 v145, v24, v145, v24
	v_exp_f32_e32 v149, v149
	v_mul_f32_e32 v145, 0x3f4c422a, v145
	v_mul_f32_e32 v145, 0xc038aa3b, v145
	v_exp_f32_e32 v145, v145
	v_add_f32_e32 v143, 1.0, v149
	v_mul_f32_e32 v149, 0x3d372713, v25
	v_mul_f32_e32 v149, v25, v149
	v_fma_f32 v149, v25, v149, v25
	v_add_f32_e32 v145, 1.0, v145
	v_rcp_f32_e32 v143, v143
	v_mul_f32_e32 v149, 0x3f4c422a, v149
	v_rcp_f32_e32 v145, v145
	v_mul_f32_e32 v149, 0xc038aa3b, v149
	v_exp_f32_e32 v149, v149
	v_mul_f32_e32 v143, v31, v143
	v_mul_f32_e32 v145, v24, v145
	v_cvt_pk_bf16_f32 v143, v143, v177
	global_store_short v[170:171], v143, off offset:256
	v_cvt_pk_bf16_f32 v145, v145, v177
	v_add_f32_e32 v143, 1.0, v149
	global_store_short v[186:187], v145, off offset:256
	v_mul_f32_e32 v145, 0x3d372713, v26
	v_mul_f32_e32 v149, 0x3d372713, v27
	v_mul_f32_e32 v145, v26, v145
	v_mul_f32_e32 v149, v27, v149
	v_fma_f32 v145, v26, v145, v26
	v_fma_f32 v149, v27, v149, v27
	v_rcp_f32_e32 v143, v143
	v_mul_f32_e32 v145, 0x3f4c422a, v145
	v_mul_f32_e32 v149, 0x3f4c422a, v149
	v_mul_f32_e32 v145, 0xc038aa3b, v145
	v_mul_f32_e32 v149, 0xc038aa3b, v149
	v_exp_f32_e32 v145, v145
	v_exp_f32_e32 v149, v149
	v_mul_f32_e32 v143, v25, v143
	v_cvt_pk_bf16_f32 v143, v143, v177
	v_add_f32_e32 v145, 1.0, v145
	global_store_short v[174:175], v143, off offset:256
	v_add_f32_e32 v143, 1.0, v149
	v_rcp_f32_e32 v145, v145
	v_rcp_f32_e32 v143, v143
	v_mul_f32_e32 v149, 0x3d372713, v83
	v_mul_f32_e32 v149, v83, v149
	v_mul_f32_e32 v145, v26, v145
	v_mul_f32_e32 v143, v27, v143
	v_cvt_pk_bf16_f32 v145, v145, v177
	global_store_short v[188:189], v145, off offset:256
	v_cvt_pk_bf16_f32 v143, v143, v177
	global_store_short v[190:191], v143, off offset:256
	v_mul_f32_e32 v143, 0x3d372713, v80
	v_mul_f32_e32 v143, v80, v143
	v_fma_f32 v143, v80, v143, v80
	v_mul_f32_e32 v145, 0x3d372713, v81
	v_mul_f32_e32 v143, 0x3f4c422a, v143
	v_mul_f32_e32 v145, v81, v145
	v_mul_f32_e32 v143, 0xc038aa3b, v143
	v_fma_f32 v145, v81, v145, v81
	v_exp_f32_e32 v143, v143
	v_mul_f32_e32 v145, 0x3f4c422a, v145
	v_mul_f32_e32 v145, 0xc038aa3b, v145
	v_exp_f32_e32 v145, v145
	v_add_f32_e32 v143, 1.0, v143
	v_rcp_f32_e32 v143, v143
	v_add_f32_e32 v145, 1.0, v145
	v_rcp_f32_e32 v145, v145
	v_mul_f32_e32 v143, v80, v143
	v_cvt_pk_bf16_f32 v143, v143, v177
	global_store_short v[152:153], v143, off offset:288
	v_mul_f32_e32 v143, v81, v145
	v_mul_f32_e32 v145, 0x3d372713, v82
	v_mul_f32_e32 v145, v82, v145
	v_fma_f32 v145, v82, v145, v82
	v_mul_f32_e32 v145, 0x3f4c422a, v145
	v_mul_f32_e32 v145, 0xc038aa3b, v145
	v_exp_f32_e32 v145, v145
	v_cvt_pk_bf16_f32 v143, v143, v177
	global_store_short v[150:151], v143, off offset:288
	v_fma_f32 v149, v83, v149, v83
	v_add_f32_e32 v145, 1.0, v145
	v_rcp_f32_e32 v145, v145
	v_mul_f32_e32 v149, 0x3f4c422a, v149
	v_mul_f32_e32 v149, 0xc038aa3b, v149
	v_exp_f32_e32 v149, v149
	v_mul_f32_e32 v145, v82, v145
	v_cvt_pk_bf16_f32 v145, v145, v177
	global_store_short v[156:157], v145, off offset:288
	v_mul_f32_e32 v145, 0x3d372713, v84
; __device__ __forceinline__ unsigned short f2bf1(float f) { return (unsigned short)(cvt_pk_bf16(f, 0.f) & 0xffffu); }
; __device__ __forceinline__ float gelu_tanh(float x) {
;     const float u = 0.7978845608f * (x + 0.044715f * x * x * x);
;     return x * __builtin_amdgcn_rcpf(1.0f + __builtin_amdgcn_exp2f(-2.885390082f * u));
; }
;     __device__ __forceinline__ void operator()(const pg8::f32x4 (&acc)[2][2][4][2], const pg8::Unit& u, int wr, int wc, int fr, int fq) const {
;     ...
;         } else if (pn == 4) {
;             bf16_t* base = isctx ? GVTc + (size_t)b * 256 * 256 : GVT + (size_t)b * 256 * 8192; const int ld = isctx ? 256 : 8192;
; #pragma unroll
;             for (int ai = 0; ai < 2; ++ai)
; #pragma unroll
;                 for (int m = 0; m < 4; ++m) { const int s = sbase + ai * HALF + m * 16;
; #pragma unroll
;                     for (int bj = 0; bj < 2; ++bj)
; #pragma unroll
;                         for (int n = 0; n < 2; ++n)
; #pragma unroll
;                             for (int j = 0; j < 4; ++j) base[(size_t)(bj * HALF + c8 + 4 * n + j) * ld + s] = f2bf1(gelu_tanh(acc[ai][bj][m][n][j])); asm volatile("" ::: "memory"); }
	v_mul_f32_e32 v145, v84, v145
	v_fma_f32 v145, v84, v145, v84
	v_mul_f32_e32 v145, 0x3f4c422a, v145
	v_mul_f32_e32 v145, 0xc038aa3b, v145
	v_exp_f32_e32 v145, v145
	v_add_f32_e32 v143, 1.0, v149
	v_rcp_f32_e32 v143, v143
	v_mul_f32_e32 v149, 0x3d372713, v85
	v_add_f32_e32 v145, 1.0, v145
	v_rcp_f32_e32 v145, v145
	v_mul_f32_e32 v143, v83, v143
	v_cvt_pk_bf16_f32 v143, v143, v177
	global_store_short v[154:155], v143, off offset:288
	v_mul_f32_e32 v145, v84, v145
	v_cvt_pk_bf16_f32 v145, v145, v177
	global_store_short v[160:161], v145, off offset:288
	v_mul_f32_e32 v145, 0x3d372713, v86
	v_mul_f32_e32 v149, v85, v149
	v_mul_f32_e32 v145, v86, v145
	v_fma_f32 v149, v85, v149, v85
	v_fma_f32 v145, v86, v145, v86
	v_mul_f32_e32 v149, 0x3f4c422a, v149
	v_mul_f32_e32 v145, 0x3f4c422a, v145
	v_mul_f32_e32 v149, 0xc038aa3b, v149
	v_mul_f32_e32 v145, 0xc038aa3b, v145
	v_exp_f32_e32 v149, v149
	v_exp_f32_e32 v145, v145
	v_add_f32_e32 v143, 1.0, v149
	v_add_f32_e32 v145, 1.0, v145
	v_rcp_f32_e32 v143, v143
	v_rcp_f32_e32 v145, v145
	v_mul_f32_e32 v149, 0x3d372713, v87
	v_mul_f32_e32 v149, v87, v149
	v_mul_f32_e32 v143, v85, v143
	v_mul_f32_e32 v145, v86, v145
	v_cvt_pk_bf16_f32 v143, v143, v177
	global_store_short v[158:159], v143, off offset:288
	v_cvt_pk_bf16_f32 v145, v145, v177
	global_store_short v[164:165], v145, off offset:288
	v_mul_f32_e32 v145, 0x3d372713, v20
	v_mul_f32_e32 v145, v20, v145
	v_fma_f32 v149, v87, v149, v87
	v_fma_f32 v145, v20, v145, v20
	v_mul_f32_e32 v149, 0x3f4c422a, v149
	v_mul_f32_e32 v145, 0x3f4c422a, v145
	v_mul_f32_e32 v149, 0xc038aa3b, v149
	v_mul_f32_e32 v145, 0xc038aa3b, v145
	v_exp_f32_e32 v149, v149
	v_exp_f32_e32 v145, v145
	v_add_f32_e32 v143, 1.0, v149
	v_add_f32_e32 v145, 1.0, v145
	v_rcp_f32_e32 v143, v143
	v_rcp_f32_e32 v145, v145
	v_mul_f32_e32 v149, 0x3d372713, v21
	v_mul_f32_e32 v149, v21, v149
	v_mul_f32_e32 v143, v87, v143
	v_mul_f32_e32 v145, v20, v145
	v_cvt_pk_bf16_f32 v143, v143, v177
	global_store_short v[162:163], v143, off offset:288
	v_cvt_pk_bf16_f32 v145, v145, v177
	global_store_short v[168:169], v145, off offset:288
	v_mul_f32_e32 v145, 0x3d372713, v22
	v_mul_f32_e32 v145, v22, v145
	v_fma_f32 v149, v21, v149, v21
	v_fma_f32 v145, v22, v145, v22
	v_mul_f32_e32 v149, 0x3f4c422a, v149
	v_mul_f32_e32 v145, 0x3f4c422a, v145
	v_mul_f32_e32 v149, 0xc038aa3b, v149
	v_mul_f32_e32 v145, 0xc038aa3b, v145
	v_exp_f32_e32 v149, v149
	v_exp_f32_e32 v145, v145
	v_add_f32_e32 v143, 1.0, v149
	v_add_f32_e32 v145, 1.0, v145
	v_rcp_f32_e32 v143, v143
	v_rcp_f32_e32 v145, v145
	v_mul_f32_e32 v149, 0x3d372713, v23
	v_mul_f32_e32 v149, v23, v149
	v_mul_f32_e32 v143, v21, v143
	v_mul_f32_e32 v145, v22, v145
	v_cvt_pk_bf16_f32 v143, v143, v177
	global_store_short v[166:167], v143, off offset:288
	v_cvt_pk_bf16_f32 v145, v145, v177
	v_fma_f32 v149, v23, v149, v23
	global_store_short v[172:173], v145, off offset:288
	v_mul_f32_e32 v145, 0x3d372713, v16
	v_mul_f32_e32 v149, 0x3f4c422a, v149
	v_mul_f32_e32 v145, v16, v145
	v_mul_f32_e32 v149, 0xc038aa3b, v149
	v_fma_f32 v145, v16, v145, v16
	v_exp_f32_e32 v149, v149
	v_mul_f32_e32 v145, 0x3f4c422a, v145
	v_mul_f32_e32 v145, 0xc038aa3b, v145
	v_exp_f32_e32 v145, v145
	v_add_f32_e32 v143, 1.0, v149
	v_mul_f32_e32 v149, 0x3d372713, v17
	v_mul_f32_e32 v149, v17, v149
	v_fma_f32 v149, v17, v149, v17
	v_add_f32_e32 v145, 1.0, v145
	v_rcp_f32_e32 v143, v143
	v_mul_f32_e32 v149, 0x3f4c422a, v149
	v_rcp_f32_e32 v145, v145
	v_mul_f32_e32 v149, 0xc038aa3b, v149
	v_exp_f32_e32 v149, v149
	v_mul_f32_e32 v143, v23, v143
	v_mul_f32_e32 v145, v16, v145
	v_cvt_pk_bf16_f32 v143, v143, v177
	global_store_short v[170:171], v143, off offset:288
	v_cvt_pk_bf16_f32 v145, v145, v177
	v_add_f32_e32 v143, 1.0, v149
	global_store_short v[186:187], v145, off offset:288
	v_mul_f32_e32 v145, 0x3d372713, v18
	v_mul_f32_e32 v149, 0x3d372713, v19
	v_mul_f32_e32 v145, v18, v145
	v_mul_f32_e32 v149, v19, v149
	v_fma_f32 v145, v18, v145, v18
	v_fma_f32 v149, v19, v149, v19
	v_rcp_f32_e32 v143, v143
	v_mul_f32_e32 v145, 0x3f4c422a, v145
	v_mul_f32_e32 v149, 0x3f4c422a, v149
	v_mul_f32_e32 v145, 0xc038aa3b, v145
	v_mul_f32_e32 v149, 0xc038aa3b, v149
	v_exp_f32_e32 v145, v145
	v_exp_f32_e32 v149, v149
	v_mul_f32_e32 v143, v17, v143
	v_cvt_pk_bf16_f32 v143, v143, v177
	v_add_f32_e32 v145, 1.0, v145
	global_store_short v[174:175], v143, off offset:288
	v_add_f32_e32 v143, 1.0, v149
	v_rcp_f32_e32 v145, v145
	v_rcp_f32_e32 v143, v143
	v_mul_f32_e32 v149, 0x3d372713, v75
	v_mul_f32_e32 v149, v75, v149
	v_mul_f32_e32 v145, v18, v145
	v_mul_f32_e32 v143, v19, v143
	v_cvt_pk_bf16_f32 v145, v145, v177
	global_store_short v[188:189], v145, off offset:288
	v_cvt_pk_bf16_f32 v143, v143, v177
	global_store_short v[190:191], v143, off offset:288
	v_mul_f32_e32 v143, 0x3d372713, v72
	v_mul_f32_e32 v143, v72, v143
	v_fma_f32 v143, v72, v143, v72
	v_mul_f32_e32 v145, 0x3d372713, v73
	v_mul_f32_e32 v143, 0x3f4c422a, v143
	v_mul_f32_e32 v145, v73, v145
	v_mul_f32_e32 v143, 0xc038aa3b, v143
	v_fma_f32 v145, v73, v145, v73
	v_exp_f32_e32 v143, v143
	v_mul_f32_e32 v145, 0x3f4c422a, v145
	v_mul_f32_e32 v145, 0xc038aa3b, v145
	v_exp_f32_e32 v145, v145
	v_add_f32_e32 v143, 1.0, v143
	v_rcp_f32_e32 v143, v143
	v_add_f32_e32 v145, 1.0, v145
	v_rcp_f32_e32 v145, v145
	v_mul_f32_e32 v143, v72, v143
	v_cvt_pk_bf16_f32 v143, v143, v177
	global_store_short v[152:153], v143, off offset:320
	v_mul_f32_e32 v143, v73, v145
	v_mul_f32_e32 v145, 0x3d372713, v74
	v_mul_f32_e32 v145, v74, v145
	v_fma_f32 v145, v74, v145, v74
	v_mul_f32_e32 v145, 0x3f4c422a, v145
	v_mul_f32_e32 v145, 0xc038aa3b, v145
	v_exp_f32_e32 v145, v145
; __device__ __forceinline__ unsigned short f2bf1(float f) { return (unsigned short)(cvt_pk_bf16(f, 0.f) & 0xffffu); }
; __device__ __forceinline__ float gelu_tanh(float x) {
;     const float u = 0.7978845608f * (x + 0.044715f * x * x * x);
;     return x * __builtin_amdgcn_rcpf(1.0f + __builtin_amdgcn_exp2f(-2.885390082f * u));
; }
;     __device__ __forceinline__ void operator()(const pg8::f32x4 (&acc)[2][2][4][2], const pg8::Unit& u, int wr, int wc, int fr, int fq) const {
;     ...
;         } else if (pn == 4) {
;             bf16_t* base = isctx ? GVTc + (size_t)b * 256 * 256 : GVT + (size_t)b * 256 * 8192; const int ld = isctx ? 256 : 8192;
; #pragma unroll
;             for (int ai = 0; ai < 2; ++ai)
; #pragma unroll
;                 for (int m = 0; m < 4; ++m) { const int s = sbase + ai * HALF + m * 16;
; #pragma unroll
;                     for (int bj = 0; bj < 2; ++bj)
; #pragma unroll
;                         for (int n = 0; n < 2; ++n)
; #pragma unroll
;                             for (int j = 0; j < 4; ++j) base[(size_t)(bj * HALF + c8 + 4 * n + j) * ld + s] = f2bf1(gelu_tanh(acc[ai][bj][m][n][j])); asm volatile("" ::: "memory"); }
	v_cvt_pk_bf16_f32 v143, v143, v177
	global_store_short v[150:151], v143, off offset:320
	v_fma_f32 v149, v75, v149, v75
	v_add_f32_e32 v145, 1.0, v145
	v_rcp_f32_e32 v145, v145
	v_mul_f32_e32 v149, 0x3f4c422a, v149
	v_mul_f32_e32 v149, 0xc038aa3b, v149
	v_exp_f32_e32 v149, v149
	v_mul_f32_e32 v145, v74, v145
	v_cvt_pk_bf16_f32 v145, v145, v177
	global_store_short v[156:157], v145, off offset:320
	v_mul_f32_e32 v145, 0x3d372713, v76
	v_mul_f32_e32 v145, v76, v145
	v_fma_f32 v145, v76, v145, v76
	v_mul_f32_e32 v145, 0x3f4c422a, v145
	v_mul_f32_e32 v145, 0xc038aa3b, v145
	v_exp_f32_e32 v145, v145
	v_add_f32_e32 v143, 1.0, v149
	v_rcp_f32_e32 v143, v143
	v_mul_f32_e32 v149, 0x3d372713, v77
	v_add_f32_e32 v145, 1.0, v145
	v_rcp_f32_e32 v145, v145
	v_mul_f32_e32 v143, v75, v143
	v_cvt_pk_bf16_f32 v143, v143, v177
	global_store_short v[154:155], v143, off offset:320
	v_mul_f32_e32 v145, v76, v145
	v_cvt_pk_bf16_f32 v145, v145, v177
	global_store_short v[160:161], v145, off offset:320
	v_mul_f32_e32 v145, 0x3d372713, v78
	v_mul_f32_e32 v149, v77, v149
	v_mul_f32_e32 v145, v78, v145
	v_fma_f32 v149, v77, v149, v77
	v_fma_f32 v145, v78, v145, v78
	v_mul_f32_e32 v149, 0x3f4c422a, v149
	v_mul_f32_e32 v145, 0x3f4c422a, v145
	v_mul_f32_e32 v149, 0xc038aa3b, v149
	v_mul_f32_e32 v145, 0xc038aa3b, v145
	v_exp_f32_e32 v149, v149
	v_exp_f32_e32 v145, v145
	v_add_f32_e32 v143, 1.0, v149
	v_add_f32_e32 v145, 1.0, v145
	v_rcp_f32_e32 v143, v143
	v_rcp_f32_e32 v145, v145
	v_mul_f32_e32 v149, 0x3d372713, v79
	v_mul_f32_e32 v149, v79, v149
	v_mul_f32_e32 v143, v77, v143
	v_mul_f32_e32 v145, v78, v145
	v_cvt_pk_bf16_f32 v143, v143, v177
	global_store_short v[158:159], v143, off offset:320
	v_cvt_pk_bf16_f32 v145, v145, v177
	global_store_short v[164:165], v145, off offset:320
	v_mul_f32_e32 v145, 0x3d372713, v12
	v_mul_f32_e32 v145, v12, v145
	v_fma_f32 v149, v79, v149, v79
	v_fma_f32 v145, v12, v145, v12
	v_mul_f32_e32 v149, 0x3f4c422a, v149
	v_mul_f32_e32 v145, 0x3f4c422a, v145
	v_mul_f32_e32 v149, 0xc038aa3b, v149
	v_mul_f32_e32 v145, 0xc038aa3b, v145
	v_exp_f32_e32 v149, v149
	v_exp_f32_e32 v145, v145
	v_add_f32_e32 v143, 1.0, v149
	v_add_f32_e32 v145, 1.0, v145
	v_rcp_f32_e32 v143, v143
	v_rcp_f32_e32 v145, v145
	v_mul_f32_e32 v149, 0x3d372713, v13
	v_mul_f32_e32 v149, v13, v149
	v_mul_f32_e32 v143, v79, v143
	v_mul_f32_e32 v145, v12, v145
	v_cvt_pk_bf16_f32 v143, v143, v177
	global_store_short v[162:163], v143, off offset:320
	v_cvt_pk_bf16_f32 v145, v145, v177
	global_store_short v[168:169], v145, off offset:320
	v_mul_f32_e32 v145, 0x3d372713, v14
	v_mul_f32_e32 v145, v14, v145
	v_fma_f32 v149, v13, v149, v13
	v_fma_f32 v145, v14, v145, v14
	v_mul_f32_e32 v149, 0x3f4c422a, v149
	v_mul_f32_e32 v145, 0x3f4c422a, v145
	v_mul_f32_e32 v149, 0xc038aa3b, v149
	v_mul_f32_e32 v145, 0xc038aa3b, v145
	v_exp_f32_e32 v149, v149
	v_exp_f32_e32 v145, v145
	v_add_f32_e32 v143, 1.0, v149
	v_add_f32_e32 v145, 1.0, v145
	v_rcp_f32_e32 v143, v143
	v_rcp_f32_e32 v145, v145
	v_mul_f32_e32 v149, 0x3d372713, v15
	v_mul_f32_e32 v149, v15, v149
	v_mul_f32_e32 v143, v13, v143
	v_mul_f32_e32 v145, v14, v145
	v_cvt_pk_bf16_f32 v143, v143, v177
	global_store_short v[166:167], v143, off offset:320
	v_cvt_pk_bf16_f32 v145, v145, v177
	v_fma_f32 v149, v15, v149, v15
	global_store_short v[172:173], v145, off offset:320
	v_mul_f32_e32 v145, 0x3d372713, v8
	v_mul_f32_e32 v149, 0x3f4c422a, v149
	v_mul_f32_e32 v145, v8, v145
	v_mul_f32_e32 v149, 0xc038aa3b, v149
	v_fma_f32 v145, v8, v145, v8
	v_exp_f32_e32 v149, v149
	v_mul_f32_e32 v145, 0x3f4c422a, v145
	v_mul_f32_e32 v145, 0xc038aa3b, v145
	v_exp_f32_e32 v145, v145
	v_add_f32_e32 v143, 1.0, v149
	v_mul_f32_e32 v149, 0x3d372713, v9
	v_mul_f32_e32 v149, v9, v149
	v_fma_f32 v149, v9, v149, v9
	v_add_f32_e32 v145, 1.0, v145
	v_rcp_f32_e32 v143, v143
	v_mul_f32_e32 v149, 0x3f4c422a, v149
	v_rcp_f32_e32 v145, v145
	v_mul_f32_e32 v149, 0xc038aa3b, v149
	v_exp_f32_e32 v149, v149
	v_mul_f32_e32 v143, v15, v143
	v_mul_f32_e32 v145, v8, v145
	v_cvt_pk_bf16_f32 v143, v143, v177
	global_store_short v[170:171], v143, off offset:320
	v_cvt_pk_bf16_f32 v145, v145, v177
	v_add_f32_e32 v143, 1.0, v149
	global_store_short v[186:187], v145, off offset:320
	v_mul_f32_e32 v145, 0x3d372713, v10
	v_mul_f32_e32 v149, 0x3d372713, v11
	v_mul_f32_e32 v145, v10, v145
	v_mul_f32_e32 v149, v11, v149
	v_fma_f32 v145, v10, v145, v10
	v_fma_f32 v149, v11, v149, v11
	v_rcp_f32_e32 v143, v143
	v_mul_f32_e32 v145, 0x3f4c422a, v145
	v_mul_f32_e32 v149, 0x3f4c422a, v149
	v_mul_f32_e32 v145, 0xc038aa3b, v145
	v_mul_f32_e32 v149, 0xc038aa3b, v149
	v_exp_f32_e32 v145, v145
	v_exp_f32_e32 v149, v149
	v_mul_f32_e32 v143, v9, v143
	v_cvt_pk_bf16_f32 v143, v143, v177
	v_add_f32_e32 v145, 1.0, v145
	global_store_short v[174:175], v143, off offset:320
	v_add_f32_e32 v143, 1.0, v149
	v_rcp_f32_e32 v145, v145
	v_rcp_f32_e32 v143, v143
	v_mul_f32_e32 v149, 0x3d372713, v67
	v_mul_f32_e32 v149, v67, v149
	v_mul_f32_e32 v145, v10, v145
	v_mul_f32_e32 v143, v11, v143
	v_cvt_pk_bf16_f32 v145, v145, v177
	global_store_short v[188:189], v145, off offset:320
	v_cvt_pk_bf16_f32 v143, v143, v177
	global_store_short v[190:191], v143, off offset:320
	v_mul_f32_e32 v143, 0x3d372713, v64
	v_mul_f32_e32 v143, v64, v143
	v_fma_f32 v143, v64, v143, v64
	v_mul_f32_e32 v145, 0x3d372713, v65
	v_mul_f32_e32 v143, 0x3f4c422a, v143
	v_mul_f32_e32 v145, v65, v145
	v_mul_f32_e32 v143, 0xc038aa3b, v143
	v_fma_f32 v145, v65, v145, v65
	v_exp_f32_e32 v143, v143
	v_mul_f32_e32 v145, 0x3f4c422a, v145
	v_mul_f32_e32 v145, 0xc038aa3b, v145
; __device__ __forceinline__ unsigned short f2bf1(float f) { return (unsigned short)(cvt_pk_bf16(f, 0.f) & 0xffffu); }
; __device__ __forceinline__ float gelu_tanh(float x) {
;     const float u = 0.7978845608f * (x + 0.044715f * x * x * x);
;     return x * __builtin_amdgcn_rcpf(1.0f + __builtin_amdgcn_exp2f(-2.885390082f * u));
; }
;     __device__ __forceinline__ void operator()(const pg8::f32x4 (&acc)[2][2][4][2], const pg8::Unit& u, int wr, int wc, int fr, int fq) const {
;     ...
;         } else if (pn == 4) {
;             bf16_t* base = isctx ? GVTc + (size_t)b * 256 * 256 : GVT + (size_t)b * 256 * 8192; const int ld = isctx ? 256 : 8192;
; #pragma unroll
;             for (int ai = 0; ai < 2; ++ai)
; #pragma unroll
;                 for (int m = 0; m < 4; ++m) { const int s = sbase + ai * HALF + m * 16;
; #pragma unroll
;                     for (int bj = 0; bj < 2; ++bj)
; #pragma unroll
;                         for (int n = 0; n < 2; ++n)
; #pragma unroll
;                             for (int j = 0; j < 4; ++j) base[(size_t)(bj * HALF + c8 + 4 * n + j) * ld + s] = f2bf1(gelu_tanh(acc[ai][bj][m][n][j])); asm volatile("" ::: "memory"); }
	v_exp_f32_e32 v145, v145
	v_add_f32_e32 v143, 1.0, v143
	v_rcp_f32_e32 v143, v143
	v_add_f32_e32 v145, 1.0, v145
	v_rcp_f32_e32 v145, v145
	v_mul_f32_e32 v143, v64, v143
	v_cvt_pk_bf16_f32 v143, v143, v177
	global_store_short v[152:153], v143, off offset:352
	v_mul_f32_e32 v143, v65, v145
	v_mul_f32_e32 v145, 0x3d372713, v66
	v_mul_f32_e32 v145, v66, v145
	v_fma_f32 v145, v66, v145, v66
	v_mul_f32_e32 v145, 0x3f4c422a, v145
	v_mul_f32_e32 v145, 0xc038aa3b, v145
	v_exp_f32_e32 v145, v145
	v_cvt_pk_bf16_f32 v143, v143, v177
	global_store_short v[150:151], v143, off offset:352
	v_fma_f32 v149, v67, v149, v67
	v_add_f32_e32 v145, 1.0, v145
	v_rcp_f32_e32 v145, v145
	v_mul_f32_e32 v149, 0x3f4c422a, v149
	v_mul_f32_e32 v149, 0xc038aa3b, v149
	v_exp_f32_e32 v149, v149
	v_mul_f32_e32 v145, v66, v145
	v_cvt_pk_bf16_f32 v145, v145, v177
	global_store_short v[156:157], v145, off offset:352
	v_mul_f32_e32 v145, 0x3d372713, v68
	v_mul_f32_e32 v145, v68, v145
	v_fma_f32 v145, v68, v145, v68
	v_mul_f32_e32 v145, 0x3f4c422a, v145
	v_mul_f32_e32 v145, 0xc038aa3b, v145
	v_exp_f32_e32 v145, v145
	v_add_f32_e32 v143, 1.0, v149
	v_rcp_f32_e32 v143, v143
	v_mul_f32_e32 v149, 0x3d372713, v69
	v_add_f32_e32 v145, 1.0, v145
	v_rcp_f32_e32 v145, v145
	v_mul_f32_e32 v143, v67, v143
	v_cvt_pk_bf16_f32 v143, v143, v177
	global_store_short v[154:155], v143, off offset:352
	v_mul_f32_e32 v145, v68, v145
	v_cvt_pk_bf16_f32 v145, v145, v177
	global_store_short v[160:161], v145, off offset:352
	v_mul_f32_e32 v145, 0x3d372713, v70
	v_mul_f32_e32 v149, v69, v149
	v_mul_f32_e32 v145, v70, v145
	v_fma_f32 v149, v69, v149, v69
	v_fma_f32 v145, v70, v145, v70
	v_mul_f32_e32 v149, 0x3f4c422a, v149
	v_mul_f32_e32 v145, 0x3f4c422a, v145
	v_mul_f32_e32 v149, 0xc038aa3b, v149
	v_mul_f32_e32 v145, 0xc038aa3b, v145
	v_exp_f32_e32 v149, v149
	v_exp_f32_e32 v145, v145
	v_add_f32_e32 v143, 1.0, v149
	v_add_f32_e32 v145, 1.0, v145
	v_rcp_f32_e32 v143, v143
	v_rcp_f32_e32 v145, v145
	v_mul_f32_e32 v149, 0x3d372713, v71
	v_mul_f32_e32 v149, v71, v149
	v_mul_f32_e32 v143, v69, v143
	v_mul_f32_e32 v145, v70, v145
	v_cvt_pk_bf16_f32 v143, v143, v177
	global_store_short v[158:159], v143, off offset:352
	v_cvt_pk_bf16_f32 v145, v145, v177
	global_store_short v[164:165], v145, off offset:352
	v_mul_f32_e32 v145, 0x3d372713, v4
	v_mul_f32_e32 v145, v4, v145
	v_fma_f32 v149, v71, v149, v71
	v_fma_f32 v145, v4, v145, v4
	v_mul_f32_e32 v149, 0x3f4c422a, v149
	v_mul_f32_e32 v145, 0x3f4c422a, v145
	v_mul_f32_e32 v149, 0xc038aa3b, v149
	v_mul_f32_e32 v145, 0xc038aa3b, v145
	v_exp_f32_e32 v149, v149
	v_exp_f32_e32 v145, v145
	v_add_f32_e32 v143, 1.0, v149
	v_add_f32_e32 v145, 1.0, v145
	v_rcp_f32_e32 v143, v143
	v_rcp_f32_e32 v145, v145
	v_mul_f32_e32 v149, 0x3d372713, v5
	v_mul_f32_e32 v149, v5, v149
	v_mul_f32_e32 v143, v71, v143
	v_mul_f32_e32 v145, v4, v145
	v_cvt_pk_bf16_f32 v143, v143, v177
	global_store_short v[162:163], v143, off offset:352
	v_cvt_pk_bf16_f32 v145, v145, v177
	global_store_short v[168:169], v145, off offset:352
	v_mul_f32_e32 v145, 0x3d372713, v6
	v_mul_f32_e32 v145, v6, v145
	v_fma_f32 v149, v5, v149, v5
	v_fma_f32 v145, v6, v145, v6
	v_mul_f32_e32 v149, 0x3f4c422a, v149
	v_mul_f32_e32 v145, 0x3f4c422a, v145
	v_mul_f32_e32 v149, 0xc038aa3b, v149
	v_mul_f32_e32 v145, 0xc038aa3b, v145
	v_exp_f32_e32 v149, v149
	v_exp_f32_e32 v145, v145
	v_add_f32_e32 v143, 1.0, v149
	v_add_f32_e32 v145, 1.0, v145
	v_rcp_f32_e32 v143, v143
	v_rcp_f32_e32 v145, v145
	v_mul_f32_e32 v149, 0x3d372713, v7
	v_mul_f32_e32 v149, v7, v149
	v_mul_f32_e32 v143, v5, v143
	v_mul_f32_e32 v145, v6, v145
	v_cvt_pk_bf16_f32 v143, v143, v177
	global_store_short v[166:167], v143, off offset:352
	v_cvt_pk_bf16_f32 v145, v145, v177
	v_fma_f32 v149, v7, v149, v7
	global_store_short v[172:173], v145, off offset:352
	v_mul_f32_e32 v145, 0x3d372713, v0
	v_mul_f32_e32 v149, 0x3f4c422a, v149
	v_mul_f32_e32 v145, v0, v145
	v_mul_f32_e32 v149, 0xc038aa3b, v149
	v_fma_f32 v145, v0, v145, v0
	v_exp_f32_e32 v149, v149
	v_mul_f32_e32 v145, 0x3f4c422a, v145
	v_mul_f32_e32 v145, 0xc038aa3b, v145
	v_exp_f32_e32 v145, v145
	v_add_f32_e32 v143, 1.0, v149
	v_mul_f32_e32 v149, 0x3d372713, v1
	v_mul_f32_e32 v149, v1, v149
	v_fma_f32 v149, v1, v149, v1
	v_add_f32_e32 v145, 1.0, v145
	v_rcp_f32_e32 v143, v143
	v_mul_f32_e32 v149, 0x3f4c422a, v149
	v_rcp_f32_e32 v145, v145
	v_mul_f32_e32 v149, 0xc038aa3b, v149
	v_exp_f32_e32 v149, v149
	v_mul_f32_e32 v143, v7, v143
	v_mul_f32_e32 v145, v0, v145
	v_cvt_pk_bf16_f32 v143, v143, v177
	global_store_short v[170:171], v143, off offset:352
	v_cvt_pk_bf16_f32 v145, v145, v177
	v_add_f32_e32 v143, 1.0, v149
	global_store_short v[186:187], v145, off offset:352
	v_mul_f32_e32 v145, 0x3d372713, v2
	v_mul_f32_e32 v149, 0x3d372713, v3
	v_mul_f32_e32 v145, v2, v145
	v_mul_f32_e32 v149, v3, v149
	v_fma_f32 v145, v2, v145, v2
	v_fma_f32 v149, v3, v149, v3
	v_rcp_f32_e32 v143, v143
	v_mul_f32_e32 v145, 0x3f4c422a, v145
	v_mul_f32_e32 v149, 0x3f4c422a, v149
	v_mul_f32_e32 v145, 0xc038aa3b, v145
	v_mul_f32_e32 v149, 0xc038aa3b, v149
	v_exp_f32_e32 v145, v145
	v_exp_f32_e32 v149, v149
	v_mul_f32_e32 v143, v1, v143
	v_cvt_pk_bf16_f32 v143, v143, v177
	v_add_f32_e32 v145, 1.0, v145
	global_store_short v[174:175], v143, off offset:352
	v_add_f32_e32 v143, 1.0, v149
	v_rcp_f32_e32 v145, v145
	v_rcp_f32_e32 v143, v143
	v_mul_f32_e32 v145, v2, v145
	v_mul_f32_e32 v143, v3, v143
	v_cvt_pk_bf16_f32 v145, v145, v177
	global_store_short v[188:189], v145, off offset:352
	v_cvt_pk_bf16_f32 v143, v143, v177
	global_store_short v[190:191], v143, off offset:352

; __device__ __forceinline__ unsigned cvt_pk_bf16(float lo, float hi) { unsigned r; asm volatile("v_cvt_pk_bf16_f32 %0, %1, %2" : "=v"(r) : "v"(lo), "v"(hi)); return r; }
; __device__ __forceinline__ float gelu_tanh(float x) {
;     const float u = 0.7978845608f * (x + 0.044715f * x * x * x);
;     return x * __builtin_amdgcn_rcpf(1.0f + __builtin_amdgcn_exp2f(-2.885390082f * u));
; }
;     __device__ __forceinline__ void operator()(const pg8::f32x4 (&acc)[2][2][4][2], const pg8::Unit& u, int wr, int wc, int fr, int fq) const {
;     ...
;         } else if (pn == 3) {
; #pragma unroll
;             for (int ai = 0; ai < 2; ++ai)
; #pragma unroll
;                 for (int m = 0; m < 4; ++m) { const size_t grow = grow0 + ai * HALF + m * 16;
; #pragma unroll
;                     for (int bj = 0; bj < 2; ++bj) { f32x4 v0 = acc[ai][bj][m][0], v1 = acc[ai][bj][m][1];
; #pragma unroll
;                         for (int j = 0; j < 4; ++j) { v0[j] = gelu_tanh(v0[j]); v1[j] = gelu_tanh(v1[j]); }
;                         u32x4 w; w.x = cvt_pk_bf16(v0[0], v0[1]); w.y = cvt_pk_bf16(v0[2], v0[3]); w.z = cvt_pk_bf16(v1[0], v1[1]); w.w = cvt_pk_bf16(v1[2], v1[3]);
;                         *(u32x4*)(UB + grow * 256 + bj * HALF + c8) = w; } asm volatile("" ::: "memory"); }
.LBB0_187:
	s_andn2_b64 vcc, exec, s[6:7]
	s_cbranch_vccnz .LBB0_189
	v_ashrrev_i32_e32 v143, 31, v142
	v_lshl_add_u64 v[150:151], v[142:143], 1, s[0:1]
	v_lshlrev_b64 v[152:153], 9, v[146:147]
	v_lshl_add_u64 v[150:151], v[150:151], 0, v[152:153]
	v_mul_f32_e32 v152, 0x3d372713, v125
	v_mul_f32_e32 v152, v125, v152
	v_fma_f32 v152, v125, v152, v125
	v_mul_f32_e32 v152, 0x3f4c422a, v152
	v_mul_f32_e32 v152, 0xc038aa3b, v152
	v_exp_f32_e32 v152, v152
	v_mul_f32_e32 v153, 0x3d372713, v122
	v_mul_f32_e32 v154, 0x3d372713, v126
	v_mul_f32_e32 v153, v122, v153
	v_mul_f32_e32 v154, v126, v154
	v_fma_f32 v153, v122, v153, v122
	v_fma_f32 v154, v126, v154, v126
	v_mul_f32_e32 v153, 0x3f4c422a, v153
	v_mul_f32_e32 v154, 0x3f4c422a, v154
	v_add_f32_e32 v152, 1.0, v152
	v_mul_f32_e32 v153, 0xc038aa3b, v153
	v_mul_f32_e32 v154, 0xc038aa3b, v154
	v_rcp_f32_e32 v152, v152
	v_exp_f32_e32 v153, v153
	v_exp_f32_e32 v154, v154
	v_mul_f32_e32 v158, 0x3d372713, v127
	v_mul_f32_e32 v155, v125, v152
	v_add_f32_e32 v152, 1.0, v153
	v_add_f32_e32 v153, 1.0, v154
	v_mul_f32_e32 v154, 0x3d372713, v123
	v_mul_f32_e32 v143, 0x3d372713, v120
	v_mul_f32_e32 v145, 0x3d372713, v124
	v_mul_f32_e32 v149, 0x3d372713, v121
	v_mul_f32_e32 v154, v123, v154
	v_mul_f32_e32 v158, v127, v158
	v_mul_f32_e32 v143, v120, v143
	v_mul_f32_e32 v145, v124, v145
	v_mul_f32_e32 v149, v121, v149
	v_fma_f32 v154, v123, v154, v123
	v_fma_f32 v158, v127, v158, v127
	v_fma_f32 v143, v120, v143, v120
	v_fma_f32 v145, v124, v145, v124
	v_fma_f32 v149, v121, v149, v121
	v_mul_f32_e32 v154, 0x3f4c422a, v154
	v_mul_f32_e32 v158, 0x3f4c422a, v158
	v_mul_f32_e32 v143, 0x3f4c422a, v143
	v_mul_f32_e32 v145, 0x3f4c422a, v145
	v_mul_f32_e32 v149, 0x3f4c422a, v149
	v_mul_f32_e32 v154, 0xc038aa3b, v154
	v_mul_f32_e32 v158, 0xc038aa3b, v158
	v_mul_f32_e32 v143, 0xc038aa3b, v143
	v_mul_f32_e32 v145, 0xc038aa3b, v145
	v_mul_f32_e32 v149, 0xc038aa3b, v149
	v_exp_f32_e32 v154, v154
	v_exp_f32_e32 v158, v158
	v_exp_f32_e32 v143, v143
	v_exp_f32_e32 v145, v145
	v_exp_f32_e32 v149, v149
	v_add_f32_e32 v154, 1.0, v154
	v_add_f32_e32 v158, 1.0, v158
	v_add_f32_e32 v143, 1.0, v143
	v_add_f32_e32 v145, 1.0, v145
	v_add_f32_e32 v149, 1.0, v149
	v_rcp_f32_e32 v153, v153
	v_rcp_f32_e32 v154, v154
	v_rcp_f32_e32 v158, v158
	v_rcp_f32_e32 v143, v143
	v_rcp_f32_e32 v145, v145
	v_rcp_f32_e32 v149, v149
	v_rcp_f32_e32 v152, v152
	s_mov_b64 s[6:7], 0x22000000
	v_lshl_add_u64 v[156:157], v[150:151], 0, s[6:7]
	v_mul_f32_e32 v160, v126, v153
	v_mul_f32_e32 v153, v123, v154
	v_mul_f32_e32 v158, v127, v158
	s_mov_b32 s6, 0x22000000
	v_mul_f32_e32 v143, v120, v143
	v_mul_f32_e32 v145, v124, v145
	v_mul_f32_e32 v149, v121, v149
	v_mul_f32_e32 v159, v122, v152
	v_cvt_pk_bf16_f32 v152, v143, v149
	v_cvt_pk_bf16_f32 v153, v159, v153
	v_cvt_pk_bf16_f32 v154, v145, v155
	v_cvt_pk_bf16_f32 v155, v160, v158
	v_add_co_u32_e32 v158, vcc, s6, v150
	v_mul_f32_e32 v143, 0x3d372713, v60
	s_nop 0
	v_addc_co_u32_e32 v159, vcc, 0, v151, vcc
	global_store_dwordx4 v[158:159], v[152:155], off
	v_mul_f32_e32 v149, 0x3d372713, v61
	v_mul_f32_e32 v143, v60, v143
	v_mul_f32_e32 v152, 0x3d372713, v57
	v_mul_f32_e32 v152, v57, v152
	v_fma_f32 v152, v57, v152, v57
	v_mul_f32_e32 v152, 0x3f4c422a, v152
	v_mul_f32_e32 v152, 0xc038aa3b, v152
	v_exp_f32_e32 v152, v152
	v_mul_f32_e32 v153, 0x3d372713, v62
	v_mul_f32_e32 v154, 0x3d372713, v58
	v_mul_f32_e32 v153, v62, v153
	v_mul_f32_e32 v154, v58, v154
	v_fma_f32 v153, v62, v153, v62
	v_fma_f32 v154, v58, v154, v58
	v_mul_f32_e32 v153, 0x3f4c422a, v153
	v_mul_f32_e32 v154, 0x3f4c422a, v154
	v_add_f32_e32 v152, 1.0, v152
	v_mul_f32_e32 v153, 0xc038aa3b, v153
	v_mul_f32_e32 v154, 0xc038aa3b, v154
	v_rcp_f32_e32 v152, v152
	v_exp_f32_e32 v153, v153
	v_exp_f32_e32 v154, v154
	v_mul_f32_e32 v145, 0x3d372713, v56
	v_mul_f32_e32 v155, v57, v152
	v_add_f32_e32 v152, 1.0, v153
	v_add_f32_e32 v153, 1.0, v154
	v_mul_f32_e32 v154, 0x3d372713, v63
	v_mul_f32_e32 v149, v61, v149
	v_mul_f32_e32 v154, v63, v154
	v_mul_f32_e32 v158, 0x3d372713, v59
	v_fma_f32 v143, v60, v143, v60
	v_mul_f32_e32 v145, v56, v145
	v_fma_f32 v149, v61, v149, v61
	v_fma_f32 v154, v63, v154, v63
	v_mul_f32_e32 v158, v59, v158
	v_mul_f32_e32 v143, 0x3f4c422a, v143
	v_fma_f32 v145, v56, v145, v56
	v_mul_f32_e32 v149, 0x3f4c422a, v149
	v_mul_f32_e32 v154, 0x3f4c422a, v154
	v_fma_f32 v158, v59, v158, v59
	v_mul_f32_e32 v143, 0xc038aa3b, v143
	v_mul_f32_e32 v145, 0x3f4c422a, v145
	v_mul_f32_e32 v149, 0xc038aa3b, v149
	v_mul_f32_e32 v154, 0xc038aa3b, v154
	v_mul_f32_e32 v158, 0x3f4c422a, v158
	v_exp_f32_e32 v143, v143
	v_mul_f32_e32 v145, 0xc038aa3b, v145
	v_exp_f32_e32 v149, v149
	v_exp_f32_e32 v154, v154
	v_mul_f32_e32 v158, 0xc038aa3b, v158
	v_exp_f32_e32 v145, v145
	v_exp_f32_e32 v158, v158
	v_add_f32_e32 v143, 1.0, v143
	v_add_f32_e32 v149, 1.0, v149
	v_add_f32_e32 v154, 1.0, v154
	v_rcp_f32_e32 v143, v143
	v_add_f32_e32 v145, 1.0, v145
	v_rcp_f32_e32 v149, v149
	v_rcp_f32_e32 v152, v152
	v_rcp_f32_e32 v153, v153
	v_rcp_f32_e32 v154, v154
	v_add_f32_e32 v158, 1.0, v158
	v_rcp_f32_e32 v145, v145
	v_rcp_f32_e32 v158, v158
	v_mul_f32_e32 v143, v60, v143
	v_mul_f32_e32 v149, v61, v149
	v_mul_f32_e32 v159, v62, v152
	v_mul_f32_e32 v160, v58, v153
	v_mul_f32_e32 v153, v63, v154
	v_cvt_pk_bf16_f32 v152, v143, v149
	v_mul_f32_e32 v145, v56, v145
	v_mul_f32_e32 v158, v59, v158
	v_cvt_pk_bf16_f32 v153, v159, v153
	v_cvt_pk_bf16_f32 v154, v145, v155
	v_cvt_pk_bf16_f32 v155, v160, v158
	global_store_dwordx4 v[156:157], v[152:155], off offset:256
	v_mul_f32_e32 v156, 0x3d372713, v119
	v_mul_f32_e32 v143, 0x3d372713, v112
	v_mul_f32_e32 v152, 0x3d372713, v117
; __device__ __forceinline__ unsigned cvt_pk_bf16(float lo, float hi) { unsigned r; asm volatile("v_cvt_pk_bf16_f32 %0, %1, %2" : "=v"(r) : "v"(lo), "v"(hi)); return r; }
; __device__ __forceinline__ float gelu_tanh(float x) {
;     const float u = 0.7978845608f * (x + 0.044715f * x * x * x);
;     return x * __builtin_amdgcn_rcpf(1.0f + __builtin_amdgcn_exp2f(-2.885390082f * u));
; }
;     __device__ __forceinline__ void operator()(const pg8::f32x4 (&acc)[2][2][4][2], const pg8::Unit& u, int wr, int wc, int fr, int fq) const {
;     ...
;         } else if (pn == 3) {
; #pragma unroll
;             for (int ai = 0; ai < 2; ++ai)
; #pragma unroll
;                 for (int m = 0; m < 4; ++m) { const size_t grow = grow0 + ai * HALF + m * 16;
; #pragma unroll
;                     for (int bj = 0; bj < 2; ++bj) { f32x4 v0 = acc[ai][bj][m][0], v1 = acc[ai][bj][m][1];
; #pragma unroll
;                         for (int j = 0; j < 4; ++j) { v0[j] = gelu_tanh(v0[j]); v1[j] = gelu_tanh(v1[j]); }
;                         u32x4 w; w.x = cvt_pk_bf16(v0[0], v0[1]); w.y = cvt_pk_bf16(v0[2], v0[3]); w.z = cvt_pk_bf16(v1[0], v1[1]); w.w = cvt_pk_bf16(v1[2], v1[3]);
;                         *(u32x4*)(UB + grow * 256 + bj * HALF + c8) = w; } asm volatile("" ::: "memory"); }
	v_mul_f32_e32 v152, v117, v152
	v_fma_f32 v152, v117, v152, v117
	v_mul_f32_e32 v152, 0x3f4c422a, v152
	v_mul_f32_e32 v152, 0xc038aa3b, v152
	v_exp_f32_e32 v152, v152
	v_mul_f32_e32 v153, 0x3d372713, v114
	v_mul_f32_e32 v154, 0x3d372713, v118
	v_mul_f32_e32 v153, v114, v153
	v_mul_f32_e32 v154, v118, v154
	v_fma_f32 v153, v114, v153, v114
	v_fma_f32 v154, v118, v154, v118
	v_mul_f32_e32 v153, 0x3f4c422a, v153
	v_mul_f32_e32 v154, 0x3f4c422a, v154
	v_add_f32_e32 v152, 1.0, v152
	v_mul_f32_e32 v153, 0xc038aa3b, v153
	v_mul_f32_e32 v154, 0xc038aa3b, v154
	v_rcp_f32_e32 v152, v152
	v_exp_f32_e32 v153, v153
	v_exp_f32_e32 v154, v154
	v_mul_f32_e32 v145, 0x3d372713, v116
	v_mul_f32_e32 v155, v117, v152
	v_add_f32_e32 v152, 1.0, v153
	v_add_f32_e32 v153, 1.0, v154
	v_mul_f32_e32 v154, 0x3d372713, v115
	v_mul_f32_e32 v149, 0x3d372713, v113
	v_mul_f32_e32 v154, v115, v154
	v_mul_f32_e32 v156, v119, v156
	v_mul_f32_e32 v143, v112, v143
	v_mul_f32_e32 v145, v116, v145
	v_mul_f32_e32 v149, v113, v149
	v_fma_f32 v154, v115, v154, v115
	v_fma_f32 v156, v119, v156, v119
	v_fma_f32 v143, v112, v143, v112
	v_fma_f32 v145, v116, v145, v116
	v_fma_f32 v149, v113, v149, v113
	v_mul_f32_e32 v154, 0x3f4c422a, v154
	v_mul_f32_e32 v156, 0x3f4c422a, v156
	v_mul_f32_e32 v143, 0x3f4c422a, v143
	v_mul_f32_e32 v145, 0x3f4c422a, v145
	v_mul_f32_e32 v149, 0x3f4c422a, v149
	v_mul_f32_e32 v154, 0xc038aa3b, v154
	v_mul_f32_e32 v156, 0xc038aa3b, v156
	v_mul_f32_e32 v143, 0xc038aa3b, v143
	v_mul_f32_e32 v145, 0xc038aa3b, v145
	v_mul_f32_e32 v149, 0xc038aa3b, v149
	v_exp_f32_e32 v154, v154
	v_exp_f32_e32 v156, v156
	v_exp_f32_e32 v143, v143
	v_exp_f32_e32 v145, v145
	v_exp_f32_e32 v149, v149
	v_add_f32_e32 v154, 1.0, v154
	v_add_f32_e32 v156, 1.0, v156
	v_add_f32_e32 v143, 1.0, v143
	v_add_f32_e32 v145, 1.0, v145
	v_add_f32_e32 v149, 1.0, v149
	v_rcp_f32_e32 v153, v153
	v_rcp_f32_e32 v154, v154
	v_rcp_f32_e32 v156, v156
	v_rcp_f32_e32 v143, v143
	v_rcp_f32_e32 v145, v145
	v_rcp_f32_e32 v149, v149
	v_rcp_f32_e32 v152, v152
	v_mul_f32_e32 v158, v118, v153
	v_mul_f32_e32 v153, v115, v154
	v_mul_f32_e32 v156, v119, v156
	s_mov_b32 s6, 0x22002000
	v_mul_f32_e32 v143, v112, v143
	v_mul_f32_e32 v145, v116, v145
	v_mul_f32_e32 v149, v113, v149
	v_mul_f32_e32 v157, v114, v152
	v_cvt_pk_bf16_f32 v152, v143, v149
	v_cvt_pk_bf16_f32 v153, v157, v153
	v_cvt_pk_bf16_f32 v154, v145, v155
	v_cvt_pk_bf16_f32 v155, v158, v156
	v_add_co_u32_e32 v156, vcc, s6, v150
	v_mul_f32_e32 v143, 0x3d372713, v52
	s_nop 0
	v_addc_co_u32_e32 v157, vcc, 0, v151, vcc
	global_store_dwordx4 v[156:157], v[152:155], off
	v_mul_f32_e32 v149, 0x3d372713, v53
	v_mul_f32_e32 v143, v52, v143
	v_mul_f32_e32 v152, 0x3d372713, v49
	v_mul_f32_e32 v152, v49, v152
	v_fma_f32 v152, v49, v152, v49
	v_mul_f32_e32 v152, 0x3f4c422a, v152
	v_mul_f32_e32 v152, 0xc038aa3b, v152
	v_exp_f32_e32 v152, v152
	v_mul_f32_e32 v153, 0x3d372713, v54
	v_mul_f32_e32 v154, 0x3d372713, v50
	v_mul_f32_e32 v153, v54, v153
	v_mul_f32_e32 v154, v50, v154
	v_fma_f32 v153, v54, v153, v54
	v_fma_f32 v154, v50, v154, v50
	v_mul_f32_e32 v153, 0x3f4c422a, v153
	v_mul_f32_e32 v154, 0x3f4c422a, v154
	v_add_f32_e32 v152, 1.0, v152
	v_mul_f32_e32 v153, 0xc038aa3b, v153
	v_mul_f32_e32 v154, 0xc038aa3b, v154
	v_rcp_f32_e32 v152, v152
	v_exp_f32_e32 v153, v153
	v_exp_f32_e32 v154, v154
	v_mul_f32_e32 v145, 0x3d372713, v48
	v_mul_f32_e32 v155, v49, v152
	v_add_f32_e32 v152, 1.0, v153
	v_add_f32_e32 v153, 1.0, v154
	v_mul_f32_e32 v154, 0x3d372713, v55
	v_mul_f32_e32 v149, v53, v149
	v_mul_f32_e32 v154, v55, v154
	v_mul_f32_e32 v158, 0x3d372713, v51
	v_fma_f32 v143, v52, v143, v52
	v_mul_f32_e32 v145, v48, v145
	v_fma_f32 v149, v53, v149, v53
	v_fma_f32 v154, v55, v154, v55
	v_mul_f32_e32 v158, v51, v158
	v_mul_f32_e32 v143, 0x3f4c422a, v143
	v_fma_f32 v145, v48, v145, v48
	v_mul_f32_e32 v149, 0x3f4c422a, v149
	v_mul_f32_e32 v154, 0x3f4c422a, v154
	v_fma_f32 v158, v51, v158, v51
	v_mul_f32_e32 v143, 0xc038aa3b, v143
	v_mul_f32_e32 v145, 0x3f4c422a, v145
	v_mul_f32_e32 v149, 0xc038aa3b, v149
	v_mul_f32_e32 v154, 0xc038aa3b, v154
	v_mul_f32_e32 v158, 0x3f4c422a, v158
	v_exp_f32_e32 v143, v143
	v_mul_f32_e32 v145, 0xc038aa3b, v145
	v_exp_f32_e32 v149, v149
	v_exp_f32_e32 v154, v154
	v_mul_f32_e32 v158, 0xc038aa3b, v158
	v_exp_f32_e32 v145, v145
	v_exp_f32_e32 v158, v158
	v_add_f32_e32 v143, 1.0, v143
	v_add_f32_e32 v149, 1.0, v149
	v_add_f32_e32 v154, 1.0, v154
	v_rcp_f32_e32 v143, v143
	v_add_f32_e32 v145, 1.0, v145
	v_rcp_f32_e32 v149, v149
	v_rcp_f32_e32 v152, v152
	v_rcp_f32_e32 v153, v153
	v_rcp_f32_e32 v154, v154
	v_add_f32_e32 v158, 1.0, v158
	v_rcp_f32_e32 v145, v145
	v_rcp_f32_e32 v158, v158
	v_mul_f32_e32 v143, v52, v143
	v_mul_f32_e32 v149, v53, v149
	v_mul_f32_e32 v159, v54, v152
	v_mul_f32_e32 v160, v50, v153
	v_mul_f32_e32 v153, v55, v154
	v_cvt_pk_bf16_f32 v152, v143, v149
	v_mul_f32_e32 v145, v48, v145
	v_mul_f32_e32 v158, v51, v158
	v_cvt_pk_bf16_f32 v153, v159, v153
	v_cvt_pk_bf16_f32 v154, v145, v155
	v_cvt_pk_bf16_f32 v155, v160, v158
	global_store_dwordx4 v[156:157], v[152:155], off offset:256
	v_mul_f32_e32 v156, 0x3d372713, v111
	v_mul_f32_e32 v143, 0x3d372713, v104
	v_mul_f32_e32 v152, 0x3d372713, v109
	v_mul_f32_e32 v152, v109, v152
	v_fma_f32 v152, v109, v152, v109
	v_mul_f32_e32 v152, 0x3f4c422a, v152
	v_mul_f32_e32 v152, 0xc038aa3b, v152
	v_exp_f32_e32 v152, v152
	v_mul_f32_e32 v153, 0x3d372713, v106
	v_mul_f32_e32 v154, 0x3d372713, v110
	v_mul_f32_e32 v153, v106, v153
	v_mul_f32_e32 v154, v110, v154
	v_fma_f32 v153, v106, v153, v106
	v_fma_f32 v154, v110, v154, v110
	v_mul_f32_e32 v153, 0x3f4c422a, v153
	v_mul_f32_e32 v154, 0x3f4c422a, v154
; __device__ __forceinline__ unsigned cvt_pk_bf16(float lo, float hi) { unsigned r; asm volatile("v_cvt_pk_bf16_f32 %0, %1, %2" : "=v"(r) : "v"(lo), "v"(hi)); return r; }
; __device__ __forceinline__ float gelu_tanh(float x) {
;     const float u = 0.7978845608f * (x + 0.044715f * x * x * x);
;     return x * __builtin_amdgcn_rcpf(1.0f + __builtin_amdgcn_exp2f(-2.885390082f * u));
; }
;     __device__ __forceinline__ void operator()(const pg8::f32x4 (&acc)[2][2][4][2], const pg8::Unit& u, int wr, int wc, int fr, int fq) const {
;     ...
;         } else if (pn == 3) {
; #pragma unroll
;             for (int ai = 0; ai < 2; ++ai)
; #pragma unroll
;                 for (int m = 0; m < 4; ++m) { const size_t grow = grow0 + ai * HALF + m * 16;
; #pragma unroll
;                     for (int bj = 0; bj < 2; ++bj) { f32x4 v0 = acc[ai][bj][m][0], v1 = acc[ai][bj][m][1];
; #pragma unroll
;                         for (int j = 0; j < 4; ++j) { v0[j] = gelu_tanh(v0[j]); v1[j] = gelu_tanh(v1[j]); }
;                         u32x4 w; w.x = cvt_pk_bf16(v0[0], v0[1]); w.y = cvt_pk_bf16(v0[2], v0[3]); w.z = cvt_pk_bf16(v1[0], v1[1]); w.w = cvt_pk_bf16(v1[2], v1[3]);
;                         *(u32x4*)(UB + grow * 256 + bj * HALF + c8) = w; } asm volatile("" ::: "memory"); }
	v_add_f32_e32 v152, 1.0, v152
	v_mul_f32_e32 v153, 0xc038aa3b, v153
	v_mul_f32_e32 v154, 0xc038aa3b, v154
	v_rcp_f32_e32 v152, v152
	v_exp_f32_e32 v153, v153
	v_exp_f32_e32 v154, v154
	v_mul_f32_e32 v145, 0x3d372713, v108
	v_mul_f32_e32 v155, v109, v152
	v_add_f32_e32 v152, 1.0, v153
	v_add_f32_e32 v153, 1.0, v154
	v_mul_f32_e32 v154, 0x3d372713, v107
	v_mul_f32_e32 v149, 0x3d372713, v105
	v_mul_f32_e32 v154, v107, v154
	v_mul_f32_e32 v156, v111, v156
	v_mul_f32_e32 v143, v104, v143
	v_mul_f32_e32 v145, v108, v145
	v_mul_f32_e32 v149, v105, v149
	v_fma_f32 v154, v107, v154, v107
	v_fma_f32 v156, v111, v156, v111
	v_fma_f32 v143, v104, v143, v104
	v_fma_f32 v145, v108, v145, v108
	v_fma_f32 v149, v105, v149, v105
	v_mul_f32_e32 v154, 0x3f4c422a, v154
	v_mul_f32_e32 v156, 0x3f4c422a, v156
	v_mul_f32_e32 v143, 0x3f4c422a, v143
	v_mul_f32_e32 v145, 0x3f4c422a, v145
	v_mul_f32_e32 v149, 0x3f4c422a, v149
	v_mul_f32_e32 v154, 0xc038aa3b, v154
	v_mul_f32_e32 v156, 0xc038aa3b, v156
	v_mul_f32_e32 v143, 0xc038aa3b, v143
	v_mul_f32_e32 v145, 0xc038aa3b, v145
	v_mul_f32_e32 v149, 0xc038aa3b, v149
	v_exp_f32_e32 v154, v154
	v_exp_f32_e32 v156, v156
	v_exp_f32_e32 v143, v143
	v_exp_f32_e32 v145, v145
	v_exp_f32_e32 v149, v149
	v_add_f32_e32 v154, 1.0, v154
	v_add_f32_e32 v156, 1.0, v156
	v_add_f32_e32 v143, 1.0, v143
	v_add_f32_e32 v145, 1.0, v145
	v_add_f32_e32 v149, 1.0, v149
	v_rcp_f32_e32 v153, v153
	v_rcp_f32_e32 v154, v154
	v_rcp_f32_e32 v156, v156
	v_rcp_f32_e32 v143, v143
	v_rcp_f32_e32 v145, v145
	v_rcp_f32_e32 v149, v149
	v_rcp_f32_e32 v152, v152
	v_mul_f32_e32 v158, v110, v153
	v_mul_f32_e32 v153, v107, v154
	v_mul_f32_e32 v156, v111, v156
	s_mov_b32 s6, 0x22004000
	v_mul_f32_e32 v143, v104, v143
	v_mul_f32_e32 v145, v108, v145
	v_mul_f32_e32 v149, v105, v149
	v_mul_f32_e32 v157, v106, v152
	v_cvt_pk_bf16_f32 v152, v143, v149
	v_cvt_pk_bf16_f32 v153, v157, v153
	v_cvt_pk_bf16_f32 v154, v145, v155
	v_cvt_pk_bf16_f32 v155, v158, v156
	v_add_co_u32_e32 v156, vcc, s6, v150
	v_mul_f32_e32 v143, 0x3d372713, v44
	s_nop 0
	v_addc_co_u32_e32 v157, vcc, 0, v151, vcc
	global_store_dwordx4 v[156:157], v[152:155], off
	v_mul_f32_e32 v149, 0x3d372713, v45
	v_mul_f32_e32 v143, v44, v143
	v_mul_f32_e32 v152, 0x3d372713, v41
	v_mul_f32_e32 v152, v41, v152
	v_fma_f32 v152, v41, v152, v41
	v_mul_f32_e32 v152, 0x3f4c422a, v152
	v_mul_f32_e32 v152, 0xc038aa3b, v152
	v_exp_f32_e32 v152, v152
	v_mul_f32_e32 v153, 0x3d372713, v46
	v_mul_f32_e32 v154, 0x3d372713, v42
	v_mul_f32_e32 v153, v46, v153
	v_mul_f32_e32 v154, v42, v154
	v_fma_f32 v153, v46, v153, v46
	v_fma_f32 v154, v42, v154, v42
	v_mul_f32_e32 v153, 0x3f4c422a, v153
	v_mul_f32_e32 v154, 0x3f4c422a, v154
	v_add_f32_e32 v152, 1.0, v152
	v_mul_f32_e32 v153, 0xc038aa3b, v153
	v_mul_f32_e32 v154, 0xc038aa3b, v154
	v_rcp_f32_e32 v152, v152
	v_exp_f32_e32 v153, v153
	v_exp_f32_e32 v154, v154
	v_mul_f32_e32 v145, 0x3d372713, v40
	v_mul_f32_e32 v155, v41, v152
	v_add_f32_e32 v152, 1.0, v153
	v_add_f32_e32 v153, 1.0, v154
	v_mul_f32_e32 v154, 0x3d372713, v47
	v_mul_f32_e32 v149, v45, v149
	v_mul_f32_e32 v154, v47, v154
	v_mul_f32_e32 v158, 0x3d372713, v43
	v_fma_f32 v143, v44, v143, v44
	v_mul_f32_e32 v145, v40, v145
	v_fma_f32 v149, v45, v149, v45
	v_fma_f32 v154, v47, v154, v47
	v_mul_f32_e32 v158, v43, v158
	v_mul_f32_e32 v143, 0x3f4c422a, v143
	v_fma_f32 v145, v40, v145, v40
	v_mul_f32_e32 v149, 0x3f4c422a, v149
	v_mul_f32_e32 v154, 0x3f4c422a, v154
	v_fma_f32 v158, v43, v158, v43
	v_mul_f32_e32 v143, 0xc038aa3b, v143
	v_mul_f32_e32 v145, 0x3f4c422a, v145
	v_mul_f32_e32 v149, 0xc038aa3b, v149
	v_mul_f32_e32 v154, 0xc038aa3b, v154
	v_mul_f32_e32 v158, 0x3f4c422a, v158
	v_exp_f32_e32 v143, v143
	v_mul_f32_e32 v145, 0xc038aa3b, v145
	v_exp_f32_e32 v149, v149
	v_exp_f32_e32 v154, v154
	v_mul_f32_e32 v158, 0xc038aa3b, v158
	v_exp_f32_e32 v145, v145
	v_exp_f32_e32 v158, v158
	v_add_f32_e32 v143, 1.0, v143
	v_add_f32_e32 v149, 1.0, v149
	v_add_f32_e32 v154, 1.0, v154
	v_rcp_f32_e32 v143, v143
	v_add_f32_e32 v145, 1.0, v145
	v_rcp_f32_e32 v149, v149
	v_rcp_f32_e32 v152, v152
	v_rcp_f32_e32 v153, v153
	v_rcp_f32_e32 v154, v154
	v_add_f32_e32 v158, 1.0, v158
	v_rcp_f32_e32 v145, v145
	v_rcp_f32_e32 v158, v158
	v_mul_f32_e32 v143, v44, v143
	v_mul_f32_e32 v149, v45, v149
	v_mul_f32_e32 v159, v46, v152
	v_mul_f32_e32 v160, v42, v153
	v_mul_f32_e32 v153, v47, v154
	v_cvt_pk_bf16_f32 v152, v143, v149
	v_mul_f32_e32 v145, v40, v145
	v_mul_f32_e32 v158, v43, v158
	v_cvt_pk_bf16_f32 v153, v159, v153
	v_cvt_pk_bf16_f32 v154, v145, v155
	v_cvt_pk_bf16_f32 v155, v160, v158
	global_store_dwordx4 v[156:157], v[152:155], off offset:256
	v_mul_f32_e32 v156, 0x3d372713, v103
	v_mul_f32_e32 v143, 0x3d372713, v96
	v_mul_f32_e32 v152, 0x3d372713, v101
	v_mul_f32_e32 v152, v101, v152
	v_fma_f32 v152, v101, v152, v101
	v_mul_f32_e32 v152, 0x3f4c422a, v152
	v_mul_f32_e32 v152, 0xc038aa3b, v152
	v_exp_f32_e32 v152, v152
	v_mul_f32_e32 v153, 0x3d372713, v98
	v_mul_f32_e32 v154, 0x3d372713, v102
	v_mul_f32_e32 v153, v98, v153
	v_mul_f32_e32 v154, v102, v154
	v_fma_f32 v153, v98, v153, v98
	v_fma_f32 v154, v102, v154, v102
	v_mul_f32_e32 v153, 0x3f4c422a, v153
	v_mul_f32_e32 v154, 0x3f4c422a, v154
	v_add_f32_e32 v152, 1.0, v152
	v_mul_f32_e32 v153, 0xc038aa3b, v153
	v_mul_f32_e32 v154, 0xc038aa3b, v154
	v_rcp_f32_e32 v152, v152
	v_exp_f32_e32 v153, v153
	v_exp_f32_e32 v154, v154
	v_mul_f32_e32 v145, 0x3d372713, v100
	v_mul_f32_e32 v155, v101, v152
	v_add_f32_e32 v152, 1.0, v153
	v_add_f32_e32 v153, 1.0, v154
	v_mul_f32_e32 v154, 0x3d372713, v99
	v_mul_f32_e32 v149, 0x3d372713, v97
	v_mul_f32_e32 v154, v99, v154
	v_mul_f32_e32 v156, v103, v156
; __device__ __forceinline__ unsigned cvt_pk_bf16(float lo, float hi) { unsigned r; asm volatile("v_cvt_pk_bf16_f32 %0, %1, %2" : "=v"(r) : "v"(lo), "v"(hi)); return r; }
; __device__ __forceinline__ float gelu_tanh(float x) {
;     const float u = 0.7978845608f * (x + 0.044715f * x * x * x);
;     return x * __builtin_amdgcn_rcpf(1.0f + __builtin_amdgcn_exp2f(-2.885390082f * u));
; }
;     __device__ __forceinline__ void operator()(const pg8::f32x4 (&acc)[2][2][4][2], const pg8::Unit& u, int wr, int wc, int fr, int fq) const {
;     ...
;         } else if (pn == 3) {
; #pragma unroll
;             for (int ai = 0; ai < 2; ++ai)
; #pragma unroll
;                 for (int m = 0; m < 4; ++m) { const size_t grow = grow0 + ai * HALF + m * 16;
; #pragma unroll
;                     for (int bj = 0; bj < 2; ++bj) { f32x4 v0 = acc[ai][bj][m][0], v1 = acc[ai][bj][m][1];
; #pragma unroll
;                         for (int j = 0; j < 4; ++j) { v0[j] = gelu_tanh(v0[j]); v1[j] = gelu_tanh(v1[j]); }
;                         u32x4 w; w.x = cvt_pk_bf16(v0[0], v0[1]); w.y = cvt_pk_bf16(v0[2], v0[3]); w.z = cvt_pk_bf16(v1[0], v1[1]); w.w = cvt_pk_bf16(v1[2], v1[3]);
;                         *(u32x4*)(UB + grow * 256 + bj * HALF + c8) = w; } asm volatile("" ::: "memory"); }
	v_mul_f32_e32 v143, v96, v143
	v_mul_f32_e32 v145, v100, v145
	v_mul_f32_e32 v149, v97, v149
	v_fma_f32 v154, v99, v154, v99
	v_fma_f32 v156, v103, v156, v103
	v_fma_f32 v143, v96, v143, v96
	v_fma_f32 v145, v100, v145, v100
	v_fma_f32 v149, v97, v149, v97
	v_mul_f32_e32 v154, 0x3f4c422a, v154
	v_mul_f32_e32 v156, 0x3f4c422a, v156
	v_mul_f32_e32 v143, 0x3f4c422a, v143
	v_mul_f32_e32 v145, 0x3f4c422a, v145
	v_mul_f32_e32 v149, 0x3f4c422a, v149
	v_mul_f32_e32 v154, 0xc038aa3b, v154
	v_mul_f32_e32 v156, 0xc038aa3b, v156
	v_mul_f32_e32 v143, 0xc038aa3b, v143
	v_mul_f32_e32 v145, 0xc038aa3b, v145
	v_mul_f32_e32 v149, 0xc038aa3b, v149
	v_exp_f32_e32 v154, v154
	v_exp_f32_e32 v156, v156
	v_exp_f32_e32 v143, v143
	v_exp_f32_e32 v145, v145
	v_exp_f32_e32 v149, v149
	v_add_f32_e32 v154, 1.0, v154
	v_add_f32_e32 v156, 1.0, v156
	v_add_f32_e32 v143, 1.0, v143
	v_add_f32_e32 v145, 1.0, v145
	v_add_f32_e32 v149, 1.0, v149
	v_rcp_f32_e32 v153, v153
	v_rcp_f32_e32 v154, v154
	v_rcp_f32_e32 v156, v156
	v_rcp_f32_e32 v143, v143
	v_rcp_f32_e32 v145, v145
	v_rcp_f32_e32 v149, v149
	v_rcp_f32_e32 v152, v152
	v_mul_f32_e32 v158, v102, v153
	v_mul_f32_e32 v153, v99, v154
	v_mul_f32_e32 v156, v103, v156
	s_mov_b32 s6, 0x22006000
	v_mul_f32_e32 v143, v96, v143
	v_mul_f32_e32 v145, v100, v145
	v_mul_f32_e32 v149, v97, v149
	v_mul_f32_e32 v157, v98, v152
	v_cvt_pk_bf16_f32 v152, v143, v149
	v_cvt_pk_bf16_f32 v153, v157, v153
	v_cvt_pk_bf16_f32 v154, v145, v155
	v_cvt_pk_bf16_f32 v155, v158, v156
	v_add_co_u32_e32 v156, vcc, s6, v150
	v_mul_f32_e32 v143, 0x3d372713, v36
	s_nop 0
	v_addc_co_u32_e32 v157, vcc, 0, v151, vcc
	global_store_dwordx4 v[156:157], v[152:155], off
	v_mul_f32_e32 v149, 0x3d372713, v37
	v_mul_f32_e32 v143, v36, v143
	v_mul_f32_e32 v152, 0x3d372713, v33
	v_mul_f32_e32 v152, v33, v152
	v_fma_f32 v152, v33, v152, v33
	v_mul_f32_e32 v152, 0x3f4c422a, v152
	v_mul_f32_e32 v152, 0xc038aa3b, v152
	v_exp_f32_e32 v152, v152
	v_mul_f32_e32 v153, 0x3d372713, v38
	v_mul_f32_e32 v154, 0x3d372713, v34
	v_mul_f32_e32 v153, v38, v153
	v_mul_f32_e32 v154, v34, v154
	v_fma_f32 v153, v38, v153, v38
	v_fma_f32 v154, v34, v154, v34
	v_mul_f32_e32 v153, 0x3f4c422a, v153
	v_mul_f32_e32 v154, 0x3f4c422a, v154
	v_add_f32_e32 v152, 1.0, v152
	v_mul_f32_e32 v153, 0xc038aa3b, v153
	v_mul_f32_e32 v154, 0xc038aa3b, v154
	v_rcp_f32_e32 v152, v152
	v_exp_f32_e32 v153, v153
	v_exp_f32_e32 v154, v154
	v_mul_f32_e32 v145, 0x3d372713, v32
	v_mul_f32_e32 v155, v33, v152
	v_add_f32_e32 v152, 1.0, v153
	v_add_f32_e32 v153, 1.0, v154
	v_mul_f32_e32 v154, 0x3d372713, v39
	v_mul_f32_e32 v149, v37, v149
	v_mul_f32_e32 v154, v39, v154
	v_mul_f32_e32 v158, 0x3d372713, v35
	v_fma_f32 v143, v36, v143, v36
	v_mul_f32_e32 v145, v32, v145
	v_fma_f32 v149, v37, v149, v37
	v_fma_f32 v154, v39, v154, v39
	v_mul_f32_e32 v158, v35, v158
	v_mul_f32_e32 v143, 0x3f4c422a, v143
	v_fma_f32 v145, v32, v145, v32
	v_mul_f32_e32 v149, 0x3f4c422a, v149
	v_mul_f32_e32 v154, 0x3f4c422a, v154
	v_fma_f32 v158, v35, v158, v35
	v_mul_f32_e32 v143, 0xc038aa3b, v143
	v_mul_f32_e32 v145, 0x3f4c422a, v145
	v_mul_f32_e32 v149, 0xc038aa3b, v149
	v_mul_f32_e32 v154, 0xc038aa3b, v154
	v_mul_f32_e32 v158, 0x3f4c422a, v158
	v_exp_f32_e32 v143, v143
	v_mul_f32_e32 v145, 0xc038aa3b, v145
	v_exp_f32_e32 v149, v149
	v_exp_f32_e32 v154, v154
	v_mul_f32_e32 v158, 0xc038aa3b, v158
	v_exp_f32_e32 v145, v145
	v_exp_f32_e32 v158, v158
	v_add_f32_e32 v143, 1.0, v143
	v_add_f32_e32 v149, 1.0, v149
	v_add_f32_e32 v154, 1.0, v154
	v_rcp_f32_e32 v143, v143
	v_add_f32_e32 v145, 1.0, v145
	v_rcp_f32_e32 v149, v149
	v_rcp_f32_e32 v152, v152
	v_rcp_f32_e32 v153, v153
	v_rcp_f32_e32 v154, v154
	v_add_f32_e32 v158, 1.0, v158
	v_rcp_f32_e32 v145, v145
	v_rcp_f32_e32 v158, v158
	v_mul_f32_e32 v143, v36, v143
	v_mul_f32_e32 v149, v37, v149
	v_mul_f32_e32 v159, v38, v152
	v_mul_f32_e32 v160, v34, v153
	v_mul_f32_e32 v153, v39, v154
	v_cvt_pk_bf16_f32 v152, v143, v149
	v_mul_f32_e32 v145, v32, v145
	v_mul_f32_e32 v158, v35, v158
	v_cvt_pk_bf16_f32 v153, v159, v153
	v_cvt_pk_bf16_f32 v154, v145, v155
	v_cvt_pk_bf16_f32 v155, v160, v158
	global_store_dwordx4 v[156:157], v[152:155], off offset:256
	v_mul_f32_e32 v156, 0x3d372713, v95
	v_mul_f32_e32 v143, 0x3d372713, v88
	v_mul_f32_e32 v152, 0x3d372713, v93
	v_mul_f32_e32 v152, v93, v152
	v_fma_f32 v152, v93, v152, v93
	v_mul_f32_e32 v152, 0x3f4c422a, v152
	v_mul_f32_e32 v152, 0xc038aa3b, v152
	v_exp_f32_e32 v152, v152
	v_mul_f32_e32 v153, 0x3d372713, v90
	v_mul_f32_e32 v154, 0x3d372713, v94
	v_mul_f32_e32 v153, v90, v153
	v_mul_f32_e32 v154, v94, v154
	v_fma_f32 v153, v90, v153, v90
	v_fma_f32 v154, v94, v154, v94
	v_mul_f32_e32 v153, 0x3f4c422a, v153
	v_mul_f32_e32 v154, 0x3f4c422a, v154
	v_add_f32_e32 v152, 1.0, v152
	v_mul_f32_e32 v153, 0xc038aa3b, v153
	v_mul_f32_e32 v154, 0xc038aa3b, v154
	v_rcp_f32_e32 v152, v152
	v_exp_f32_e32 v153, v153
	v_exp_f32_e32 v154, v154
	v_mul_f32_e32 v145, 0x3d372713, v92
	v_mul_f32_e32 v155, v93, v152
	v_add_f32_e32 v152, 1.0, v153
	v_add_f32_e32 v153, 1.0, v154
	v_mul_f32_e32 v154, 0x3d372713, v91
	v_mul_f32_e32 v149, 0x3d372713, v89
	v_mul_f32_e32 v154, v91, v154
	v_mul_f32_e32 v156, v95, v156
	v_mul_f32_e32 v143, v88, v143
	v_mul_f32_e32 v145, v92, v145
	v_mul_f32_e32 v149, v89, v149
	v_fma_f32 v154, v91, v154, v91
	v_fma_f32 v156, v95, v156, v95
	v_fma_f32 v143, v88, v143, v88
	v_fma_f32 v145, v92, v145, v92
	v_fma_f32 v149, v89, v149, v89
	v_mul_f32_e32 v154, 0x3f4c422a, v154
	v_mul_f32_e32 v156, 0x3f4c422a, v156
	v_mul_f32_e32 v143, 0x3f4c422a, v143
	v_mul_f32_e32 v145, 0x3f4c422a, v145
	v_mul_f32_e32 v149, 0x3f4c422a, v149
	v_mul_f32_e32 v154, 0xc038aa3b, v154
; __device__ __forceinline__ unsigned cvt_pk_bf16(float lo, float hi) { unsigned r; asm volatile("v_cvt_pk_bf16_f32 %0, %1, %2" : "=v"(r) : "v"(lo), "v"(hi)); return r; }
; __device__ __forceinline__ float gelu_tanh(float x) {
;     const float u = 0.7978845608f * (x + 0.044715f * x * x * x);
;     return x * __builtin_amdgcn_rcpf(1.0f + __builtin_amdgcn_exp2f(-2.885390082f * u));
; }
;     __device__ __forceinline__ void operator()(const pg8::f32x4 (&acc)[2][2][4][2], const pg8::Unit& u, int wr, int wc, int fr, int fq) const {
;     ...
; #pragma unroll
;             for (int ai = 0; ai < 2; ++ai)
; #pragma unroll
;                 for (int m = 0; m < 4; ++m) { const size_t grow = grow0 + ai * HALF + m * 16;
; #pragma unroll
;                     for (int bj = 0; bj < 2; ++bj) { f32x4 v0 = acc[ai][bj][m][0], v1 = acc[ai][bj][m][1];
; #pragma unroll
;                         for (int j = 0; j < 4; ++j) { v0[j] = gelu_tanh(v0[j]); v1[j] = gelu_tanh(v1[j]); }
;                         u32x4 w; w.x = cvt_pk_bf16(v0[0], v0[1]); w.y = cvt_pk_bf16(v0[2], v0[3]); w.z = cvt_pk_bf16(v1[0], v1[1]); w.w = cvt_pk_bf16(v1[2], v1[3]);
;                         *(u32x4*)(UB + grow * 256 + bj * HALF + c8) = w; } asm volatile("" ::: "memory"); }
	v_mul_f32_e32 v156, 0xc038aa3b, v156
	v_mul_f32_e32 v143, 0xc038aa3b, v143
	v_mul_f32_e32 v145, 0xc038aa3b, v145
	v_mul_f32_e32 v149, 0xc038aa3b, v149
	v_exp_f32_e32 v154, v154
	v_exp_f32_e32 v156, v156
	v_exp_f32_e32 v143, v143
	v_exp_f32_e32 v145, v145
	v_exp_f32_e32 v149, v149
	v_add_f32_e32 v154, 1.0, v154
	v_add_f32_e32 v156, 1.0, v156
	v_add_f32_e32 v143, 1.0, v143
	v_add_f32_e32 v145, 1.0, v145
	v_add_f32_e32 v149, 1.0, v149
	v_rcp_f32_e32 v153, v153
	v_rcp_f32_e32 v154, v154
	v_rcp_f32_e32 v156, v156
	v_rcp_f32_e32 v143, v143
	v_rcp_f32_e32 v145, v145
	v_rcp_f32_e32 v149, v149
	v_rcp_f32_e32 v152, v152
	v_mul_f32_e32 v158, v94, v153
	v_mul_f32_e32 v153, v91, v154
	v_mul_f32_e32 v156, v95, v156
	s_mov_b32 s6, 0x22010000
	v_mul_f32_e32 v143, v88, v143
	v_mul_f32_e32 v145, v92, v145
	v_mul_f32_e32 v149, v89, v149
	v_mul_f32_e32 v157, v90, v152
	v_cvt_pk_bf16_f32 v152, v143, v149
	v_cvt_pk_bf16_f32 v153, v157, v153
	v_cvt_pk_bf16_f32 v154, v145, v155
	v_cvt_pk_bf16_f32 v155, v158, v156
	v_add_co_u32_e32 v156, vcc, s6, v150
	v_mul_f32_e32 v143, 0x3d372713, v28
	s_nop 0
	v_addc_co_u32_e32 v157, vcc, 0, v151, vcc
	global_store_dwordx4 v[156:157], v[152:155], off
	v_mul_f32_e32 v149, 0x3d372713, v29
	v_mul_f32_e32 v143, v28, v143
	v_mul_f32_e32 v152, 0x3d372713, v25
	v_mul_f32_e32 v152, v25, v152
	v_fma_f32 v152, v25, v152, v25
	v_mul_f32_e32 v152, 0x3f4c422a, v152
	v_mul_f32_e32 v152, 0xc038aa3b, v152
	v_exp_f32_e32 v152, v152
	v_mul_f32_e32 v153, 0x3d372713, v30
	v_mul_f32_e32 v154, 0x3d372713, v26
	v_mul_f32_e32 v153, v30, v153
	v_mul_f32_e32 v154, v26, v154
	v_fma_f32 v153, v30, v153, v30
	v_fma_f32 v154, v26, v154, v26
	v_mul_f32_e32 v153, 0x3f4c422a, v153
	v_mul_f32_e32 v154, 0x3f4c422a, v154
	v_add_f32_e32 v152, 1.0, v152
	v_mul_f32_e32 v153, 0xc038aa3b, v153
	v_mul_f32_e32 v154, 0xc038aa3b, v154
	v_rcp_f32_e32 v152, v152
	v_exp_f32_e32 v153, v153
	v_exp_f32_e32 v154, v154
	v_mul_f32_e32 v145, 0x3d372713, v24
	v_mul_f32_e32 v155, v25, v152
	v_add_f32_e32 v152, 1.0, v153
	v_add_f32_e32 v153, 1.0, v154
	v_mul_f32_e32 v154, 0x3d372713, v31
	v_mul_f32_e32 v149, v29, v149
	v_mul_f32_e32 v154, v31, v154
	v_mul_f32_e32 v158, 0x3d372713, v27
	v_fma_f32 v143, v28, v143, v28
	v_mul_f32_e32 v145, v24, v145
	v_fma_f32 v149, v29, v149, v29
	v_fma_f32 v154, v31, v154, v31
	v_mul_f32_e32 v158, v27, v158
	v_mul_f32_e32 v143, 0x3f4c422a, v143
	v_fma_f32 v145, v24, v145, v24
	v_mul_f32_e32 v149, 0x3f4c422a, v149
	v_mul_f32_e32 v154, 0x3f4c422a, v154
	v_fma_f32 v158, v27, v158, v27
	v_mul_f32_e32 v143, 0xc038aa3b, v143
	v_mul_f32_e32 v145, 0x3f4c422a, v145
	v_mul_f32_e32 v149, 0xc038aa3b, v149
	v_mul_f32_e32 v154, 0xc038aa3b, v154
	v_mul_f32_e32 v158, 0x3f4c422a, v158
	v_exp_f32_e32 v143, v143
	v_mul_f32_e32 v145, 0xc038aa3b, v145
	v_exp_f32_e32 v149, v149
	v_exp_f32_e32 v154, v154
	v_mul_f32_e32 v158, 0xc038aa3b, v158
	v_exp_f32_e32 v145, v145
	v_exp_f32_e32 v158, v158
	v_add_f32_e32 v143, 1.0, v143
	v_add_f32_e32 v149, 1.0, v149
	v_add_f32_e32 v154, 1.0, v154
	v_rcp_f32_e32 v143, v143
	v_add_f32_e32 v145, 1.0, v145
	v_rcp_f32_e32 v149, v149
	v_rcp_f32_e32 v152, v152
	v_rcp_f32_e32 v153, v153
	v_rcp_f32_e32 v154, v154
	v_add_f32_e32 v158, 1.0, v158
	v_rcp_f32_e32 v145, v145
	v_rcp_f32_e32 v158, v158
	v_mul_f32_e32 v143, v28, v143
	v_mul_f32_e32 v149, v29, v149
	v_mul_f32_e32 v159, v30, v152
	v_mul_f32_e32 v160, v26, v153
	v_mul_f32_e32 v153, v31, v154
	v_cvt_pk_bf16_f32 v152, v143, v149
	v_mul_f32_e32 v145, v24, v145
	v_mul_f32_e32 v158, v27, v158
	v_cvt_pk_bf16_f32 v153, v159, v153
	v_cvt_pk_bf16_f32 v154, v145, v155
	v_cvt_pk_bf16_f32 v155, v160, v158
	global_store_dwordx4 v[156:157], v[152:155], off offset:256
	v_mul_f32_e32 v156, 0x3d372713, v87
	v_mul_f32_e32 v143, 0x3d372713, v80
	v_mul_f32_e32 v152, 0x3d372713, v85
	v_mul_f32_e32 v152, v85, v152
	v_fma_f32 v152, v85, v152, v85
	v_mul_f32_e32 v152, 0x3f4c422a, v152
	v_mul_f32_e32 v152, 0xc038aa3b, v152
	v_exp_f32_e32 v152, v152
	v_mul_f32_e32 v153, 0x3d372713, v82
	v_mul_f32_e32 v154, 0x3d372713, v86
	v_mul_f32_e32 v153, v82, v153
	v_mul_f32_e32 v154, v86, v154
	v_fma_f32 v153, v82, v153, v82
	v_fma_f32 v154, v86, v154, v86
	v_mul_f32_e32 v153, 0x3f4c422a, v153
	v_mul_f32_e32 v154, 0x3f4c422a, v154
	v_add_f32_e32 v152, 1.0, v152
	v_mul_f32_e32 v153, 0xc038aa3b, v153
	v_mul_f32_e32 v154, 0xc038aa3b, v154
	v_rcp_f32_e32 v152, v152
	v_exp_f32_e32 v153, v153
	v_exp_f32_e32 v154, v154
	v_mul_f32_e32 v145, 0x3d372713, v84
	v_mul_f32_e32 v155, v85, v152
	v_add_f32_e32 v152, 1.0, v153
	v_add_f32_e32 v153, 1.0, v154
	v_mul_f32_e32 v154, 0x3d372713, v83
	v_mul_f32_e32 v149, 0x3d372713, v81
	v_mul_f32_e32 v154, v83, v154
	v_mul_f32_e32 v156, v87, v156
	v_mul_f32_e32 v143, v80, v143
	v_mul_f32_e32 v145, v84, v145
	v_mul_f32_e32 v149, v81, v149
	v_fma_f32 v154, v83, v154, v83
	v_fma_f32 v156, v87, v156, v87
	v_fma_f32 v143, v80, v143, v80
	v_fma_f32 v145, v84, v145, v84
	v_fma_f32 v149, v81, v149, v81
	v_mul_f32_e32 v154, 0x3f4c422a, v154
	v_mul_f32_e32 v156, 0x3f4c422a, v156
	v_mul_f32_e32 v143, 0x3f4c422a, v143
	v_mul_f32_e32 v145, 0x3f4c422a, v145
	v_mul_f32_e32 v149, 0x3f4c422a, v149
	v_mul_f32_e32 v154, 0xc038aa3b, v154
	v_mul_f32_e32 v156, 0xc038aa3b, v156
	v_mul_f32_e32 v143, 0xc038aa3b, v143
	v_mul_f32_e32 v145, 0xc038aa3b, v145
	v_mul_f32_e32 v149, 0xc038aa3b, v149
	v_exp_f32_e32 v154, v154
	v_exp_f32_e32 v156, v156
	v_exp_f32_e32 v143, v143
	v_exp_f32_e32 v145, v145
	v_exp_f32_e32 v149, v149
	v_add_f32_e32 v154, 1.0, v154
	v_add_f32_e32 v156, 1.0, v156
	v_add_f32_e32 v143, 1.0, v143
	v_add_f32_e32 v145, 1.0, v145
	v_add_f32_e32 v149, 1.0, v149
	v_rcp_f32_e32 v153, v153
	v_rcp_f32_e32 v154, v154
; __device__ __forceinline__ unsigned cvt_pk_bf16(float lo, float hi) { unsigned r; asm volatile("v_cvt_pk_bf16_f32 %0, %1, %2" : "=v"(r) : "v"(lo), "v"(hi)); return r; }
; __device__ __forceinline__ float gelu_tanh(float x) {
;     const float u = 0.7978845608f * (x + 0.044715f * x * x * x);
;     return x * __builtin_amdgcn_rcpf(1.0f + __builtin_amdgcn_exp2f(-2.885390082f * u));
; }
;     __device__ __forceinline__ void operator()(const pg8::f32x4 (&acc)[2][2][4][2], const pg8::Unit& u, int wr, int wc, int fr, int fq) const {
;     ...
; #pragma unroll
;             for (int ai = 0; ai < 2; ++ai)
; #pragma unroll
;                 for (int m = 0; m < 4; ++m) { const size_t grow = grow0 + ai * HALF + m * 16;
; #pragma unroll
;                     for (int bj = 0; bj < 2; ++bj) { f32x4 v0 = acc[ai][bj][m][0], v1 = acc[ai][bj][m][1];
; #pragma unroll
;                         for (int j = 0; j < 4; ++j) { v0[j] = gelu_tanh(v0[j]); v1[j] = gelu_tanh(v1[j]); }
;                         u32x4 w; w.x = cvt_pk_bf16(v0[0], v0[1]); w.y = cvt_pk_bf16(v0[2], v0[3]); w.z = cvt_pk_bf16(v1[0], v1[1]); w.w = cvt_pk_bf16(v1[2], v1[3]);
;                         *(u32x4*)(UB + grow * 256 + bj * HALF + c8) = w; } asm volatile("" ::: "memory"); }
	v_rcp_f32_e32 v156, v156
	v_rcp_f32_e32 v143, v143
	v_rcp_f32_e32 v145, v145
	v_rcp_f32_e32 v149, v149
	v_rcp_f32_e32 v152, v152
	v_mul_f32_e32 v158, v86, v153
	v_mul_f32_e32 v153, v83, v154
	v_mul_f32_e32 v156, v87, v156
	s_mov_b32 s6, 0x22012000
	v_mul_f32_e32 v143, v80, v143
	v_mul_f32_e32 v145, v84, v145
	v_mul_f32_e32 v149, v81, v149
	v_mul_f32_e32 v157, v82, v152
	v_cvt_pk_bf16_f32 v152, v143, v149
	v_cvt_pk_bf16_f32 v153, v157, v153
	v_cvt_pk_bf16_f32 v154, v145, v155
	v_cvt_pk_bf16_f32 v155, v158, v156
	v_add_co_u32_e32 v156, vcc, s6, v150
	v_mul_f32_e32 v143, 0x3d372713, v20
	s_nop 0
	v_addc_co_u32_e32 v157, vcc, 0, v151, vcc
	global_store_dwordx4 v[156:157], v[152:155], off
	v_mul_f32_e32 v149, 0x3d372713, v21
	v_mul_f32_e32 v143, v20, v143
	v_mul_f32_e32 v152, 0x3d372713, v17
	v_mul_f32_e32 v152, v17, v152
	v_fma_f32 v152, v17, v152, v17
	v_mul_f32_e32 v152, 0x3f4c422a, v152
	v_mul_f32_e32 v152, 0xc038aa3b, v152
	v_exp_f32_e32 v152, v152
	v_mul_f32_e32 v153, 0x3d372713, v22
	v_mul_f32_e32 v154, 0x3d372713, v18
	v_mul_f32_e32 v153, v22, v153
	v_mul_f32_e32 v154, v18, v154
	v_fma_f32 v153, v22, v153, v22
	v_fma_f32 v154, v18, v154, v18
	v_mul_f32_e32 v153, 0x3f4c422a, v153
	v_mul_f32_e32 v154, 0x3f4c422a, v154
	v_add_f32_e32 v152, 1.0, v152
	v_mul_f32_e32 v153, 0xc038aa3b, v153
	v_mul_f32_e32 v154, 0xc038aa3b, v154
	v_rcp_f32_e32 v152, v152
	v_exp_f32_e32 v153, v153
	v_exp_f32_e32 v154, v154
	v_mul_f32_e32 v145, 0x3d372713, v16
	v_mul_f32_e32 v155, v17, v152
	v_add_f32_e32 v152, 1.0, v153
	v_add_f32_e32 v153, 1.0, v154
	v_mul_f32_e32 v154, 0x3d372713, v23
	v_mul_f32_e32 v149, v21, v149
	v_mul_f32_e32 v154, v23, v154
	v_mul_f32_e32 v158, 0x3d372713, v19
	v_fma_f32 v143, v20, v143, v20
	v_mul_f32_e32 v145, v16, v145
	v_fma_f32 v149, v21, v149, v21
	v_fma_f32 v154, v23, v154, v23
	v_mul_f32_e32 v158, v19, v158
	v_mul_f32_e32 v143, 0x3f4c422a, v143
	v_fma_f32 v145, v16, v145, v16
	v_mul_f32_e32 v149, 0x3f4c422a, v149
	v_mul_f32_e32 v154, 0x3f4c422a, v154
	v_fma_f32 v158, v19, v158, v19
	v_mul_f32_e32 v143, 0xc038aa3b, v143
	v_mul_f32_e32 v145, 0x3f4c422a, v145
	v_mul_f32_e32 v149, 0xc038aa3b, v149
	v_mul_f32_e32 v154, 0xc038aa3b, v154
	v_mul_f32_e32 v158, 0x3f4c422a, v158
	v_exp_f32_e32 v143, v143
	v_mul_f32_e32 v145, 0xc038aa3b, v145
	v_exp_f32_e32 v149, v149
	v_exp_f32_e32 v154, v154
	v_mul_f32_e32 v158, 0xc038aa3b, v158
	v_exp_f32_e32 v145, v145
	v_exp_f32_e32 v158, v158
	v_add_f32_e32 v143, 1.0, v143
	v_add_f32_e32 v149, 1.0, v149
	v_add_f32_e32 v154, 1.0, v154
	v_rcp_f32_e32 v143, v143
	v_add_f32_e32 v145, 1.0, v145
	v_rcp_f32_e32 v149, v149
	v_rcp_f32_e32 v152, v152
	v_rcp_f32_e32 v153, v153
	v_rcp_f32_e32 v154, v154
	v_add_f32_e32 v158, 1.0, v158
	v_rcp_f32_e32 v145, v145
	v_rcp_f32_e32 v158, v158
	v_mul_f32_e32 v143, v20, v143
	v_mul_f32_e32 v149, v21, v149
	v_mul_f32_e32 v159, v22, v152
	v_mul_f32_e32 v160, v18, v153
	v_mul_f32_e32 v153, v23, v154
	v_cvt_pk_bf16_f32 v152, v143, v149
	v_mul_f32_e32 v145, v16, v145
	v_mul_f32_e32 v158, v19, v158
	v_cvt_pk_bf16_f32 v153, v159, v153
	v_cvt_pk_bf16_f32 v154, v145, v155
	v_cvt_pk_bf16_f32 v155, v160, v158
	global_store_dwordx4 v[156:157], v[152:155], off offset:256
	v_mul_f32_e32 v156, 0x3d372713, v79
	v_mul_f32_e32 v143, 0x3d372713, v72
	v_mul_f32_e32 v152, 0x3d372713, v77
	v_mul_f32_e32 v152, v77, v152
	v_fma_f32 v152, v77, v152, v77
	v_mul_f32_e32 v152, 0x3f4c422a, v152
	v_mul_f32_e32 v152, 0xc038aa3b, v152
	v_exp_f32_e32 v152, v152
	v_mul_f32_e32 v153, 0x3d372713, v74
	v_mul_f32_e32 v154, 0x3d372713, v78
	v_mul_f32_e32 v153, v74, v153
	v_mul_f32_e32 v154, v78, v154
	v_fma_f32 v153, v74, v153, v74
	v_fma_f32 v154, v78, v154, v78
	v_mul_f32_e32 v153, 0x3f4c422a, v153
	v_mul_f32_e32 v154, 0x3f4c422a, v154
	v_add_f32_e32 v152, 1.0, v152
	v_mul_f32_e32 v153, 0xc038aa3b, v153
	v_mul_f32_e32 v154, 0xc038aa3b, v154
	v_rcp_f32_e32 v152, v152
	v_exp_f32_e32 v153, v153
	v_exp_f32_e32 v154, v154
	v_mul_f32_e32 v145, 0x3d372713, v76
	v_mul_f32_e32 v155, v77, v152
	v_add_f32_e32 v152, 1.0, v153
	v_add_f32_e32 v153, 1.0, v154
	v_mul_f32_e32 v154, 0x3d372713, v75
	v_mul_f32_e32 v149, 0x3d372713, v73
	v_mul_f32_e32 v154, v75, v154
	v_mul_f32_e32 v156, v79, v156
	v_mul_f32_e32 v143, v72, v143
	v_mul_f32_e32 v145, v76, v145
	v_mul_f32_e32 v149, v73, v149
	v_fma_f32 v154, v75, v154, v75
	v_fma_f32 v156, v79, v156, v79
	v_fma_f32 v143, v72, v143, v72
	v_fma_f32 v145, v76, v145, v76
	v_fma_f32 v149, v73, v149, v73
	v_mul_f32_e32 v154, 0x3f4c422a, v154
	v_mul_f32_e32 v156, 0x3f4c422a, v156
	v_mul_f32_e32 v143, 0x3f4c422a, v143
	v_mul_f32_e32 v145, 0x3f4c422a, v145
	v_mul_f32_e32 v149, 0x3f4c422a, v149
	v_mul_f32_e32 v154, 0xc038aa3b, v154
	v_mul_f32_e32 v156, 0xc038aa3b, v156
	v_mul_f32_e32 v143, 0xc038aa3b, v143
	v_mul_f32_e32 v145, 0xc038aa3b, v145
	v_mul_f32_e32 v149, 0xc038aa3b, v149
	v_exp_f32_e32 v154, v154
	v_exp_f32_e32 v156, v156
	v_exp_f32_e32 v143, v143
	v_exp_f32_e32 v145, v145
	v_exp_f32_e32 v149, v149
	v_add_f32_e32 v154, 1.0, v154
	v_add_f32_e32 v156, 1.0, v156
	v_add_f32_e32 v143, 1.0, v143
	v_add_f32_e32 v145, 1.0, v145
	v_add_f32_e32 v149, 1.0, v149
	v_rcp_f32_e32 v153, v153
	v_rcp_f32_e32 v154, v154
	v_rcp_f32_e32 v156, v156
	v_rcp_f32_e32 v143, v143
	v_rcp_f32_e32 v145, v145
	v_rcp_f32_e32 v149, v149
	v_rcp_f32_e32 v152, v152
	v_mul_f32_e32 v158, v78, v153
	v_mul_f32_e32 v153, v75, v154
	v_mul_f32_e32 v156, v79, v156
	s_mov_b32 s6, 0x22014000
	v_mul_f32_e32 v143, v72, v143
	v_mul_f32_e32 v145, v76, v145
	v_mul_f32_e32 v149, v73, v149
	v_mul_f32_e32 v157, v74, v152
	v_cvt_pk_bf16_f32 v152, v143, v149
	v_cvt_pk_bf16_f32 v153, v157, v153
	v_cvt_pk_bf16_f32 v154, v145, v155
; __device__ __forceinline__ unsigned cvt_pk_bf16(float lo, float hi) { unsigned r; asm volatile("v_cvt_pk_bf16_f32 %0, %1, %2" : "=v"(r) : "v"(lo), "v"(hi)); return r; }
; __device__ __forceinline__ float gelu_tanh(float x) {
;     const float u = 0.7978845608f * (x + 0.044715f * x * x * x);
;     return x * __builtin_amdgcn_rcpf(1.0f + __builtin_amdgcn_exp2f(-2.885390082f * u));
; }
;     __device__ __forceinline__ void operator()(const pg8::f32x4 (&acc)[2][2][4][2], const pg8::Unit& u, int wr, int wc, int fr, int fq) const {
;     ...
; #pragma unroll
;             for (int ai = 0; ai < 2; ++ai)
; #pragma unroll
;                 for (int m = 0; m < 4; ++m) { const size_t grow = grow0 + ai * HALF + m * 16;
; #pragma unroll
;                     for (int bj = 0; bj < 2; ++bj) { f32x4 v0 = acc[ai][bj][m][0], v1 = acc[ai][bj][m][1];
; #pragma unroll
;                         for (int j = 0; j < 4; ++j) { v0[j] = gelu_tanh(v0[j]); v1[j] = gelu_tanh(v1[j]); }
;                         u32x4 w; w.x = cvt_pk_bf16(v0[0], v0[1]); w.y = cvt_pk_bf16(v0[2], v0[3]); w.z = cvt_pk_bf16(v1[0], v1[1]); w.w = cvt_pk_bf16(v1[2], v1[3]);
;                         *(u32x4*)(UB + grow * 256 + bj * HALF + c8) = w; } asm volatile("" ::: "memory"); }
	v_cvt_pk_bf16_f32 v155, v158, v156
	v_add_co_u32_e32 v156, vcc, s6, v150
	v_mul_f32_e32 v143, 0x3d372713, v12
	s_nop 0
	v_addc_co_u32_e32 v157, vcc, 0, v151, vcc
	global_store_dwordx4 v[156:157], v[152:155], off
	v_mul_f32_e32 v149, 0x3d372713, v13
	v_mul_f32_e32 v143, v12, v143
	v_mul_f32_e32 v152, 0x3d372713, v9
	v_mul_f32_e32 v152, v9, v152
	v_fma_f32 v152, v9, v152, v9
	v_mul_f32_e32 v152, 0x3f4c422a, v152
	v_mul_f32_e32 v152, 0xc038aa3b, v152
	v_exp_f32_e32 v152, v152
	v_mul_f32_e32 v153, 0x3d372713, v14
	v_mul_f32_e32 v154, 0x3d372713, v10
	v_mul_f32_e32 v153, v14, v153
	v_mul_f32_e32 v154, v10, v154
	v_fma_f32 v153, v14, v153, v14
	v_fma_f32 v154, v10, v154, v10
	v_mul_f32_e32 v153, 0x3f4c422a, v153
	v_mul_f32_e32 v154, 0x3f4c422a, v154
	v_add_f32_e32 v152, 1.0, v152
	v_mul_f32_e32 v153, 0xc038aa3b, v153
	v_mul_f32_e32 v154, 0xc038aa3b, v154
	v_rcp_f32_e32 v152, v152
	v_exp_f32_e32 v153, v153
	v_exp_f32_e32 v154, v154
	v_mul_f32_e32 v145, 0x3d372713, v8
	v_mul_f32_e32 v155, v9, v152
	v_add_f32_e32 v152, 1.0, v153
	v_add_f32_e32 v153, 1.0, v154
	v_mul_f32_e32 v154, 0x3d372713, v15
	v_mul_f32_e32 v149, v13, v149
	v_mul_f32_e32 v154, v15, v154
	v_mul_f32_e32 v158, 0x3d372713, v11
	v_fma_f32 v143, v12, v143, v12
	v_mul_f32_e32 v145, v8, v145
	v_fma_f32 v149, v13, v149, v13
	v_fma_f32 v154, v15, v154, v15
	v_mul_f32_e32 v158, v11, v158
	v_mul_f32_e32 v143, 0x3f4c422a, v143
	v_fma_f32 v145, v8, v145, v8
	v_mul_f32_e32 v149, 0x3f4c422a, v149
	v_mul_f32_e32 v154, 0x3f4c422a, v154
	v_fma_f32 v158, v11, v158, v11
	v_mul_f32_e32 v143, 0xc038aa3b, v143
	v_mul_f32_e32 v145, 0x3f4c422a, v145
	v_mul_f32_e32 v149, 0xc038aa3b, v149
	v_mul_f32_e32 v154, 0xc038aa3b, v154
	v_mul_f32_e32 v158, 0x3f4c422a, v158
	v_exp_f32_e32 v143, v143
	v_mul_f32_e32 v145, 0xc038aa3b, v145
	v_exp_f32_e32 v149, v149
	v_exp_f32_e32 v154, v154
	v_mul_f32_e32 v158, 0xc038aa3b, v158
	v_exp_f32_e32 v145, v145
	v_exp_f32_e32 v158, v158
	v_add_f32_e32 v143, 1.0, v143
	v_add_f32_e32 v149, 1.0, v149
	v_add_f32_e32 v154, 1.0, v154
	v_rcp_f32_e32 v143, v143
	v_add_f32_e32 v145, 1.0, v145
	v_rcp_f32_e32 v149, v149
	v_rcp_f32_e32 v152, v152
	v_rcp_f32_e32 v153, v153
	v_rcp_f32_e32 v154, v154
	v_add_f32_e32 v158, 1.0, v158
	v_rcp_f32_e32 v145, v145
	v_rcp_f32_e32 v158, v158
	v_mul_f32_e32 v143, v12, v143
	v_mul_f32_e32 v149, v13, v149
	v_mul_f32_e32 v159, v14, v152
	v_mul_f32_e32 v160, v10, v153
	v_mul_f32_e32 v153, v15, v154
	v_cvt_pk_bf16_f32 v152, v143, v149
	v_mul_f32_e32 v145, v8, v145
	v_mul_f32_e32 v158, v11, v158
	v_cvt_pk_bf16_f32 v153, v159, v153
	v_cvt_pk_bf16_f32 v154, v145, v155
	v_cvt_pk_bf16_f32 v155, v160, v158
	global_store_dwordx4 v[156:157], v[152:155], off offset:256
	v_mul_f32_e32 v156, 0x3d372713, v71
	v_mul_f32_e32 v143, 0x3d372713, v64
	v_mul_f32_e32 v152, 0x3d372713, v69
	v_mul_f32_e32 v152, v69, v152
	v_fma_f32 v152, v69, v152, v69
	v_mul_f32_e32 v152, 0x3f4c422a, v152
	v_mul_f32_e32 v152, 0xc038aa3b, v152
	v_exp_f32_e32 v152, v152
	v_mul_f32_e32 v153, 0x3d372713, v66
	v_mul_f32_e32 v154, 0x3d372713, v70
	v_mul_f32_e32 v153, v66, v153
	v_mul_f32_e32 v154, v70, v154
	v_fma_f32 v153, v66, v153, v66
	v_fma_f32 v154, v70, v154, v70
	v_mul_f32_e32 v153, 0x3f4c422a, v153
	v_mul_f32_e32 v154, 0x3f4c422a, v154
	v_add_f32_e32 v152, 1.0, v152
	v_mul_f32_e32 v153, 0xc038aa3b, v153
	v_mul_f32_e32 v154, 0xc038aa3b, v154
	v_rcp_f32_e32 v152, v152
	v_exp_f32_e32 v153, v153
	v_exp_f32_e32 v154, v154
	v_mul_f32_e32 v145, 0x3d372713, v68
	v_mul_f32_e32 v155, v69, v152
	v_add_f32_e32 v152, 1.0, v153
	v_add_f32_e32 v153, 1.0, v154
	v_mul_f32_e32 v154, 0x3d372713, v67
	v_mul_f32_e32 v149, 0x3d372713, v65
	v_mul_f32_e32 v154, v67, v154
	v_mul_f32_e32 v156, v71, v156
	v_mul_f32_e32 v143, v64, v143
	v_mul_f32_e32 v145, v68, v145
	v_mul_f32_e32 v149, v65, v149
	v_fma_f32 v154, v67, v154, v67
	v_fma_f32 v156, v71, v156, v71
	v_fma_f32 v143, v64, v143, v64
; __device__ __forceinline__ unsigned cvt_pk_bf16(float lo, float hi) { unsigned r; asm volatile("v_cvt_pk_bf16_f32 %0, %1, %2" : "=v"(r) : "v"(lo), "v"(hi)); return r; }
; __device__ __forceinline__ float gelu_tanh(float x) {
;     const float u = 0.7978845608f * (x + 0.044715f * x * x * x);
;     return x * __builtin_amdgcn_rcpf(1.0f + __builtin_amdgcn_exp2f(-2.885390082f * u));
; }
;     __device__ __forceinline__ void operator()(const pg8::f32x4 (&acc)[2][2][4][2], const pg8::Unit& u, int wr, int wc, int fr, int fq) const {
;     ...
; #pragma unroll
;             for (int ai = 0; ai < 2; ++ai)
; #pragma unroll
;                 for (int m = 0; m < 4; ++m) { const size_t grow = grow0 + ai * HALF + m * 16;
; #pragma unroll
;                     for (int bj = 0; bj < 2; ++bj) { f32x4 v0 = acc[ai][bj][m][0], v1 = acc[ai][bj][m][1];
; #pragma unroll
;                         for (int j = 0; j < 4; ++j) { v0[j] = gelu_tanh(v0[j]); v1[j] = gelu_tanh(v1[j]); }
;                         u32x4 w; w.x = cvt_pk_bf16(v0[0], v0[1]); w.y = cvt_pk_bf16(v0[2], v0[3]); w.z = cvt_pk_bf16(v1[0], v1[1]); w.w = cvt_pk_bf16(v1[2], v1[3]);
;                         *(u32x4*)(UB + grow * 256 + bj * HALF + c8) = w; } asm volatile("" ::: "memory"); }
	v_fma_f32 v145, v68, v145, v68
	v_fma_f32 v149, v65, v149, v65
	v_mul_f32_e32 v154, 0x3f4c422a, v154
	v_mul_f32_e32 v156, 0x3f4c422a, v156
	v_mul_f32_e32 v143, 0x3f4c422a, v143
	v_mul_f32_e32 v145, 0x3f4c422a, v145
	v_mul_f32_e32 v149, 0x3f4c422a, v149
	v_mul_f32_e32 v154, 0xc038aa3b, v154
	v_mul_f32_e32 v156, 0xc038aa3b, v156
	v_mul_f32_e32 v143, 0xc038aa3b, v143
	v_mul_f32_e32 v145, 0xc038aa3b, v145
	v_mul_f32_e32 v149, 0xc038aa3b, v149
	v_exp_f32_e32 v154, v154
	v_exp_f32_e32 v156, v156
	v_exp_f32_e32 v143, v143
	v_exp_f32_e32 v145, v145
	v_exp_f32_e32 v149, v149
	v_add_f32_e32 v154, 1.0, v154
	v_add_f32_e32 v156, 1.0, v156
	v_add_f32_e32 v143, 1.0, v143
	v_add_f32_e32 v145, 1.0, v145
	v_add_f32_e32 v149, 1.0, v149
	v_rcp_f32_e32 v153, v153
	v_rcp_f32_e32 v154, v154
	v_rcp_f32_e32 v156, v156
	v_rcp_f32_e32 v143, v143
	v_rcp_f32_e32 v145, v145
	v_rcp_f32_e32 v149, v149
	v_rcp_f32_e32 v152, v152
	v_mul_f32_e32 v158, v70, v153
	v_mul_f32_e32 v153, v67, v154
	v_mul_f32_e32 v156, v71, v156
	s_mov_b32 s6, 0x22016000
	v_mul_f32_e32 v143, v64, v143
	v_mul_f32_e32 v145, v68, v145
	v_mul_f32_e32 v149, v65, v149
	v_mul_f32_e32 v157, v66, v152
	v_cvt_pk_bf16_f32 v152, v143, v149
	v_cvt_pk_bf16_f32 v153, v157, v153
	v_cvt_pk_bf16_f32 v154, v145, v155
	v_cvt_pk_bf16_f32 v155, v158, v156
	v_add_co_u32_e32 v156, vcc, s6, v150
	v_mul_f32_e32 v150, 0x3d372713, v1
	v_mul_f32_e32 v150, v1, v150
	v_fma_f32 v150, v1, v150, v1
	v_mul_f32_e32 v150, 0x3f4c422a, v150
	v_addc_co_u32_e32 v157, vcc, 0, v151, vcc
	v_mul_f32_e32 v150, 0xc038aa3b, v150
	global_store_dwordx4 v[156:157], v[152:155], off
	v_exp_f32_e32 v150, v150
	v_mul_f32_e32 v151, 0x3d372713, v6
	v_mul_f32_e32 v152, 0x3d372713, v2
	v_mul_f32_e32 v151, v6, v151
	v_mul_f32_e32 v152, v2, v152
	v_fma_f32 v151, v6, v151, v6
	v_fma_f32 v152, v2, v152, v2
	v_mul_f32_e32 v151, 0x3f4c422a, v151
	v_mul_f32_e32 v152, 0x3f4c422a, v152
	v_add_f32_e32 v150, 1.0, v150
	v_mul_f32_e32 v151, 0xc038aa3b, v151
	v_mul_f32_e32 v152, 0xc038aa3b, v152
	v_rcp_f32_e32 v150, v150
	v_exp_f32_e32 v151, v151
	v_exp_f32_e32 v152, v152
	v_mul_f32_e32 v143, 0x3d372713, v4
	v_mul_f32_e32 v153, v1, v150
	v_add_f32_e32 v150, 1.0, v151
	v_add_f32_e32 v151, 1.0, v152
	v_mul_f32_e32 v152, 0x3d372713, v7
	v_mul_f32_e32 v145, 0x3d372713, v0
	v_mul_f32_e32 v149, 0x3d372713, v5
	v_mul_f32_e32 v152, v7, v152
	v_mul_f32_e32 v154, 0x3d372713, v3
	v_mul_f32_e32 v143, v4, v143
	v_mul_f32_e32 v145, v0, v145
	v_mul_f32_e32 v149, v5, v149
	v_fma_f32 v152, v7, v152, v7
	v_mul_f32_e32 v154, v3, v154
	v_fma_f32 v143, v4, v143, v4
	v_fma_f32 v145, v0, v145, v0
	v_fma_f32 v149, v5, v149, v5
	v_mul_f32_e32 v152, 0x3f4c422a, v152
	v_fma_f32 v154, v3, v154, v3
	v_mul_f32_e32 v143, 0x3f4c422a, v143
	v_mul_f32_e32 v145, 0x3f4c422a, v145
	v_mul_f32_e32 v149, 0x3f4c422a, v149
	v_mul_f32_e32 v152, 0xc038aa3b, v152
	v_mul_f32_e32 v154, 0x3f4c422a, v154
	v_mul_f32_e32 v143, 0xc038aa3b, v143
	v_mul_f32_e32 v145, 0xc038aa3b, v145
	v_mul_f32_e32 v149, 0xc038aa3b, v149
	v_exp_f32_e32 v152, v152
	v_mul_f32_e32 v154, 0xc038aa3b, v154
	v_exp_f32_e32 v143, v143
	v_exp_f32_e32 v145, v145
	v_exp_f32_e32 v149, v149
	v_exp_f32_e32 v154, v154
	v_add_f32_e32 v152, 1.0, v152
	v_add_f32_e32 v143, 1.0, v143
	v_add_f32_e32 v145, 1.0, v145
	v_add_f32_e32 v149, 1.0, v149
	v_rcp_f32_e32 v151, v151
	v_rcp_f32_e32 v152, v152
	v_add_f32_e32 v154, 1.0, v154
	v_rcp_f32_e32 v143, v143
	v_rcp_f32_e32 v145, v145
	v_rcp_f32_e32 v149, v149
	v_rcp_f32_e32 v150, v150
	v_rcp_f32_e32 v154, v154
	v_mul_f32_e32 v158, v2, v151
	v_mul_f32_e32 v151, v7, v152
	v_mul_f32_e32 v143, v4, v143
	v_mul_f32_e32 v145, v0, v145
	v_mul_f32_e32 v149, v5, v149
	v_mul_f32_e32 v155, v6, v150
	v_mul_f32_e32 v154, v3, v154
	v_cvt_pk_bf16_f32 v150, v143, v149
	v_cvt_pk_bf16_f32 v151, v155, v151
	v_cvt_pk_bf16_f32 v152, v145, v153
	v_cvt_pk_bf16_f32 v153, v158, v154
	global_store_dwordx4 v[156:157], v[150:153], off offset:256

; __device__ __forceinline__ unsigned cvt_pk_bf16(float lo, float hi) { unsigned r; asm volatile("v_cvt_pk_bf16_f32 %0, %1, %2" : "=v"(r) : "v"(lo), "v"(hi)); return r; }
;     __device__ __forceinline__ void operator()(const pg8::f32x4 (&acc)[2][2][4][2], const pg8::Unit& u, int wr, int wc, int fr, int fq) const {
;     ...
;                     const int i0 = 8 * (fq & 1); const bool odd = (wc & 1) != 0; const float sgn = (fq < 2) ? -1.f : 1.f;
; #pragma unroll
;                     for (int ai = 0; ai < 2; ++ai)
; #pragma unroll
;                         for (int m = 0; m < 4; ++m) { const int s = sbase + ai * HALF + m * 16;
;                             f32x4 v0 = acc[ai][bj][m][0], v1 = acc[ai][bj][m][1];
;                             if (!isctx) {
;                                 const int pos = odd ? (s & 63) : (s >> 6);
;                                 const f32x4 c0 = *(const f32x4*)(ropeC + pos * 16 + i0), c1 = *(const f32x4*)(ropeC + pos * 16 + i0 + 4);
;                                 const f32x4 s0 = *(const f32x4*)(ropeS + pos * 16 + i0), s1 = *(const f32x4*)(ropeS + pos * 16 + i0 + 4);
; #pragma unroll
;                                 for (int j = 0; j < 4; ++j) { const float p0 = __shfl_xor(v0[j], 32), p1 = __shfl_xor(v1[j], 32);
;                                     v0[j] = v0[j] * c0[j] + sgn * p0 * s0[j]; v1[j] = v1[j] * c1[j] + sgn * p1 * s1[j]; }
;                             }
;                             if (pn < 2) { v0 = v0 * QSCALE; v1 = v1 * QSCALE; }
;                             u32x4 w; w.x = cvt_pk_bf16(v0[0], v0[1]); w.y = cvt_pk_bf16(v0[2], v0[3]); w.z = cvt_pk_bf16(v1[0], v1[1]); w.w = cvt_pk_bf16(v1[2], v1[3]);
;                             const size_t grow = grow0 + ai * HALF + m * 16;
;                             if (pn < 2) *(u32x4*)(QB + grow * 512 + pn * 256 + bj * HALF + c8) = w; else *(u32x4*)(KB + grow * 128 + c8) = w; asm volatile("" ::: "memory"); }
.LBB0_193:
	s_cmp_lg_u32 s91, 2
	s_cselect_b64 s[70:71], -1, 0
	s_lshl_b32 s8, s91, 8
	s_ashr_i32 s9, s8, 31
	s_lshl_b64 s[8:9], s[8:9], 1
	s_add_u32 s8, s0, s8
	v_ashrrev_i32_e32 v143, 31, v142
	s_addc_u32 s9, s1, s9
	v_lshlrev_b64 v[158:159], 1, v[142:143]
	v_lshl_add_u64 v[156:157], s[8:9], 0, v[158:159]
	s_mov_b64 s[8:9], 0x1bc00000
	s_cmp_eq_u32 s91, 2
	v_lshl_add_u64 v[156:157], v[156:157], 0, s[8:9]
	v_lshl_add_u64 v[158:159], s[0:1], 0, v[158:159]
	s_mov_b64 s[8:9], 0x1fe00000
	v_lshl_add_u64 v[158:159], v[158:159], 0, s[8:9]
	s_cselect_b64 s[8:9], -1, 0
	v_pk_mul_f32 v[160:161], v[122:123], s[48:49] op_sel_hi:[1,0]
	v_pk_mul_f32 v[162:163], v[120:121], s[48:49] op_sel_hi:[1,0]
	v_pk_mul_f32 v[164:165], v[126:127], s[48:49] op_sel_hi:[1,0]
	v_pk_mul_f32 v[166:167], v[124:125], s[48:49] op_sel_hi:[1,0]
	s_and_b64 s[18:19], s[8:9], exec
	v_cndmask_b32_e64 v126, v164, v126, s[8:9]
	v_cndmask_b32_e64 v127, v165, v127, s[8:9]
	v_cndmask_b32_e64 v124, v166, v124, s[8:9]
	v_cndmask_b32_e64 v125, v167, v125, s[8:9]
	v_cndmask_b32_e64 v123, v161, v123, s[8:9]
	v_cndmask_b32_e64 v120, v162, v120, s[8:9]
	v_cndmask_b32_e64 v121, v163, v121, s[8:9]
	s_cselect_b32 s18, 8, 10
	v_cndmask_b32_e64 v151, v160, v122, s[8:9]
	v_cvt_pk_bf16_f32 v122, v120, v121
	v_cvt_pk_bf16_f32 v123, v151, v123
	v_cvt_pk_bf16_f32 v124, v124, v125
	v_cvt_pk_bf16_f32 v125, v126, v127
	v_cndmask_b32_e64 v121, v157, v159, s[8:9]
	v_cndmask_b32_e64 v120, v156, v158, s[8:9]
	v_lshlrev_b64 v[126:127], s18, v[146:147]
	v_lshl_add_u64 v[126:127], v[120:121], 0, v[126:127]
	global_store_dwordx4 v[126:127], v[122:125], off
	v_add_u32_e32 v145, 16, v148
	v_and_b32_e32 v145, 63, v145
	s_and_b64 vcc, exec, s[6:7]
	s_cbranch_vccnz .LBB0_195
	v_add_u32_e32 v122, 16, v144
	v_ashrrev_i32_e32 v122, 6, v122
	v_cndmask_b32_e64 v122, v145, v122, s[10:11]
	v_lshlrev_b32_e32 v122, 4, v122
	v_ashrrev_i32_e32 v123, 31, v122
	v_lshlrev_b64 v[126:127], 2, v[122:123]
	v_lshl_add_u64 v[158:159], v[154:155], 0, v[126:127]
	flat_load_dwordx4 v[122:125], v[158:159]
	s_nop 0
	flat_load_dwordx4 v[158:161], v[158:159] offset:16
	v_lshl_add_u64 v[126:127], v[152:153], 0, v[126:127]
	flat_load_dwordx4 v[162:165], v[126:127]
	flat_load_dwordx4 v[166:169], v[126:127] offset:16
	v_and_b32_e32 v127, 64, v232
	v_xor_b32_e32 v126, 32, v232
	v_add_u32_e32 v127, 64, v127
	v_cmp_lt_i32_e32 vcc, v126, v127
	s_nop 1
	v_cndmask_b32_e32 v126, v232, v126, vcc
	v_lshlrev_b32_e32 v151, 2, v126
	ds_bpermute_b32 v126, v151, v112
	ds_bpermute_b32 v170, v151, v116
	ds_bpermute_b32 v127, v151, v113
	ds_bpermute_b32 v171, v151, v117
	s_waitcnt vmcnt(0) lgkmcnt(0)
	v_pk_mul_f32 v[112:113], v[112:113], v[122:123]
	v_pk_mul_f32 v[116:117], v[116:117], v[158:159]
	ds_bpermute_b32 v158, v151, v114
	ds_bpermute_b32 v159, v151, v118
	v_pk_mul_f32 v[122:123], v[150:151], v[126:127] op_sel_hi:[0,1]
	v_pk_mul_f32 v[126:127], v[150:151], v[170:171] op_sel_hi:[0,1]
	v_mul_f32_e32 v114, v114, v124
	s_waitcnt lgkmcnt(1)
	v_mul_f32_e32 v124, v150, v158
	s_waitcnt lgkmcnt(0)
	v_mul_f32_e32 v158, v150, v159
	ds_bpermute_b32 v159, v151, v115
	ds_bpermute_b32 v151, v151, v119
	v_mul_f32_e32 v124, v164, v124
	v_mul_f32_e32 v158, v168, v158
	v_mov_b32_e32 v164, v115
	s_waitcnt lgkmcnt(1)
	v_mul_f32_e32 v171, v150, v159
	v_mov_b32_e32 v170, v125
	v_pk_fma_f32 v[112:113], v[162:163], v[122:123], v[112:113]
	s_waitcnt lgkmcnt(0)
	v_mul_f32_e32 v123, v150, v151
	v_mov_b32_e32 v168, v119
	v_mov_b32_e32 v122, v161
	v_pk_mul_f32 v[164:165], v[164:165], v[170:171]
	v_pk_mul_f32 v[122:123], v[168:169], v[122:123]
	v_mul_f32_e32 v118, v118, v160
	v_mov_b32_e32 v115, v164
	v_mov_b32_e32 v125, v165
	v_mov_b32_e32 v119, v122
	v_mov_b32_e32 v159, v123
	v_pk_add_f32 v[114:115], v[114:115], v[124:125]
	v_pk_fma_f32 v[116:117], v[166:167], v[126:127], v[116:117]
	v_pk_add_f32 v[118:119], v[118:119], v[158:159]
.LBB0_195:
	v_pk_mul_f32 v[124:125], v[114:115], s[48:49] op_sel_hi:[1,0]
	v_pk_mul_f32 v[126:127], v[112:113], s[48:49] op_sel_hi:[1,0]
	v_pk_mul_f32 v[160:161], v[116:117], s[48:49] op_sel_hi:[1,0]
	v_cndmask_b32_e64 v114, v124, v114, s[8:9]
	v_cndmask_b32_e64 v116, v160, v116, s[8:9]
	v_cndmask_b32_e64 v117, v161, v117, s[8:9]
	v_cndmask_b32_e64 v112, v126, v112, s[8:9]
	v_cndmask_b32_e64 v113, v127, v113, s[8:9]
	v_cndmask_b32_e64 v115, v125, v115, s[8:9]
	v_cvt_pk_bf16_f32 v112, v112, v113
	v_cvt_pk_bf16_f32 v113, v114, v115
	v_cvt_pk_bf16_f32 v114, v116, v117
	v_lshl_add_u64 v[116:117], v[146:147], 0, 16
	v_lshlrev_b64 v[116:117], s18, v[116:117]
	v_pk_mul_f32 v[158:159], v[118:119], s[48:49] op_sel_hi:[1,0]
	v_lshl_add_u64 v[116:117], v[120:121], 0, v[116:117]
	v_cndmask_b32_e64 v118, v158, v118, s[8:9]
	v_cndmask_b32_e64 v119, v159, v119, s[8:9]
	v_cvt_pk_bf16_f32 v115, v118, v119
	global_store_dwordx4 v[116:117], v[112:115], off
	v_xor_b32_e32 v122, 32, v149
	s_and_b64 vcc, exec, s[6:7]
	s_cbranch_vccnz .LBB0_197
	v_add_u32_e32 v112, 32, v144
	v_ashrrev_i32_e32 v112, 6, v112
	v_cndmask_b32_e64 v112, v122, v112, s[10:11]
	v_lshlrev_b32_e32 v112, 4, v112
	v_ashrrev_i32_e32 v113, 31, v112
	v_lshlrev_b64 v[124:125], 2, v[112:113]
	v_lshl_add_u64 v[116:117], v[154:155], 0, v[124:125]
	flat_load_dwordx4 v[112:115], v[116:117]
	s_nop 0
	flat_load_dwordx4 v[116:119], v[116:117] offset:16
	v_lshl_add_u64 v[158:159], v[152:153], 0, v[124:125]
	flat_load_dwordx4 v[124:127], v[158:159]
	s_nop 0
	flat_load_dwordx4 v[158:161], v[158:159] offset:16
	v_and_b32_e32 v151, 64, v232
	v_xor_b32_e32 v123, 32, v232
	v_add_u32_e32 v151, 64, v151
	v_cmp_lt_i32_e32 vcc, v123, v151
	s_nop 1
	v_cndmask_b32_e32 v123, v232, v123, vcc
	v_lshlrev_b32_e32 v123, 2, v123
	ds_bpermute_b32 v162, v123, v104
	ds_bpermute_b32 v164, v123, v108
	ds_bpermute_b32 v163, v123, v105
	ds_bpermute_b32 v165, v123, v109
	s_waitcnt vmcnt(0) lgkmcnt(0)
	v_pk_mul_f32 v[104:105], v[104:105], v[112:113]
	v_pk_mul_f32 v[112:113], v[150:151], v[162:163] op_sel_hi:[0,1]
	v_pk_mul_f32 v[108:109], v[108:109], v[116:117]
	v_pk_mul_f32 v[116:117], v[150:151], v[164:165] op_sel_hi:[0,1]
	ds_bpermute_b32 v151, v123, v106
	ds_bpermute_b32 v162, v123, v110
	v_mul_f32_e32 v106, v106, v114
	v_mul_f32_e32 v110, v110, v118
	v_pk_fma_f32 v[104:105], v[124:125], v[112:113], v[104:105]
	s_waitcnt lgkmcnt(1)
	v_mul_f32_e32 v114, v150, v151
	v_mul_f32_e32 v114, v126, v114
	ds_bpermute_b32 v126, v123, v107
	ds_bpermute_b32 v123, v123, v111
	s_waitcnt lgkmcnt(2)
	v_mul_f32_e32 v118, v150, v162
	v_mul_f32_e32 v118, v160, v118
	v_mov_b32_e32 v162, v115
	s_waitcnt lgkmcnt(1)
	v_mul_f32_e32 v163, v150, v126
	v_mov_b32_e32 v126, v107
	s_waitcnt lgkmcnt(0)
	v_mul_f32_e32 v113, v150, v123
	v_mov_b32_e32 v160, v111
	v_mov_b32_e32 v112, v119
	v_pk_mul_f32 v[126:127], v[126:127], v[162:163]
	v_pk_mul_f32 v[112:113], v[160:161], v[112:113]
	v_mov_b32_e32 v107, v126
	v_mov_b32_e32 v115, v127
	v_mov_b32_e32 v111, v112
	v_mov_b32_e32 v119, v113
	v_pk_add_f32 v[106:107], v[106:107], v[114:115]
	v_pk_fma_f32 v[108:109], v[158:159], v[116:117], v[108:109]
	v_pk_add_f32 v[110:111], v[110:111], v[118:119]
; __device__ __forceinline__ unsigned cvt_pk_bf16(float lo, float hi) { unsigned r; asm volatile("v_cvt_pk_bf16_f32 %0, %1, %2" : "=v"(r) : "v"(lo), "v"(hi)); return r; }
;     __device__ __forceinline__ void operator()(const pg8::f32x4 (&acc)[2][2][4][2], const pg8::Unit& u, int wr, int wc, int fr, int fq) const {
;     ...
;                     const int i0 = 8 * (fq & 1); const bool odd = (wc & 1) != 0; const float sgn = (fq < 2) ? -1.f : 1.f;
; #pragma unroll
;                     for (int ai = 0; ai < 2; ++ai)
; #pragma unroll
;                         for (int m = 0; m < 4; ++m) { const int s = sbase + ai * HALF + m * 16;
;                             f32x4 v0 = acc[ai][bj][m][0], v1 = acc[ai][bj][m][1];
;                             if (!isctx) {
;                                 const int pos = odd ? (s & 63) : (s >> 6);
;                                 const f32x4 c0 = *(const f32x4*)(ropeC + pos * 16 + i0), c1 = *(const f32x4*)(ropeC + pos * 16 + i0 + 4);
;                                 const f32x4 s0 = *(const f32x4*)(ropeS + pos * 16 + i0), s1 = *(const f32x4*)(ropeS + pos * 16 + i0 + 4);
; #pragma unroll
;                                 for (int j = 0; j < 4; ++j) { const float p0 = __shfl_xor(v0[j], 32), p1 = __shfl_xor(v1[j], 32);
;                                     v0[j] = v0[j] * c0[j] + sgn * p0 * s0[j]; v1[j] = v1[j] * c1[j] + sgn * p1 * s1[j]; }
;                             }
;                             if (pn < 2) { v0 = v0 * QSCALE; v1 = v1 * QSCALE; }
;                             u32x4 w; w.x = cvt_pk_bf16(v0[0], v0[1]); w.y = cvt_pk_bf16(v0[2], v0[3]); w.z = cvt_pk_bf16(v1[0], v1[1]); w.w = cvt_pk_bf16(v1[2], v1[3]);
;                             const size_t grow = grow0 + ai * HALF + m * 16;
;                             if (pn < 2) *(u32x4*)(QB + grow * 512 + pn * 256 + bj * HALF + c8) = w; else *(u32x4*)(KB + grow * 128 + c8) = w; asm volatile("" ::: "memory"); }
.LBB0_197:
	v_pk_mul_f32 v[114:115], v[106:107], s[48:49] op_sel_hi:[1,0]
	v_pk_mul_f32 v[116:117], v[104:105], s[48:49] op_sel_hi:[1,0]
	v_pk_mul_f32 v[124:125], v[108:109], s[48:49] op_sel_hi:[1,0]
	v_cndmask_b32_e64 v106, v114, v106, s[8:9]
	v_cndmask_b32_e64 v108, v124, v108, s[8:9]
	v_cndmask_b32_e64 v109, v125, v109, s[8:9]
	v_cndmask_b32_e64 v104, v116, v104, s[8:9]
	v_cndmask_b32_e64 v105, v117, v105, s[8:9]
	v_cndmask_b32_e64 v107, v115, v107, s[8:9]
	v_cvt_pk_bf16_f32 v104, v104, v105
	v_cvt_pk_bf16_f32 v105, v106, v107
	v_cvt_pk_bf16_f32 v106, v108, v109
	v_lshl_add_u64 v[108:109], v[146:147], 0, 32
	v_lshlrev_b64 v[108:109], s18, v[108:109]
	v_pk_mul_f32 v[118:119], v[110:111], s[48:49] op_sel_hi:[1,0]
	v_lshl_add_u64 v[108:109], v[120:121], 0, v[108:109]
	v_cndmask_b32_e64 v110, v118, v110, s[8:9]
	v_cndmask_b32_e64 v111, v119, v111, s[8:9]
	v_cvt_pk_bf16_f32 v107, v110, v111
	global_store_dwordx4 v[108:109], v[104:107], off
	v_add_u32_e32 v112, 48, v148
	v_and_b32_e32 v112, 63, v112
	s_and_b64 vcc, exec, s[6:7]
	s_cbranch_vccnz .LBB0_199
	v_add_u32_e32 v104, 48, v144
	v_ashrrev_i32_e32 v104, 6, v104
	v_cndmask_b32_e64 v104, v112, v104, s[10:11]
	v_lshlrev_b32_e32 v104, 4, v104
	v_ashrrev_i32_e32 v105, 31, v104
	v_lshlrev_b64 v[114:115], 2, v[104:105]
	v_lshl_add_u64 v[108:109], v[154:155], 0, v[114:115]
	flat_load_dwordx4 v[104:107], v[108:109]
	s_nop 0
	flat_load_dwordx4 v[108:111], v[108:109] offset:16
	v_lshl_add_u64 v[118:119], v[152:153], 0, v[114:115]
	flat_load_dwordx4 v[114:117], v[118:119]
	flat_load_dwordx4 v[124:127], v[118:119] offset:16
	v_and_b32_e32 v118, 64, v232
	v_xor_b32_e32 v113, 32, v232
	v_add_u32_e32 v118, 64, v118
	v_cmp_lt_i32_e32 vcc, v113, v118
	s_nop 1
	v_cndmask_b32_e32 v113, v232, v113, vcc
	v_lshlrev_b32_e32 v113, 2, v113
	ds_bpermute_b32 v118, v113, v96
	ds_bpermute_b32 v119, v113, v97
	ds_bpermute_b32 v158, v113, v100
	ds_bpermute_b32 v159, v113, v101
	s_waitcnt vmcnt(0) lgkmcnt(0)
	v_pk_mul_f32 v[96:97], v[96:97], v[104:105]
	v_pk_mul_f32 v[104:105], v[150:151], v[118:119] op_sel_hi:[0,1]
	ds_bpermute_b32 v118, v113, v98
	ds_bpermute_b32 v119, v113, v102
	v_mul_f32_e32 v98, v98, v106
	v_mul_f32_e32 v102, v102, v110
	v_pk_fma_f32 v[96:97], v[114:115], v[104:105], v[96:97]
	s_waitcnt lgkmcnt(1)
	v_mul_f32_e32 v106, v150, v118
	v_mul_f32_e32 v106, v116, v106
	ds_bpermute_b32 v116, v113, v99
	ds_bpermute_b32 v113, v113, v103
	s_waitcnt lgkmcnt(2)
	v_mul_f32_e32 v110, v150, v119
	v_mul_f32_e32 v110, v126, v110
	v_mov_b32_e32 v118, v107
	s_waitcnt lgkmcnt(1)
	v_mul_f32_e32 v119, v150, v116
	v_mov_b32_e32 v116, v99
	s_waitcnt lgkmcnt(0)
	v_mul_f32_e32 v105, v150, v113
	v_mov_b32_e32 v126, v103
	v_mov_b32_e32 v104, v111
	v_pk_mul_f32 v[116:117], v[116:117], v[118:119]
	v_pk_mul_f32 v[104:105], v[126:127], v[104:105]
	v_pk_mul_f32 v[100:101], v[100:101], v[108:109]
	v_pk_mul_f32 v[108:109], v[150:151], v[158:159] op_sel_hi:[0,1]
	v_mov_b32_e32 v99, v116
	v_mov_b32_e32 v107, v117
	v_mov_b32_e32 v103, v104
	v_mov_b32_e32 v111, v105
	v_pk_add_f32 v[98:99], v[98:99], v[106:107]
	v_pk_fma_f32 v[100:101], v[124:125], v[108:109], v[100:101]
	v_pk_add_f32 v[102:103], v[102:103], v[110:111]
.LBB0_199:
	v_pk_mul_f32 v[104:105], v[98:99], s[48:49] op_sel_hi:[1,0]
	v_pk_mul_f32 v[106:107], v[96:97], s[48:49] op_sel_hi:[1,0]
	v_pk_mul_f32 v[110:111], v[100:101], s[48:49] op_sel_hi:[1,0]
	v_cndmask_b32_e64 v98, v104, v98, s[8:9]
	v_cndmask_b32_e64 v100, v110, v100, s[8:9]
	v_cndmask_b32_e64 v101, v111, v101, s[8:9]
	v_cndmask_b32_e64 v96, v106, v96, s[8:9]
	v_cndmask_b32_e64 v97, v107, v97, s[8:9]
	v_cndmask_b32_e64 v99, v105, v99, s[8:9]
	v_cvt_pk_bf16_f32 v96, v96, v97
	v_cvt_pk_bf16_f32 v97, v98, v99
	v_cvt_pk_bf16_f32 v98, v100, v101
	v_lshl_add_u64 v[100:101], v[146:147], 0, 48
	v_lshlrev_b64 v[100:101], s18, v[100:101]
	v_pk_mul_f32 v[108:109], v[102:103], s[48:49] op_sel_hi:[1,0]
	v_lshl_add_u64 v[100:101], v[120:121], 0, v[100:101]
	v_cndmask_b32_e64 v102, v108, v102, s[8:9]
	v_cndmask_b32_e64 v103, v109, v103, s[8:9]
	v_cvt_pk_bf16_f32 v99, v102, v103
	global_store_dwordx4 v[100:101], v[96:99], off
	s_and_b64 vcc, exec, s[6:7]
	s_cbranch_vccnz .LBB0_201
	v_add_u32_e32 v96, 0x80, v144
	v_ashrrev_i32_e32 v96, 6, v96
	v_cndmask_b32_e64 v96, v149, v96, s[10:11]
	v_lshlrev_b32_e32 v96, 4, v96
	v_ashrrev_i32_e32 v97, 31, v96
	v_lshlrev_b64 v[104:105], 2, v[96:97]
	v_lshl_add_u64 v[100:101], v[154:155], 0, v[104:105]
	flat_load_dwordx4 v[96:99], v[100:101]
	s_nop 0
	flat_load_dwordx4 v[100:103], v[100:101] offset:16
	v_lshl_add_u64 v[108:109], v[152:153], 0, v[104:105]
	flat_load_dwordx4 v[104:107], v[108:109]
	s_nop 0
	flat_load_dwordx4 v[108:111], v[108:109] offset:16
	v_and_b32_e32 v114, 64, v232
	v_xor_b32_e32 v113, 32, v232
	v_add_u32_e32 v114, 64, v114
	v_cmp_lt_i32_e32 vcc, v113, v114
	s_nop 1
	v_cndmask_b32_e32 v113, v232, v113, vcc
	v_lshlrev_b32_e32 v113, 2, v113
	ds_bpermute_b32 v114, v113, v88
	ds_bpermute_b32 v115, v113, v89
	ds_bpermute_b32 v116, v113, v92
	ds_bpermute_b32 v117, v113, v93
	s_waitcnt vmcnt(0) lgkmcnt(0)
	v_pk_mul_f32 v[88:89], v[88:89], v[96:97]
	v_pk_mul_f32 v[96:97], v[150:151], v[114:115] op_sel_hi:[0,1]
	ds_bpermute_b32 v114, v113, v90
	ds_bpermute_b32 v115, v113, v94
	v_mul_f32_e32 v90, v90, v98
	v_mul_f32_e32 v94, v94, v102
	v_pk_fma_f32 v[88:89], v[104:105], v[96:97], v[88:89]
	s_waitcnt lgkmcnt(1)
	v_mul_f32_e32 v98, v150, v114
	s_waitcnt lgkmcnt(0)
	v_mul_f32_e32 v102, v150, v115
	v_mul_f32_e32 v98, v106, v98
	v_mul_f32_e32 v102, v110, v102
	ds_bpermute_b32 v106, v113, v91
	ds_bpermute_b32 v110, v113, v95
	v_mov_b32_e32 v114, v99
	v_mov_b32_e32 v96, v103
	v_pk_mul_f32 v[92:93], v[92:93], v[100:101]
	s_waitcnt lgkmcnt(1)
	v_mul_f32_e32 v115, v150, v106
	v_mov_b32_e32 v106, v91
	s_waitcnt lgkmcnt(0)
	v_mul_f32_e32 v97, v150, v110
	v_mov_b32_e32 v110, v95
	v_pk_mul_f32 v[106:107], v[106:107], v[114:115]
	v_pk_mul_f32 v[96:97], v[110:111], v[96:97]
	v_pk_mul_f32 v[100:101], v[150:151], v[116:117] op_sel_hi:[0,1]
	v_mov_b32_e32 v91, v106
	v_mov_b32_e32 v99, v107
	v_mov_b32_e32 v95, v96
	v_mov_b32_e32 v103, v97
	v_pk_add_f32 v[90:91], v[90:91], v[98:99]
	v_pk_fma_f32 v[92:93], v[108:109], v[100:101], v[92:93]
	v_pk_add_f32 v[94:95], v[94:95], v[102:103]
; __device__ __forceinline__ unsigned cvt_pk_bf16(float lo, float hi) { unsigned r; asm volatile("v_cvt_pk_bf16_f32 %0, %1, %2" : "=v"(r) : "v"(lo), "v"(hi)); return r; }
;     __device__ __forceinline__ void operator()(const pg8::f32x4 (&acc)[2][2][4][2], const pg8::Unit& u, int wr, int wc, int fr, int fq) const {
;     ...
;                     const int i0 = 8 * (fq & 1); const bool odd = (wc & 1) != 0; const float sgn = (fq < 2) ? -1.f : 1.f;
; #pragma unroll
;                     for (int ai = 0; ai < 2; ++ai)
; #pragma unroll
;                         for (int m = 0; m < 4; ++m) { const int s = sbase + ai * HALF + m * 16;
;                             f32x4 v0 = acc[ai][bj][m][0], v1 = acc[ai][bj][m][1];
;                             if (!isctx) {
;                                 const int pos = odd ? (s & 63) : (s >> 6);
;                                 const f32x4 c0 = *(const f32x4*)(ropeC + pos * 16 + i0), c1 = *(const f32x4*)(ropeC + pos * 16 + i0 + 4);
;                                 const f32x4 s0 = *(const f32x4*)(ropeS + pos * 16 + i0), s1 = *(const f32x4*)(ropeS + pos * 16 + i0 + 4);
; #pragma unroll
;                                 for (int j = 0; j < 4; ++j) { const float p0 = __shfl_xor(v0[j], 32), p1 = __shfl_xor(v1[j], 32);
;                                     v0[j] = v0[j] * c0[j] + sgn * p0 * s0[j]; v1[j] = v1[j] * c1[j] + sgn * p1 * s1[j]; }
;                             }
;                             if (pn < 2) { v0 = v0 * QSCALE; v1 = v1 * QSCALE; }
;                             u32x4 w; w.x = cvt_pk_bf16(v0[0], v0[1]); w.y = cvt_pk_bf16(v0[2], v0[3]); w.z = cvt_pk_bf16(v1[0], v1[1]); w.w = cvt_pk_bf16(v1[2], v1[3]);
;                             const size_t grow = grow0 + ai * HALF + m * 16;
;                             if (pn < 2) *(u32x4*)(QB + grow * 512 + pn * 256 + bj * HALF + c8) = w; else *(u32x4*)(KB + grow * 128 + c8) = w; asm volatile("" ::: "memory"); }
.LBB0_201:
	v_pk_mul_f32 v[98:99], v[90:91], s[48:49] op_sel_hi:[1,0]
	v_pk_mul_f32 v[100:101], v[88:89], s[48:49] op_sel_hi:[1,0]
	v_pk_mul_f32 v[104:105], v[92:93], s[48:49] op_sel_hi:[1,0]
	v_lshl_add_u64 v[96:97], v[146:147], 0, s[44:45]
	v_cndmask_b32_e64 v92, v104, v92, s[8:9]
	v_cndmask_b32_e64 v93, v105, v93, s[8:9]
	v_cndmask_b32_e64 v90, v98, v90, s[8:9]
	v_cndmask_b32_e64 v88, v100, v88, s[8:9]
	v_cndmask_b32_e64 v89, v101, v89, s[8:9]
	v_cndmask_b32_e64 v91, v99, v91, s[8:9]
	v_cvt_pk_bf16_f32 v88, v88, v89
	v_cvt_pk_bf16_f32 v89, v90, v91
	v_cvt_pk_bf16_f32 v90, v92, v93
	v_lshlrev_b64 v[92:93], s18, v[96:97]
	v_pk_mul_f32 v[102:103], v[94:95], s[48:49] op_sel_hi:[1,0]
	v_lshl_add_u64 v[92:93], v[120:121], 0, v[92:93]
	v_cndmask_b32_e64 v94, v102, v94, s[8:9]
	v_cndmask_b32_e64 v95, v103, v95, s[8:9]
	v_cvt_pk_bf16_f32 v91, v94, v95
	global_store_dwordx4 v[92:93], v[88:91], off
	s_and_b64 vcc, exec, s[6:7]
	s_cbranch_vccnz .LBB0_203
	v_add_u32_e32 v88, 0x90, v144
	v_ashrrev_i32_e32 v88, 6, v88
	v_cndmask_b32_e64 v88, v145, v88, s[10:11]
	v_lshlrev_b32_e32 v88, 4, v88
	v_ashrrev_i32_e32 v89, 31, v88
	v_lshlrev_b64 v[96:97], 2, v[88:89]
	v_lshl_add_u64 v[92:93], v[154:155], 0, v[96:97]
	flat_load_dwordx4 v[88:91], v[92:93]
	s_nop 0
	flat_load_dwordx4 v[92:95], v[92:93] offset:16
	v_lshl_add_u64 v[100:101], v[152:153], 0, v[96:97]
	flat_load_dwordx4 v[96:99], v[100:101]
	s_nop 0
	flat_load_dwordx4 v[100:103], v[100:101] offset:16
	v_and_b32_e32 v105, 64, v232
	v_xor_b32_e32 v104, 32, v232
	v_add_u32_e32 v105, 64, v105
	v_cmp_lt_i32_e32 vcc, v104, v105
	s_nop 1
	v_cndmask_b32_e32 v104, v232, v104, vcc
	v_lshlrev_b32_e32 v108, 2, v104
	ds_bpermute_b32 v104, v108, v80
	ds_bpermute_b32 v105, v108, v81
	ds_bpermute_b32 v106, v108, v84
	ds_bpermute_b32 v107, v108, v85
	s_waitcnt vmcnt(0) lgkmcnt(0)
	v_pk_mul_f32 v[80:81], v[80:81], v[88:89]
	v_pk_mul_f32 v[88:89], v[150:151], v[104:105] op_sel_hi:[0,1]
	ds_bpermute_b32 v104, v108, v82
	ds_bpermute_b32 v105, v108, v86
	v_mul_f32_e32 v82, v82, v90
	v_mul_f32_e32 v86, v86, v94
	v_pk_fma_f32 v[80:81], v[96:97], v[88:89], v[80:81]
	s_waitcnt lgkmcnt(1)
	v_mul_f32_e32 v90, v150, v104
	s_waitcnt lgkmcnt(0)
	v_mul_f32_e32 v94, v150, v105
	v_mul_f32_e32 v90, v98, v90
	v_mul_f32_e32 v94, v102, v94
	ds_bpermute_b32 v98, v108, v83
	ds_bpermute_b32 v102, v108, v87
	v_mov_b32_e32 v104, v91
	v_mov_b32_e32 v88, v95
	v_pk_mul_f32 v[84:85], v[84:85], v[92:93]
	s_waitcnt lgkmcnt(1)
	v_mul_f32_e32 v105, v150, v98
	v_mov_b32_e32 v98, v83
	s_waitcnt lgkmcnt(0)
	v_mul_f32_e32 v89, v150, v102
	v_mov_b32_e32 v102, v87
	v_pk_mul_f32 v[98:99], v[98:99], v[104:105]
	v_pk_mul_f32 v[88:89], v[102:103], v[88:89]
	v_pk_mul_f32 v[92:93], v[150:151], v[106:107] op_sel_hi:[0,1]
	v_mov_b32_e32 v83, v98
	v_mov_b32_e32 v91, v99
	v_mov_b32_e32 v87, v88
	v_mov_b32_e32 v95, v89
	v_pk_add_f32 v[82:83], v[82:83], v[90:91]
	v_pk_fma_f32 v[84:85], v[100:101], v[92:93], v[84:85]
	v_pk_add_f32 v[86:87], v[86:87], v[94:95]
.LBB0_203:
	v_pk_mul_f32 v[88:89], v[82:83], s[48:49] op_sel_hi:[1,0]
	v_pk_mul_f32 v[90:91], v[80:81], s[48:49] op_sel_hi:[1,0]
	v_pk_mul_f32 v[94:95], v[84:85], s[48:49] op_sel_hi:[1,0]
	v_cndmask_b32_e64 v82, v88, v82, s[8:9]
	v_cndmask_b32_e64 v84, v94, v84, s[8:9]
	v_cndmask_b32_e64 v85, v95, v85, s[8:9]
	v_cndmask_b32_e64 v80, v90, v80, s[8:9]
	v_cndmask_b32_e64 v81, v91, v81, s[8:9]
	s_mov_b64 s[24:25], 0x90
	v_cndmask_b32_e64 v83, v89, v83, s[8:9]
	v_cvt_pk_bf16_f32 v80, v80, v81
	v_cvt_pk_bf16_f32 v81, v82, v83
	v_cvt_pk_bf16_f32 v82, v84, v85
	v_lshl_add_u64 v[84:85], v[146:147], 0, s[24:25]
	v_lshlrev_b64 v[84:85], s18, v[84:85]
	v_pk_mul_f32 v[92:93], v[86:87], s[48:49] op_sel_hi:[1,0]
	v_lshl_add_u64 v[84:85], v[120:121], 0, v[84:85]
	v_cndmask_b32_e64 v86, v92, v86, s[8:9]
	v_cndmask_b32_e64 v87, v93, v87, s[8:9]
	v_cvt_pk_bf16_f32 v83, v86, v87
	global_store_dwordx4 v[84:85], v[80:83], off
	s_and_b64 vcc, exec, s[6:7]
	s_cbranch_vccnz .LBB0_205
	v_add_u32_e32 v80, 0xa0, v144
	v_ashrrev_i32_e32 v80, 6, v80
	v_cndmask_b32_e64 v80, v122, v80, s[10:11]
	v_lshlrev_b32_e32 v80, 4, v80
	v_ashrrev_i32_e32 v81, 31, v80
	v_lshlrev_b64 v[88:89], 2, v[80:81]
	v_lshl_add_u64 v[84:85], v[154:155], 0, v[88:89]
	flat_load_dwordx4 v[80:83], v[84:85]
	s_nop 0
	flat_load_dwordx4 v[84:87], v[84:85] offset:16
	v_lshl_add_u64 v[92:93], v[152:153], 0, v[88:89]
	flat_load_dwordx4 v[88:91], v[92:93]
	s_nop 0
	flat_load_dwordx4 v[92:95], v[92:93] offset:16
	v_and_b32_e32 v97, 64, v232
	v_xor_b32_e32 v96, 32, v232
	v_add_u32_e32 v97, 64, v97
	v_cmp_lt_i32_e32 vcc, v96, v97
	s_nop 1
	v_cndmask_b32_e32 v96, v232, v96, vcc
	v_lshlrev_b32_e32 v100, 2, v96
	ds_bpermute_b32 v96, v100, v72
	ds_bpermute_b32 v97, v100, v73
	ds_bpermute_b32 v98, v100, v76
	ds_bpermute_b32 v99, v100, v77
	s_waitcnt vmcnt(0) lgkmcnt(0)
	v_pk_mul_f32 v[72:73], v[72:73], v[80:81]
	v_pk_mul_f32 v[80:81], v[150:151], v[96:97] op_sel_hi:[0,1]
	ds_bpermute_b32 v96, v100, v74
	ds_bpermute_b32 v97, v100, v78
	v_mul_f32_e32 v74, v74, v82
	v_mul_f32_e32 v78, v78, v86
	v_pk_fma_f32 v[72:73], v[88:89], v[80:81], v[72:73]
	s_waitcnt lgkmcnt(1)
	v_mul_f32_e32 v82, v150, v96
	s_waitcnt lgkmcnt(0)
	v_mul_f32_e32 v86, v150, v97
	v_mul_f32_e32 v82, v90, v82
	v_mul_f32_e32 v86, v94, v86
	ds_bpermute_b32 v90, v100, v75
	ds_bpermute_b32 v94, v100, v79
	v_mov_b32_e32 v96, v83
	v_mov_b32_e32 v80, v87
	v_pk_mul_f32 v[76:77], v[76:77], v[84:85]
	s_waitcnt lgkmcnt(1)
	v_mul_f32_e32 v97, v150, v90
	v_mov_b32_e32 v90, v75
	s_waitcnt lgkmcnt(0)
	v_mul_f32_e32 v81, v150, v94
	v_mov_b32_e32 v94, v79
	v_pk_mul_f32 v[90:91], v[90:91], v[96:97]
	v_pk_mul_f32 v[80:81], v[94:95], v[80:81]
	v_pk_mul_f32 v[84:85], v[150:151], v[98:99] op_sel_hi:[0,1]
	v_mov_b32_e32 v75, v90
	v_mov_b32_e32 v83, v91
	v_mov_b32_e32 v79, v80
	v_mov_b32_e32 v87, v81
	v_pk_add_f32 v[74:75], v[74:75], v[82:83]
	v_pk_fma_f32 v[76:77], v[92:93], v[84:85], v[76:77]
	v_pk_add_f32 v[78:79], v[78:79], v[86:87]
; __device__ __forceinline__ unsigned cvt_pk_bf16(float lo, float hi) { unsigned r; asm volatile("v_cvt_pk_bf16_f32 %0, %1, %2" : "=v"(r) : "v"(lo), "v"(hi)); return r; }
;     __device__ __forceinline__ void operator()(const pg8::f32x4 (&acc)[2][2][4][2], const pg8::Unit& u, int wr, int wc, int fr, int fq) const {
;     ...
;                     const int i0 = 8 * (fq & 1); const bool odd = (wc & 1) != 0; const float sgn = (fq < 2) ? -1.f : 1.f;
; #pragma unroll
;                     for (int ai = 0; ai < 2; ++ai)
; #pragma unroll
;                         for (int m = 0; m < 4; ++m) { const int s = sbase + ai * HALF + m * 16;
;                             f32x4 v0 = acc[ai][bj][m][0], v1 = acc[ai][bj][m][1];
;                             if (!isctx) {
;                                 const int pos = odd ? (s & 63) : (s >> 6);
;                                 const f32x4 c0 = *(const f32x4*)(ropeC + pos * 16 + i0), c1 = *(const f32x4*)(ropeC + pos * 16 + i0 + 4);
;                                 const f32x4 s0 = *(const f32x4*)(ropeS + pos * 16 + i0), s1 = *(const f32x4*)(ropeS + pos * 16 + i0 + 4);
; #pragma unroll
;                                 for (int j = 0; j < 4; ++j) { const float p0 = __shfl_xor(v0[j], 32), p1 = __shfl_xor(v1[j], 32);
;                                     v0[j] = v0[j] * c0[j] + sgn * p0 * s0[j]; v1[j] = v1[j] * c1[j] + sgn * p1 * s1[j]; }
;                             }
;                             if (pn < 2) { v0 = v0 * QSCALE; v1 = v1 * QSCALE; }
;                             u32x4 w; w.x = cvt_pk_bf16(v0[0], v0[1]); w.y = cvt_pk_bf16(v0[2], v0[3]); w.z = cvt_pk_bf16(v1[0], v1[1]); w.w = cvt_pk_bf16(v1[2], v1[3]);
;                             const size_t grow = grow0 + ai * HALF + m * 16;
;                             if (pn < 2) *(u32x4*)(QB + grow * 512 + pn * 256 + bj * HALF + c8) = w; else *(u32x4*)(KB + grow * 128 + c8) = w; asm volatile("" ::: "memory"); }
.LBB0_205:
	v_pk_mul_f32 v[80:81], v[74:75], s[48:49] op_sel_hi:[1,0]
	v_pk_mul_f32 v[82:83], v[72:73], s[48:49] op_sel_hi:[1,0]
	v_pk_mul_f32 v[86:87], v[76:77], s[48:49] op_sel_hi:[1,0]
	v_cndmask_b32_e64 v74, v80, v74, s[8:9]
	v_cndmask_b32_e64 v76, v86, v76, s[8:9]
	v_cndmask_b32_e64 v77, v87, v77, s[8:9]
	v_cndmask_b32_e64 v72, v82, v72, s[8:9]
	v_cndmask_b32_e64 v73, v83, v73, s[8:9]
	s_mov_b64 s[24:25], 0xa0
	v_cndmask_b32_e64 v75, v81, v75, s[8:9]
	v_cvt_pk_bf16_f32 v72, v72, v73
	v_cvt_pk_bf16_f32 v73, v74, v75
	v_cvt_pk_bf16_f32 v74, v76, v77
	v_lshl_add_u64 v[76:77], v[146:147], 0, s[24:25]
	v_lshlrev_b64 v[76:77], s18, v[76:77]
	v_pk_mul_f32 v[84:85], v[78:79], s[48:49] op_sel_hi:[1,0]
	v_lshl_add_u64 v[76:77], v[120:121], 0, v[76:77]
	v_cndmask_b32_e64 v78, v84, v78, s[8:9]
	v_cndmask_b32_e64 v79, v85, v79, s[8:9]
	v_cvt_pk_bf16_f32 v75, v78, v79
	global_store_dwordx4 v[76:77], v[72:75], off
	s_and_b64 vcc, exec, s[6:7]
	s_cbranch_vccnz .LBB0_207
	v_add_u32_e32 v72, 0xb0, v144
	v_ashrrev_i32_e32 v72, 6, v72
	v_cndmask_b32_e64 v72, v112, v72, s[10:11]
	v_lshlrev_b32_e32 v72, 4, v72
	v_ashrrev_i32_e32 v73, 31, v72
	v_lshlrev_b64 v[80:81], 2, v[72:73]
	v_lshl_add_u64 v[76:77], v[154:155], 0, v[80:81]
	flat_load_dwordx4 v[72:75], v[76:77]
	s_nop 0
	flat_load_dwordx4 v[76:79], v[76:77] offset:16
	v_lshl_add_u64 v[84:85], v[152:153], 0, v[80:81]
	flat_load_dwordx4 v[80:83], v[84:85]
	s_nop 0
	flat_load_dwordx4 v[84:87], v[84:85] offset:16
	v_and_b32_e32 v89, 64, v232
	v_xor_b32_e32 v88, 32, v232
	v_add_u32_e32 v89, 64, v89
	v_cmp_lt_i32_e32 vcc, v88, v89
	s_nop 1
	v_cndmask_b32_e32 v88, v232, v88, vcc
	v_lshlrev_b32_e32 v92, 2, v88
	ds_bpermute_b32 v88, v92, v64
	ds_bpermute_b32 v89, v92, v65
	ds_bpermute_b32 v90, v92, v68
	ds_bpermute_b32 v91, v92, v69
	s_waitcnt vmcnt(0) lgkmcnt(0)
	v_pk_mul_f32 v[64:65], v[64:65], v[72:73]
	v_pk_mul_f32 v[72:73], v[150:151], v[88:89] op_sel_hi:[0,1]
	ds_bpermute_b32 v88, v92, v66
	ds_bpermute_b32 v89, v92, v70
	v_mul_f32_e32 v66, v66, v74
	v_mul_f32_e32 v70, v70, v78
	v_pk_fma_f32 v[64:65], v[80:81], v[72:73], v[64:65]
	s_waitcnt lgkmcnt(1)
	v_mul_f32_e32 v74, v150, v88
	s_waitcnt lgkmcnt(0)
	v_mul_f32_e32 v78, v150, v89
	v_mul_f32_e32 v74, v82, v74
	v_mul_f32_e32 v78, v86, v78
	ds_bpermute_b32 v82, v92, v67
	ds_bpermute_b32 v86, v92, v71
	v_mov_b32_e32 v88, v75
	v_mov_b32_e32 v72, v79
	v_pk_mul_f32 v[68:69], v[68:69], v[76:77]
	s_waitcnt lgkmcnt(1)
	v_mul_f32_e32 v89, v150, v82
	v_mov_b32_e32 v82, v67
	s_waitcnt lgkmcnt(0)
	v_mul_f32_e32 v73, v150, v86
	v_mov_b32_e32 v86, v71
	v_pk_mul_f32 v[82:83], v[82:83], v[88:89]
	v_pk_mul_f32 v[72:73], v[86:87], v[72:73]
	v_pk_mul_f32 v[76:77], v[150:151], v[90:91] op_sel_hi:[0,1]
	v_mov_b32_e32 v67, v82
	v_mov_b32_e32 v75, v83
	v_mov_b32_e32 v71, v72
	v_mov_b32_e32 v79, v73
	v_pk_add_f32 v[66:67], v[66:67], v[74:75]
	v_pk_fma_f32 v[68:69], v[84:85], v[76:77], v[68:69]
	v_pk_add_f32 v[70:71], v[70:71], v[78:79]
.LBB0_207:
	v_pk_mul_f32 v[72:73], v[66:67], s[48:49] op_sel_hi:[1,0]
	v_pk_mul_f32 v[74:75], v[64:65], s[48:49] op_sel_hi:[1,0]
	v_pk_mul_f32 v[76:77], v[70:71], s[48:49] op_sel_hi:[1,0]
	v_pk_mul_f32 v[78:79], v[68:69], s[48:49] op_sel_hi:[1,0]
	v_cndmask_b32_e64 v70, v76, v70, s[8:9]
	v_cndmask_b32_e64 v71, v77, v71, s[8:9]
	v_cndmask_b32_e64 v68, v78, v68, s[8:9]
	v_cndmask_b32_e64 v69, v79, v69, s[8:9]
	v_cndmask_b32_e64 v66, v72, v66, s[8:9]
	v_cndmask_b32_e64 v67, v73, v67, s[8:9]
	v_cndmask_b32_e64 v64, v74, v64, s[8:9]
	v_cndmask_b32_e64 v65, v75, v65, s[8:9]
	s_mov_b64 s[8:9], 0xb0
	v_cvt_pk_bf16_f32 v64, v64, v65
	v_cvt_pk_bf16_f32 v65, v66, v67
	v_cvt_pk_bf16_f32 v66, v68, v69
	v_lshl_add_u64 v[68:69], v[146:147], 0, s[8:9]
	v_lshlrev_b64 v[68:69], s18, v[68:69]
	v_lshl_add_u64 v[68:69], v[120:121], 0, v[68:69]
	v_cvt_pk_bf16_f32 v67, v70, v71
	global_store_dwordx4 v[68:69], v[64:67], off
	s_andn2_b64 vcc, exec, s[70:71]
	s_mov_b64 s[8:9], -1
	s_cbranch_vccnz .LBB0_233
	s_and_b64 vcc, exec, s[6:7]
	s_cbranch_vccnz .LBB0_210
	v_ashrrev_i32_e32 v64, 6, v144
	v_cndmask_b32_e64 v64, v149, v64, s[10:11]
	v_lshlrev_b32_e32 v64, 4, v64
	v_ashrrev_i32_e32 v65, 31, v64
	v_lshlrev_b64 v[72:73], 2, v[64:65]
	v_lshl_add_u64 v[68:69], v[154:155], 0, v[72:73]
	v_lshl_add_u64 v[76:77], v[152:153], 0, v[72:73]
	flat_load_dwordx4 v[64:67], v[68:69]
	s_nop 0
	flat_load_dwordx4 v[68:71], v[68:69] offset:16
	s_nop 0
	flat_load_dwordx4 v[72:75], v[76:77]
	s_nop 0
	flat_load_dwordx4 v[76:79], v[76:77] offset:16
	v_and_b32_e32 v81, 64, v232
	v_xor_b32_e32 v80, 32, v232
	v_add_u32_e32 v81, 64, v81
	v_cmp_lt_i32_e32 vcc, v80, v81
	s_waitcnt vmcnt(0) lgkmcnt(0)
	v_pk_mul_f32 v[64:65], v[60:61], v[64:65]
	v_cndmask_b32_e32 v80, v232, v80, vcc
	v_lshlrev_b32_e32 v85, 2, v80
	ds_bpermute_b32 v84, v85, v62
	ds_bpermute_b32 v86, v85, v58
	ds_bpermute_b32 v80, v85, v60
	ds_bpermute_b32 v81, v85, v61
	ds_bpermute_b32 v82, v85, v56
	s_waitcnt lgkmcnt(4)
	v_mul_f32_e32 v84, v150, v84
	v_mul_f32_e32 v84, v74, v84
	s_waitcnt lgkmcnt(3)
	v_mul_f32_e32 v74, v150, v86
	v_mul_f32_e32 v86, v78, v74
	ds_bpermute_b32 v74, v85, v63
	ds_bpermute_b32 v78, v85, v59
	ds_bpermute_b32 v83, v85, v57
	s_waitcnt lgkmcnt(4)
	v_pk_mul_f32 v[80:81], v[150:151], v[80:81] op_sel_hi:[0,1]
	v_mov_b32_e32 v88, v67
	s_waitcnt lgkmcnt(2)
	v_mul_f32_e32 v89, v150, v74
	v_mov_b32_e32 v74, v63
	v_pk_fma_f32 v[64:65], v[72:73], v[80:81], v[64:65]
	s_waitcnt lgkmcnt(1)
	v_mul_f32_e32 v73, v150, v78
	v_mov_b32_e32 v78, v59
	v_mov_b32_e32 v72, v71
	v_pk_mul_f32 v[74:75], v[74:75], v[88:89]
	v_pk_mul_f32 v[72:73], v[78:79], v[72:73]
	v_pk_mul_f32 v[68:69], v[56:57], v[68:69]
	s_waitcnt lgkmcnt(0)
	v_pk_mul_f32 v[82:83], v[150:151], v[82:83] op_sel_hi:[0,1]
	v_mul_f32_e32 v66, v62, v66
	v_mul_f32_e32 v70, v58, v70
	v_mov_b32_e32 v67, v74
	v_mov_b32_e32 v85, v75
	v_mov_b32_e32 v71, v72
	v_mov_b32_e32 v87, v73
	v_pk_add_f32 v[66:67], v[66:67], v[84:85]
	v_pk_fma_f32 v[68:69], v[76:77], v[82:83], v[68:69]
	v_pk_add_f32 v[70:71], v[70:71], v[86:87]
	s_branch .LBB0_211

; __device__ __forceinline__ unsigned cvt_pk_bf16(float lo, float hi) { unsigned r; asm volatile("v_cvt_pk_bf16_f32 %0, %1, %2" : "=v"(r) : "v"(lo), "v"(hi)); return r; }
;     __device__ __forceinline__ void operator()(const pg8::f32x4 (&acc)[2][2][4][2], const pg8::Unit& u, int wr, int wc, int fr, int fq) const {
;     ...
;                     const int i0 = 8 * (fq & 1); const bool odd = (wc & 1) != 0; const float sgn = (fq < 2) ? -1.f : 1.f;
; #pragma unroll
;                     for (int ai = 0; ai < 2; ++ai)
; #pragma unroll
;                         for (int m = 0; m < 4; ++m) { const int s = sbase + ai * HALF + m * 16;
;                             f32x4 v0 = acc[ai][bj][m][0], v1 = acc[ai][bj][m][1];
;                             if (!isctx) {
;                                 const int pos = odd ? (s & 63) : (s >> 6);
;                                 const f32x4 c0 = *(const f32x4*)(ropeC + pos * 16 + i0), c1 = *(const f32x4*)(ropeC + pos * 16 + i0 + 4);
;                                 const f32x4 s0 = *(const f32x4*)(ropeS + pos * 16 + i0), s1 = *(const f32x4*)(ropeS + pos * 16 + i0 + 4);
; #pragma unroll
;                                 for (int j = 0; j < 4; ++j) { const float p0 = __shfl_xor(v0[j], 32), p1 = __shfl_xor(v1[j], 32);
;                                     v0[j] = v0[j] * c0[j] + sgn * p0 * s0[j]; v1[j] = v1[j] * c1[j] + sgn * p1 * s1[j]; }
;                             }
;                             if (pn < 2) { v0 = v0 * QSCALE; v1 = v1 * QSCALE; }
;                             u32x4 w; w.x = cvt_pk_bf16(v0[0], v0[1]); w.y = cvt_pk_bf16(v0[2], v0[3]); w.z = cvt_pk_bf16(v1[0], v1[1]); w.w = cvt_pk_bf16(v1[2], v1[3]);
;                             const size_t grow = grow0 + ai * HALF + m * 16;
;                             if (pn < 2) *(u32x4*)(QB + grow * 512 + pn * 256 + bj * HALF + c8) = w; else *(u32x4*)(KB + grow * 128 + c8) = w; asm volatile("" ::: "memory"); }
.LBB0_211:
	v_pk_mul_f32 v[66:67], v[66:67], s[48:49] op_sel_hi:[1,0]
	v_pk_mul_f32 v[64:65], v[64:65], s[48:49] op_sel_hi:[1,0]
	v_pk_mul_f32 v[68:69], v[68:69], s[48:49] op_sel_hi:[1,0]
	v_cvt_pk_bf16_f32 v64, v64, v65
	v_cvt_pk_bf16_f32 v65, v66, v67
	v_pk_mul_f32 v[70:71], v[70:71], s[48:49] op_sel_hi:[1,0]
	v_cvt_pk_bf16_f32 v66, v68, v69
	v_lshlrev_b64 v[68:69], 10, v[146:147]
	v_lshl_add_u64 v[72:73], v[156:157], 0, v[68:69]
	v_cvt_pk_bf16_f32 v67, v70, v71
	global_store_dwordx4 v[72:73], v[64:67], off offset:256
	s_and_b64 vcc, exec, s[6:7]
	s_cbranch_vccnz .LBB0_213
	v_add_u32_e32 v64, 16, v144
	v_ashrrev_i32_e32 v64, 6, v64
	v_cndmask_b32_e64 v64, v145, v64, s[10:11]
	v_lshlrev_b32_e32 v64, 4, v64
	v_ashrrev_i32_e32 v65, 31, v64
	v_lshlrev_b64 v[74:75], 2, v[64:65]
	v_lshl_add_u64 v[68:69], v[154:155], 0, v[74:75]
	v_lshl_add_u64 v[78:79], v[152:153], 0, v[74:75]
	flat_load_dwordx4 v[64:67], v[68:69]
	s_nop 0
	flat_load_dwordx4 v[68:71], v[68:69] offset:16
	s_nop 0
	flat_load_dwordx4 v[74:77], v[78:79]
	s_nop 0
	flat_load_dwordx4 v[78:81], v[78:79] offset:16
	v_and_b32_e32 v83, 64, v232
	v_xor_b32_e32 v82, 32, v232
	v_add_u32_e32 v83, 64, v83
	v_cmp_lt_i32_e32 vcc, v82, v83
	s_waitcnt vmcnt(0) lgkmcnt(0)
	v_pk_mul_f32 v[64:65], v[52:53], v[64:65]
	v_cndmask_b32_e32 v82, v232, v82, vcc
	v_lshlrev_b32_e32 v87, 2, v82
	ds_bpermute_b32 v86, v87, v54
	ds_bpermute_b32 v88, v87, v50
	ds_bpermute_b32 v82, v87, v52
	ds_bpermute_b32 v83, v87, v53
	ds_bpermute_b32 v84, v87, v48
	s_waitcnt lgkmcnt(4)
	v_mul_f32_e32 v86, v150, v86
	v_mul_f32_e32 v86, v76, v86
	s_waitcnt lgkmcnt(3)
	v_mul_f32_e32 v76, v150, v88
	v_mul_f32_e32 v88, v80, v76
	ds_bpermute_b32 v76, v87, v55
	ds_bpermute_b32 v80, v87, v51
	ds_bpermute_b32 v85, v87, v49
	s_waitcnt lgkmcnt(4)
	v_pk_mul_f32 v[82:83], v[150:151], v[82:83] op_sel_hi:[0,1]
	v_mov_b32_e32 v90, v67
	s_waitcnt lgkmcnt(2)
	v_mul_f32_e32 v91, v150, v76
	v_mov_b32_e32 v76, v55
	v_pk_fma_f32 v[64:65], v[74:75], v[82:83], v[64:65]
	s_waitcnt lgkmcnt(1)
	v_mul_f32_e32 v75, v150, v80
	v_mov_b32_e32 v80, v51
	v_mov_b32_e32 v74, v71
	v_pk_mul_f32 v[76:77], v[76:77], v[90:91]
	v_pk_mul_f32 v[74:75], v[80:81], v[74:75]
	v_pk_mul_f32 v[68:69], v[48:49], v[68:69]
	s_waitcnt lgkmcnt(0)
	v_pk_mul_f32 v[84:85], v[150:151], v[84:85] op_sel_hi:[0,1]
	v_mul_f32_e32 v66, v54, v66
	v_mul_f32_e32 v70, v50, v70
	v_mov_b32_e32 v67, v76
	v_mov_b32_e32 v87, v77
	v_mov_b32_e32 v71, v74
	v_mov_b32_e32 v89, v75
	v_pk_add_f32 v[66:67], v[66:67], v[86:87]
	v_pk_fma_f32 v[68:69], v[78:79], v[84:85], v[68:69]
	v_pk_add_f32 v[70:71], v[70:71], v[88:89]
	s_branch .LBB0_214

; __device__ __forceinline__ unsigned cvt_pk_bf16(float lo, float hi) { unsigned r; asm volatile("v_cvt_pk_bf16_f32 %0, %1, %2" : "=v"(r) : "v"(lo), "v"(hi)); return r; }
;     __device__ __forceinline__ void operator()(const pg8::f32x4 (&acc)[2][2][4][2], const pg8::Unit& u, int wr, int wc, int fr, int fq) const {
;     ...
;                     const int i0 = 8 * (fq & 1); const bool odd = (wc & 1) != 0; const float sgn = (fq < 2) ? -1.f : 1.f;
; #pragma unroll
;                     for (int ai = 0; ai < 2; ++ai)
; #pragma unroll
;                         for (int m = 0; m < 4; ++m) { const int s = sbase + ai * HALF + m * 16;
;                             f32x4 v0 = acc[ai][bj][m][0], v1 = acc[ai][bj][m][1];
;                             if (!isctx) {
;                                 const int pos = odd ? (s & 63) : (s >> 6);
;                                 const f32x4 c0 = *(const f32x4*)(ropeC + pos * 16 + i0), c1 = *(const f32x4*)(ropeC + pos * 16 + i0 + 4);
;                                 const f32x4 s0 = *(const f32x4*)(ropeS + pos * 16 + i0), s1 = *(const f32x4*)(ropeS + pos * 16 + i0 + 4);
; #pragma unroll
;                                 for (int j = 0; j < 4; ++j) { const float p0 = __shfl_xor(v0[j], 32), p1 = __shfl_xor(v1[j], 32);
;                                     v0[j] = v0[j] * c0[j] + sgn * p0 * s0[j]; v1[j] = v1[j] * c1[j] + sgn * p1 * s1[j]; }
;                             }
;                             if (pn < 2) { v0 = v0 * QSCALE; v1 = v1 * QSCALE; }
;                             u32x4 w; w.x = cvt_pk_bf16(v0[0], v0[1]); w.y = cvt_pk_bf16(v0[2], v0[3]); w.z = cvt_pk_bf16(v1[0], v1[1]); w.w = cvt_pk_bf16(v1[2], v1[3]);
;                             const size_t grow = grow0 + ai * HALF + m * 16;
;                             if (pn < 2) *(u32x4*)(QB + grow * 512 + pn * 256 + bj * HALF + c8) = w; else *(u32x4*)(KB + grow * 128 + c8) = w; asm volatile("" ::: "memory"); }
.LBB0_214:
	s_mov_b64 s[8:9], 0x100
	v_lshl_add_u64 v[72:73], v[72:73], 0, s[8:9]
	v_pk_mul_f32 v[66:67], v[66:67], s[48:49] op_sel_hi:[1,0]
	v_pk_mul_f32 v[64:65], v[64:65], s[48:49] op_sel_hi:[1,0]
	v_pk_mul_f32 v[68:69], v[68:69], s[48:49] op_sel_hi:[1,0]
	v_cvt_pk_bf16_f32 v64, v64, v65
	v_cvt_pk_bf16_f32 v65, v66, v67
	v_pk_mul_f32 v[70:71], v[70:71], s[48:49] op_sel_hi:[1,0]
	v_cvt_pk_bf16_f32 v66, v68, v69
	v_add_co_u32_e32 v68, vcc, 0x4000, v72
	v_cvt_pk_bf16_f32 v67, v70, v71
	s_nop 1
	v_addc_co_u32_e32 v69, vcc, 0, v73, vcc
	global_store_dwordx4 v[68:69], v[64:67], off
	s_and_b64 vcc, exec, s[6:7]
	s_cbranch_vccnz .LBB0_216
	v_add_u32_e32 v64, 32, v144
	v_ashrrev_i32_e32 v64, 6, v64
	v_cndmask_b32_e64 v64, v122, v64, s[10:11]
	v_lshlrev_b32_e32 v64, 4, v64
	v_ashrrev_i32_e32 v65, 31, v64
	v_lshlrev_b64 v[74:75], 2, v[64:65]
	v_lshl_add_u64 v[68:69], v[154:155], 0, v[74:75]
	v_lshl_add_u64 v[78:79], v[152:153], 0, v[74:75]
	flat_load_dwordx4 v[64:67], v[68:69]
	s_nop 0
	flat_load_dwordx4 v[68:71], v[68:69] offset:16
	s_nop 0
	flat_load_dwordx4 v[74:77], v[78:79]
	s_nop 0
	flat_load_dwordx4 v[78:81], v[78:79] offset:16
	v_and_b32_e32 v83, 64, v232
	v_xor_b32_e32 v82, 32, v232
	v_add_u32_e32 v83, 64, v83
	v_cmp_lt_i32_e32 vcc, v82, v83
	s_waitcnt vmcnt(0) lgkmcnt(0)
	v_pk_mul_f32 v[64:65], v[44:45], v[64:65]
	v_cndmask_b32_e32 v82, v232, v82, vcc
	v_lshlrev_b32_e32 v87, 2, v82
	ds_bpermute_b32 v86, v87, v46
	ds_bpermute_b32 v88, v87, v42
	ds_bpermute_b32 v82, v87, v44
	ds_bpermute_b32 v83, v87, v45
	ds_bpermute_b32 v84, v87, v40
	s_waitcnt lgkmcnt(4)
	v_mul_f32_e32 v86, v150, v86
	v_mul_f32_e32 v86, v76, v86
	s_waitcnt lgkmcnt(3)
	v_mul_f32_e32 v76, v150, v88
	v_mul_f32_e32 v88, v80, v76
	ds_bpermute_b32 v76, v87, v47
	ds_bpermute_b32 v80, v87, v43
	ds_bpermute_b32 v85, v87, v41
	s_waitcnt lgkmcnt(4)
	v_pk_mul_f32 v[82:83], v[150:151], v[82:83] op_sel_hi:[0,1]
	v_mov_b32_e32 v90, v67
	s_waitcnt lgkmcnt(2)
	v_mul_f32_e32 v91, v150, v76
	v_mov_b32_e32 v76, v47
	v_pk_fma_f32 v[64:65], v[74:75], v[82:83], v[64:65]
	s_waitcnt lgkmcnt(1)
	v_mul_f32_e32 v75, v150, v80
	v_mov_b32_e32 v80, v43
	v_mov_b32_e32 v74, v71
	v_pk_mul_f32 v[76:77], v[76:77], v[90:91]
	v_pk_mul_f32 v[74:75], v[80:81], v[74:75]
	v_pk_mul_f32 v[68:69], v[40:41], v[68:69]
	s_waitcnt lgkmcnt(0)
	v_pk_mul_f32 v[84:85], v[150:151], v[84:85] op_sel_hi:[0,1]
	v_mul_f32_e32 v66, v46, v66
	v_mul_f32_e32 v70, v42, v70
	v_mov_b32_e32 v67, v76
	v_mov_b32_e32 v87, v77
	v_mov_b32_e32 v71, v74
	v_mov_b32_e32 v89, v75
	v_pk_add_f32 v[66:67], v[66:67], v[86:87]
	v_pk_fma_f32 v[68:69], v[78:79], v[84:85], v[68:69]
	v_pk_add_f32 v[70:71], v[70:71], v[88:89]
	s_branch .LBB0_217

; __device__ __forceinline__ unsigned cvt_pk_bf16(float lo, float hi) { unsigned r; asm volatile("v_cvt_pk_bf16_f32 %0, %1, %2" : "=v"(r) : "v"(lo), "v"(hi)); return r; }
;     __device__ __forceinline__ void operator()(const pg8::f32x4 (&acc)[2][2][4][2], const pg8::Unit& u, int wr, int wc, int fr, int fq) const {
;     ...
;                     const int i0 = 8 * (fq & 1); const bool odd = (wc & 1) != 0; const float sgn = (fq < 2) ? -1.f : 1.f;
; #pragma unroll
;                     for (int ai = 0; ai < 2; ++ai)
; #pragma unroll
;                         for (int m = 0; m < 4; ++m) { const int s = sbase + ai * HALF + m * 16;
;                             f32x4 v0 = acc[ai][bj][m][0], v1 = acc[ai][bj][m][1];
;                             if (!isctx) {
;                                 const int pos = odd ? (s & 63) : (s >> 6);
;                                 const f32x4 c0 = *(const f32x4*)(ropeC + pos * 16 + i0), c1 = *(const f32x4*)(ropeC + pos * 16 + i0 + 4);
;                                 const f32x4 s0 = *(const f32x4*)(ropeS + pos * 16 + i0), s1 = *(const f32x4*)(ropeS + pos * 16 + i0 + 4);
; #pragma unroll
;                                 for (int j = 0; j < 4; ++j) { const float p0 = __shfl_xor(v0[j], 32), p1 = __shfl_xor(v1[j], 32);
;                                     v0[j] = v0[j] * c0[j] + sgn * p0 * s0[j]; v1[j] = v1[j] * c1[j] + sgn * p1 * s1[j]; }
;                             }
;                             if (pn < 2) { v0 = v0 * QSCALE; v1 = v1 * QSCALE; }
;                             u32x4 w; w.x = cvt_pk_bf16(v0[0], v0[1]); w.y = cvt_pk_bf16(v0[2], v0[3]); w.z = cvt_pk_bf16(v1[0], v1[1]); w.w = cvt_pk_bf16(v1[2], v1[3]);
;                             const size_t grow = grow0 + ai * HALF + m * 16;
;                             if (pn < 2) *(u32x4*)(QB + grow * 512 + pn * 256 + bj * HALF + c8) = w; else *(u32x4*)(KB + grow * 128 + c8) = w; asm volatile("" ::: "memory"); }
.LBB0_217:
	v_pk_mul_f32 v[66:67], v[66:67], s[48:49] op_sel_hi:[1,0]
	v_pk_mul_f32 v[64:65], v[64:65], s[48:49] op_sel_hi:[1,0]
	v_pk_mul_f32 v[68:69], v[68:69], s[48:49] op_sel_hi:[1,0]
	v_cvt_pk_bf16_f32 v64, v64, v65
	v_cvt_pk_bf16_f32 v65, v66, v67
	v_pk_mul_f32 v[70:71], v[70:71], s[48:49] op_sel_hi:[1,0]
	v_cvt_pk_bf16_f32 v66, v68, v69
	v_add_co_u32_e32 v68, vcc, 0x8000, v72
	v_cvt_pk_bf16_f32 v67, v70, v71
	s_nop 1
	v_addc_co_u32_e32 v69, vcc, 0, v73, vcc
	global_store_dwordx4 v[68:69], v[64:67], off
	s_and_b64 vcc, exec, s[6:7]
	s_cbranch_vccnz .LBB0_219
	v_add_u32_e32 v64, 48, v144
	v_ashrrev_i32_e32 v64, 6, v64
	v_cndmask_b32_e64 v64, v112, v64, s[10:11]
	v_lshlrev_b32_e32 v64, 4, v64
	v_ashrrev_i32_e32 v65, 31, v64
	v_lshlrev_b64 v[74:75], 2, v[64:65]
	v_lshl_add_u64 v[68:69], v[154:155], 0, v[74:75]
	v_lshl_add_u64 v[78:79], v[152:153], 0, v[74:75]
	flat_load_dwordx4 v[64:67], v[68:69]
	s_nop 0
	flat_load_dwordx4 v[68:71], v[68:69] offset:16
	s_nop 0
	flat_load_dwordx4 v[74:77], v[78:79]
	s_nop 0
	flat_load_dwordx4 v[78:81], v[78:79] offset:16
	v_and_b32_e32 v83, 64, v232
	v_xor_b32_e32 v82, 32, v232
	v_add_u32_e32 v83, 64, v83
	v_cmp_lt_i32_e32 vcc, v82, v83
	s_waitcnt vmcnt(0) lgkmcnt(0)
	v_pk_mul_f32 v[64:65], v[36:37], v[64:65]
	v_cndmask_b32_e32 v82, v232, v82, vcc
	v_lshlrev_b32_e32 v87, 2, v82
	ds_bpermute_b32 v86, v87, v38
	ds_bpermute_b32 v88, v87, v34
	ds_bpermute_b32 v82, v87, v36
	ds_bpermute_b32 v83, v87, v37
	ds_bpermute_b32 v84, v87, v32
	s_waitcnt lgkmcnt(4)
	v_mul_f32_e32 v86, v150, v86
	v_mul_f32_e32 v86, v76, v86
	s_waitcnt lgkmcnt(3)
	v_mul_f32_e32 v76, v150, v88
	v_mul_f32_e32 v88, v80, v76
	ds_bpermute_b32 v76, v87, v39
	ds_bpermute_b32 v80, v87, v35
	ds_bpermute_b32 v85, v87, v33
	s_waitcnt lgkmcnt(4)
	v_pk_mul_f32 v[82:83], v[150:151], v[82:83] op_sel_hi:[0,1]
	v_mov_b32_e32 v90, v67
	s_waitcnt lgkmcnt(2)
	v_mul_f32_e32 v91, v150, v76
	v_mov_b32_e32 v76, v39
	v_pk_fma_f32 v[64:65], v[74:75], v[82:83], v[64:65]
	s_waitcnt lgkmcnt(1)
	v_mul_f32_e32 v75, v150, v80
	v_mov_b32_e32 v80, v35
	v_mov_b32_e32 v74, v71
	v_pk_mul_f32 v[76:77], v[76:77], v[90:91]
	v_pk_mul_f32 v[74:75], v[80:81], v[74:75]
	v_pk_mul_f32 v[68:69], v[32:33], v[68:69]
	s_waitcnt lgkmcnt(0)
	v_pk_mul_f32 v[84:85], v[150:151], v[84:85] op_sel_hi:[0,1]
	v_mul_f32_e32 v66, v38, v66
	v_mul_f32_e32 v70, v34, v70
	v_mov_b32_e32 v67, v76
	v_mov_b32_e32 v87, v77
	v_mov_b32_e32 v71, v74
	v_mov_b32_e32 v89, v75
	v_pk_add_f32 v[66:67], v[66:67], v[86:87]
	v_pk_fma_f32 v[68:69], v[78:79], v[84:85], v[68:69]
	v_pk_add_f32 v[70:71], v[70:71], v[88:89]
	s_branch .LBB0_220

; __device__ __forceinline__ unsigned cvt_pk_bf16(float lo, float hi) { unsigned r; asm volatile("v_cvt_pk_bf16_f32 %0, %1, %2" : "=v"(r) : "v"(lo), "v"(hi)); return r; }
;     __device__ __forceinline__ void operator()(const pg8::f32x4 (&acc)[2][2][4][2], const pg8::Unit& u, int wr, int wc, int fr, int fq) const {
;     ...
;                     const int i0 = 8 * (fq & 1); const bool odd = (wc & 1) != 0; const float sgn = (fq < 2) ? -1.f : 1.f;
; #pragma unroll
;                     for (int ai = 0; ai < 2; ++ai)
; #pragma unroll
;                         for (int m = 0; m < 4; ++m) { const int s = sbase + ai * HALF + m * 16;
;                             f32x4 v0 = acc[ai][bj][m][0], v1 = acc[ai][bj][m][1];
;                             if (!isctx) {
;                                 const int pos = odd ? (s & 63) : (s >> 6);
;                                 const f32x4 c0 = *(const f32x4*)(ropeC + pos * 16 + i0), c1 = *(const f32x4*)(ropeC + pos * 16 + i0 + 4);
;                                 const f32x4 s0 = *(const f32x4*)(ropeS + pos * 16 + i0), s1 = *(const f32x4*)(ropeS + pos * 16 + i0 + 4);
; #pragma unroll
;                                 for (int j = 0; j < 4; ++j) { const float p0 = __shfl_xor(v0[j], 32), p1 = __shfl_xor(v1[j], 32);
;                                     v0[j] = v0[j] * c0[j] + sgn * p0 * s0[j]; v1[j] = v1[j] * c1[j] + sgn * p1 * s1[j]; }
;                             }
;                             if (pn < 2) { v0 = v0 * QSCALE; v1 = v1 * QSCALE; }
;                             u32x4 w; w.x = cvt_pk_bf16(v0[0], v0[1]); w.y = cvt_pk_bf16(v0[2], v0[3]); w.z = cvt_pk_bf16(v1[0], v1[1]); w.w = cvt_pk_bf16(v1[2], v1[3]);
;                             const size_t grow = grow0 + ai * HALF + m * 16;
;                             if (pn < 2) *(u32x4*)(QB + grow * 512 + pn * 256 + bj * HALF + c8) = w; else *(u32x4*)(KB + grow * 128 + c8) = w; asm volatile("" ::: "memory"); }
.LBB0_220:
	v_pk_mul_f32 v[66:67], v[66:67], s[48:49] op_sel_hi:[1,0]
	v_pk_mul_f32 v[64:65], v[64:65], s[48:49] op_sel_hi:[1,0]
	v_pk_mul_f32 v[68:69], v[68:69], s[48:49] op_sel_hi:[1,0]
	v_cvt_pk_bf16_f32 v64, v64, v65
	v_cvt_pk_bf16_f32 v65, v66, v67
	v_pk_mul_f32 v[70:71], v[70:71], s[48:49] op_sel_hi:[1,0]
	v_cvt_pk_bf16_f32 v66, v68, v69
	v_add_co_u32_e32 v68, vcc, 0xc000, v72
	v_cvt_pk_bf16_f32 v67, v70, v71
	s_nop 1
	v_addc_co_u32_e32 v69, vcc, 0, v73, vcc
	global_store_dwordx4 v[68:69], v[64:67], off
	s_and_b64 vcc, exec, s[6:7]
	s_cbranch_vccnz .LBB0_222
	v_add_u32_e32 v64, 0x80, v144
	v_ashrrev_i32_e32 v64, 6, v64
	v_cndmask_b32_e64 v64, v149, v64, s[10:11]
	v_lshlrev_b32_e32 v64, 4, v64
	v_ashrrev_i32_e32 v65, 31, v64
	v_lshlrev_b64 v[74:75], 2, v[64:65]
	v_lshl_add_u64 v[68:69], v[154:155], 0, v[74:75]
	v_lshl_add_u64 v[78:79], v[152:153], 0, v[74:75]
	flat_load_dwordx4 v[64:67], v[68:69]
	s_nop 0
	flat_load_dwordx4 v[68:71], v[68:69] offset:16
	s_nop 0
	flat_load_dwordx4 v[74:77], v[78:79]
	s_nop 0
	flat_load_dwordx4 v[78:81], v[78:79] offset:16
	v_and_b32_e32 v83, 64, v232
	v_xor_b32_e32 v82, 32, v232
	v_add_u32_e32 v83, 64, v83
	v_cmp_lt_i32_e32 vcc, v82, v83
	s_waitcnt vmcnt(0) lgkmcnt(0)
	v_pk_mul_f32 v[64:65], v[28:29], v[64:65]
	v_cndmask_b32_e32 v82, v232, v82, vcc
	v_lshlrev_b32_e32 v87, 2, v82
	ds_bpermute_b32 v86, v87, v30
	ds_bpermute_b32 v88, v87, v26
	ds_bpermute_b32 v82, v87, v28
	ds_bpermute_b32 v83, v87, v29
	ds_bpermute_b32 v84, v87, v24
	s_waitcnt lgkmcnt(4)
	v_mul_f32_e32 v86, v150, v86
	v_mul_f32_e32 v86, v76, v86
	s_waitcnt lgkmcnt(3)
	v_mul_f32_e32 v76, v150, v88
	v_mul_f32_e32 v88, v80, v76
	ds_bpermute_b32 v76, v87, v31
	ds_bpermute_b32 v80, v87, v27
	ds_bpermute_b32 v85, v87, v25
	s_waitcnt lgkmcnt(4)
	v_pk_mul_f32 v[82:83], v[150:151], v[82:83] op_sel_hi:[0,1]
	v_mov_b32_e32 v90, v67
	s_waitcnt lgkmcnt(2)
	v_mul_f32_e32 v91, v150, v76
	v_mov_b32_e32 v76, v31
	v_pk_fma_f32 v[64:65], v[74:75], v[82:83], v[64:65]
	s_waitcnt lgkmcnt(1)
	v_mul_f32_e32 v75, v150, v80
	v_mov_b32_e32 v80, v27
	v_mov_b32_e32 v74, v71
	v_pk_mul_f32 v[76:77], v[76:77], v[90:91]
	v_pk_mul_f32 v[74:75], v[80:81], v[74:75]
	v_pk_mul_f32 v[68:69], v[24:25], v[68:69]
	s_waitcnt lgkmcnt(0)
	v_pk_mul_f32 v[84:85], v[150:151], v[84:85] op_sel_hi:[0,1]
	v_mul_f32_e32 v66, v30, v66
	v_mul_f32_e32 v70, v26, v70
	v_mov_b32_e32 v67, v76
	v_mov_b32_e32 v87, v77
	v_mov_b32_e32 v71, v74
	v_mov_b32_e32 v89, v75
	v_pk_add_f32 v[66:67], v[66:67], v[86:87]
	v_pk_fma_f32 v[68:69], v[78:79], v[84:85], v[68:69]
	v_pk_add_f32 v[70:71], v[70:71], v[88:89]
	s_branch .LBB0_223

; __device__ __forceinline__ unsigned cvt_pk_bf16(float lo, float hi) { unsigned r; asm volatile("v_cvt_pk_bf16_f32 %0, %1, %2" : "=v"(r) : "v"(lo), "v"(hi)); return r; }
;     __device__ __forceinline__ void operator()(const pg8::f32x4 (&acc)[2][2][4][2], const pg8::Unit& u, int wr, int wc, int fr, int fq) const {
;     ...
;                     const int i0 = 8 * (fq & 1); const bool odd = (wc & 1) != 0; const float sgn = (fq < 2) ? -1.f : 1.f;
; #pragma unroll
;                     for (int ai = 0; ai < 2; ++ai)
; #pragma unroll
;                         for (int m = 0; m < 4; ++m) { const int s = sbase + ai * HALF + m * 16;
;                             f32x4 v0 = acc[ai][bj][m][0], v1 = acc[ai][bj][m][1];
;                             if (!isctx) {
;                                 const int pos = odd ? (s & 63) : (s >> 6);
;                                 const f32x4 c0 = *(const f32x4*)(ropeC + pos * 16 + i0), c1 = *(const f32x4*)(ropeC + pos * 16 + i0 + 4);
;                                 const f32x4 s0 = *(const f32x4*)(ropeS + pos * 16 + i0), s1 = *(const f32x4*)(ropeS + pos * 16 + i0 + 4);
; #pragma unroll
;                                 for (int j = 0; j < 4; ++j) { const float p0 = __shfl_xor(v0[j], 32), p1 = __shfl_xor(v1[j], 32);
;                                     v0[j] = v0[j] * c0[j] + sgn * p0 * s0[j]; v1[j] = v1[j] * c1[j] + sgn * p1 * s1[j]; }
;                             }
;                             if (pn < 2) { v0 = v0 * QSCALE; v1 = v1 * QSCALE; }
;                             u32x4 w; w.x = cvt_pk_bf16(v0[0], v0[1]); w.y = cvt_pk_bf16(v0[2], v0[3]); w.z = cvt_pk_bf16(v1[0], v1[1]); w.w = cvt_pk_bf16(v1[2], v1[3]);
;                             const size_t grow = grow0 + ai * HALF + m * 16;
;                             if (pn < 2) *(u32x4*)(QB + grow * 512 + pn * 256 + bj * HALF + c8) = w; else *(u32x4*)(KB + grow * 128 + c8) = w; asm volatile("" ::: "memory"); }
.LBB0_223:
	v_pk_mul_f32 v[66:67], v[66:67], s[48:49] op_sel_hi:[1,0]
	v_pk_mul_f32 v[64:65], v[64:65], s[48:49] op_sel_hi:[1,0]
	v_pk_mul_f32 v[68:69], v[68:69], s[48:49] op_sel_hi:[1,0]
	v_cvt_pk_bf16_f32 v64, v64, v65
	v_cvt_pk_bf16_f32 v65, v66, v67
	v_pk_mul_f32 v[70:71], v[70:71], s[48:49] op_sel_hi:[1,0]
	v_cvt_pk_bf16_f32 v66, v68, v69
	v_add_co_u32_e32 v68, vcc, 0x20000, v72
	v_cvt_pk_bf16_f32 v67, v70, v71
	s_nop 1
	v_addc_co_u32_e32 v69, vcc, 0, v73, vcc
	global_store_dwordx4 v[68:69], v[64:67], off
	s_and_b64 vcc, exec, s[6:7]
	s_cbranch_vccnz .LBB0_225
	v_add_u32_e32 v64, 0x90, v144
	v_ashrrev_i32_e32 v64, 6, v64
	v_cndmask_b32_e64 v64, v145, v64, s[10:11]
	v_lshlrev_b32_e32 v64, 4, v64
	v_ashrrev_i32_e32 v65, 31, v64
	v_lshlrev_b64 v[74:75], 2, v[64:65]
	v_lshl_add_u64 v[68:69], v[154:155], 0, v[74:75]
	v_lshl_add_u64 v[78:79], v[152:153], 0, v[74:75]
	flat_load_dwordx4 v[64:67], v[68:69]
	s_nop 0
	flat_load_dwordx4 v[68:71], v[68:69] offset:16
	s_nop 0
	flat_load_dwordx4 v[74:77], v[78:79]
	s_nop 0
	flat_load_dwordx4 v[78:81], v[78:79] offset:16
	v_and_b32_e32 v83, 64, v232
	v_xor_b32_e32 v82, 32, v232
	v_add_u32_e32 v83, 64, v83
	v_cmp_lt_i32_e32 vcc, v82, v83
	s_waitcnt vmcnt(0) lgkmcnt(0)
	v_pk_mul_f32 v[64:65], v[20:21], v[64:65]
	v_cndmask_b32_e32 v82, v232, v82, vcc
	v_lshlrev_b32_e32 v87, 2, v82
	ds_bpermute_b32 v86, v87, v22
	ds_bpermute_b32 v88, v87, v18
	ds_bpermute_b32 v82, v87, v20
	ds_bpermute_b32 v83, v87, v21
	ds_bpermute_b32 v84, v87, v16
	s_waitcnt lgkmcnt(4)
	v_mul_f32_e32 v86, v150, v86
	v_mul_f32_e32 v86, v76, v86
	s_waitcnt lgkmcnt(3)
	v_mul_f32_e32 v76, v150, v88
	v_mul_f32_e32 v88, v80, v76
	ds_bpermute_b32 v76, v87, v23
	ds_bpermute_b32 v80, v87, v19
	ds_bpermute_b32 v85, v87, v17
	s_waitcnt lgkmcnt(4)
	v_pk_mul_f32 v[82:83], v[150:151], v[82:83] op_sel_hi:[0,1]
	v_mov_b32_e32 v90, v67
	s_waitcnt lgkmcnt(2)
	v_mul_f32_e32 v91, v150, v76
	v_mov_b32_e32 v76, v23
	v_pk_fma_f32 v[64:65], v[74:75], v[82:83], v[64:65]
	s_waitcnt lgkmcnt(1)
	v_mul_f32_e32 v75, v150, v80
	v_mov_b32_e32 v80, v19
	v_mov_b32_e32 v74, v71
	v_pk_mul_f32 v[76:77], v[76:77], v[90:91]
	v_pk_mul_f32 v[74:75], v[80:81], v[74:75]
	v_pk_mul_f32 v[68:69], v[16:17], v[68:69]
	s_waitcnt lgkmcnt(0)
	v_pk_mul_f32 v[84:85], v[150:151], v[84:85] op_sel_hi:[0,1]
	v_mul_f32_e32 v66, v22, v66
	v_mul_f32_e32 v70, v18, v70
	v_mov_b32_e32 v67, v76
	v_mov_b32_e32 v87, v77
	v_mov_b32_e32 v71, v74
	v_mov_b32_e32 v89, v75
	v_pk_add_f32 v[66:67], v[66:67], v[86:87]
	v_pk_fma_f32 v[68:69], v[78:79], v[84:85], v[68:69]
	v_pk_add_f32 v[70:71], v[70:71], v[88:89]
	s_branch .LBB0_226

; __device__ __forceinline__ unsigned cvt_pk_bf16(float lo, float hi) { unsigned r; asm volatile("v_cvt_pk_bf16_f32 %0, %1, %2" : "=v"(r) : "v"(lo), "v"(hi)); return r; }
;     __device__ __forceinline__ void operator()(const pg8::f32x4 (&acc)[2][2][4][2], const pg8::Unit& u, int wr, int wc, int fr, int fq) const {
;     ...
;                     const int i0 = 8 * (fq & 1); const bool odd = (wc & 1) != 0; const float sgn = (fq < 2) ? -1.f : 1.f;
; #pragma unroll
;                     for (int ai = 0; ai < 2; ++ai)
; #pragma unroll
;                         for (int m = 0; m < 4; ++m) { const int s = sbase + ai * HALF + m * 16;
;                             f32x4 v0 = acc[ai][bj][m][0], v1 = acc[ai][bj][m][1];
;                             if (!isctx) {
;                                 const int pos = odd ? (s & 63) : (s >> 6);
;                                 const f32x4 c0 = *(const f32x4*)(ropeC + pos * 16 + i0), c1 = *(const f32x4*)(ropeC + pos * 16 + i0 + 4);
;                                 const f32x4 s0 = *(const f32x4*)(ropeS + pos * 16 + i0), s1 = *(const f32x4*)(ropeS + pos * 16 + i0 + 4);
; #pragma unroll
;                                 for (int j = 0; j < 4; ++j) { const float p0 = __shfl_xor(v0[j], 32), p1 = __shfl_xor(v1[j], 32);
;                                     v0[j] = v0[j] * c0[j] + sgn * p0 * s0[j]; v1[j] = v1[j] * c1[j] + sgn * p1 * s1[j]; }
;                             }
;                             if (pn < 2) { v0 = v0 * QSCALE; v1 = v1 * QSCALE; }
;                             u32x4 w; w.x = cvt_pk_bf16(v0[0], v0[1]); w.y = cvt_pk_bf16(v0[2], v0[3]); w.z = cvt_pk_bf16(v1[0], v1[1]); w.w = cvt_pk_bf16(v1[2], v1[3]);
;                             const size_t grow = grow0 + ai * HALF + m * 16;
;                             if (pn < 2) *(u32x4*)(QB + grow * 512 + pn * 256 + bj * HALF + c8) = w; else *(u32x4*)(KB + grow * 128 + c8) = w; asm volatile("" ::: "memory"); }
.LBB0_226:
	v_pk_mul_f32 v[66:67], v[66:67], s[48:49] op_sel_hi:[1,0]
	v_pk_mul_f32 v[64:65], v[64:65], s[48:49] op_sel_hi:[1,0]
	v_pk_mul_f32 v[68:69], v[68:69], s[48:49] op_sel_hi:[1,0]
	v_cvt_pk_bf16_f32 v64, v64, v65
	v_cvt_pk_bf16_f32 v65, v66, v67
	v_pk_mul_f32 v[70:71], v[70:71], s[48:49] op_sel_hi:[1,0]
	v_cvt_pk_bf16_f32 v66, v68, v69
	v_add_co_u32_e32 v68, vcc, 0x24000, v72
	v_cvt_pk_bf16_f32 v67, v70, v71
	s_nop 1
	v_addc_co_u32_e32 v69, vcc, 0, v73, vcc
	global_store_dwordx4 v[68:69], v[64:67], off
	s_and_b64 vcc, exec, s[6:7]
	s_cbranch_vccnz .LBB0_228
	v_add_u32_e32 v64, 0xa0, v144
	v_ashrrev_i32_e32 v64, 6, v64
	v_cndmask_b32_e64 v64, v122, v64, s[10:11]
	v_lshlrev_b32_e32 v64, 4, v64
	v_ashrrev_i32_e32 v65, 31, v64
	v_lshlrev_b64 v[74:75], 2, v[64:65]
	v_lshl_add_u64 v[68:69], v[154:155], 0, v[74:75]
	v_lshl_add_u64 v[78:79], v[152:153], 0, v[74:75]
	flat_load_dwordx4 v[64:67], v[68:69]
	s_nop 0
	flat_load_dwordx4 v[68:71], v[68:69] offset:16
	s_nop 0
	flat_load_dwordx4 v[74:77], v[78:79]
	s_nop 0
	flat_load_dwordx4 v[78:81], v[78:79] offset:16
	v_and_b32_e32 v83, 64, v232
	v_xor_b32_e32 v82, 32, v232
	v_add_u32_e32 v83, 64, v83
	v_cmp_lt_i32_e32 vcc, v82, v83
	s_waitcnt vmcnt(0) lgkmcnt(0)
	v_pk_mul_f32 v[64:65], v[12:13], v[64:65]
	v_cndmask_b32_e32 v82, v232, v82, vcc
	v_lshlrev_b32_e32 v87, 2, v82
	ds_bpermute_b32 v86, v87, v14
	ds_bpermute_b32 v88, v87, v10
	ds_bpermute_b32 v82, v87, v12
	ds_bpermute_b32 v83, v87, v13
	ds_bpermute_b32 v84, v87, v8
	s_waitcnt lgkmcnt(4)
	v_mul_f32_e32 v86, v150, v86
	v_mul_f32_e32 v86, v76, v86
	s_waitcnt lgkmcnt(3)
	v_mul_f32_e32 v76, v150, v88
	v_mul_f32_e32 v88, v80, v76
	ds_bpermute_b32 v76, v87, v15
	ds_bpermute_b32 v80, v87, v11
	ds_bpermute_b32 v85, v87, v9
	s_waitcnt lgkmcnt(4)
	v_pk_mul_f32 v[82:83], v[150:151], v[82:83] op_sel_hi:[0,1]
	v_mov_b32_e32 v90, v67
	s_waitcnt lgkmcnt(2)
	v_mul_f32_e32 v91, v150, v76
	v_mov_b32_e32 v76, v15
	v_pk_fma_f32 v[64:65], v[74:75], v[82:83], v[64:65]
	s_waitcnt lgkmcnt(1)
	v_mul_f32_e32 v75, v150, v80
	v_mov_b32_e32 v80, v11
	v_mov_b32_e32 v74, v71
	v_pk_mul_f32 v[76:77], v[76:77], v[90:91]
	v_pk_mul_f32 v[74:75], v[80:81], v[74:75]
	v_pk_mul_f32 v[68:69], v[8:9], v[68:69]
	s_waitcnt lgkmcnt(0)
	v_pk_mul_f32 v[84:85], v[150:151], v[84:85] op_sel_hi:[0,1]
	v_mul_f32_e32 v66, v14, v66
	v_mul_f32_e32 v70, v10, v70
	v_mov_b32_e32 v67, v76
	v_mov_b32_e32 v87, v77
	v_mov_b32_e32 v71, v74
	v_mov_b32_e32 v89, v75
	v_pk_add_f32 v[66:67], v[66:67], v[86:87]
	v_pk_fma_f32 v[68:69], v[78:79], v[84:85], v[68:69]
	v_pk_add_f32 v[70:71], v[70:71], v[88:89]
	s_branch .LBB0_229

; __device__ __forceinline__ unsigned cvt_pk_bf16(float lo, float hi) { unsigned r; asm volatile("v_cvt_pk_bf16_f32 %0, %1, %2" : "=v"(r) : "v"(lo), "v"(hi)); return r; }
;     __device__ __forceinline__ void operator()(const pg8::f32x4 (&acc)[2][2][4][2], const pg8::Unit& u, int wr, int wc, int fr, int fq) const {
;     ...
;                     const int i0 = 8 * (fq & 1); const bool odd = (wc & 1) != 0; const float sgn = (fq < 2) ? -1.f : 1.f;
; #pragma unroll
;                     for (int ai = 0; ai < 2; ++ai)
; #pragma unroll
;                         for (int m = 0; m < 4; ++m) { const int s = sbase + ai * HALF + m * 16;
;                             f32x4 v0 = acc[ai][bj][m][0], v1 = acc[ai][bj][m][1];
;                             if (!isctx) {
;                                 const int pos = odd ? (s & 63) : (s >> 6);
;                                 const f32x4 c0 = *(const f32x4*)(ropeC + pos * 16 + i0), c1 = *(const f32x4*)(ropeC + pos * 16 + i0 + 4);
;                                 const f32x4 s0 = *(const f32x4*)(ropeS + pos * 16 + i0), s1 = *(const f32x4*)(ropeS + pos * 16 + i0 + 4);
; #pragma unroll
;                                 for (int j = 0; j < 4; ++j) { const float p0 = __shfl_xor(v0[j], 32), p1 = __shfl_xor(v1[j], 32);
;                                     v0[j] = v0[j] * c0[j] + sgn * p0 * s0[j]; v1[j] = v1[j] * c1[j] + sgn * p1 * s1[j]; }
;                             }
;                             if (pn < 2) { v0 = v0 * QSCALE; v1 = v1 * QSCALE; }
;                             u32x4 w; w.x = cvt_pk_bf16(v0[0], v0[1]); w.y = cvt_pk_bf16(v0[2], v0[3]); w.z = cvt_pk_bf16(v1[0], v1[1]); w.w = cvt_pk_bf16(v1[2], v1[3]);
;                             const size_t grow = grow0 + ai * HALF + m * 16;
;                             if (pn < 2) *(u32x4*)(QB + grow * 512 + pn * 256 + bj * HALF + c8) = w; else *(u32x4*)(KB + grow * 128 + c8) = w; asm volatile("" ::: "memory"); }
.LBB0_229:
	v_pk_mul_f32 v[66:67], v[66:67], s[48:49] op_sel_hi:[1,0]
	v_pk_mul_f32 v[64:65], v[64:65], s[48:49] op_sel_hi:[1,0]
	v_pk_mul_f32 v[68:69], v[68:69], s[48:49] op_sel_hi:[1,0]
	v_cvt_pk_bf16_f32 v64, v64, v65
	v_cvt_pk_bf16_f32 v65, v66, v67
	v_pk_mul_f32 v[70:71], v[70:71], s[48:49] op_sel_hi:[1,0]
	v_cvt_pk_bf16_f32 v66, v68, v69
	v_add_co_u32_e32 v68, vcc, 0x28000, v72
	v_cvt_pk_bf16_f32 v67, v70, v71
	s_nop 1
	v_addc_co_u32_e32 v69, vcc, 0, v73, vcc
	global_store_dwordx4 v[68:69], v[64:67], off
	s_and_b64 vcc, exec, s[6:7]
	s_cbranch_vccnz .LBB0_231
	v_add_u32_e32 v64, 0xb0, v144
	v_ashrrev_i32_e32 v64, 6, v64
	v_cndmask_b32_e64 v64, v112, v64, s[10:11]
	v_lshlrev_b32_e32 v64, 4, v64
	v_ashrrev_i32_e32 v65, 31, v64
	v_lshlrev_b64 v[74:75], 2, v[64:65]
	v_lshl_add_u64 v[68:69], v[154:155], 0, v[74:75]
	v_lshl_add_u64 v[78:79], v[152:153], 0, v[74:75]
	flat_load_dwordx4 v[64:67], v[68:69]
	s_nop 0
	flat_load_dwordx4 v[68:71], v[68:69] offset:16
	s_nop 0
	flat_load_dwordx4 v[74:77], v[78:79]
	s_nop 0
	flat_load_dwordx4 v[78:81], v[78:79] offset:16
	v_and_b32_e32 v83, 64, v232
	v_xor_b32_e32 v82, 32, v232
	v_add_u32_e32 v83, 64, v83
	v_cmp_lt_i32_e32 vcc, v82, v83
	s_waitcnt vmcnt(0) lgkmcnt(0)
	v_pk_mul_f32 v[64:65], v[4:5], v[64:65]
	v_cndmask_b32_e32 v82, v232, v82, vcc
	v_lshlrev_b32_e32 v87, 2, v82
	ds_bpermute_b32 v86, v87, v6
	ds_bpermute_b32 v88, v87, v2
	ds_bpermute_b32 v82, v87, v4
	ds_bpermute_b32 v83, v87, v5
	ds_bpermute_b32 v84, v87, v0
	s_waitcnt lgkmcnt(4)
	v_mul_f32_e32 v86, v150, v86
	v_mul_f32_e32 v86, v76, v86
	s_waitcnt lgkmcnt(3)
	v_mul_f32_e32 v76, v150, v88
	v_mul_f32_e32 v88, v80, v76
	ds_bpermute_b32 v76, v87, v7
	ds_bpermute_b32 v80, v87, v3
	ds_bpermute_b32 v85, v87, v1
	s_waitcnt lgkmcnt(4)
	v_pk_mul_f32 v[82:83], v[150:151], v[82:83] op_sel_hi:[0,1]
	v_mov_b32_e32 v90, v67
	s_waitcnt lgkmcnt(2)
	v_mul_f32_e32 v91, v150, v76
	v_mov_b32_e32 v76, v7
	v_pk_fma_f32 v[64:65], v[74:75], v[82:83], v[64:65]
	s_waitcnt lgkmcnt(1)
	v_mul_f32_e32 v75, v150, v80
	v_mov_b32_e32 v80, v3
	v_mov_b32_e32 v74, v71
	v_pk_mul_f32 v[76:77], v[76:77], v[90:91]
	v_pk_mul_f32 v[74:75], v[80:81], v[74:75]
	v_pk_mul_f32 v[68:69], v[0:1], v[68:69]
	s_waitcnt lgkmcnt(0)
	v_pk_mul_f32 v[84:85], v[150:151], v[84:85] op_sel_hi:[0,1]
	v_mul_f32_e32 v66, v6, v66
	v_mul_f32_e32 v70, v2, v70
	v_mov_b32_e32 v67, v76
	v_mov_b32_e32 v87, v77
	v_mov_b32_e32 v71, v74
	v_mov_b32_e32 v89, v75
	v_pk_add_f32 v[66:67], v[66:67], v[86:87]
	v_pk_fma_f32 v[68:69], v[78:79], v[84:85], v[68:69]
	v_pk_add_f32 v[70:71], v[70:71], v[88:89]
	s_branch .LBB0_232

; __device__ __forceinline__ unsigned cvt_pk_bf16(float lo, float hi) { unsigned r; asm volatile("v_cvt_pk_bf16_f32 %0, %1, %2" : "=v"(r) : "v"(lo), "v"(hi)); return r; }
;     __device__ __forceinline__ void operator()(const pg8::f32x4 (&acc)[2][2][4][2], const pg8::Unit& u, int wr, int wc, int fr, int fq) const {
;     ...
;                     const int i0 = 8 * (fq & 1); const bool odd = (wc & 1) != 0; const float sgn = (fq < 2) ? -1.f : 1.f;
; #pragma unroll
;                     for (int ai = 0; ai < 2; ++ai)
; #pragma unroll
;                         for (int m = 0; m < 4; ++m) { const int s = sbase + ai * HALF + m * 16;
;                             f32x4 v0 = acc[ai][bj][m][0], v1 = acc[ai][bj][m][1];
;                             if (!isctx) {
;                                 const int pos = odd ? (s & 63) : (s >> 6);
;                                 const f32x4 c0 = *(const f32x4*)(ropeC + pos * 16 + i0), c1 = *(const f32x4*)(ropeC + pos * 16 + i0 + 4);
;                                 const f32x4 s0 = *(const f32x4*)(ropeS + pos * 16 + i0), s1 = *(const f32x4*)(ropeS + pos * 16 + i0 + 4);
; #pragma unroll
;                                 for (int j = 0; j < 4; ++j) { const float p0 = __shfl_xor(v0[j], 32), p1 = __shfl_xor(v1[j], 32);
;                                     v0[j] = v0[j] * c0[j] + sgn * p0 * s0[j]; v1[j] = v1[j] * c1[j] + sgn * p1 * s1[j]; }
;                             }
;                             if (pn < 2) { v0 = v0 * QSCALE; v1 = v1 * QSCALE; }
;                             u32x4 w; w.x = cvt_pk_bf16(v0[0], v0[1]); w.y = cvt_pk_bf16(v0[2], v0[3]); w.z = cvt_pk_bf16(v1[0], v1[1]); w.w = cvt_pk_bf16(v1[2], v1[3]);
;                             const size_t grow = grow0 + ai * HALF + m * 16;
;                             if (pn < 2) *(u32x4*)(QB + grow * 512 + pn * 256 + bj * HALF + c8) = w; else *(u32x4*)(KB + grow * 128 + c8) = w; asm volatile("" ::: "memory"); }
.LBB0_232:
	v_pk_mul_f32 v[66:67], v[66:67], s[48:49] op_sel_hi:[1,0]
	v_pk_mul_f32 v[64:65], v[64:65], s[48:49] op_sel_hi:[1,0]
	v_pk_mul_f32 v[68:69], v[68:69], s[48:49] op_sel_hi:[1,0]
	v_cvt_pk_bf16_f32 v64, v64, v65
	v_cvt_pk_bf16_f32 v65, v66, v67
	v_pk_mul_f32 v[70:71], v[70:71], s[48:49] op_sel_hi:[1,0]
	v_cvt_pk_bf16_f32 v66, v68, v69
	v_add_co_u32_e32 v68, vcc, 0x2c000, v72
	v_cvt_pk_bf16_f32 v67, v70, v71
	s_mov_b64 s[8:9], 0
	s_nop 0
	v_addc_co_u32_e32 v69, vcc, 0, v73, vcc
	global_store_dwordx4 v[68:69], v[64:67], off
; __device__ __forceinline__ unsigned short f2bf1(float f) { return (unsigned short)(cvt_pk_bf16(f, 0.f) & 0xffffu); }
;     __device__ __forceinline__ void operator()(const pg8::f32x4 (&acc)[2][2][4][2], const pg8::Unit& u, int wr, int wc, int fr, int fq) const {
;     ...
;                 if (pn == 2 && bj == 1) {
;                     bf16_t* base = isctx ? VTc + (size_t)b * 128 * 256 : VT + (size_t)b * 128 * 8192; const int ld = isctx ? 256 : 8192;
; #pragma unroll
;                     for (int ai = 0; ai < 2; ++ai)
; #pragma unroll
;                         for (int m = 0; m < 4; ++m) { const int s = sbase + ai * HALF + m * 16;
; #pragma unroll
;                             for (int n = 0; n < 2; ++n)
; #pragma unroll
;                                 for (int j = 0; j < 4; ++j) base[(size_t)(c8 + 4 * n + j) * ld + s] = f2bf1(acc[ai][1][m][n][j]); asm volatile("" ::: "memory"); }
.LBB0_233:
	s_and_b64 vcc, exec, s[8:9]
	s_cbranch_vccz .LBB0_235
	s_ashr_i32 s69, s68, 31
	s_lshl_b64 s[6:7], s[68:69], 21
	s_add_u32 s6, s0, s6
	s_addc_u32 s7, s1, s7
	s_add_u32 s8, s6, 0x20f00000
	s_addc_u32 s9, s7, 0
	s_lshl_b64 s[6:7], s[46:47], 16
	s_add_u32 s0, s0, s6
	s_addc_u32 s1, s1, s7
	s_add_u32 s6, s0, 0x21f00000
	s_addc_u32 s7, s1, 0
	s_and_b64 s[0:1], s[64:65], exec
	s_cselect_b32 s0, s7, s9
	s_cselect_b32 s1, s6, s8
	v_mov_b32_e32 v64, s1
	v_mov_b32_e32 v65, s0
	v_ashrrev_i32_e32 v145, 31, v144
	s_cselect_b32 s0, 8, 13
	v_lshl_add_u64 v[64:65], v[144:145], 1, v[64:65]
	v_lshlrev_b64 v[66:67], s0, v[142:143]
	v_cvt_pk_bf16_f32 v60, v60, v177
	v_lshl_add_u64 v[66:67], v[66:67], 1, v[64:65]
	global_store_short v[66:67], v60, off
	v_or_b32_e32 v60, 1, v142
	v_cvt_pk_bf16_f32 v68, v61, v177
	v_ashrrev_i32_e32 v61, 31, v60
	v_lshlrev_b64 v[60:61], s0, v[60:61]
	v_lshl_add_u64 v[60:61], v[60:61], 1, v[64:65]
	global_store_short v[60:61], v68, off
	v_or_b32_e32 v68, 2, v142
	v_ashrrev_i32_e32 v69, 31, v68
	v_lshlrev_b64 v[68:69], s0, v[68:69]
	v_cvt_pk_bf16_f32 v62, v62, v177
	v_lshl_add_u64 v[68:69], v[68:69], 1, v[64:65]
	global_store_short v[68:69], v62, off
	v_or_b32_e32 v62, 3, v142
	v_cvt_pk_bf16_f32 v70, v63, v177
	v_ashrrev_i32_e32 v63, 31, v62
	v_lshlrev_b64 v[62:63], s0, v[62:63]
	v_lshl_add_u64 v[62:63], v[62:63], 1, v[64:65]
	global_store_short v[62:63], v70, off
	v_or_b32_e32 v70, 4, v142
	v_ashrrev_i32_e32 v71, 31, v70
	v_lshlrev_b64 v[70:71], s0, v[70:71]
	v_cvt_pk_bf16_f32 v56, v56, v177
	v_lshl_add_u64 v[70:71], v[70:71], 1, v[64:65]
	global_store_short v[70:71], v56, off
	v_or_b32_e32 v56, 5, v142
	v_cvt_pk_bf16_f32 v72, v57, v177
	v_ashrrev_i32_e32 v57, 31, v56
	v_lshlrev_b64 v[56:57], s0, v[56:57]
	v_lshl_add_u64 v[56:57], v[56:57], 1, v[64:65]
	global_store_short v[56:57], v72, off
	v_or_b32_e32 v72, 6, v142
	v_ashrrev_i32_e32 v73, 31, v72
	v_lshlrev_b64 v[72:73], s0, v[72:73]
	v_cvt_pk_bf16_f32 v58, v58, v177
	v_lshl_add_u64 v[72:73], v[72:73], 1, v[64:65]
	global_store_short v[72:73], v58, off
	v_or_b32_e32 v58, 7, v142
	v_cvt_pk_bf16_f32 v74, v59, v177
	v_ashrrev_i32_e32 v59, 31, v58
	v_lshlrev_b64 v[58:59], s0, v[58:59]
	v_lshl_add_u64 v[58:59], v[58:59], 1, v[64:65]
	global_store_short v[58:59], v74, off
	v_cvt_pk_bf16_f32 v52, v52, v177
	global_store_short v[66:67], v52, off offset:32
	v_cvt_pk_bf16_f32 v52, v53, v177
	global_store_short v[60:61], v52, off offset:32
	v_cvt_pk_bf16_f32 v52, v54, v177
	global_store_short v[68:69], v52, off offset:32
	v_cvt_pk_bf16_f32 v52, v55, v177
	global_store_short v[62:63], v52, off offset:32
	v_cvt_pk_bf16_f32 v48, v48, v177
	global_store_short v[70:71], v48, off offset:32
	v_cvt_pk_bf16_f32 v48, v49, v177
	global_store_short v[56:57], v48, off offset:32
	v_cvt_pk_bf16_f32 v48, v50, v177
	global_store_short v[72:73], v48, off offset:32
	v_cvt_pk_bf16_f32 v48, v51, v177
	global_store_short v[58:59], v48, off offset:32
	v_cvt_pk_bf16_f32 v44, v44, v177
	global_store_short v[66:67], v44, off offset:64
	v_cvt_pk_bf16_f32 v44, v45, v177
	global_store_short v[60:61], v44, off offset:64
	v_cvt_pk_bf16_f32 v44, v46, v177
	global_store_short v[68:69], v44, off offset:64
	v_cvt_pk_bf16_f32 v44, v47, v177
	global_store_short v[62:63], v44, off offset:64
	v_cvt_pk_bf16_f32 v40, v40, v177
	global_store_short v[70:71], v40, off offset:64
	v_cvt_pk_bf16_f32 v40, v41, v177
	global_store_short v[56:57], v40, off offset:64
	v_cvt_pk_bf16_f32 v40, v42, v177
	global_store_short v[72:73], v40, off offset:64
	v_cvt_pk_bf16_f32 v40, v43, v177
	global_store_short v[58:59], v40, off offset:64
	v_cvt_pk_bf16_f32 v36, v36, v177
	global_store_short v[66:67], v36, off offset:96
	v_cvt_pk_bf16_f32 v36, v37, v177
	global_store_short v[60:61], v36, off offset:96
	v_cvt_pk_bf16_f32 v36, v38, v177
	global_store_short v[68:69], v36, off offset:96
	v_cvt_pk_bf16_f32 v36, v39, v177
	global_store_short v[62:63], v36, off offset:96
	v_cvt_pk_bf16_f32 v32, v32, v177
	global_store_short v[70:71], v32, off offset:96
	v_cvt_pk_bf16_f32 v32, v33, v177
	global_store_short v[56:57], v32, off offset:96
	v_cvt_pk_bf16_f32 v32, v34, v177
	global_store_short v[72:73], v32, off offset:96
	v_cvt_pk_bf16_f32 v32, v35, v177
	global_store_short v[58:59], v32, off offset:96
	v_cvt_pk_bf16_f32 v28, v28, v177
	global_store_short v[66:67], v28, off offset:256
	v_cvt_pk_bf16_f32 v28, v29, v177
	global_store_short v[60:61], v28, off offset:256
	v_cvt_pk_bf16_f32 v28, v30, v177
	global_store_short v[68:69], v28, off offset:256
	v_cvt_pk_bf16_f32 v28, v31, v177
	global_store_short v[62:63], v28, off offset:256
	v_cvt_pk_bf16_f32 v24, v24, v177
	global_store_short v[70:71], v24, off offset:256
	v_cvt_pk_bf16_f32 v24, v25, v177
	global_store_short v[56:57], v24, off offset:256
	v_cvt_pk_bf16_f32 v24, v26, v177
	global_store_short v[72:73], v24, off offset:256
	v_cvt_pk_bf16_f32 v24, v27, v177
	global_store_short v[58:59], v24, off offset:256
	v_cvt_pk_bf16_f32 v20, v20, v177
	global_store_short v[66:67], v20, off offset:288
	v_cvt_pk_bf16_f32 v20, v21, v177
	global_store_short v[60:61], v20, off offset:288
	v_cvt_pk_bf16_f32 v20, v22, v177
	global_store_short v[68:69], v20, off offset:288
	v_cvt_pk_bf16_f32 v20, v23, v177
	global_store_short v[62:63], v20, off offset:288
	v_cvt_pk_bf16_f32 v16, v16, v177
	global_store_short v[70:71], v16, off offset:288
	v_cvt_pk_bf16_f32 v16, v17, v177
	global_store_short v[56:57], v16, off offset:288
	v_cvt_pk_bf16_f32 v16, v18, v177
	global_store_short v[72:73], v16, off offset:288
	v_cvt_pk_bf16_f32 v16, v19, v177
	global_store_short v[58:59], v16, off offset:288
	v_cvt_pk_bf16_f32 v12, v12, v177
	global_store_short v[66:67], v12, off offset:320
	v_cvt_pk_bf16_f32 v12, v13, v177
	global_store_short v[60:61], v12, off offset:320
	v_cvt_pk_bf16_f32 v12, v14, v177
	global_store_short v[68:69], v12, off offset:320
	v_cvt_pk_bf16_f32 v12, v15, v177
	global_store_short v[62:63], v12, off offset:320
	v_cvt_pk_bf16_f32 v8, v8, v177
	global_store_short v[70:71], v8, off offset:320
	v_cvt_pk_bf16_f32 v8, v9, v177
	global_store_short v[56:57], v8, off offset:320
	v_cvt_pk_bf16_f32 v8, v10, v177
	global_store_short v[72:73], v8, off offset:320
	v_cvt_pk_bf16_f32 v8, v11, v177
	global_store_short v[58:59], v8, off offset:320
	v_cvt_pk_bf16_f32 v4, v4, v177
	global_store_short v[66:67], v4, off offset:352
	v_cvt_pk_bf16_f32 v4, v5, v177
	global_store_short v[60:61], v4, off offset:352
	v_cvt_pk_bf16_f32 v4, v6, v177
	global_store_short v[68:69], v4, off offset:352
	v_cvt_pk_bf16_f32 v4, v7, v177
	global_store_short v[62:63], v4, off offset:352
	v_cvt_pk_bf16_f32 v0, v0, v177
	global_store_short v[70:71], v0, off offset:352
	v_cvt_pk_bf16_f32 v0, v1, v177
	global_store_short v[56:57], v0, off offset:352
	v_cvt_pk_bf16_f32 v0, v2, v177
	global_store_short v[72:73], v0, off offset:352
	v_cvt_pk_bf16_f32 v0, v3, v177
	global_store_short v[58:59], v0, off offset:352

; template <class Epi, class Sched, bool ALIGN_EPI = false, bool SP2 = false>
; __device__ __forceinline__ void gemm_phase(PG8_LAS unsigned char* lds, const Gemm g, const Sched& S, const Epi& E) {
;     ...
;         const bool has_next = S.next(ui + 1, nxt);
;         const char* nA = has_next ? (const char*)g.A + (size_t)nxt.pm * tstep + nxt.ko : cA; const char* nB = has_next ? (const char*)g.Bt + (size_t)nxt.pn * tstep + nxt.ko : cB;
;         for (int t = 0; t < nt; t += 2) {
;             const bool last = (t == nt - 2);
;             const char* a1 = cA + (size_t)(t + 1) * kstep;
;             const char* a2 = last ? nA : cA + (size_t)(t + 2) * kstep; const char* b2 = last ? nB : cB + (size_t)(t + 2) * kstep;
;             const char* a3 = a2 + kstep; const char* b3 = b2 + kstep;
;             if (last && has_next) S.a_ready(nxt);
;     ...
; #pragma unroll
;         for (int a = 0; a < 2; ++a)
; #pragma unroll
;             for (int b = 0; b < 2; ++b)
; #pragma unroll
;                 for (int m = 0; m < 4; ++m)
; #pragma unroll
;                     for (int n = 0; n < 2; ++n) acc[a][b][m][n] = (f32x4){0.f, 0.f, 0.f, 0.f};
;         cur = nxt; cA = nA; cB = nB; ++ui;
.LBB0_569:
	s_ashr_i32 s27, s26, 31
	s_lshl_b64 s[18:19], s[26:27], 19
	v_readlane_b32 s34, v253, 53
	v_readlane_b32 s35, v253, 54
	s_add_u32 s34, s34, s18
	s_addc_u32 s35, s35, s19
	s_and_b64 s[18:19], s[6:7], exec
	s_cselect_b32 s18, s35, s5
	s_cselect_b32 s19, s34, s4
	s_ashr_i32 s13, s12, 31
	s_lshl_b64 s[36:37], s[12:13], 19
	s_add_u32 s36, s22, s36
	s_addc_u32 s37, s23, s37
	s_and_b64 s[38:39], s[6:7], exec
	s_cselect_b32 s13, s37, s65
	s_cselect_b32 s27, s36, s64
	s_add_u32 s40, s4, 0x40080
	s_addc_u32 s41, s5, 0
	s_add_u32 s70, s64, 0x100
	v_mov_b32_e32 v0, 0
	s_addc_u32 s71, s65, 0
	s_mov_b32 s72, -2
	s_cmp_lg_u32 s67, 1
	s_cbranch_scc1 .Lg2_peel
	v_mov_b64_e32 v[0:1], 0
	v_mov_b64_e32 v[2:3], 0
	v_mov_b64_e32 v[4:5], 0
	v_mov_b64_e32 v[6:7], 0
	v_mov_b64_e32 v[8:9], 0
	v_mov_b64_e32 v[10:11], 0
	v_mov_b64_e32 v[12:13], 0
	v_mov_b64_e32 v[14:15], 0
	v_mov_b64_e32 v[16:17], 0
	v_mov_b64_e32 v[18:19], 0
	v_mov_b64_e32 v[20:21], 0
	v_mov_b64_e32 v[22:23], 0
	v_mov_b64_e32 v[24:25], 0
	v_mov_b64_e32 v[26:27], 0
	v_mov_b64_e32 v[28:29], 0
	v_mov_b64_e32 v[30:31], 0
	v_mov_b64_e32 v[32:33], 0
	v_mov_b64_e32 v[34:35], 0
	v_mov_b64_e32 v[36:37], 0
	v_mov_b64_e32 v[38:39], 0
	v_mov_b64_e32 v[40:41], 0
	v_mov_b64_e32 v[42:43], 0
	v_mov_b64_e32 v[44:45], 0
	v_mov_b64_e32 v[46:47], 0
	v_mov_b64_e32 v[48:49], 0
	v_mov_b64_e32 v[50:51], 0
	v_mov_b64_e32 v[52:53], 0
	v_mov_b64_e32 v[54:55], 0
	v_mov_b64_e32 v[56:57], 0
	v_mov_b64_e32 v[58:59], 0
	v_mov_b64_e32 v[60:61], 0
	v_mov_b64_e32 v[62:63], 0
	v_mov_b64_e32 v[64:65], 0
	v_mov_b64_e32 v[66:67], 0
	v_mov_b64_e32 v[68:69], 0
	v_mov_b64_e32 v[70:71], 0
	v_mov_b64_e32 v[72:73], 0
	v_mov_b64_e32 v[74:75], 0
	v_mov_b64_e32 v[76:77], 0
	v_mov_b64_e32 v[78:79], 0
	v_mov_b64_e32 v[80:81], 0
	v_mov_b64_e32 v[82:83], 0
	v_mov_b64_e32 v[84:85], 0
	v_mov_b64_e32 v[86:87], 0
	v_mov_b64_e32 v[88:89], 0
	v_mov_b64_e32 v[90:91], 0
	v_mov_b64_e32 v[92:93], 0
	v_mov_b64_e32 v[94:95], 0
	v_mov_b64_e32 v[96:97], 0
	v_mov_b64_e32 v[98:99], 0
	v_mov_b64_e32 v[100:101], 0
	v_mov_b64_e32 v[102:103], 0
	v_mov_b64_e32 v[104:105], 0
	v_mov_b64_e32 v[106:107], 0
	v_mov_b64_e32 v[108:109], 0
	v_mov_b64_e32 v[110:111], 0
	v_mov_b64_e32 v[112:113], 0
	v_mov_b64_e32 v[114:115], 0
	v_mov_b64_e32 v[116:117], 0
	v_mov_b64_e32 v[118:119], 0
	v_mov_b64_e32 v[120:121], 0
	v_mov_b64_e32 v[122:123], 0
	v_mov_b64_e32 v[124:125], 0
	v_mov_b64_e32 v[126:127], 0

; #define PG8_BAR __builtin_amdgcn_s_barrier()
; template <class Epi, class Sched, bool ALIGN_EPI = false, bool SP2 = false>
; __device__ __forceinline__ void gemm_phase(PG8_LAS unsigned char* lds, const Gemm g, const Sched& S, const Epi& E) {
;     ...
;         if constexpr (ALIGN_EPI) { if (wr == 0) PG8_BAR; }
;         if constexpr (!Epi::AFTER_DRAIN) { E(acc, cur, wr, wc, fr, fq); S.done(cur); }
;         if (!has_next) break;
.Lg2_post:
	s_and_b64 vcc, exec, s[10:11]
	s_mov_b32 s48, 0x358637bd
	s_mov_b32 s72, 0x3a800000
	s_cbranch_vccz .LBB0_573
	s_barrier

; #define PG8_STAGE(bufoff, gbase, voff) do { _Pragma("unroll") for (int _i = 0; _i < 2; ++_i) \
;         __builtin_amdgcn_global_load_lds((const unsigned*)((const char*)(gbase) + (voff)[_i]), (PG8_LAS unsigned*)(lds + (bufoff) + ldsw + _i * 8192), 16, 0, 0); } while (0)
; #define PG8_LDA(dst, b, h) do { _Pragma("unroll") for (int m = 0; m < 4; ++m) _Pragma("unroll") for (int k = 0; k < 2; ++k) dst[m][k] = *(const PG8_LAS bf16x8*)(lds + PG8_SA(b, h) + aoff + m * 2048 + k * 1024); } while (0)
; #define PG8_LDB(dst, b, h) do { _Pragma("unroll") for (int n = 0; n < 2; ++n) _Pragma("unroll") for (int k = 0; k < 2; ++k) dst[n][k] = *(const PG8_LAS bf16x8*)(lds + PG8_SB(b, h) + boff + n * 2048 + k * 1024); } while (0)
; #define PG8_MMA(ai, bj, At, Bt) do { __builtin_amdgcn_s_setprio(1); _Pragma("unroll") for (int m = 0; m < 4; ++m) _Pragma("unroll") for (int n = 0; n < 2; ++n) _Pragma("unroll") for (int k = 0; k < 2; ++k) \
;         acc[ai][bj][m][n] = __builtin_amdgcn_mfma_f32_16x16x32_bf16(Bt[n][k], At[m][k], acc[ai][bj][m][n], 0, 0, 0); __builtin_amdgcn_s_setprio(0); } while (0)
; #define PG8_WAIT_V(n) asm volatile("s_waitcnt vmcnt(" #n ")" ::: "memory")
; #define PG8_WAIT_L(n) asm volatile("s_waitcnt lgkmcnt(" #n ")" ::: "memory")
; #define PG8_BAR __builtin_amdgcn_s_barrier()
; #define PG8_SCHED __builtin_amdgcn_sched_barrier(0)
; template <class Epi, class Sched, bool ALIGN_EPI = false, bool SP2 = false>
; __device__ __forceinline__ void gemm_phase(PG8_LAS unsigned char* lds, const Gemm g, const Sched& S, const Epi& E) {
;     ...
;             if constexpr (SP2) {
;             PG8_LDB(B0, 0, 0); PG8_LDB(B1, 0, 1); PG8_SCHED; PG8_LDA(At, 0, 0); PG8_STAGE(PG8_SA(1, 1), a1 + hstep, voffA);
;             PG8_WAIT_V(8); PG8_WAIT_L(0); PG8_BAR; PG8_MMA(0, 0, At, B0); PG8_MMA(0, 1, At, B1); PG8_BAR; PG8_SCHED;
;             PG8_LDA(At, 0, 1); PG8_STAGE(PG8_SB(0, 0), b2, voffB); PG8_STAGE(PG8_SB(0, 1), b2 + hstep, voffB); PG8_STAGE(PG8_SA(0, 0), a2, voffA);
;             PG8_WAIT_V(8); PG8_WAIT_L(0); PG8_BAR; PG8_MMA(1, 0, At, B0); PG8_MMA(1, 1, At, B1); PG8_BAR; PG8_SCHED;
.Lg2_peel:
	s_add_u32 s4, s40, 0xfffc0080
	s_addc_u32 s5, s41, -1
	s_add_i32 s28, 0, 0x10000
	s_cmp_eq_u32 s72, 12
	s_cselect_b32 s65, s18, s5
	s_cselect_b32 s64, s19, s4
	v_add_u32_e32 v138, s28, v142
	s_cselect_b32 s5, s13, s71
	s_cselect_b32 s4, s27, s70
	s_add_i32 s48, 0, 0x14000
	ds_read_b128 v[144:147], v138
	ds_read_b128 v[148:151], v138 offset:1024
	ds_read_b128 v[152:155], v138 offset:2048
	ds_read_b128 v[156:159], v138 offset:3072
	v_add_u32_e32 v138, s48, v142
	ds_read_b128 v[160:163], v138
	ds_read_b128 v[164:167], v138 offset:1024
	ds_read_b128 v[168:171], v138 offset:2048
	ds_read_b128 v[172:175], v138 offset:3072
	v_lshl_add_u64 v[138:139], s[40:41], 0, v[134:135]
	s_add_i32 m0, s25, 0xc000
	ds_read_b128 v[182:185], v143
	ds_read_b128 v[186:189], v143 offset:1024
	ds_read_b128 v[190:193], v143 offset:2048
	ds_read_b128 v[194:197], v143 offset:3072
	ds_read_b128 v[198:201], v143 offset:4096
	ds_read_b128 v[202:205], v143 offset:5120
	ds_read_b128 v[206:209], v143 offset:6144
	ds_read_b128 v[210:213], v143 offset:7168
	global_load_lds_dwordx4 v[138:139], off
	v_lshl_add_u64 v[138:139], s[40:41], 0, v[136:137]
	s_add_i32 m0, s25, 0xe000
	s_nop 0
	global_load_lds_dwordx4 v[138:139], off
	s_waitcnt vmcnt(24)
	s_waitcnt lgkmcnt(0)
	s_barrier
	s_setprio 1
	s_waitcnt lgkmcnt(0)
	v_mfma_f32_16x16x32_bf16 v[124:127], v[144:147], v[182:185], 0
	v_mfma_f32_16x16x32_bf16 v[120:123], v[152:155], v[182:185], 0
	v_mfma_f32_16x16x32_bf16 v[116:119], v[144:147], v[190:193], 0
	v_mfma_f32_16x16x32_bf16 v[108:111], v[152:155], v[190:193], 0
	v_mfma_f32_16x16x32_bf16 v[100:103], v[144:147], v[198:201], 0
	v_mfma_f32_16x16x32_bf16 v[92:95], v[152:155], v[198:201], 0
	v_mfma_f32_16x16x32_bf16 v[84:87], v[144:147], v[206:209], 0
	v_mfma_f32_16x16x32_bf16 v[76:79], v[152:155], v[206:209], 0
	v_mfma_f32_16x16x32_bf16 v[124:127], v[148:151], v[186:189], v[124:127]
	v_mfma_f32_16x16x32_bf16 v[120:123], v[156:159], v[186:189], v[120:123]
	v_mfma_f32_16x16x32_bf16 v[116:119], v[148:151], v[194:197], v[116:119]
	v_mfma_f32_16x16x32_bf16 v[108:111], v[156:159], v[194:197], v[108:111]
	v_mfma_f32_16x16x32_bf16 v[100:103], v[148:151], v[202:205], v[100:103]
	v_mfma_f32_16x16x32_bf16 v[92:95], v[156:159], v[202:205], v[92:95]
	v_mfma_f32_16x16x32_bf16 v[84:87], v[148:151], v[210:213], v[84:87]
	v_mfma_f32_16x16x32_bf16 v[76:79], v[156:159], v[210:213], v[76:79]
	s_setprio 0
	s_setprio 1
	v_mfma_f32_16x16x32_bf16 v[112:115], v[160:163], v[182:185], 0
	v_mfma_f32_16x16x32_bf16 v[104:107], v[168:171], v[182:185], 0
	v_mfma_f32_16x16x32_bf16 v[96:99], v[160:163], v[190:193], 0
	v_mfma_f32_16x16x32_bf16 v[88:91], v[168:171], v[190:193], 0
	v_mfma_f32_16x16x32_bf16 v[80:83], v[160:163], v[198:201], 0
	v_mfma_f32_16x16x32_bf16 v[72:75], v[168:171], v[198:201], 0
	v_mfma_f32_16x16x32_bf16 v[68:71], v[160:163], v[206:209], 0
	v_mfma_f32_16x16x32_bf16 v[64:67], v[168:171], v[206:209], 0
	v_mfma_f32_16x16x32_bf16 v[112:115], v[164:167], v[186:189], v[112:115]
	v_mfma_f32_16x16x32_bf16 v[104:107], v[172:175], v[186:189], v[104:107]
	v_mfma_f32_16x16x32_bf16 v[96:99], v[164:167], v[194:197], v[96:99]
	v_mfma_f32_16x16x32_bf16 v[88:91], v[172:175], v[194:197], v[88:91]
	v_mfma_f32_16x16x32_bf16 v[80:83], v[164:167], v[202:205], v[80:83]
	v_mfma_f32_16x16x32_bf16 v[72:75], v[172:175], v[202:205], v[72:75]
	v_mfma_f32_16x16x32_bf16 v[68:71], v[164:167], v[210:213], v[68:71]
	v_mfma_f32_16x16x32_bf16 v[64:67], v[172:175], v[210:213], v[64:67]
	s_setprio 0
	s_barrier
	s_add_i32 s28, s28, s24
	v_lshl_add_u64 v[138:139], s[4:5], 0, v[176:177]
	s_mov_b32 m0, s28
	ds_read_b128 v[182:185], v143 offset:16384
	ds_read_b128 v[186:189], v143 offset:17408
	ds_read_b128 v[190:193], v143 offset:18432
	ds_read_b128 v[194:197], v143 offset:19456
	ds_read_b128 v[198:201], v143 offset:20480
	ds_read_b128 v[202:205], v143 offset:21504
	ds_read_b128 v[206:209], v143 offset:22528
	ds_read_b128 v[210:213], v143 offset:23552
	global_load_lds_dwordx4 v[138:139], off
	s_add_i32 m0, s28, 0x2000
	s_add_u32 s38, s4, 0x40000
	v_lshl_add_u64 v[214:215], s[4:5], 0, v[128:129]
	s_addc_u32 s39, s5, 0
	s_add_i32 s28, s48, s24
	global_load_lds_dwordx4 v[214:215], off
	v_lshl_add_u64 v[216:217], s[38:39], 0, v[176:177]
	s_mov_b32 m0, s28
	v_lshl_add_u64 v[218:219], s[64:65], 0, v[130:131]
	global_load_lds_dwordx4 v[216:217], off
	v_lshl_add_u64 v[216:217], s[38:39], 0, v[128:129]
	s_add_i32 m0, s28, 0x2000
	s_nop 0
	global_load_lds_dwordx4 v[216:217], off
	v_lshl_add_u64 v[216:217], s[64:65], 0, v[132:133]
	s_mov_b32 m0, s25
	s_nop 0
	global_load_lds_dwordx4 v[216:217], off
	s_mov_b32 m0, s30
	s_nop 0
	global_load_lds_dwordx4 v[218:219], off
	s_waitcnt vmcnt(24)
	s_waitcnt lgkmcnt(0)
	s_barrier
; #define PG8_STAGE(bufoff, gbase, voff) do { _Pragma("unroll") for (int _i = 0; _i < 2; ++_i) \
;         __builtin_amdgcn_global_load_lds((const unsigned*)((const char*)(gbase) + (voff)[_i]), (PG8_LAS unsigned*)(lds + (bufoff) + ldsw + _i * 8192), 16, 0, 0); } while (0)
; #define PG8_LDA(dst, b, h) do { _Pragma("unroll") for (int m = 0; m < 4; ++m) _Pragma("unroll") for (int k = 0; k < 2; ++k) dst[m][k] = *(const PG8_LAS bf16x8*)(lds + PG8_SA(b, h) + aoff + m * 2048 + k * 1024); } while (0)
; #define PG8_LDB(dst, b, h) do { _Pragma("unroll") for (int n = 0; n < 2; ++n) _Pragma("unroll") for (int k = 0; k < 2; ++k) dst[n][k] = *(const PG8_LAS bf16x8*)(lds + PG8_SB(b, h) + boff + n * 2048 + k * 1024); } while (0)
; #define PG8_MMA(ai, bj, At, Bt) do { __builtin_amdgcn_s_setprio(1); _Pragma("unroll") for (int m = 0; m < 4; ++m) _Pragma("unroll") for (int n = 0; n < 2; ++n) _Pragma("unroll") for (int k = 0; k < 2; ++k) \
;         acc[ai][bj][m][n] = __builtin_amdgcn_mfma_f32_16x16x32_bf16(Bt[n][k], At[m][k], acc[ai][bj][m][n], 0, 0, 0); __builtin_amdgcn_s_setprio(0); } while (0)
; #define PG8_WAIT_V(n) asm volatile("s_waitcnt vmcnt(" #n ")" ::: "memory")
; #define PG8_WAIT_L(n) asm volatile("s_waitcnt lgkmcnt(" #n ")" ::: "memory")
; #define PG8_BAR __builtin_amdgcn_s_barrier()
; #define PG8_SCHED __builtin_amdgcn_sched_barrier(0)
; template <class Epi, class Sched, bool ALIGN_EPI = false, bool SP2 = false>
; __device__ __forceinline__ void gemm_phase(PG8_LAS unsigned char* lds, const Gemm g, const Sched& S, const Epi& E) {
;     ...
;             PG8_WAIT_V(8); PG8_WAIT_L(0); PG8_BAR; PG8_MMA(1, 0, At, B0); PG8_MMA(1, 1, At, B1); PG8_BAR; PG8_SCHED;
;             PG8_LDB(B0, 1, 0); PG8_LDB(B1, 1, 1); PG8_SCHED; PG8_LDA(At, 1, 0); PG8_STAGE(PG8_SA(0, 1), a2 + hstep, voffA);
;             PG8_WAIT_V(8); PG8_WAIT_L(0); PG8_BAR; PG8_MMA(0, 0, At, B0); PG8_MMA(0, 1, At, B1); PG8_BAR; PG8_SCHED;
	s_setprio 1
	s_waitcnt lgkmcnt(0)
	v_mfma_f32_16x16x32_bf16 v[60:63], v[144:147], v[182:185], 0
	v_mfma_f32_16x16x32_bf16 v[56:59], v[152:155], v[182:185], 0
	v_mfma_f32_16x16x32_bf16 v[52:55], v[144:147], v[190:193], 0
	v_mfma_f32_16x16x32_bf16 v[44:47], v[152:155], v[190:193], 0
	v_mfma_f32_16x16x32_bf16 v[36:39], v[144:147], v[198:201], 0
	v_mfma_f32_16x16x32_bf16 v[28:31], v[152:155], v[198:201], 0
	v_mfma_f32_16x16x32_bf16 v[20:23], v[144:147], v[206:209], 0
	v_mfma_f32_16x16x32_bf16 v[12:15], v[152:155], v[206:209], 0
	v_mfma_f32_16x16x32_bf16 v[60:63], v[148:151], v[186:189], v[60:63]
	v_mfma_f32_16x16x32_bf16 v[56:59], v[156:159], v[186:189], v[56:59]
	v_mfma_f32_16x16x32_bf16 v[52:55], v[148:151], v[194:197], v[52:55]
	v_mfma_f32_16x16x32_bf16 v[44:47], v[156:159], v[194:197], v[44:47]
	v_mfma_f32_16x16x32_bf16 v[36:39], v[148:151], v[202:205], v[36:39]
	v_mfma_f32_16x16x32_bf16 v[28:31], v[156:159], v[202:205], v[28:31]
	v_mfma_f32_16x16x32_bf16 v[20:23], v[148:151], v[210:213], v[20:23]
	v_mfma_f32_16x16x32_bf16 v[12:15], v[156:159], v[210:213], v[12:15]
	s_setprio 0
	s_setprio 1
	v_mfma_f32_16x16x32_bf16 v[48:51], v[160:163], v[182:185], 0
	v_mfma_f32_16x16x32_bf16 v[40:43], v[168:171], v[182:185], 0
	v_mfma_f32_16x16x32_bf16 v[32:35], v[160:163], v[190:193], 0
	v_mfma_f32_16x16x32_bf16 v[24:27], v[168:171], v[190:193], 0
	v_mfma_f32_16x16x32_bf16 v[16:19], v[160:163], v[198:201], 0
	v_mfma_f32_16x16x32_bf16 v[8:11], v[168:171], v[198:201], 0
	v_mfma_f32_16x16x32_bf16 v[4:7], v[160:163], v[206:209], 0
	v_mfma_f32_16x16x32_bf16 v[0:3], v[168:171], v[206:209], 0
	v_mfma_f32_16x16x32_bf16 v[48:51], v[164:167], v[186:189], v[48:51]
	v_mfma_f32_16x16x32_bf16 v[40:43], v[172:175], v[186:189], v[40:43]
	v_mfma_f32_16x16x32_bf16 v[32:35], v[164:167], v[194:197], v[32:35]
	v_mfma_f32_16x16x32_bf16 v[24:27], v[172:175], v[194:197], v[24:27]
	v_mfma_f32_16x16x32_bf16 v[16:19], v[164:167], v[202:205], v[16:19]
	v_mfma_f32_16x16x32_bf16 v[8:11], v[172:175], v[202:205], v[8:11]
	v_mfma_f32_16x16x32_bf16 v[4:7], v[164:167], v[210:213], v[4:7]
	v_mfma_f32_16x16x32_bf16 v[0:3], v[172:175], v[210:213], v[0:3]
	s_setprio 0
	s_barrier
	s_add_i32 s28, 0, 0x18000
	s_add_i32 s48, 0, 0x1c000
	v_add_u32_e32 v156, s28, v142
	v_add_u32_e32 v172, s48, v142
	ds_read_b128 v[144:147], v156
	ds_read_b128 v[148:151], v156 offset:1024
	ds_read_b128 v[152:155], v156 offset:2048
	ds_read_b128 v[156:159], v156 offset:3072
	ds_read_b128 v[160:163], v172
	ds_read_b128 v[164:167], v172 offset:1024
	ds_read_b128 v[168:171], v172 offset:2048
	ds_read_b128 v[172:175], v172 offset:3072
	s_add_u32 s38, s64, 0x40000
	s_addc_u32 s39, s65, 0
	s_mov_b32 m0, s31
	v_lshl_add_u64 v[220:221], s[38:39], 0, v[132:133]
	ds_read_b128 v[182:185], v143 offset:32768
	ds_read_b128 v[186:189], v143 offset:33792
	ds_read_b128 v[190:193], v143 offset:34816
	ds_read_b128 v[194:197], v143 offset:35840
	ds_read_b128 v[198:201], v143 offset:36864
	ds_read_b128 v[202:205], v143 offset:37888
	ds_read_b128 v[206:209], v143 offset:38912
	ds_read_b128 v[210:213], v143 offset:39936
	global_load_lds_dwordx4 v[220:221], off
	v_lshl_add_u64 v[220:221], s[38:39], 0, v[130:131]
	s_mov_b32 m0, s42
	s_nop 0
	global_load_lds_dwordx4 v[220:221], off
	s_waitcnt vmcnt(8)
	s_waitcnt lgkmcnt(0)
	s_barrier
	s_setprio 1
	s_waitcnt lgkmcnt(0)
	v_mfma_f32_16x16x32_bf16 v[124:127], v[144:147], v[182:185], v[124:127]
	v_mfma_f32_16x16x32_bf16 v[120:123], v[152:155], v[182:185], v[120:123]
	v_mfma_f32_16x16x32_bf16 v[116:119], v[144:147], v[190:193], v[116:119]
	v_mfma_f32_16x16x32_bf16 v[108:111], v[152:155], v[190:193], v[108:111]
	v_mfma_f32_16x16x32_bf16 v[100:103], v[144:147], v[198:201], v[100:103]
	v_mfma_f32_16x16x32_bf16 v[92:95], v[152:155], v[198:201], v[92:95]
	v_mfma_f32_16x16x32_bf16 v[84:87], v[144:147], v[206:209], v[84:87]
	v_mfma_f32_16x16x32_bf16 v[76:79], v[152:155], v[206:209], v[76:79]
	v_mfma_f32_16x16x32_bf16 v[124:127], v[148:151], v[186:189], v[124:127]
	v_mfma_f32_16x16x32_bf16 v[120:123], v[156:159], v[186:189], v[120:123]
	v_mfma_f32_16x16x32_bf16 v[116:119], v[148:151], v[194:197], v[116:119]
	v_mfma_f32_16x16x32_bf16 v[108:111], v[156:159], v[194:197], v[108:111]
	v_mfma_f32_16x16x32_bf16 v[100:103], v[148:151], v[202:205], v[100:103]
	v_mfma_f32_16x16x32_bf16 v[92:95], v[156:159], v[202:205], v[92:95]
	v_mfma_f32_16x16x32_bf16 v[84:87], v[148:151], v[210:213], v[84:87]
	v_mfma_f32_16x16x32_bf16 v[76:79], v[156:159], v[210:213], v[76:79]
	s_setprio 0
	s_setprio 1
	v_mfma_f32_16x16x32_bf16 v[112:115], v[160:163], v[182:185], v[112:115]
	v_mfma_f32_16x16x32_bf16 v[104:107], v[168:171], v[182:185], v[104:107]
	v_mfma_f32_16x16x32_bf16 v[96:99], v[160:163], v[190:193], v[96:99]
	v_mfma_f32_16x16x32_bf16 v[88:91], v[168:171], v[190:193], v[88:91]
	v_mfma_f32_16x16x32_bf16 v[80:83], v[160:163], v[198:201], v[80:83]
	v_mfma_f32_16x16x32_bf16 v[72:75], v[168:171], v[198:201], v[72:75]
	v_mfma_f32_16x16x32_bf16 v[68:71], v[160:163], v[206:209], v[68:71]
	v_mfma_f32_16x16x32_bf16 v[64:67], v[168:171], v[206:209], v[64:67]
	v_mfma_f32_16x16x32_bf16 v[112:115], v[164:167], v[186:189], v[112:115]
	v_mfma_f32_16x16x32_bf16 v[104:107], v[172:175], v[186:189], v[104:107]
	v_mfma_f32_16x16x32_bf16 v[96:99], v[164:167], v[194:197], v[96:99]
	v_mfma_f32_16x16x32_bf16 v[88:91], v[172:175], v[194:197], v[88:91]
	v_mfma_f32_16x16x32_bf16 v[80:83], v[164:167], v[202:205], v[80:83]
	v_mfma_f32_16x16x32_bf16 v[72:75], v[172:175], v[202:205], v[72:75]
	v_mfma_f32_16x16x32_bf16 v[68:71], v[164:167], v[210:213], v[68:71]
	v_mfma_f32_16x16x32_bf16 v[64:67], v[172:175], v[210:213], v[64:67]
	s_setprio 0
	s_barrier
; #define PG8_STAGE(bufoff, gbase, voff) do { _Pragma("unroll") for (int _i = 0; _i < 2; ++_i) \
;         __builtin_amdgcn_global_load_lds((const unsigned*)((const char*)(gbase) + (voff)[_i]), (PG8_LAS unsigned*)(lds + (bufoff) + ldsw + _i * 8192), 16, 0, 0); } while (0)
; #define PG8_LDA(dst, b, h) do { _Pragma("unroll") for (int m = 0; m < 4; ++m) _Pragma("unroll") for (int k = 0; k < 2; ++k) dst[m][k] = *(const PG8_LAS bf16x8*)(lds + PG8_SA(b, h) + aoff + m * 2048 + k * 1024); } while (0)
; #define PG8_MMA(ai, bj, At, Bt) do { __builtin_amdgcn_s_setprio(1); _Pragma("unroll") for (int m = 0; m < 4; ++m) _Pragma("unroll") for (int n = 0; n < 2; ++n) _Pragma("unroll") for (int k = 0; k < 2; ++k) \
;         acc[ai][bj][m][n] = __builtin_amdgcn_mfma_f32_16x16x32_bf16(Bt[n][k], At[m][k], acc[ai][bj][m][n], 0, 0, 0); __builtin_amdgcn_s_setprio(0); } while (0)
; #define PG8_WAIT_V(n) asm volatile("s_waitcnt vmcnt(" #n ")" ::: "memory")
; #define PG8_WAIT_L(n) asm volatile("s_waitcnt lgkmcnt(" #n ")" ::: "memory")
; #define PG8_BAR __builtin_amdgcn_s_barrier()
; #define PG8_SCHED __builtin_amdgcn_sched_barrier(0)
; template <class Epi, class Sched, bool ALIGN_EPI = false, bool SP2 = false>
; __device__ __forceinline__ void gemm_phase(PG8_LAS unsigned char* lds, const Gemm g, const Sched& S, const Epi& E) {
;     ...
;             PG8_WAIT_V(8); PG8_WAIT_L(0); PG8_BAR; PG8_MMA(0, 0, At, B0); PG8_MMA(0, 1, At, B1); PG8_BAR; PG8_SCHED;
;             PG8_LDA(At, 1, 1); PG8_STAGE(PG8_SB(1, 0), b3, voffB); PG8_STAGE(PG8_SB(1, 1), b3 + hstep, voffB); PG8_STAGE(PG8_SA(1, 0), a3, voffA);
;             PG8_WAIT_V(8); PG8_WAIT_L(0); PG8_BAR; PG8_MMA(1, 0, At, B0); PG8_MMA(1, 1, At, B1); PG8_BAR; PG8_SCHED;
	s_add_i32 s28, s28, s24
	v_lshl_add_u64 v[138:139], v[138:139], 0, s[44:45]
	s_mov_b32 m0, s28
	ds_read_b128 v[182:185], v143 offset:49152
	ds_read_b128 v[186:189], v143 offset:50176
	ds_read_b128 v[190:193], v143 offset:51200
	ds_read_b128 v[194:197], v143 offset:52224
	ds_read_b128 v[198:201], v143 offset:53248
	ds_read_b128 v[202:205], v143 offset:54272
	ds_read_b128 v[206:209], v143 offset:55296
	ds_read_b128 v[210:213], v143 offset:56320
	global_load_lds_dwordx4 v[138:139], off
	s_add_i32 m0, s28, 0x2000
	s_add_u32 s4, s4, 0x40080
	v_lshl_add_u64 v[138:139], v[214:215], 0, s[44:45]
	s_addc_u32 s5, s5, 0
	s_add_i32 s28, s48, s24
	global_load_lds_dwordx4 v[138:139], off
	v_lshl_add_u64 v[138:139], s[4:5], 0, v[176:177]
	s_mov_b32 m0, s28
	s_nop 0
	global_load_lds_dwordx4 v[138:139], off
	v_lshl_add_u64 v[138:139], s[4:5], 0, v[128:129]
	s_add_i32 m0, s28, 0x2000
	s_nop 0
	global_load_lds_dwordx4 v[138:139], off
	v_lshl_add_u64 v[138:139], v[216:217], 0, s[44:45]
	s_mov_b32 m0, s63
	s_nop 0
	global_load_lds_dwordx4 v[138:139], off
	v_lshl_add_u64 v[138:139], v[218:219], 0, s[44:45]
	s_mov_b32 m0, s66
	s_nop 0
	global_load_lds_dwordx4 v[138:139], off
	s_waitcnt vmcnt(8)
	s_waitcnt lgkmcnt(0)
	s_barrier
	s_setprio 1
	s_waitcnt lgkmcnt(0)
	v_mfma_f32_16x16x32_bf16 v[60:63], v[144:147], v[182:185], v[60:63]
	v_mfma_f32_16x16x32_bf16 v[56:59], v[152:155], v[182:185], v[56:59]
	v_mfma_f32_16x16x32_bf16 v[52:55], v[144:147], v[190:193], v[52:55]
	v_mfma_f32_16x16x32_bf16 v[44:47], v[152:155], v[190:193], v[44:47]
	v_mfma_f32_16x16x32_bf16 v[36:39], v[144:147], v[198:201], v[36:39]
	v_mfma_f32_16x16x32_bf16 v[28:31], v[152:155], v[198:201], v[28:31]
	v_mfma_f32_16x16x32_bf16 v[20:23], v[144:147], v[206:209], v[20:23]
	v_mfma_f32_16x16x32_bf16 v[12:15], v[152:155], v[206:209], v[12:15]
	v_mfma_f32_16x16x32_bf16 v[60:63], v[148:151], v[186:189], v[60:63]
	v_mfma_f32_16x16x32_bf16 v[56:59], v[156:159], v[186:189], v[56:59]
	v_mfma_f32_16x16x32_bf16 v[52:55], v[148:151], v[194:197], v[52:55]
	v_mfma_f32_16x16x32_bf16 v[44:47], v[156:159], v[194:197], v[44:47]
	v_mfma_f32_16x16x32_bf16 v[36:39], v[148:151], v[202:205], v[36:39]
	v_mfma_f32_16x16x32_bf16 v[28:31], v[156:159], v[202:205], v[28:31]
	v_mfma_f32_16x16x32_bf16 v[20:23], v[148:151], v[210:213], v[20:23]
	v_mfma_f32_16x16x32_bf16 v[12:15], v[156:159], v[210:213], v[12:15]
	s_setprio 0
	s_setprio 1
	v_mfma_f32_16x16x32_bf16 v[48:51], v[160:163], v[182:185], v[48:51]
	v_mfma_f32_16x16x32_bf16 v[40:43], v[168:171], v[182:185], v[40:43]
	v_mfma_f32_16x16x32_bf16 v[32:35], v[160:163], v[190:193], v[32:35]
	v_mfma_f32_16x16x32_bf16 v[24:27], v[168:171], v[190:193], v[24:27]
	v_mfma_f32_16x16x32_bf16 v[16:19], v[160:163], v[198:201], v[16:19]
	v_mfma_f32_16x16x32_bf16 v[8:11], v[168:171], v[198:201], v[8:11]
	v_mfma_f32_16x16x32_bf16 v[4:7], v[160:163], v[206:209], v[4:7]
	v_mfma_f32_16x16x32_bf16 v[0:3], v[168:171], v[206:209], v[0:3]
	v_mfma_f32_16x16x32_bf16 v[48:51], v[164:167], v[186:189], v[48:51]
	v_mfma_f32_16x16x32_bf16 v[40:43], v[172:175], v[186:189], v[40:43]
	v_mfma_f32_16x16x32_bf16 v[32:35], v[164:167], v[194:197], v[32:35]
	v_mfma_f32_16x16x32_bf16 v[24:27], v[172:175], v[194:197], v[24:27]
	v_mfma_f32_16x16x32_bf16 v[16:19], v[164:167], v[202:205], v[16:19]
	v_mfma_f32_16x16x32_bf16 v[8:11], v[172:175], v[202:205], v[8:11]
	v_mfma_f32_16x16x32_bf16 v[4:7], v[164:167], v[210:213], v[4:7]
	v_mfma_f32_16x16x32_bf16 v[0:3], v[172:175], v[210:213], v[0:3]
	s_setprio 0
	s_barrier
	s_add_i32 s72, s72, 2
	s_add_u32 s40, s40, 0x100
	s_addc_u32 s41, s41, 0
	s_add_u32 s70, s70, 0x100
	s_addc_u32 s71, s71, 0
	s_cmp_gt_u32 s72, 13
	s_cbranch_scc0 .LBB0_570
	s_branch .Lg2_post

; #define PG8_STAGE(bufoff, gbase, voff) do { _Pragma("unroll") for (int _i = 0; _i < 2; ++_i) \
;         __builtin_amdgcn_global_load_lds((const unsigned*)((const char*)(gbase) + (voff)[_i]), (PG8_LAS unsigned*)(lds + (bufoff) + ldsw + _i * 8192), 16, 0, 0); } while (0)
; #define PG8_LDA(dst, b, h) do { _Pragma("unroll") for (int m = 0; m < 4; ++m) _Pragma("unroll") for (int k = 0; k < 2; ++k) dst[m][k] = *(const PG8_LAS bf16x8*)(lds + PG8_SA(b, h) + aoff + m * 2048 + k * 1024); } while (0)
; #define PG8_LDB(dst, b, h) do { _Pragma("unroll") for (int n = 0; n < 2; ++n) _Pragma("unroll") for (int k = 0; k < 2; ++k) dst[n][k] = *(const PG8_LAS bf16x8*)(lds + PG8_SB(b, h) + boff + n * 2048 + k * 1024); } while (0)
; #define PG8_WAIT_V(n) asm volatile("s_waitcnt vmcnt(" #n ")" ::: "memory")
; #define PG8_WAIT_L(n) asm volatile("s_waitcnt lgkmcnt(" #n ")" ::: "memory")
; #define PG8_BAR __builtin_amdgcn_s_barrier()
; template <class Epi, class Sched, bool ALIGN_EPI = false, bool SP2 = false>
; __device__ __forceinline__ void gemm_phase(PG8_LAS unsigned char* lds, const Gemm g, const Sched& S, const Epi& E) {
;     ...
;         const bool has_next = S.next(ui + 1, nxt);
;         const char* nA = has_next ? (const char*)g.A + (size_t)nxt.pm * tstep + nxt.ko : cA; const char* nB = has_next ? (const char*)g.Bt + (size_t)nxt.pn * tstep + nxt.ko : cB;
;         for (int t = 0; t < nt; t += 2) {
;             const bool last = (t == nt - 2);
;             const char* a1 = cA + (size_t)(t + 1) * kstep;
;             const char* a2 = last ? nA : cA + (size_t)(t + 2) * kstep; const char* b2 = last ? nB : cB + (size_t)(t + 2) * kstep;
;             const char* a3 = a2 + kstep; const char* b3 = b2 + kstep;
;             if (last && has_next) S.a_ready(nxt);
;             if constexpr (SP2) {
;             PG8_LDB(B0, 0, 0); PG8_LDB(B1, 0, 1); PG8_SCHED; PG8_LDA(At, 0, 0); PG8_STAGE(PG8_SA(1, 1), a1 + hstep, voffA);
;             PG8_WAIT_V(8); PG8_WAIT_L(0); PG8_BAR; PG8_MMA(0, 0, At, B0); PG8_MMA(0, 1, At, B1); PG8_BAR; PG8_SCHED;
;     ...
; #pragma unroll
;         for (int a = 0; a < 2; ++a)
; #pragma unroll
;             for (int b = 0; b < 2; ++b)
; #pragma unroll
;                 for (int m = 0; m < 4; ++m)
; #pragma unroll
;                     for (int n = 0; n < 2; ++n) acc[a][b][m][n] = (f32x4){0.f, 0.f, 0.f, 0.f};
;         cur = nxt; cA = nA; cB = nB; ++ui;
.LBB0_717:
	s_ashr_i32 s41, s40, 31
	s_lshl_b64 s[4:5], s[40:41], 19
	s_add_u32 s6, s50, s4
	s_addc_u32 s7, s51, s5
	s_and_b64 s[4:5], s[12:13], exec
	s_cselect_b32 s41, s7, s65
	s_cselect_b32 s76, s6, s64
	s_ashr_i32 s37, s36, 31
	s_lshl_b64 s[4:5], s[36:37], 19
	s_add_u32 s4, s19, s4
	s_addc_u32 s5, s22, s5
	s_and_b64 s[38:39], s[12:13], exec
	s_cselect_b32 s37, s5, s67
	s_cselect_b32 s77, s4, s66
	s_add_u32 vcc_lo, s64, 0x40080
	s_addc_u32 vcc_hi, s65, 0
	s_add_u32 s78, s66, 0x100
	v_mov_b32_e32 v0, 0
	s_addc_u32 s79, s67, 0
	s_mov_b32 s80, -2
	s_cmp_lg_u32 s75, 1
	s_cbranch_scc1 .Lg3_peel
	v_mov_b64_e32 v[0:1], 0
	v_mov_b64_e32 v[2:3], 0
	v_mov_b64_e32 v[4:5], 0
	v_mov_b64_e32 v[6:7], 0
	v_mov_b64_e32 v[8:9], 0
	v_mov_b64_e32 v[10:11], 0
	v_mov_b64_e32 v[12:13], 0
	v_mov_b64_e32 v[14:15], 0
	v_mov_b64_e32 v[16:17], 0
	v_mov_b64_e32 v[18:19], 0
	v_mov_b64_e32 v[20:21], 0
	v_mov_b64_e32 v[22:23], 0
	v_mov_b64_e32 v[24:25], 0
	v_mov_b64_e32 v[26:27], 0
	v_mov_b64_e32 v[28:29], 0
	v_mov_b64_e32 v[30:31], 0
	v_mov_b64_e32 v[32:33], 0
	v_mov_b64_e32 v[34:35], 0
	v_mov_b64_e32 v[36:37], 0
	v_mov_b64_e32 v[38:39], 0
	v_mov_b64_e32 v[40:41], 0
	v_mov_b64_e32 v[42:43], 0
	v_mov_b64_e32 v[44:45], 0
	v_mov_b64_e32 v[46:47], 0
	v_mov_b64_e32 v[48:49], 0
	v_mov_b64_e32 v[50:51], 0
	v_mov_b64_e32 v[52:53], 0
	v_mov_b64_e32 v[54:55], 0
	v_mov_b64_e32 v[56:57], 0
	v_mov_b64_e32 v[58:59], 0
	v_mov_b64_e32 v[60:61], 0
	v_mov_b64_e32 v[62:63], 0
	v_mov_b64_e32 v[64:65], 0
	v_mov_b64_e32 v[66:67], 0
	v_mov_b64_e32 v[68:69], 0
	v_mov_b64_e32 v[70:71], 0
	v_mov_b64_e32 v[72:73], 0
	v_mov_b64_e32 v[74:75], 0
	v_mov_b64_e32 v[76:77], 0
	v_mov_b64_e32 v[78:79], 0
	v_mov_b64_e32 v[80:81], 0
	v_mov_b64_e32 v[82:83], 0
	v_mov_b64_e32 v[84:85], 0
	v_mov_b64_e32 v[86:87], 0
	v_mov_b64_e32 v[88:89], 0
	v_mov_b64_e32 v[90:91], 0
	v_mov_b64_e32 v[92:93], 0
	v_mov_b64_e32 v[94:95], 0
	v_mov_b64_e32 v[96:97], 0
	v_mov_b64_e32 v[98:99], 0
	v_mov_b64_e32 v[100:101], 0
	v_mov_b64_e32 v[102:103], 0
	v_mov_b64_e32 v[104:105], 0
	v_mov_b64_e32 v[106:107], 0
	v_mov_b64_e32 v[108:109], 0
	v_mov_b64_e32 v[110:111], 0
	v_mov_b64_e32 v[112:113], 0
	v_mov_b64_e32 v[114:115], 0
	v_mov_b64_e32 v[116:117], 0
	v_mov_b64_e32 v[118:119], 0
	v_mov_b64_e32 v[120:121], 0
	v_mov_b64_e32 v[122:123], 0
	v_mov_b64_e32 v[124:125], 0
	v_mov_b64_e32 v[126:127], 0
.LBB0_718:
	s_add_u32 s28, vcc_lo, 0xfffc0080
	s_addc_u32 s38, vcc_hi, -1
	s_add_i32 s39, 0, 0x10000
	s_cmp_eq_u32 s80, 12
	s_cselect_b32 s67, s41, s38
	s_cselect_b32 s66, s76, s28
	v_add_u32_e32 v138, s39, v142
	s_cselect_b32 s65, s37, s79
	s_cselect_b32 s64, s77, s78
	s_add_i32 s28, 0, 0x14000
	ds_read_b128 v[144:147], v138
	ds_read_b128 v[148:151], v138 offset:1024
	ds_read_b128 v[152:155], v138 offset:2048
	ds_read_b128 v[156:159], v138 offset:3072
	v_add_u32_e32 v138, s28, v142
	ds_read_b128 v[160:163], v138
	ds_read_b128 v[164:167], v138 offset:1024
	ds_read_b128 v[168:171], v138 offset:2048
	ds_read_b128 v[172:175], v138 offset:3072
	v_lshl_add_u64 v[138:139], vcc, 0, v[134:135]
	s_add_i32 m0, s30, 0xc000
	ds_read_b128 v[182:185], v143
	ds_read_b128 v[186:189], v143 offset:1024
	ds_read_b128 v[190:193], v143 offset:2048
	ds_read_b128 v[194:197], v143 offset:3072
	ds_read_b128 v[198:201], v143 offset:4096
	ds_read_b128 v[202:205], v143 offset:5120
	ds_read_b128 v[206:209], v143 offset:6144
	ds_read_b128 v[210:213], v143 offset:7168
	global_load_lds_dwordx4 v[138:139], off
	v_lshl_add_u64 v[138:139], vcc, 0, v[136:137]
	s_add_i32 m0, s30, 0xe000
	s_nop 0
	global_load_lds_dwordx4 v[138:139], off
	s_waitcnt vmcnt(8)
	s_waitcnt lgkmcnt(0)
	s_barrier
	s_setprio 1
	s_waitcnt lgkmcnt(0)
	v_mfma_f32_16x16x32_bf16 v[124:127], v[144:147], v[182:185], v[124:127]
	v_mfma_f32_16x16x32_bf16 v[120:123], v[152:155], v[182:185], v[120:123]
	v_mfma_f32_16x16x32_bf16 v[108:111], v[144:147], v[190:193], v[108:111]
	v_mfma_f32_16x16x32_bf16 v[104:107], v[152:155], v[190:193], v[104:107]
	v_mfma_f32_16x16x32_bf16 v[92:95], v[144:147], v[198:201], v[92:95]
	v_mfma_f32_16x16x32_bf16 v[88:91], v[152:155], v[198:201], v[88:91]
	v_mfma_f32_16x16x32_bf16 v[76:79], v[144:147], v[206:209], v[76:79]
	v_mfma_f32_16x16x32_bf16 v[72:75], v[152:155], v[206:209], v[72:75]
	v_mfma_f32_16x16x32_bf16 v[124:127], v[148:151], v[186:189], v[124:127]
	v_mfma_f32_16x16x32_bf16 v[120:123], v[156:159], v[186:189], v[120:123]
	v_mfma_f32_16x16x32_bf16 v[108:111], v[148:151], v[194:197], v[108:111]
	v_mfma_f32_16x16x32_bf16 v[104:107], v[156:159], v[194:197], v[104:107]
	v_mfma_f32_16x16x32_bf16 v[92:95], v[148:151], v[202:205], v[92:95]
	v_mfma_f32_16x16x32_bf16 v[88:91], v[156:159], v[202:205], v[88:91]
	v_mfma_f32_16x16x32_bf16 v[76:79], v[148:151], v[210:213], v[76:79]
	v_mfma_f32_16x16x32_bf16 v[72:75], v[156:159], v[210:213], v[72:75]
	s_setprio 0
	s_setprio 1
	v_mfma_f32_16x16x32_bf16 v[116:119], v[160:163], v[182:185], v[116:119]
	v_mfma_f32_16x16x32_bf16 v[112:115], v[168:171], v[182:185], v[112:115]
	v_mfma_f32_16x16x32_bf16 v[100:103], v[160:163], v[190:193], v[100:103]
	v_mfma_f32_16x16x32_bf16 v[96:99], v[168:171], v[190:193], v[96:99]
	v_mfma_f32_16x16x32_bf16 v[84:87], v[160:163], v[198:201], v[84:87]
	v_mfma_f32_16x16x32_bf16 v[80:83], v[168:171], v[198:201], v[80:83]
	v_mfma_f32_16x16x32_bf16 v[68:71], v[160:163], v[206:209], v[68:71]
	v_mfma_f32_16x16x32_bf16 v[64:67], v[168:171], v[206:209], v[64:67]
	v_mfma_f32_16x16x32_bf16 v[116:119], v[164:167], v[186:189], v[116:119]
	v_mfma_f32_16x16x32_bf16 v[112:115], v[172:175], v[186:189], v[112:115]
	v_mfma_f32_16x16x32_bf16 v[100:103], v[164:167], v[194:197], v[100:103]
	v_mfma_f32_16x16x32_bf16 v[96:99], v[172:175], v[194:197], v[96:99]
	v_mfma_f32_16x16x32_bf16 v[84:87], v[164:167], v[202:205], v[84:87]
	v_mfma_f32_16x16x32_bf16 v[80:83], v[172:175], v[202:205], v[80:83]
	v_mfma_f32_16x16x32_bf16 v[68:71], v[164:167], v[210:213], v[68:71]
	v_mfma_f32_16x16x32_bf16 v[64:67], v[172:175], v[210:213], v[64:67]
	s_setprio 0
	s_barrier
; #define PG8_STAGE(bufoff, gbase, voff) do { _Pragma("unroll") for (int _i = 0; _i < 2; ++_i) \
;         __builtin_amdgcn_global_load_lds((const unsigned*)((const char*)(gbase) + (voff)[_i]), (PG8_LAS unsigned*)(lds + (bufoff) + ldsw + _i * 8192), 16, 0, 0); } while (0)
; #define PG8_LDA(dst, b, h) do { _Pragma("unroll") for (int m = 0; m < 4; ++m) _Pragma("unroll") for (int k = 0; k < 2; ++k) dst[m][k] = *(const PG8_LAS bf16x8*)(lds + PG8_SA(b, h) + aoff + m * 2048 + k * 1024); } while (0)
; #define PG8_LDB(dst, b, h) do { _Pragma("unroll") for (int n = 0; n < 2; ++n) _Pragma("unroll") for (int k = 0; k < 2; ++k) dst[n][k] = *(const PG8_LAS bf16x8*)(lds + PG8_SB(b, h) + boff + n * 2048 + k * 1024); } while (0)
; #define PG8_MMA(ai, bj, At, Bt) do { __builtin_amdgcn_s_setprio(1); _Pragma("unroll") for (int m = 0; m < 4; ++m) _Pragma("unroll") for (int n = 0; n < 2; ++n) _Pragma("unroll") for (int k = 0; k < 2; ++k) \
;         acc[ai][bj][m][n] = __builtin_amdgcn_mfma_f32_16x16x32_bf16(Bt[n][k], At[m][k], acc[ai][bj][m][n], 0, 0, 0); __builtin_amdgcn_s_setprio(0); } while (0)
; #define PG8_WAIT_V(n) asm volatile("s_waitcnt vmcnt(" #n ")" ::: "memory")
; #define PG8_WAIT_L(n) asm volatile("s_waitcnt lgkmcnt(" #n ")" ::: "memory")
; #define PG8_BAR __builtin_amdgcn_s_barrier()
; #define PG8_SCHED __builtin_amdgcn_sched_barrier(0)
; template <class Epi, class Sched, bool ALIGN_EPI = false, bool SP2 = false>
; __device__ __forceinline__ void gemm_phase(PG8_LAS unsigned char* lds, const Gemm g, const Sched& S, const Epi& E) {
;     ...
;             PG8_WAIT_V(8); PG8_WAIT_L(0); PG8_BAR; PG8_MMA(0, 0, At, B0); PG8_MMA(0, 1, At, B1); PG8_BAR; PG8_SCHED;
;             PG8_LDA(At, 0, 1); PG8_STAGE(PG8_SB(0, 0), b2, voffB); PG8_STAGE(PG8_SB(0, 1), b2 + hstep, voffB); PG8_STAGE(PG8_SA(0, 0), a2, voffA);
;             PG8_WAIT_V(8); PG8_WAIT_L(0); PG8_BAR; PG8_MMA(1, 0, At, B0); PG8_MMA(1, 1, At, B1); PG8_BAR; PG8_SCHED;
;             PG8_LDB(B0, 1, 0); PG8_LDB(B1, 1, 1); PG8_SCHED; PG8_LDA(At, 1, 0); PG8_STAGE(PG8_SA(0, 1), a2 + hstep, voffA);
;             PG8_WAIT_V(8); PG8_WAIT_L(0); PG8_BAR; PG8_MMA(0, 0, At, B0); PG8_MMA(0, 1, At, B1); PG8_BAR; PG8_SCHED;
	s_add_i32 s38, s39, s23
	v_lshl_add_u64 v[138:139], s[64:65], 0, v[176:177]
	s_mov_b32 m0, s38
	ds_read_b128 v[182:185], v143 offset:16384
	ds_read_b128 v[186:189], v143 offset:17408
	ds_read_b128 v[190:193], v143 offset:18432
	ds_read_b128 v[194:197], v143 offset:19456
	ds_read_b128 v[198:201], v143 offset:20480
	ds_read_b128 v[202:205], v143 offset:21504
	ds_read_b128 v[206:209], v143 offset:22528
	ds_read_b128 v[210:213], v143 offset:23552
	global_load_lds_dwordx4 v[138:139], off
	s_add_i32 m0, s38, 0x2000
	s_add_u32 s38, s64, 0x40000
	v_lshl_add_u64 v[214:215], s[64:65], 0, v[128:129]
	s_addc_u32 s39, s65, 0
	s_add_i32 s28, s28, s23
	global_load_lds_dwordx4 v[214:215], off
	v_lshl_add_u64 v[216:217], s[38:39], 0, v[176:177]
	s_mov_b32 m0, s28
	v_lshl_add_u64 v[218:219], s[66:67], 0, v[130:131]
	global_load_lds_dwordx4 v[216:217], off
	v_lshl_add_u64 v[216:217], s[38:39], 0, v[128:129]
	s_add_i32 m0, s28, 0x2000
	s_nop 0
	global_load_lds_dwordx4 v[216:217], off
	v_lshl_add_u64 v[216:217], s[66:67], 0, v[132:133]
	s_mov_b32 m0, s30
	s_nop 0
	global_load_lds_dwordx4 v[216:217], off
	s_mov_b32 m0, s31
	s_nop 0
	global_load_lds_dwordx4 v[218:219], off
	s_waitcnt vmcnt(8)
	s_waitcnt lgkmcnt(0)
	s_barrier
	s_setprio 1
	s_waitcnt lgkmcnt(0)
	v_mfma_f32_16x16x32_bf16 v[60:63], v[144:147], v[182:185], v[60:63]
	v_mfma_f32_16x16x32_bf16 v[56:59], v[152:155], v[182:185], v[56:59]
	v_mfma_f32_16x16x32_bf16 v[44:47], v[144:147], v[190:193], v[44:47]
	v_mfma_f32_16x16x32_bf16 v[40:43], v[152:155], v[190:193], v[40:43]
	v_mfma_f32_16x16x32_bf16 v[28:31], v[144:147], v[198:201], v[28:31]
	v_mfma_f32_16x16x32_bf16 v[24:27], v[152:155], v[198:201], v[24:27]
	v_mfma_f32_16x16x32_bf16 v[12:15], v[144:147], v[206:209], v[12:15]
	v_mfma_f32_16x16x32_bf16 v[8:11], v[152:155], v[206:209], v[8:11]
	v_mfma_f32_16x16x32_bf16 v[60:63], v[148:151], v[186:189], v[60:63]
	v_mfma_f32_16x16x32_bf16 v[56:59], v[156:159], v[186:189], v[56:59]
	v_mfma_f32_16x16x32_bf16 v[44:47], v[148:151], v[194:197], v[44:47]
	v_mfma_f32_16x16x32_bf16 v[40:43], v[156:159], v[194:197], v[40:43]
	v_mfma_f32_16x16x32_bf16 v[28:31], v[148:151], v[202:205], v[28:31]
	v_mfma_f32_16x16x32_bf16 v[24:27], v[156:159], v[202:205], v[24:27]
	v_mfma_f32_16x16x32_bf16 v[12:15], v[148:151], v[210:213], v[12:15]
	v_mfma_f32_16x16x32_bf16 v[8:11], v[156:159], v[210:213], v[8:11]
	s_setprio 0
	s_setprio 1
	v_mfma_f32_16x16x32_bf16 v[52:55], v[160:163], v[182:185], v[52:55]
	v_mfma_f32_16x16x32_bf16 v[48:51], v[168:171], v[182:185], v[48:51]
	v_mfma_f32_16x16x32_bf16 v[36:39], v[160:163], v[190:193], v[36:39]
	v_mfma_f32_16x16x32_bf16 v[32:35], v[168:171], v[190:193], v[32:35]
	v_mfma_f32_16x16x32_bf16 v[20:23], v[160:163], v[198:201], v[20:23]
	v_mfma_f32_16x16x32_bf16 v[16:19], v[168:171], v[198:201], v[16:19]
	v_mfma_f32_16x16x32_bf16 v[4:7], v[160:163], v[206:209], v[4:7]
	v_mfma_f32_16x16x32_bf16 v[0:3], v[168:171], v[206:209], v[0:3]
	v_mfma_f32_16x16x32_bf16 v[52:55], v[164:167], v[186:189], v[52:55]
	v_mfma_f32_16x16x32_bf16 v[48:51], v[172:175], v[186:189], v[48:51]
	v_mfma_f32_16x16x32_bf16 v[36:39], v[164:167], v[194:197], v[36:39]
	v_mfma_f32_16x16x32_bf16 v[32:35], v[172:175], v[194:197], v[32:35]
	v_mfma_f32_16x16x32_bf16 v[20:23], v[164:167], v[202:205], v[20:23]
	v_mfma_f32_16x16x32_bf16 v[16:19], v[172:175], v[202:205], v[16:19]
	v_mfma_f32_16x16x32_bf16 v[4:7], v[164:167], v[210:213], v[4:7]
	v_mfma_f32_16x16x32_bf16 v[0:3], v[172:175], v[210:213], v[0:3]
	s_setprio 0
	s_barrier
	s_add_i32 s28, 0, 0x18000
	s_add_i32 s48, 0, 0x1c000
	v_add_u32_e32 v156, s28, v142
	v_add_u32_e32 v172, s48, v142
	ds_read_b128 v[144:147], v156
	ds_read_b128 v[148:151], v156 offset:1024
	ds_read_b128 v[152:155], v156 offset:2048
	ds_read_b128 v[156:159], v156 offset:3072
	ds_read_b128 v[160:163], v172
	ds_read_b128 v[164:167], v172 offset:1024
	ds_read_b128 v[168:171], v172 offset:2048
	ds_read_b128 v[172:175], v172 offset:3072
	s_add_u32 s38, s66, 0x40000
	s_addc_u32 s39, s67, 0
	s_mov_b32 m0, s63
	v_lshl_add_u64 v[220:221], s[38:39], 0, v[132:133]
	ds_read_b128 v[182:185], v143 offset:32768
	ds_read_b128 v[186:189], v143 offset:33792
	ds_read_b128 v[190:193], v143 offset:34816
	ds_read_b128 v[194:197], v143 offset:35840
	ds_read_b128 v[198:201], v143 offset:36864
	ds_read_b128 v[202:205], v143 offset:37888
	ds_read_b128 v[206:209], v143 offset:38912
	ds_read_b128 v[210:213], v143 offset:39936
	global_load_lds_dwordx4 v[220:221], off
	v_lshl_add_u64 v[220:221], s[38:39], 0, v[130:131]
	s_mov_b32 m0, s69
	s_nop 0
	global_load_lds_dwordx4 v[220:221], off
	s_waitcnt vmcnt(8)
	s_waitcnt lgkmcnt(0)
	s_barrier
; #define PG8_STAGE(bufoff, gbase, voff) do { _Pragma("unroll") for (int _i = 0; _i < 2; ++_i) \
;         __builtin_amdgcn_global_load_lds((const unsigned*)((const char*)(gbase) + (voff)[_i]), (PG8_LAS unsigned*)(lds + (bufoff) + ldsw + _i * 8192), 16, 0, 0); } while (0)
; #define PG8_LDA(dst, b, h) do { _Pragma("unroll") for (int m = 0; m < 4; ++m) _Pragma("unroll") for (int k = 0; k < 2; ++k) dst[m][k] = *(const PG8_LAS bf16x8*)(lds + PG8_SA(b, h) + aoff + m * 2048 + k * 1024); } while (0)
; #define PG8_MMA(ai, bj, At, Bt) do { __builtin_amdgcn_s_setprio(1); _Pragma("unroll") for (int m = 0; m < 4; ++m) _Pragma("unroll") for (int n = 0; n < 2; ++n) _Pragma("unroll") for (int k = 0; k < 2; ++k) \
;         acc[ai][bj][m][n] = __builtin_amdgcn_mfma_f32_16x16x32_bf16(Bt[n][k], At[m][k], acc[ai][bj][m][n], 0, 0, 0); __builtin_amdgcn_s_setprio(0); } while (0)
; #define PG8_WAIT_V(n) asm volatile("s_waitcnt vmcnt(" #n ")" ::: "memory")
; #define PG8_WAIT_L(n) asm volatile("s_waitcnt lgkmcnt(" #n ")" ::: "memory")
; #define PG8_BAR __builtin_amdgcn_s_barrier()
; #define PG8_SCHED __builtin_amdgcn_sched_barrier(0)
; template <class Epi, class Sched, bool ALIGN_EPI = false, bool SP2 = false>
; __device__ __forceinline__ void gemm_phase(PG8_LAS unsigned char* lds, const Gemm g, const Sched& S, const Epi& E) {
;     ...
;         for (int t = 0; t < nt; t += 2) {
;     ...
;             PG8_WAIT_V(8); PG8_WAIT_L(0); PG8_BAR; PG8_MMA(0, 0, At, B0); PG8_MMA(0, 1, At, B1); PG8_BAR; PG8_SCHED;
;             PG8_LDA(At, 1, 1); PG8_STAGE(PG8_SB(1, 0), b3, voffB); PG8_STAGE(PG8_SB(1, 1), b3 + hstep, voffB); PG8_STAGE(PG8_SA(1, 0), a3, voffA);
;             PG8_WAIT_V(8); PG8_WAIT_L(0); PG8_BAR; PG8_MMA(1, 0, At, B0); PG8_MMA(1, 1, At, B1); PG8_BAR; PG8_SCHED;
	s_setprio 1
	s_waitcnt lgkmcnt(0)
	v_mfma_f32_16x16x32_bf16 v[124:127], v[144:147], v[182:185], v[124:127]
	v_mfma_f32_16x16x32_bf16 v[120:123], v[152:155], v[182:185], v[120:123]
	v_mfma_f32_16x16x32_bf16 v[108:111], v[144:147], v[190:193], v[108:111]
	v_mfma_f32_16x16x32_bf16 v[104:107], v[152:155], v[190:193], v[104:107]
	v_mfma_f32_16x16x32_bf16 v[92:95], v[144:147], v[198:201], v[92:95]
	v_mfma_f32_16x16x32_bf16 v[88:91], v[152:155], v[198:201], v[88:91]
	v_mfma_f32_16x16x32_bf16 v[76:79], v[144:147], v[206:209], v[76:79]
	v_mfma_f32_16x16x32_bf16 v[72:75], v[152:155], v[206:209], v[72:75]
	v_mfma_f32_16x16x32_bf16 v[124:127], v[148:151], v[186:189], v[124:127]
	v_mfma_f32_16x16x32_bf16 v[120:123], v[156:159], v[186:189], v[120:123]
	v_mfma_f32_16x16x32_bf16 v[108:111], v[148:151], v[194:197], v[108:111]
	v_mfma_f32_16x16x32_bf16 v[104:107], v[156:159], v[194:197], v[104:107]
	v_mfma_f32_16x16x32_bf16 v[92:95], v[148:151], v[202:205], v[92:95]
	v_mfma_f32_16x16x32_bf16 v[88:91], v[156:159], v[202:205], v[88:91]
	v_mfma_f32_16x16x32_bf16 v[76:79], v[148:151], v[210:213], v[76:79]
	v_mfma_f32_16x16x32_bf16 v[72:75], v[156:159], v[210:213], v[72:75]
	s_setprio 0
	s_setprio 1
	v_mfma_f32_16x16x32_bf16 v[116:119], v[160:163], v[182:185], v[116:119]
	v_mfma_f32_16x16x32_bf16 v[112:115], v[168:171], v[182:185], v[112:115]
	v_mfma_f32_16x16x32_bf16 v[100:103], v[160:163], v[190:193], v[100:103]
	v_mfma_f32_16x16x32_bf16 v[96:99], v[168:171], v[190:193], v[96:99]
	v_mfma_f32_16x16x32_bf16 v[84:87], v[160:163], v[198:201], v[84:87]
	v_mfma_f32_16x16x32_bf16 v[80:83], v[168:171], v[198:201], v[80:83]
	v_mfma_f32_16x16x32_bf16 v[68:71], v[160:163], v[206:209], v[68:71]
	v_mfma_f32_16x16x32_bf16 v[64:67], v[168:171], v[206:209], v[64:67]
	v_mfma_f32_16x16x32_bf16 v[116:119], v[164:167], v[186:189], v[116:119]
	v_mfma_f32_16x16x32_bf16 v[112:115], v[172:175], v[186:189], v[112:115]
	v_mfma_f32_16x16x32_bf16 v[100:103], v[164:167], v[194:197], v[100:103]
	v_mfma_f32_16x16x32_bf16 v[96:99], v[172:175], v[194:197], v[96:99]
	v_mfma_f32_16x16x32_bf16 v[84:87], v[164:167], v[202:205], v[84:87]
	v_mfma_f32_16x16x32_bf16 v[80:83], v[172:175], v[202:205], v[80:83]
	v_mfma_f32_16x16x32_bf16 v[68:71], v[164:167], v[210:213], v[68:71]
	v_mfma_f32_16x16x32_bf16 v[64:67], v[172:175], v[210:213], v[64:67]
	s_setprio 0
	s_barrier
	s_add_i32 s28, s28, s23
	v_lshl_add_u64 v[138:139], v[138:139], 0, s[44:45]
	s_mov_b32 m0, s28
	ds_read_b128 v[182:185], v143 offset:49152
	ds_read_b128 v[186:189], v143 offset:50176
	ds_read_b128 v[190:193], v143 offset:51200
	ds_read_b128 v[194:197], v143 offset:52224
	ds_read_b128 v[198:201], v143 offset:53248
	ds_read_b128 v[202:205], v143 offset:54272
	ds_read_b128 v[206:209], v143 offset:55296
	ds_read_b128 v[210:213], v143 offset:56320
	global_load_lds_dwordx4 v[138:139], off
	s_add_i32 m0, s28, 0x2000
	s_add_u32 s38, s64, 0x40080
	v_lshl_add_u64 v[138:139], v[214:215], 0, s[44:45]
	s_addc_u32 s39, s65, 0
	s_add_i32 s28, s48, s23
	global_load_lds_dwordx4 v[138:139], off
	v_lshl_add_u64 v[138:139], s[38:39], 0, v[176:177]
	s_mov_b32 m0, s28
	s_nop 0
	global_load_lds_dwordx4 v[138:139], off
	v_lshl_add_u64 v[138:139], s[38:39], 0, v[128:129]
	s_add_i32 m0, s28, 0x2000
	s_nop 0
	global_load_lds_dwordx4 v[138:139], off
	v_lshl_add_u64 v[138:139], v[216:217], 0, s[44:45]
	s_mov_b32 m0, s73
	s_nop 0
	global_load_lds_dwordx4 v[138:139], off
	v_lshl_add_u64 v[138:139], v[218:219], 0, s[44:45]
	s_mov_b32 m0, s74
	s_nop 0
	global_load_lds_dwordx4 v[138:139], off
	s_waitcnt vmcnt(8)
	s_waitcnt lgkmcnt(0)
	s_barrier
	s_setprio 1
	s_waitcnt lgkmcnt(0)
	v_mfma_f32_16x16x32_bf16 v[60:63], v[144:147], v[182:185], v[60:63]
	v_mfma_f32_16x16x32_bf16 v[56:59], v[152:155], v[182:185], v[56:59]
	v_mfma_f32_16x16x32_bf16 v[44:47], v[144:147], v[190:193], v[44:47]
	v_mfma_f32_16x16x32_bf16 v[40:43], v[152:155], v[190:193], v[40:43]
	v_mfma_f32_16x16x32_bf16 v[28:31], v[144:147], v[198:201], v[28:31]
	v_mfma_f32_16x16x32_bf16 v[24:27], v[152:155], v[198:201], v[24:27]
	v_mfma_f32_16x16x32_bf16 v[12:15], v[144:147], v[206:209], v[12:15]
	v_mfma_f32_16x16x32_bf16 v[8:11], v[152:155], v[206:209], v[8:11]
	v_mfma_f32_16x16x32_bf16 v[60:63], v[148:151], v[186:189], v[60:63]
	v_mfma_f32_16x16x32_bf16 v[56:59], v[156:159], v[186:189], v[56:59]
	v_mfma_f32_16x16x32_bf16 v[44:47], v[148:151], v[194:197], v[44:47]
	v_mfma_f32_16x16x32_bf16 v[40:43], v[156:159], v[194:197], v[40:43]
	v_mfma_f32_16x16x32_bf16 v[28:31], v[148:151], v[202:205], v[28:31]
	v_mfma_f32_16x16x32_bf16 v[24:27], v[156:159], v[202:205], v[24:27]
	v_mfma_f32_16x16x32_bf16 v[12:15], v[148:151], v[210:213], v[12:15]
	v_mfma_f32_16x16x32_bf16 v[8:11], v[156:159], v[210:213], v[8:11]
	s_setprio 0
	s_setprio 1
	v_mfma_f32_16x16x32_bf16 v[52:55], v[160:163], v[182:185], v[52:55]
	v_mfma_f32_16x16x32_bf16 v[48:51], v[168:171], v[182:185], v[48:51]
	v_mfma_f32_16x16x32_bf16 v[36:39], v[160:163], v[190:193], v[36:39]
	v_mfma_f32_16x16x32_bf16 v[32:35], v[168:171], v[190:193], v[32:35]
	v_mfma_f32_16x16x32_bf16 v[20:23], v[160:163], v[198:201], v[20:23]
	v_mfma_f32_16x16x32_bf16 v[16:19], v[168:171], v[198:201], v[16:19]
	v_mfma_f32_16x16x32_bf16 v[4:7], v[160:163], v[206:209], v[4:7]
	v_mfma_f32_16x16x32_bf16 v[0:3], v[168:171], v[206:209], v[0:3]
	v_mfma_f32_16x16x32_bf16 v[52:55], v[164:167], v[186:189], v[52:55]
	v_mfma_f32_16x16x32_bf16 v[48:51], v[172:175], v[186:189], v[48:51]
	v_mfma_f32_16x16x32_bf16 v[36:39], v[164:167], v[194:197], v[36:39]
	v_mfma_f32_16x16x32_bf16 v[32:35], v[172:175], v[194:197], v[32:35]
	v_mfma_f32_16x16x32_bf16 v[20:23], v[164:167], v[202:205], v[20:23]
	v_mfma_f32_16x16x32_bf16 v[16:19], v[172:175], v[202:205], v[16:19]
	v_mfma_f32_16x16x32_bf16 v[4:7], v[164:167], v[210:213], v[4:7]
	v_mfma_f32_16x16x32_bf16 v[0:3], v[172:175], v[210:213], v[0:3]
	s_setprio 0
	s_barrier
	s_add_i32 s80, s80, 2
	s_add_u32 vcc_lo, vcc_lo, 0x100
	s_addc_u32 vcc_hi, vcc_hi, 0
	s_add_u32 s78, s78, 0x100
	s_addc_u32 s79, s79, 0
	s_cmp_gt_u32 s80, 13
	s_cbranch_scc0 .LBB0_718
; __device__ __forceinline__ unsigned cvt_pk_bf16(float lo, float hi) { unsigned r; asm volatile("v_cvt_pk_bf16_f32 %0, %1, %2" : "=v"(r) : "v"(lo), "v"(hi)); return r; }
; #define PG8_BAR __builtin_amdgcn_s_barrier()
;     __device__ __forceinline__ void operator()(const f32x4 (&acc)[2][2][4][2], const Unit& u, int wr, int wc, int fr, int fq) const {
;         asm volatile("" : "+v"(fr), "+v"(fq));
;         const int row0 = (REMAP ? u.pn * BM : u.pm * BM) + wr * 64 + fr; const int col0 = (REMAP ? 0 : u.pn * BM) + wc * 32 + 8 * fq;
; #pragma unroll
;         for (int ai = 0; ai < 2; ++ai)
; #pragma unroll
;             for (int m = 0; m < 4; ++m) { bf16_t* rowp = O + (size_t)(row0 + ai * HALF + m * 16) * ldc + col0;
; #pragma unroll
;                 for (int bj = 0; bj < 2; ++bj) { f32x4 v0 = acc[ai][bj][m][0], v1 = acc[ai][bj][m][1];
;                     if (ACT == 1) {
; #pragma unroll
;                         for (int j = 0; j < 4; ++j) { float a = fmaxf(v0[j], 0.f), b = fmaxf(v1[j], 0.f); v0[j] = a * a; v1[j] = b * b; } }
;                     v0 = v0 * scale; v1 = v1 * scale;
;                     u32x4 w; w.x = cvt_pk_bf16(v0[0], v0[1]); w.y = cvt_pk_bf16(v0[2], v0[3]); w.z = cvt_pk_bf16(v1[0], v1[1]); w.w = cvt_pk_bf16(v1[2], v1[3]);
;                     *(u32x4*)(rowp + bj * HALF) = w; } }
; template <class Epi, class Sched, bool ALIGN_EPI = false, bool SP2 = false>
; __device__ __forceinline__ void gemm_phase(PG8_LAS unsigned char* lds, const Gemm g, const Sched& S, const Epi& E) {
;     ...
;         if constexpr (ALIGN_EPI) { if (wr == 0) PG8_BAR; }
.Lg3_post:
	s_and_b64 vcc, exec, s[34:35]
	s_cbranch_vccz .LBB0_721
	s_barrier
.LBB0_721:
	v_mov_b32_e32 v139, v141
	v_mov_b32_e32 v138, v140
	s_lshl_b32 s28, s70, 8
	s_add_i32 s28, s28, s71
	v_add_u32_e32 v138, s28, v138
	s_lshl_b32 s28, s68, 8
	s_or_b32 s28, s28, s72
	v_lshl_add_u32 v144, v139, 3, s28
	v_ashrrev_i32_e32 v139, 31, v138
	v_readlane_b32 s38, v253, 63
	v_lshlrev_b64 v[138:139], 13, v[138:139]
	v_readlane_b32 s39, v254, 0
	v_ashrrev_i32_e32 v145, 31, v144
	s_nop 0
	v_lshl_add_u64 v[138:139], s[38:39], 0, v[138:139]
	v_max_f32_e32 v120, 0, v120
	v_lshl_add_u64 v[138:139], v[144:145], 1, v[138:139]
	v_mul_f32_e32 v144, v120, v120
	v_max_f32_e32 v120, 0, v125
	v_max_f32_e32 v121, 0, v121
	v_max_f32_e32 v122, 0, v122
	v_mul_f32_e32 v125, v121, v121
	v_max_f32_e32 v121, 0, v126
	v_mul_f32_e32 v126, v122, v122
	v_max_f32_e32 v122, 0, v127
	v_max_f32_e32 v124, 0, v124
	v_mul_f32_e32 v120, v120, v120
	v_max_f32_e32 v123, 0, v123
	v_mul_f32_e32 v124, v124, v124
	v_mul_f32_e32 v121, v121, v121
	v_mul_f32_e32 v122, v122, v122
	v_mul_f32_e32 v123, v123, v123
	v_cvt_pk_bf16_f32 v120, v124, v120
	v_max_f32_e32 v112, 0, v112
	v_max_f32_e32 v113, 0, v113
	v_max_f32_e32 v114, 0, v114
	v_cvt_pk_bf16_f32 v121, v121, v122
	v_cvt_pk_bf16_f32 v122, v144, v125
	v_cvt_pk_bf16_f32 v123, v126, v123
	global_store_dwordx4 v[138:139], v[120:123], off
	s_nop 1
	v_mul_f32_e32 v120, v112, v112
	v_max_f32_e32 v112, 0, v117
	v_mul_f32_e32 v117, v113, v113
	v_max_f32_e32 v113, 0, v118
	v_mul_f32_e32 v118, v114, v114
	v_max_f32_e32 v114, 0, v119
	v_max_f32_e32 v116, 0, v116
	v_mul_f32_e32 v112, v112, v112
	v_mul_f32_e32 v113, v113, v113
	v_max_f32_e32 v115, 0, v115
	v_mul_f32_e32 v114, v114, v114
	v_mul_f32_e32 v116, v116, v116
	v_mul_f32_e32 v115, v115, v115
	v_cvt_pk_bf16_f32 v112, v116, v112
	v_cvt_pk_bf16_f32 v113, v113, v114
	v_cvt_pk_bf16_f32 v114, v120, v117
	v_max_f32_e32 v104, 0, v104
	v_cvt_pk_bf16_f32 v115, v118, v115
	global_store_dwordx4 v[138:139], v[112:115], off offset:256
	v_max_f32_e32 v105, 0, v105
	s_nop 0
	v_mul_f32_e32 v114, v104, v104
	v_max_f32_e32 v104, 0, v109
	v_max_f32_e32 v106, 0, v106
	v_max_f32_e32 v108, 0, v108
	v_mul_f32_e32 v109, v105, v105
	v_max_f32_e32 v105, 0, v110
	v_mul_f32_e32 v110, v106, v106
	v_max_f32_e32 v106, 0, v111
	v_mul_f32_e32 v108, v108, v108
	v_mul_f32_e32 v104, v104, v104
	v_mul_f32_e32 v105, v105, v105
	v_max_f32_e32 v107, 0, v107
	v_mul_f32_e32 v106, v106, v106
	v_cvt_pk_bf16_f32 v104, v108, v104
	v_add_co_u32_e32 v108, vcc, s49, v138
	v_mul_f32_e32 v107, v107, v107
	v_cvt_pk_bf16_f32 v105, v105, v106
	v_cvt_pk_bf16_f32 v106, v114, v109
	v_addc_co_u32_e32 v109, vcc, 0, v139, vcc
	v_max_f32_e32 v96, 0, v96
	v_max_f32_e32 v97, 0, v97
	v_max_f32_e32 v98, 0, v98
	v_cvt_pk_bf16_f32 v107, v110, v107
	global_store_dwordx4 v[108:109], v[104:107], off
	s_nop 1
	v_mul_f32_e32 v104, v96, v96
	v_max_f32_e32 v96, 0, v101
	v_mul_f32_e32 v101, v97, v97
	v_max_f32_e32 v97, 0, v102
	v_mul_f32_e32 v102, v98, v98
	v_max_f32_e32 v98, 0, v103
	s_mov_b64 s[38:39], 0x20000
	v_max_f32_e32 v100, 0, v100
	v_mul_f32_e32 v96, v96, v96
	v_mul_f32_e32 v97, v97, v97
	v_max_f32_e32 v99, 0, v99
	v_mul_f32_e32 v98, v98, v98
	v_lshl_add_u64 v[112:113], v[138:139], 0, s[38:39]
	v_mul_f32_e32 v100, v100, v100
	v_mul_f32_e32 v99, v99, v99
	v_cvt_pk_bf16_f32 v96, v100, v96
	v_cvt_pk_bf16_f32 v97, v97, v98
	v_cvt_pk_bf16_f32 v98, v104, v101
	v_max_f32_e32 v88, 0, v88
	v_cvt_pk_bf16_f32 v99, v102, v99
	global_store_dwordx4 v[112:113], v[96:99], off offset:256
	v_max_f32_e32 v89, 0, v89
	s_nop 0
	v_mul_f32_e32 v98, v88, v88
	v_max_f32_e32 v88, 0, v93
	v_max_f32_e32 v90, 0, v90
	v_max_f32_e32 v92, 0, v92
	v_mul_f32_e32 v93, v89, v89
	v_max_f32_e32 v89, 0, v94
	v_mul_f32_e32 v94, v90, v90
	v_max_f32_e32 v90, 0, v95
	v_mul_f32_e32 v92, v92, v92
	v_mul_f32_e32 v88, v88, v88
	s_mov_b32 s28, 0x40000
	v_mul_f32_e32 v89, v89, v89
	v_max_f32_e32 v91, 0, v91
	v_mul_f32_e32 v90, v90, v90
	v_cvt_pk_bf16_f32 v88, v92, v88
	v_add_co_u32_e32 v92, vcc, s28, v138
	v_mul_f32_e32 v91, v91, v91
	v_cvt_pk_bf16_f32 v89, v89, v90
	v_cvt_pk_bf16_f32 v90, v98, v93
	v_addc_co_u32_e32 v93, vcc, 0, v139, vcc
	v_max_f32_e32 v80, 0, v80
	v_max_f32_e32 v81, 0, v81
	v_max_f32_e32 v82, 0, v82
	v_cvt_pk_bf16_f32 v91, v94, v91
	global_store_dwordx4 v[92:93], v[88:91], off
	s_nop 1
	v_mul_f32_e32 v88, v80, v80
	v_max_f32_e32 v80, 0, v85
	v_mul_f32_e32 v85, v81, v81
	v_max_f32_e32 v81, 0, v86
	v_mul_f32_e32 v86, v82, v82
	v_max_f32_e32 v82, 0, v87
	s_mov_b64 s[38:39], 0x40000
	v_max_f32_e32 v84, 0, v84
	v_mul_f32_e32 v80, v80, v80
	v_mul_f32_e32 v81, v81, v81
	v_max_f32_e32 v83, 0, v83
	v_mul_f32_e32 v82, v82, v82
	v_lshl_add_u64 v[96:97], v[138:139], 0, s[38:39]
	v_mul_f32_e32 v84, v84, v84
	v_mul_f32_e32 v83, v83, v83
	v_cvt_pk_bf16_f32 v80, v84, v80
	v_cvt_pk_bf16_f32 v81, v81, v82
	v_cvt_pk_bf16_f32 v82, v88, v85
	v_max_f32_e32 v72, 0, v72
	v_cvt_pk_bf16_f32 v83, v86, v83
	global_store_dwordx4 v[96:97], v[80:83], off offset:256
	v_max_f32_e32 v73, 0, v73
	s_nop 0
	v_mul_f32_e32 v82, v72, v72
	v_max_f32_e32 v72, 0, v77
	v_max_f32_e32 v74, 0, v74
	v_max_f32_e32 v76, 0, v76
	v_mul_f32_e32 v77, v73, v73
	v_max_f32_e32 v73, 0, v78
	v_mul_f32_e32 v78, v74, v74
	v_max_f32_e32 v74, 0, v79
	v_mul_f32_e32 v76, v76, v76
	v_mul_f32_e32 v72, v72, v72
	s_mov_b32 s28, 0x60000
	v_mul_f32_e32 v73, v73, v73
	v_max_f32_e32 v75, 0, v75
	v_mul_f32_e32 v74, v74, v74
	v_cvt_pk_bf16_f32 v72, v76, v72
	v_add_co_u32_e32 v76, vcc, s28, v138
	v_mul_f32_e32 v75, v75, v75
	v_cvt_pk_bf16_f32 v73, v73, v74
	v_cvt_pk_bf16_f32 v74, v82, v77
	v_addc_co_u32_e32 v77, vcc, 0, v139, vcc
	v_max_f32_e32 v64, 0, v64
; __device__ __forceinline__ unsigned cvt_pk_bf16(float lo, float hi) { unsigned r; asm volatile("v_cvt_pk_bf16_f32 %0, %1, %2" : "=v"(r) : "v"(lo), "v"(hi)); return r; }
;     __device__ __forceinline__ void operator()(const f32x4 (&acc)[2][2][4][2], const Unit& u, int wr, int wc, int fr, int fq) const {
;         asm volatile("" : "+v"(fr), "+v"(fq));
;         const int row0 = (REMAP ? u.pn * BM : u.pm * BM) + wr * 64 + fr; const int col0 = (REMAP ? 0 : u.pn * BM) + wc * 32 + 8 * fq;
; #pragma unroll
;         for (int ai = 0; ai < 2; ++ai)
; #pragma unroll
;             for (int m = 0; m < 4; ++m) { bf16_t* rowp = O + (size_t)(row0 + ai * HALF + m * 16) * ldc + col0;
; #pragma unroll
;                 for (int bj = 0; bj < 2; ++bj) { f32x4 v0 = acc[ai][bj][m][0], v1 = acc[ai][bj][m][1];
;                     if (ACT == 1) {
; #pragma unroll
;                         for (int j = 0; j < 4; ++j) { float a = fmaxf(v0[j], 0.f), b = fmaxf(v1[j], 0.f); v0[j] = a * a; v1[j] = b * b; } }
;                     v0 = v0 * scale; v1 = v1 * scale;
;                     u32x4 w; w.x = cvt_pk_bf16(v0[0], v0[1]); w.y = cvt_pk_bf16(v0[2], v0[3]); w.z = cvt_pk_bf16(v1[0], v1[1]); w.w = cvt_pk_bf16(v1[2], v1[3]);
;                     *(u32x4*)(rowp + bj * HALF) = w; } }
	v_max_f32_e32 v65, 0, v65
	v_max_f32_e32 v66, 0, v66
	v_cvt_pk_bf16_f32 v75, v78, v75
	global_store_dwordx4 v[76:77], v[72:75], off
	s_nop 1
	v_mul_f32_e32 v72, v64, v64
	v_max_f32_e32 v64, 0, v69
	v_mul_f32_e32 v69, v65, v65
	v_max_f32_e32 v65, 0, v70
	v_mul_f32_e32 v70, v66, v66
	v_max_f32_e32 v66, 0, v71
	s_mov_b64 s[38:39], 0x60000
	v_max_f32_e32 v68, 0, v68
	v_mul_f32_e32 v64, v64, v64
	v_mul_f32_e32 v65, v65, v65
	v_max_f32_e32 v67, 0, v67
	v_mul_f32_e32 v66, v66, v66
	v_lshl_add_u64 v[80:81], v[138:139], 0, s[38:39]
	v_mul_f32_e32 v68, v68, v68
	v_mul_f32_e32 v67, v67, v67
	v_cvt_pk_bf16_f32 v64, v68, v64
	v_cvt_pk_bf16_f32 v65, v65, v66
	v_cvt_pk_bf16_f32 v66, v72, v69
	v_max_f32_e32 v56, 0, v56
	v_cvt_pk_bf16_f32 v67, v70, v67
	global_store_dwordx4 v[80:81], v[64:67], off offset:256
	v_max_f32_e32 v57, 0, v57
	s_nop 0
	v_mul_f32_e32 v66, v56, v56
	v_max_f32_e32 v56, 0, v61
	v_max_f32_e32 v58, 0, v58
	v_max_f32_e32 v60, 0, v60
	v_mul_f32_e32 v61, v57, v57
	v_max_f32_e32 v57, 0, v62
	v_mul_f32_e32 v62, v58, v58
	v_max_f32_e32 v58, 0, v63
	v_mul_f32_e32 v60, v60, v60
	v_mul_f32_e32 v56, v56, v56
	s_mov_b32 s28, 0x100000
	v_mul_f32_e32 v57, v57, v57
	v_max_f32_e32 v59, 0, v59
	v_mul_f32_e32 v58, v58, v58
	v_cvt_pk_bf16_f32 v56, v60, v56
	v_add_co_u32_e32 v60, vcc, s28, v138
	v_mul_f32_e32 v59, v59, v59
	v_cvt_pk_bf16_f32 v57, v57, v58
	v_cvt_pk_bf16_f32 v58, v66, v61
	v_addc_co_u32_e32 v61, vcc, 0, v139, vcc
	v_max_f32_e32 v48, 0, v48
	v_max_f32_e32 v49, 0, v49
	v_max_f32_e32 v50, 0, v50
	v_cvt_pk_bf16_f32 v59, v62, v59
	global_store_dwordx4 v[60:61], v[56:59], off
	s_nop 1
	v_mul_f32_e32 v56, v48, v48
	v_max_f32_e32 v48, 0, v53
	v_mul_f32_e32 v53, v49, v49
	v_max_f32_e32 v49, 0, v54
	v_mul_f32_e32 v54, v50, v50
	v_max_f32_e32 v50, 0, v55
	s_mov_b64 s[38:39], 0x100000
	v_max_f32_e32 v52, 0, v52
	v_mul_f32_e32 v48, v48, v48
	v_mul_f32_e32 v49, v49, v49
	v_max_f32_e32 v51, 0, v51
	v_mul_f32_e32 v50, v50, v50
	v_lshl_add_u64 v[64:65], v[138:139], 0, s[38:39]
	v_mul_f32_e32 v52, v52, v52
	v_mul_f32_e32 v51, v51, v51
	v_cvt_pk_bf16_f32 v48, v52, v48
	v_cvt_pk_bf16_f32 v49, v49, v50
	v_cvt_pk_bf16_f32 v50, v56, v53
	v_max_f32_e32 v40, 0, v40
	v_cvt_pk_bf16_f32 v51, v54, v51
	global_store_dwordx4 v[64:65], v[48:51], off offset:256
	v_max_f32_e32 v41, 0, v41
	s_nop 0
	v_mul_f32_e32 v50, v40, v40
	v_max_f32_e32 v40, 0, v45
	v_max_f32_e32 v42, 0, v42
	v_max_f32_e32 v44, 0, v44
	v_mul_f32_e32 v45, v41, v41
	v_max_f32_e32 v41, 0, v46
	v_mul_f32_e32 v46, v42, v42
	v_max_f32_e32 v42, 0, v47
	v_mul_f32_e32 v44, v44, v44
	v_mul_f32_e32 v40, v40, v40
	s_mov_b32 s28, 0x120000
	v_mul_f32_e32 v41, v41, v41
	v_max_f32_e32 v43, 0, v43
	v_mul_f32_e32 v42, v42, v42
	v_cvt_pk_bf16_f32 v40, v44, v40
	v_add_co_u32_e32 v44, vcc, s28, v138
	v_mul_f32_e32 v43, v43, v43
	v_cvt_pk_bf16_f32 v41, v41, v42
	v_cvt_pk_bf16_f32 v42, v50, v45
	v_addc_co_u32_e32 v45, vcc, 0, v139, vcc
	v_max_f32_e32 v32, 0, v32
	v_max_f32_e32 v33, 0, v33
	v_max_f32_e32 v34, 0, v34
	v_cvt_pk_bf16_f32 v43, v46, v43
	global_store_dwordx4 v[44:45], v[40:43], off
	s_nop 1
	v_mul_f32_e32 v40, v32, v32
	v_max_f32_e32 v32, 0, v37
	v_mul_f32_e32 v37, v33, v33
	v_max_f32_e32 v33, 0, v38
	v_mul_f32_e32 v38, v34, v34
	v_max_f32_e32 v34, 0, v39
	s_mov_b64 s[38:39], 0x120000
	v_max_f32_e32 v36, 0, v36
	v_mul_f32_e32 v32, v32, v32
	v_mul_f32_e32 v33, v33, v33
	v_max_f32_e32 v35, 0, v35
	v_mul_f32_e32 v34, v34, v34
	v_lshl_add_u64 v[48:49], v[138:139], 0, s[38:39]
	v_mul_f32_e32 v36, v36, v36
	v_mul_f32_e32 v35, v35, v35
	v_cvt_pk_bf16_f32 v32, v36, v32
	v_cvt_pk_bf16_f32 v33, v33, v34
	v_cvt_pk_bf16_f32 v34, v40, v37
	v_max_f32_e32 v24, 0, v24
	v_cvt_pk_bf16_f32 v35, v38, v35
	global_store_dwordx4 v[48:49], v[32:35], off offset:256
	v_max_f32_e32 v25, 0, v25
	s_nop 0
	v_mul_f32_e32 v34, v24, v24
	v_max_f32_e32 v24, 0, v29
	v_max_f32_e32 v26, 0, v26
	v_max_f32_e32 v28, 0, v28
	v_mul_f32_e32 v29, v25, v25
	v_max_f32_e32 v25, 0, v30
	v_mul_f32_e32 v30, v26, v26
	v_max_f32_e32 v26, 0, v31
	v_mul_f32_e32 v28, v28, v28
	v_mul_f32_e32 v24, v24, v24
	s_mov_b32 s28, 0x140000
	v_mul_f32_e32 v25, v25, v25
	v_max_f32_e32 v27, 0, v27
	v_mul_f32_e32 v26, v26, v26
	v_cvt_pk_bf16_f32 v24, v28, v24
	v_add_co_u32_e32 v28, vcc, s28, v138
	v_mul_f32_e32 v27, v27, v27
	v_cvt_pk_bf16_f32 v25, v25, v26
	v_cvt_pk_bf16_f32 v26, v34, v29
	v_addc_co_u32_e32 v29, vcc, 0, v139, vcc
	v_max_f32_e32 v16, 0, v16
	v_max_f32_e32 v17, 0, v17
	v_max_f32_e32 v18, 0, v18
	v_cvt_pk_bf16_f32 v27, v30, v27
	global_store_dwordx4 v[28:29], v[24:27], off
	s_nop 1
	v_mul_f32_e32 v24, v16, v16
	v_max_f32_e32 v16, 0, v21
	v_mul_f32_e32 v21, v17, v17
	v_max_f32_e32 v17, 0, v22
	v_mul_f32_e32 v22, v18, v18
	v_max_f32_e32 v18, 0, v23
	s_mov_b64 s[38:39], 0x140000
	v_max_f32_e32 v20, 0, v20
	v_mul_f32_e32 v16, v16, v16
	v_mul_f32_e32 v17, v17, v17
	v_max_f32_e32 v19, 0, v19
	v_mul_f32_e32 v18, v18, v18
	v_lshl_add_u64 v[32:33], v[138:139], 0, s[38:39]
	v_mul_f32_e32 v20, v20, v20
	v_mul_f32_e32 v19, v19, v19
	v_cvt_pk_bf16_f32 v16, v20, v16
	v_cvt_pk_bf16_f32 v17, v17, v18
	v_cvt_pk_bf16_f32 v18, v24, v21
	v_max_f32_e32 v8, 0, v8
	v_cvt_pk_bf16_f32 v19, v22, v19
	global_store_dwordx4 v[32:33], v[16:19], off offset:256
	v_max_f32_e32 v9, 0, v9
	s_nop 0
	v_mul_f32_e32 v18, v8, v8
	v_max_f32_e32 v8, 0, v13
	v_max_f32_e32 v10, 0, v10
	v_max_f32_e32 v12, 0, v12
	v_mul_f32_e32 v13, v9, v9
	v_max_f32_e32 v9, 0, v14
	v_mul_f32_e32 v14, v10, v10
	v_max_f32_e32 v10, 0, v15
	v_mul_f32_e32 v12, v12, v12
	v_mul_f32_e32 v8, v8, v8
	s_mov_b32 s28, 0x160000
	v_mul_f32_e32 v9, v9, v9
	v_max_f32_e32 v11, 0, v11
	v_mul_f32_e32 v10, v10, v10
	v_cvt_pk_bf16_f32 v8, v12, v8
; __device__ __forceinline__ unsigned cvt_pk_bf16(float lo, float hi) { unsigned r; asm volatile("v_cvt_pk_bf16_f32 %0, %1, %2" : "=v"(r) : "v"(lo), "v"(hi)); return r; }
; #define PG8_STAGE(bufoff, gbase, voff) do { _Pragma("unroll") for (int _i = 0; _i < 2; ++_i) \
;         __builtin_amdgcn_global_load_lds((const unsigned*)((const char*)(gbase) + (voff)[_i]), (PG8_LAS unsigned*)(lds + (bufoff) + ldsw + _i * 8192), 16, 0, 0); } while (0)
; #define PG8_LDA(dst, b, h) do { _Pragma("unroll") for (int m = 0; m < 4; ++m) _Pragma("unroll") for (int k = 0; k < 2; ++k) dst[m][k] = *(const PG8_LAS bf16x8*)(lds + PG8_SA(b, h) + aoff + m * 2048 + k * 1024); } while (0)
; #define PG8_WAIT_V(n) asm volatile("s_waitcnt vmcnt(" #n ")" ::: "memory")
; #define PG8_BAR __builtin_amdgcn_s_barrier()
;     __device__ __forceinline__ void operator()(const f32x4 (&acc)[2][2][4][2], const Unit& u, int wr, int wc, int fr, int fq) const {
;         asm volatile("" : "+v"(fr), "+v"(fq));
;         const int row0 = (REMAP ? u.pn * BM : u.pm * BM) + wr * 64 + fr; const int col0 = (REMAP ? 0 : u.pn * BM) + wc * 32 + 8 * fq;
; #pragma unroll
;         for (int ai = 0; ai < 2; ++ai)
; #pragma unroll
;             for (int m = 0; m < 4; ++m) { bf16_t* rowp = O + (size_t)(row0 + ai * HALF + m * 16) * ldc + col0;
; #pragma unroll
;                 for (int bj = 0; bj < 2; ++bj) { f32x4 v0 = acc[ai][bj][m][0], v1 = acc[ai][bj][m][1];
;                     if (ACT == 1) {
; #pragma unroll
;                         for (int j = 0; j < 4; ++j) { float a = fmaxf(v0[j], 0.f), b = fmaxf(v1[j], 0.f); v0[j] = a * a; v1[j] = b * b; } }
;                     v0 = v0 * scale; v1 = v1 * scale;
;                     u32x4 w; w.x = cvt_pk_bf16(v0[0], v0[1]); w.y = cvt_pk_bf16(v0[2], v0[3]); w.z = cvt_pk_bf16(v1[0], v1[1]); w.w = cvt_pk_bf16(v1[2], v1[3]);
;                     *(u32x4*)(rowp + bj * HALF) = w; } }
; template <class Epi, class Sched, bool ALIGN_EPI = false, bool SP2 = false>
; __device__ __forceinline__ void gemm_phase(PG8_LAS unsigned char* lds, const Gemm g, const Sched& S, const Epi& E) {
;     ...
;             if constexpr (SP2) {
;             PG8_LDB(B0, 0, 0); PG8_LDB(B1, 0, 1); PG8_SCHED; PG8_LDA(At, 0, 0); PG8_STAGE(PG8_SA(1, 1), a1 + hstep, voffA);
;             PG8_WAIT_V(8); PG8_WAIT_L(0); PG8_BAR; PG8_MMA(0, 0, At, B0); PG8_MMA(0, 1, At, B1); PG8_BAR; PG8_SCHED;
	v_add_co_u32_e32 v12, vcc, s28, v138
	v_mul_f32_e32 v11, v11, v11
	v_cvt_pk_bf16_f32 v9, v9, v10
	v_cvt_pk_bf16_f32 v10, v18, v13
	v_addc_co_u32_e32 v13, vcc, 0, v139, vcc
	v_max_f32_e32 v0, 0, v0
	v_max_f32_e32 v1, 0, v1
	v_max_f32_e32 v2, 0, v2
	v_cvt_pk_bf16_f32 v11, v14, v11
	global_store_dwordx4 v[12:13], v[8:11], off
	s_mov_b64 s[38:39], 0x160000
	s_nop 0
	v_mul_f32_e32 v8, v0, v0
	v_max_f32_e32 v0, 0, v5
	v_mul_f32_e32 v5, v1, v1
	v_max_f32_e32 v1, 0, v6
	v_mul_f32_e32 v6, v2, v2
	v_max_f32_e32 v2, 0, v7
	v_max_f32_e32 v3, 0, v3
	v_readlane_b32 s80, v254, 45
	v_readlane_b32 s76, v254, 41
	v_readlane_b32 s78, v254, 43
	v_lshl_add_u64 v[16:17], v[138:139], 0, s[38:39]
	v_max_f32_e32 v4, 0, v4
	v_mul_f32_e32 v0, v0, v0
	v_mul_f32_e32 v1, v1, v1
	v_mul_f32_e32 v2, v2, v2
	v_mul_f32_e32 v3, v3, v3
	s_andn2_b64 vcc, exec, s[12:13]
	s_mov_b64 s[12:13], -1
	v_readlane_b32 s81, v254, 46
	v_readlane_b32 s82, v254, 47
	v_readlane_b32 s83, v254, 48
	v_readlane_b32 s84, v254, 49
	v_readlane_b32 s85, v254, 50
	v_readlane_b32 s86, v254, 51
	v_readlane_b32 s87, v254, 52
	v_readlane_b32 s88, v254, 53
	v_readlane_b32 s89, v254, 54
	v_readlane_b32 s92, v254, 57
	v_readlane_b32 s93, v254, 58
	v_readlane_b32 s94, v254, 59
	v_readlane_b32 s95, v254, 60
	v_readlane_b32 s77, v254, 42
	v_readlane_b32 s79, v254, 44
	v_mul_f32_e32 v4, v4, v4
	v_cvt_pk_bf16_f32 v0, v4, v0
	v_cvt_pk_bf16_f32 v1, v1, v2
	v_cvt_pk_bf16_f32 v2, v8, v5
	v_cvt_pk_bf16_f32 v3, v6, v3
	global_store_dwordx4 v[16:17], v[0:3], off offset:256
	v_readlane_b32 s90, v254, 55
	v_readlane_b32 s91, v254, 56
	s_cbranch_vccnz .LBB0_714
	s_andn2_b64 vcc, exec, s[26:27]
	s_cbranch_vccnz .LBB0_713
	s_barrier
	s_branch .LBB0_713
.Lg3_peel:
	s_add_u32 s28, vcc_lo, 0xfffc0080
	s_addc_u32 s38, vcc_hi, -1
	s_add_i32 s39, 0, 0x10000
	s_cmp_eq_u32 s80, 12
	s_cselect_b32 s67, s41, s38
	s_cselect_b32 s66, s76, s28
	v_add_u32_e32 v138, s39, v142
	s_cselect_b32 s65, s37, s79
	s_cselect_b32 s64, s77, s78
	s_add_i32 s28, 0, 0x14000
	ds_read_b128 v[144:147], v138
	ds_read_b128 v[148:151], v138 offset:1024
	ds_read_b128 v[152:155], v138 offset:2048
	ds_read_b128 v[156:159], v138 offset:3072
	v_add_u32_e32 v138, s28, v142
	ds_read_b128 v[160:163], v138
	ds_read_b128 v[164:167], v138 offset:1024
	ds_read_b128 v[168:171], v138 offset:2048
	ds_read_b128 v[172:175], v138 offset:3072
	v_lshl_add_u64 v[138:139], vcc, 0, v[134:135]
	s_add_i32 m0, s30, 0xc000
	ds_read_b128 v[182:185], v143
	ds_read_b128 v[186:189], v143 offset:1024
	ds_read_b128 v[190:193], v143 offset:2048
	ds_read_b128 v[194:197], v143 offset:3072
	ds_read_b128 v[198:201], v143 offset:4096
	ds_read_b128 v[202:205], v143 offset:5120
	ds_read_b128 v[206:209], v143 offset:6144
	ds_read_b128 v[210:213], v143 offset:7168
	global_load_lds_dwordx4 v[138:139], off
	v_lshl_add_u64 v[138:139], vcc, 0, v[136:137]
	s_add_i32 m0, s30, 0xe000
	s_nop 0
	global_load_lds_dwordx4 v[138:139], off
	s_waitcnt vmcnt(24)
	s_waitcnt lgkmcnt(0)
	s_barrier
	s_setprio 1
	s_waitcnt lgkmcnt(0)
	v_mfma_f32_16x16x32_bf16 v[124:127], v[144:147], v[182:185], 0
	v_mfma_f32_16x16x32_bf16 v[120:123], v[152:155], v[182:185], 0
	v_mfma_f32_16x16x32_bf16 v[108:111], v[144:147], v[190:193], 0
	v_mfma_f32_16x16x32_bf16 v[104:107], v[152:155], v[190:193], 0
	v_mfma_f32_16x16x32_bf16 v[92:95], v[144:147], v[198:201], 0
	v_mfma_f32_16x16x32_bf16 v[88:91], v[152:155], v[198:201], 0
	v_mfma_f32_16x16x32_bf16 v[76:79], v[144:147], v[206:209], 0
	v_mfma_f32_16x16x32_bf16 v[72:75], v[152:155], v[206:209], 0
	v_mfma_f32_16x16x32_bf16 v[124:127], v[148:151], v[186:189], v[124:127]
	v_mfma_f32_16x16x32_bf16 v[120:123], v[156:159], v[186:189], v[120:123]
	v_mfma_f32_16x16x32_bf16 v[108:111], v[148:151], v[194:197], v[108:111]
	v_mfma_f32_16x16x32_bf16 v[104:107], v[156:159], v[194:197], v[104:107]
	v_mfma_f32_16x16x32_bf16 v[92:95], v[148:151], v[202:205], v[92:95]
	v_mfma_f32_16x16x32_bf16 v[88:91], v[156:159], v[202:205], v[88:91]
	v_mfma_f32_16x16x32_bf16 v[76:79], v[148:151], v[210:213], v[76:79]
	v_mfma_f32_16x16x32_bf16 v[72:75], v[156:159], v[210:213], v[72:75]
	s_setprio 0
	s_setprio 1
	v_mfma_f32_16x16x32_bf16 v[116:119], v[160:163], v[182:185], 0
	v_mfma_f32_16x16x32_bf16 v[112:115], v[168:171], v[182:185], 0
	v_mfma_f32_16x16x32_bf16 v[100:103], v[160:163], v[190:193], 0
	v_mfma_f32_16x16x32_bf16 v[96:99], v[168:171], v[190:193], 0
	v_mfma_f32_16x16x32_bf16 v[84:87], v[160:163], v[198:201], 0
	v_mfma_f32_16x16x32_bf16 v[80:83], v[168:171], v[198:201], 0
	v_mfma_f32_16x16x32_bf16 v[68:71], v[160:163], v[206:209], 0
	v_mfma_f32_16x16x32_bf16 v[64:67], v[168:171], v[206:209], 0
	v_mfma_f32_16x16x32_bf16 v[116:119], v[164:167], v[186:189], v[116:119]
	v_mfma_f32_16x16x32_bf16 v[112:115], v[172:175], v[186:189], v[112:115]
	v_mfma_f32_16x16x32_bf16 v[100:103], v[164:167], v[194:197], v[100:103]
	v_mfma_f32_16x16x32_bf16 v[96:99], v[172:175], v[194:197], v[96:99]
	v_mfma_f32_16x16x32_bf16 v[84:87], v[164:167], v[202:205], v[84:87]
	v_mfma_f32_16x16x32_bf16 v[80:83], v[172:175], v[202:205], v[80:83]
	v_mfma_f32_16x16x32_bf16 v[68:71], v[164:167], v[210:213], v[68:71]
	v_mfma_f32_16x16x32_bf16 v[64:67], v[172:175], v[210:213], v[64:67]
	s_setprio 0
	s_barrier
; #define PG8_STAGE(bufoff, gbase, voff) do { _Pragma("unroll") for (int _i = 0; _i < 2; ++_i) \
;         __builtin_amdgcn_global_load_lds((const unsigned*)((const char*)(gbase) + (voff)[_i]), (PG8_LAS unsigned*)(lds + (bufoff) + ldsw + _i * 8192), 16, 0, 0); } while (0)
; #define PG8_LDA(dst, b, h) do { _Pragma("unroll") for (int m = 0; m < 4; ++m) _Pragma("unroll") for (int k = 0; k < 2; ++k) dst[m][k] = *(const PG8_LAS bf16x8*)(lds + PG8_SA(b, h) + aoff + m * 2048 + k * 1024); } while (0)
; #define PG8_LDB(dst, b, h) do { _Pragma("unroll") for (int n = 0; n < 2; ++n) _Pragma("unroll") for (int k = 0; k < 2; ++k) dst[n][k] = *(const PG8_LAS bf16x8*)(lds + PG8_SB(b, h) + boff + n * 2048 + k * 1024); } while (0)
; #define PG8_MMA(ai, bj, At, Bt) do { __builtin_amdgcn_s_setprio(1); _Pragma("unroll") for (int m = 0; m < 4; ++m) _Pragma("unroll") for (int n = 0; n < 2; ++n) _Pragma("unroll") for (int k = 0; k < 2; ++k) \
;         acc[ai][bj][m][n] = __builtin_amdgcn_mfma_f32_16x16x32_bf16(Bt[n][k], At[m][k], acc[ai][bj][m][n], 0, 0, 0); __builtin_amdgcn_s_setprio(0); } while (0)
; #define PG8_WAIT_V(n) asm volatile("s_waitcnt vmcnt(" #n ")" ::: "memory")
; #define PG8_WAIT_L(n) asm volatile("s_waitcnt lgkmcnt(" #n ")" ::: "memory")
; #define PG8_BAR __builtin_amdgcn_s_barrier()
; #define PG8_SCHED __builtin_amdgcn_sched_barrier(0)
; template <class Epi, class Sched, bool ALIGN_EPI = false, bool SP2 = false>
; __device__ __forceinline__ void gemm_phase(PG8_LAS unsigned char* lds, const Gemm g, const Sched& S, const Epi& E) {
;     ...
;             PG8_LDA(At, 0, 1); PG8_STAGE(PG8_SB(0, 0), b2, voffB); PG8_STAGE(PG8_SB(0, 1), b2 + hstep, voffB); PG8_STAGE(PG8_SA(0, 0), a2, voffA);
;             PG8_WAIT_V(8); PG8_WAIT_L(0); PG8_BAR; PG8_MMA(1, 0, At, B0); PG8_MMA(1, 1, At, B1); PG8_BAR; PG8_SCHED;
;             PG8_LDB(B0, 1, 0); PG8_LDB(B1, 1, 1); PG8_SCHED; PG8_LDA(At, 1, 0); PG8_STAGE(PG8_SA(0, 1), a2 + hstep, voffA);
;             PG8_WAIT_V(8); PG8_WAIT_L(0); PG8_BAR; PG8_MMA(0, 0, At, B0); PG8_MMA(0, 1, At, B1); PG8_BAR; PG8_SCHED;
	s_add_i32 s38, s39, s23
	v_lshl_add_u64 v[138:139], s[64:65], 0, v[176:177]
	s_mov_b32 m0, s38
	ds_read_b128 v[182:185], v143 offset:16384
	ds_read_b128 v[186:189], v143 offset:17408
	ds_read_b128 v[190:193], v143 offset:18432
	ds_read_b128 v[194:197], v143 offset:19456
	ds_read_b128 v[198:201], v143 offset:20480
	ds_read_b128 v[202:205], v143 offset:21504
	ds_read_b128 v[206:209], v143 offset:22528
	ds_read_b128 v[210:213], v143 offset:23552
	global_load_lds_dwordx4 v[138:139], off
	s_add_i32 m0, s38, 0x2000
	s_add_u32 s38, s64, 0x40000
	v_lshl_add_u64 v[214:215], s[64:65], 0, v[128:129]
	s_addc_u32 s39, s65, 0
	s_add_i32 s28, s28, s23
	global_load_lds_dwordx4 v[214:215], off
	v_lshl_add_u64 v[216:217], s[38:39], 0, v[176:177]
	s_mov_b32 m0, s28
	v_lshl_add_u64 v[218:219], s[66:67], 0, v[130:131]
	global_load_lds_dwordx4 v[216:217], off
	v_lshl_add_u64 v[216:217], s[38:39], 0, v[128:129]
	s_add_i32 m0, s28, 0x2000
	s_nop 0
	global_load_lds_dwordx4 v[216:217], off
	v_lshl_add_u64 v[216:217], s[66:67], 0, v[132:133]
	s_mov_b32 m0, s30
	s_nop 0
	global_load_lds_dwordx4 v[216:217], off
	s_mov_b32 m0, s31
	s_nop 0
	global_load_lds_dwordx4 v[218:219], off
	s_waitcnt vmcnt(24)
	s_waitcnt lgkmcnt(0)
	s_barrier
	s_setprio 1
	s_waitcnt lgkmcnt(0)
	v_mfma_f32_16x16x32_bf16 v[60:63], v[144:147], v[182:185], 0
	v_mfma_f32_16x16x32_bf16 v[56:59], v[152:155], v[182:185], 0
	v_mfma_f32_16x16x32_bf16 v[44:47], v[144:147], v[190:193], 0
	v_mfma_f32_16x16x32_bf16 v[40:43], v[152:155], v[190:193], 0
	v_mfma_f32_16x16x32_bf16 v[28:31], v[144:147], v[198:201], 0
	v_mfma_f32_16x16x32_bf16 v[24:27], v[152:155], v[198:201], 0
	v_mfma_f32_16x16x32_bf16 v[12:15], v[144:147], v[206:209], 0
	v_mfma_f32_16x16x32_bf16 v[8:11], v[152:155], v[206:209], 0
	v_mfma_f32_16x16x32_bf16 v[60:63], v[148:151], v[186:189], v[60:63]
	v_mfma_f32_16x16x32_bf16 v[56:59], v[156:159], v[186:189], v[56:59]
	v_mfma_f32_16x16x32_bf16 v[44:47], v[148:151], v[194:197], v[44:47]
	v_mfma_f32_16x16x32_bf16 v[40:43], v[156:159], v[194:197], v[40:43]
	v_mfma_f32_16x16x32_bf16 v[28:31], v[148:151], v[202:205], v[28:31]
	v_mfma_f32_16x16x32_bf16 v[24:27], v[156:159], v[202:205], v[24:27]
	v_mfma_f32_16x16x32_bf16 v[12:15], v[148:151], v[210:213], v[12:15]
	v_mfma_f32_16x16x32_bf16 v[8:11], v[156:159], v[210:213], v[8:11]
	s_setprio 0
	s_setprio 1
	v_mfma_f32_16x16x32_bf16 v[52:55], v[160:163], v[182:185], 0
	v_mfma_f32_16x16x32_bf16 v[48:51], v[168:171], v[182:185], 0
	v_mfma_f32_16x16x32_bf16 v[36:39], v[160:163], v[190:193], 0
	v_mfma_f32_16x16x32_bf16 v[32:35], v[168:171], v[190:193], 0
	v_mfma_f32_16x16x32_bf16 v[20:23], v[160:163], v[198:201], 0
	v_mfma_f32_16x16x32_bf16 v[16:19], v[168:171], v[198:201], 0
	v_mfma_f32_16x16x32_bf16 v[4:7], v[160:163], v[206:209], 0
	v_mfma_f32_16x16x32_bf16 v[0:3], v[168:171], v[206:209], 0
	v_mfma_f32_16x16x32_bf16 v[52:55], v[164:167], v[186:189], v[52:55]
	v_mfma_f32_16x16x32_bf16 v[48:51], v[172:175], v[186:189], v[48:51]
	v_mfma_f32_16x16x32_bf16 v[36:39], v[164:167], v[194:197], v[36:39]
	v_mfma_f32_16x16x32_bf16 v[32:35], v[172:175], v[194:197], v[32:35]
	v_mfma_f32_16x16x32_bf16 v[20:23], v[164:167], v[202:205], v[20:23]
	v_mfma_f32_16x16x32_bf16 v[16:19], v[172:175], v[202:205], v[16:19]
	v_mfma_f32_16x16x32_bf16 v[4:7], v[164:167], v[210:213], v[4:7]
	v_mfma_f32_16x16x32_bf16 v[0:3], v[172:175], v[210:213], v[0:3]
	s_setprio 0
	s_barrier
	s_add_i32 s28, 0, 0x18000
	s_add_i32 s48, 0, 0x1c000
	v_add_u32_e32 v156, s28, v142
	v_add_u32_e32 v172, s48, v142
	ds_read_b128 v[144:147], v156
	ds_read_b128 v[148:151], v156 offset:1024
	ds_read_b128 v[152:155], v156 offset:2048
	ds_read_b128 v[156:159], v156 offset:3072
	ds_read_b128 v[160:163], v172
	ds_read_b128 v[164:167], v172 offset:1024
	ds_read_b128 v[168:171], v172 offset:2048
	ds_read_b128 v[172:175], v172 offset:3072
	s_add_u32 s38, s66, 0x40000
	s_addc_u32 s39, s67, 0
	s_mov_b32 m0, s63
	v_lshl_add_u64 v[220:221], s[38:39], 0, v[132:133]
	ds_read_b128 v[182:185], v143 offset:32768
	ds_read_b128 v[186:189], v143 offset:33792
	ds_read_b128 v[190:193], v143 offset:34816
	ds_read_b128 v[194:197], v143 offset:35840
	ds_read_b128 v[198:201], v143 offset:36864
	ds_read_b128 v[202:205], v143 offset:37888
	ds_read_b128 v[206:209], v143 offset:38912
	ds_read_b128 v[210:213], v143 offset:39936
	global_load_lds_dwordx4 v[220:221], off
	v_lshl_add_u64 v[220:221], s[38:39], 0, v[130:131]
	s_mov_b32 m0, s69
	s_nop 0
	global_load_lds_dwordx4 v[220:221], off
	s_waitcnt vmcnt(8)
	s_waitcnt lgkmcnt(0)
	s_barrier
; #define PG8_STAGE(bufoff, gbase, voff) do { _Pragma("unroll") for (int _i = 0; _i < 2; ++_i) \
;         __builtin_amdgcn_global_load_lds((const unsigned*)((const char*)(gbase) + (voff)[_i]), (PG8_LAS unsigned*)(lds + (bufoff) + ldsw + _i * 8192), 16, 0, 0); } while (0)
; #define PG8_LDA(dst, b, h) do { _Pragma("unroll") for (int m = 0; m < 4; ++m) _Pragma("unroll") for (int k = 0; k < 2; ++k) dst[m][k] = *(const PG8_LAS bf16x8*)(lds + PG8_SA(b, h) + aoff + m * 2048 + k * 1024); } while (0)
; #define PG8_MMA(ai, bj, At, Bt) do { __builtin_amdgcn_s_setprio(1); _Pragma("unroll") for (int m = 0; m < 4; ++m) _Pragma("unroll") for (int n = 0; n < 2; ++n) _Pragma("unroll") for (int k = 0; k < 2; ++k) \
;         acc[ai][bj][m][n] = __builtin_amdgcn_mfma_f32_16x16x32_bf16(Bt[n][k], At[m][k], acc[ai][bj][m][n], 0, 0, 0); __builtin_amdgcn_s_setprio(0); } while (0)
; #define PG8_WAIT_V(n) asm volatile("s_waitcnt vmcnt(" #n ")" ::: "memory")
; #define PG8_WAIT_L(n) asm volatile("s_waitcnt lgkmcnt(" #n ")" ::: "memory")
; #define PG8_BAR __builtin_amdgcn_s_barrier()
; #define PG8_SCHED __builtin_amdgcn_sched_barrier(0)
; template <class Epi, class Sched, bool ALIGN_EPI = false, bool SP2 = false>
; __device__ __forceinline__ void gemm_phase(PG8_LAS unsigned char* lds, const Gemm g, const Sched& S, const Epi& E) {
;     ...
;         for (int t = 0; t < nt; t += 2) {
;             const bool last = (t == nt - 2);
;             const char* a1 = cA + (size_t)(t + 1) * kstep;
;             const char* a2 = last ? nA : cA + (size_t)(t + 2) * kstep; const char* b2 = last ? nB : cB + (size_t)(t + 2) * kstep;
;     ...
;             PG8_WAIT_V(8); PG8_WAIT_L(0); PG8_BAR; PG8_MMA(0, 0, At, B0); PG8_MMA(0, 1, At, B1); PG8_BAR; PG8_SCHED;
;             PG8_LDA(At, 1, 1); PG8_STAGE(PG8_SB(1, 0), b3, voffB); PG8_STAGE(PG8_SB(1, 1), b3 + hstep, voffB); PG8_STAGE(PG8_SA(1, 0), a3, voffA);
;             PG8_WAIT_V(8); PG8_WAIT_L(0); PG8_BAR; PG8_MMA(1, 0, At, B0); PG8_MMA(1, 1, At, B1); PG8_BAR; PG8_SCHED;
	s_setprio 1
	s_waitcnt lgkmcnt(0)
	v_mfma_f32_16x16x32_bf16 v[124:127], v[144:147], v[182:185], v[124:127]
	v_mfma_f32_16x16x32_bf16 v[120:123], v[152:155], v[182:185], v[120:123]
	v_mfma_f32_16x16x32_bf16 v[108:111], v[144:147], v[190:193], v[108:111]
	v_mfma_f32_16x16x32_bf16 v[104:107], v[152:155], v[190:193], v[104:107]
	v_mfma_f32_16x16x32_bf16 v[92:95], v[144:147], v[198:201], v[92:95]
	v_mfma_f32_16x16x32_bf16 v[88:91], v[152:155], v[198:201], v[88:91]
	v_mfma_f32_16x16x32_bf16 v[76:79], v[144:147], v[206:209], v[76:79]
	v_mfma_f32_16x16x32_bf16 v[72:75], v[152:155], v[206:209], v[72:75]
	v_mfma_f32_16x16x32_bf16 v[124:127], v[148:151], v[186:189], v[124:127]
	v_mfma_f32_16x16x32_bf16 v[120:123], v[156:159], v[186:189], v[120:123]
	v_mfma_f32_16x16x32_bf16 v[108:111], v[148:151], v[194:197], v[108:111]
	v_mfma_f32_16x16x32_bf16 v[104:107], v[156:159], v[194:197], v[104:107]
	v_mfma_f32_16x16x32_bf16 v[92:95], v[148:151], v[202:205], v[92:95]
	v_mfma_f32_16x16x32_bf16 v[88:91], v[156:159], v[202:205], v[88:91]
	v_mfma_f32_16x16x32_bf16 v[76:79], v[148:151], v[210:213], v[76:79]
	v_mfma_f32_16x16x32_bf16 v[72:75], v[156:159], v[210:213], v[72:75]
	s_setprio 0
	s_setprio 1
	v_mfma_f32_16x16x32_bf16 v[116:119], v[160:163], v[182:185], v[116:119]
	v_mfma_f32_16x16x32_bf16 v[112:115], v[168:171], v[182:185], v[112:115]
	v_mfma_f32_16x16x32_bf16 v[100:103], v[160:163], v[190:193], v[100:103]
	v_mfma_f32_16x16x32_bf16 v[96:99], v[168:171], v[190:193], v[96:99]
	v_mfma_f32_16x16x32_bf16 v[84:87], v[160:163], v[198:201], v[84:87]
	v_mfma_f32_16x16x32_bf16 v[80:83], v[168:171], v[198:201], v[80:83]
	v_mfma_f32_16x16x32_bf16 v[68:71], v[160:163], v[206:209], v[68:71]
	v_mfma_f32_16x16x32_bf16 v[64:67], v[168:171], v[206:209], v[64:67]
	v_mfma_f32_16x16x32_bf16 v[116:119], v[164:167], v[186:189], v[116:119]
	v_mfma_f32_16x16x32_bf16 v[112:115], v[172:175], v[186:189], v[112:115]
	v_mfma_f32_16x16x32_bf16 v[100:103], v[164:167], v[194:197], v[100:103]
	v_mfma_f32_16x16x32_bf16 v[96:99], v[172:175], v[194:197], v[96:99]
	v_mfma_f32_16x16x32_bf16 v[84:87], v[164:167], v[202:205], v[84:87]
	v_mfma_f32_16x16x32_bf16 v[80:83], v[172:175], v[202:205], v[80:83]
	v_mfma_f32_16x16x32_bf16 v[68:71], v[164:167], v[210:213], v[68:71]
	v_mfma_f32_16x16x32_bf16 v[64:67], v[172:175], v[210:213], v[64:67]
	s_setprio 0
	s_barrier
	s_add_i32 s28, s28, s23
	v_lshl_add_u64 v[138:139], v[138:139], 0, s[44:45]
	s_mov_b32 m0, s28
	ds_read_b128 v[182:185], v143 offset:49152
	ds_read_b128 v[186:189], v143 offset:50176
	ds_read_b128 v[190:193], v143 offset:51200
	ds_read_b128 v[194:197], v143 offset:52224
	ds_read_b128 v[198:201], v143 offset:53248
	ds_read_b128 v[202:205], v143 offset:54272
	ds_read_b128 v[206:209], v143 offset:55296
	ds_read_b128 v[210:213], v143 offset:56320
	global_load_lds_dwordx4 v[138:139], off
	s_add_i32 m0, s28, 0x2000
	s_add_u32 s38, s64, 0x40080
	v_lshl_add_u64 v[138:139], v[214:215], 0, s[44:45]
	s_addc_u32 s39, s65, 0
	s_add_i32 s28, s48, s23
	global_load_lds_dwordx4 v[138:139], off
	v_lshl_add_u64 v[138:139], s[38:39], 0, v[176:177]
	s_mov_b32 m0, s28
	s_nop 0
	global_load_lds_dwordx4 v[138:139], off
	v_lshl_add_u64 v[138:139], s[38:39], 0, v[128:129]
	s_add_i32 m0, s28, 0x2000
	s_nop 0
	global_load_lds_dwordx4 v[138:139], off
	v_lshl_add_u64 v[138:139], v[216:217], 0, s[44:45]
	s_mov_b32 m0, s73
	s_nop 0
	global_load_lds_dwordx4 v[138:139], off
	v_lshl_add_u64 v[138:139], v[218:219], 0, s[44:45]
	s_mov_b32 m0, s74
	s_nop 0
	global_load_lds_dwordx4 v[138:139], off
	s_waitcnt vmcnt(8)
	s_waitcnt lgkmcnt(0)
	s_barrier
	s_setprio 1
	s_waitcnt lgkmcnt(0)
	v_mfma_f32_16x16x32_bf16 v[60:63], v[144:147], v[182:185], v[60:63]
	v_mfma_f32_16x16x32_bf16 v[56:59], v[152:155], v[182:185], v[56:59]
	v_mfma_f32_16x16x32_bf16 v[44:47], v[144:147], v[190:193], v[44:47]
	v_mfma_f32_16x16x32_bf16 v[40:43], v[152:155], v[190:193], v[40:43]
	v_mfma_f32_16x16x32_bf16 v[28:31], v[144:147], v[198:201], v[28:31]
	v_mfma_f32_16x16x32_bf16 v[24:27], v[152:155], v[198:201], v[24:27]
	v_mfma_f32_16x16x32_bf16 v[12:15], v[144:147], v[206:209], v[12:15]
	v_mfma_f32_16x16x32_bf16 v[8:11], v[152:155], v[206:209], v[8:11]
	v_mfma_f32_16x16x32_bf16 v[60:63], v[148:151], v[186:189], v[60:63]
	v_mfma_f32_16x16x32_bf16 v[56:59], v[156:159], v[186:189], v[56:59]
	v_mfma_f32_16x16x32_bf16 v[44:47], v[148:151], v[194:197], v[44:47]
	v_mfma_f32_16x16x32_bf16 v[40:43], v[156:159], v[194:197], v[40:43]
	v_mfma_f32_16x16x32_bf16 v[28:31], v[148:151], v[202:205], v[28:31]
	v_mfma_f32_16x16x32_bf16 v[24:27], v[156:159], v[202:205], v[24:27]
	v_mfma_f32_16x16x32_bf16 v[12:15], v[148:151], v[210:213], v[12:15]
	v_mfma_f32_16x16x32_bf16 v[8:11], v[156:159], v[210:213], v[8:11]
	s_setprio 0
	s_setprio 1
	v_mfma_f32_16x16x32_bf16 v[52:55], v[160:163], v[182:185], v[52:55]
	v_mfma_f32_16x16x32_bf16 v[48:51], v[168:171], v[182:185], v[48:51]
	v_mfma_f32_16x16x32_bf16 v[36:39], v[160:163], v[190:193], v[36:39]
	v_mfma_f32_16x16x32_bf16 v[32:35], v[168:171], v[190:193], v[32:35]
	v_mfma_f32_16x16x32_bf16 v[20:23], v[160:163], v[198:201], v[20:23]
	v_mfma_f32_16x16x32_bf16 v[16:19], v[168:171], v[198:201], v[16:19]
	v_mfma_f32_16x16x32_bf16 v[4:7], v[160:163], v[206:209], v[4:7]
	v_mfma_f32_16x16x32_bf16 v[0:3], v[168:171], v[206:209], v[0:3]
	v_mfma_f32_16x16x32_bf16 v[52:55], v[164:167], v[186:189], v[52:55]
	v_mfma_f32_16x16x32_bf16 v[48:51], v[172:175], v[186:189], v[48:51]
	v_mfma_f32_16x16x32_bf16 v[36:39], v[164:167], v[194:197], v[36:39]
	v_mfma_f32_16x16x32_bf16 v[32:35], v[172:175], v[194:197], v[32:35]
	v_mfma_f32_16x16x32_bf16 v[20:23], v[164:167], v[202:205], v[20:23]
	v_mfma_f32_16x16x32_bf16 v[16:19], v[172:175], v[202:205], v[16:19]
	v_mfma_f32_16x16x32_bf16 v[4:7], v[164:167], v[210:213], v[4:7]
	v_mfma_f32_16x16x32_bf16 v[0:3], v[172:175], v[210:213], v[0:3]
	s_setprio 0
	s_barrier
	s_add_i32 s80, s80, 2
	s_add_u32 vcc_lo, vcc_lo, 0x100
	s_addc_u32 vcc_hi, vcc_hi, 0
	s_add_u32 s78, s78, 0x100
	s_addc_u32 s79, s79, 0
	s_cmp_gt_u32 s80, 13
	s_cbranch_scc0 .LBB0_718
	s_branch .Lg3_post

; template <class Epi, class Sched, bool ALIGN_EPI = false, bool SP2 = false>
; __device__ __forceinline__ void gemm_phase(PG8_LAS unsigned char* lds, const Gemm g, const Sched& S, const Epi& E) {
;     ...
;         const char* nA = has_next ? (const char*)g.A + (size_t)nxt.pm * tstep + nxt.ko : cA; const char* nB = has_next ? (const char*)g.Bt + (size_t)nxt.pn * tstep + nxt.ko : cB;
;     ...
;         for (int a = 0; a < 2; ++a)
; #pragma unroll
;             for (int b = 0; b < 2; ++b)
; #pragma unroll
;                 for (int m = 0; m < 4; ++m)
; #pragma unroll
;                     for (int n = 0; n < 2; ++n) acc[a][b][m][n] = (f32x4){0.f, 0.f, 0.f, 0.f};
;         cur = nxt; cA = nA; cB = nB; ++ui;
.LBB0_789:
	s_ashr_i32 s35, s34, 31
	s_lshl_b64 s[6:7], s[34:35], 21
	v_readlane_b32 s36, v253, 63
	v_readlane_b32 s37, v254, 0
	s_add_u32 s36, s36, s6
	s_addc_u32 s37, s37, s7
	s_and_b64 s[6:7], s[8:9], exec
	s_cselect_b32 s35, s37, s5
	s_cselect_b32 s72, s36, s4
	s_ashr_i32 s27, s26, 31
	s_lshl_b64 s[6:7], s[26:27], 21
	s_add_u32 s40, s18, s6
	s_addc_u32 s41, s19, s7
	s_and_b64 s[6:7], s[8:9], exec
	s_cselect_b32 s27, s41, s67
	s_cselect_b32 s73, s40, s66
	s_add_u32 s64, s4, 0x100080
	s_addc_u32 s65, s5, 0
	s_add_u32 s66, s66, 0x100
	v_mov_b32_e32 v0, 0
	s_addc_u32 s67, s67, 0
	s_mov_b32 s74, -2
	s_cmp_lg_u32 s69, 1
	s_cbranch_scc1 .Lg4_peel
	v_mov_b64_e32 v[0:1], 0
	v_mov_b64_e32 v[2:3], 0
	v_mov_b64_e32 v[4:5], 0
	v_mov_b64_e32 v[6:7], 0
	v_mov_b64_e32 v[8:9], 0
	v_mov_b64_e32 v[10:11], 0
	v_mov_b64_e32 v[12:13], 0
	v_mov_b64_e32 v[14:15], 0
	v_mov_b64_e32 v[16:17], 0
	v_mov_b64_e32 v[18:19], 0
	v_mov_b64_e32 v[20:21], 0
	v_mov_b64_e32 v[22:23], 0
	v_mov_b64_e32 v[24:25], 0
	v_mov_b64_e32 v[26:27], 0
	v_mov_b64_e32 v[28:29], 0
	v_mov_b64_e32 v[30:31], 0
	v_mov_b64_e32 v[32:33], 0
	v_mov_b64_e32 v[34:35], 0
	v_mov_b64_e32 v[36:37], 0
	v_mov_b64_e32 v[38:39], 0
	v_mov_b64_e32 v[40:41], 0
	v_mov_b64_e32 v[42:43], 0
	v_mov_b64_e32 v[44:45], 0
	v_mov_b64_e32 v[46:47], 0
	v_mov_b64_e32 v[48:49], 0
	v_mov_b64_e32 v[50:51], 0
	v_mov_b64_e32 v[52:53], 0
	v_mov_b64_e32 v[54:55], 0
	v_mov_b64_e32 v[56:57], 0
	v_mov_b64_e32 v[58:59], 0
	v_mov_b64_e32 v[60:61], 0
	v_mov_b64_e32 v[62:63], 0
	v_mov_b64_e32 v[64:65], 0
	v_mov_b64_e32 v[66:67], 0
	v_mov_b64_e32 v[68:69], 0
	v_mov_b64_e32 v[70:71], 0
	v_mov_b64_e32 v[72:73], 0
	v_mov_b64_e32 v[74:75], 0
	v_mov_b64_e32 v[76:77], 0
	v_mov_b64_e32 v[78:79], 0
	v_mov_b64_e32 v[80:81], 0
	v_mov_b64_e32 v[82:83], 0
	v_mov_b64_e32 v[84:85], 0
	v_mov_b64_e32 v[86:87], 0
	v_mov_b64_e32 v[88:89], 0
	v_mov_b64_e32 v[90:91], 0
	v_mov_b64_e32 v[92:93], 0
	v_mov_b64_e32 v[94:95], 0
	v_mov_b64_e32 v[96:97], 0
	v_mov_b64_e32 v[98:99], 0
	v_mov_b64_e32 v[100:101], 0
	v_mov_b64_e32 v[102:103], 0
	v_mov_b64_e32 v[104:105], 0
	v_mov_b64_e32 v[106:107], 0
	v_mov_b64_e32 v[108:109], 0
	v_mov_b64_e32 v[110:111], 0
	v_mov_b64_e32 v[112:113], 0
	v_mov_b64_e32 v[114:115], 0
	v_mov_b64_e32 v[116:117], 0
	v_mov_b64_e32 v[118:119], 0
	v_mov_b64_e32 v[120:121], 0
	v_mov_b64_e32 v[122:123], 0
	v_mov_b64_e32 v[124:125], 0
	v_mov_b64_e32 v[126:127], 0

; #define PG8_BAR __builtin_amdgcn_s_barrier()
; template <class Epi, class Sched, bool ALIGN_EPI = false, bool SP2 = false>
; __device__ __forceinline__ void gemm_phase(PG8_LAS unsigned char* lds, const Gemm g, const Sched& S, const Epi& E) {
;     ...
;         if constexpr (ALIGN_EPI) { if (wr == 0) PG8_BAR; }
;         if constexpr (!Epi::AFTER_DRAIN) { E(acc, cur, wr, wc, fr, fq); S.done(cur); }
.Lg4_post:
	s_and_b64 vcc, exec, s[12:13]
	s_mov_b32 s48, 0x358637bd
	s_mov_b32 s72, 0x3a800000
	s_cbranch_vccz .LBB0_793
	s_barrier

; #define PG8_STAGE(bufoff, gbase, voff) do { _Pragma("unroll") for (int _i = 0; _i < 2; ++_i) \
;         __builtin_amdgcn_global_load_lds((const unsigned*)((const char*)(gbase) + (voff)[_i]), (PG8_LAS unsigned*)(lds + (bufoff) + ldsw + _i * 8192), 16, 0, 0); } while (0)
; #define PG8_LDA(dst, b, h) do { _Pragma("unroll") for (int m = 0; m < 4; ++m) _Pragma("unroll") for (int k = 0; k < 2; ++k) dst[m][k] = *(const PG8_LAS bf16x8*)(lds + PG8_SA(b, h) + aoff + m * 2048 + k * 1024); } while (0)
; #define PG8_LDB(dst, b, h) do { _Pragma("unroll") for (int n = 0; n < 2; ++n) _Pragma("unroll") for (int k = 0; k < 2; ++k) dst[n][k] = *(const PG8_LAS bf16x8*)(lds + PG8_SB(b, h) + boff + n * 2048 + k * 1024); } while (0)
; #define PG8_MMA(ai, bj, At, Bt) do { __builtin_amdgcn_s_setprio(1); _Pragma("unroll") for (int m = 0; m < 4; ++m) _Pragma("unroll") for (int n = 0; n < 2; ++n) _Pragma("unroll") for (int k = 0; k < 2; ++k) \
;         acc[ai][bj][m][n] = __builtin_amdgcn_mfma_f32_16x16x32_bf16(Bt[n][k], At[m][k], acc[ai][bj][m][n], 0, 0, 0); __builtin_amdgcn_s_setprio(0); } while (0)
; #define PG8_WAIT_V(n) asm volatile("s_waitcnt vmcnt(" #n ")" ::: "memory")
; #define PG8_WAIT_L(n) asm volatile("s_waitcnt lgkmcnt(" #n ")" ::: "memory")
; template <class Epi, class Sched, bool ALIGN_EPI = false, bool SP2 = false>
; __device__ __forceinline__ void gemm_phase(PG8_LAS unsigned char* lds, const Gemm g, const Sched& S, const Epi& E) {
;     ...
;             const bool last = (t == nt - 2);
;             const char* a1 = cA + (size_t)(t + 1) * kstep;
;             const char* a2 = last ? nA : cA + (size_t)(t + 2) * kstep; const char* b2 = last ? nB : cB + (size_t)(t + 2) * kstep;
;             const char* a3 = a2 + kstep; const char* b3 = b2 + kstep;
;             if (last && has_next) S.a_ready(nxt);
;             if constexpr (SP2) {
;             PG8_LDB(B0, 0, 0); PG8_LDB(B1, 0, 1); PG8_SCHED; PG8_LDA(At, 0, 0); PG8_STAGE(PG8_SA(1, 1), a1 + hstep, voffA);
;             PG8_WAIT_V(8); PG8_WAIT_L(0); PG8_BAR; PG8_MMA(0, 0, At, B0); PG8_MMA(0, 1, At, B1); PG8_BAR; PG8_SCHED;
;             PG8_LDA(At, 0, 1); PG8_STAGE(PG8_SB(0, 0), b2, voffB); PG8_STAGE(PG8_SB(0, 1), b2 + hstep, voffB); PG8_STAGE(PG8_SA(0, 0), a2, voffA);
;             PG8_WAIT_V(8); PG8_WAIT_L(0); PG8_BAR; PG8_MMA(1, 0, At, B0); PG8_MMA(1, 1, At, B1); PG8_BAR; PG8_SCHED;
.Lg4_peel:
	s_add_u32 s4, s64, 0xfff00080
	s_addc_u32 s5, s65, -1
	s_add_i32 s28, 0, 0x10000
	s_cmp_eq_u32 s74, 60
	s_cselect_b32 s7, s35, s5
	s_cselect_b32 s6, s72, s4
	v_add_u32_e32 v138, s28, v142
	s_cselect_b32 s5, s27, s67
	s_cselect_b32 s4, s73, s66
	s_add_i32 s48, 0, 0x14000
	ds_read_b128 v[144:147], v138
	ds_read_b128 v[148:151], v138 offset:1024
	ds_read_b128 v[152:155], v138 offset:2048
	ds_read_b128 v[156:159], v138 offset:3072
	v_add_u32_e32 v138, s48, v142
	ds_read_b128 v[160:163], v138
	ds_read_b128 v[164:167], v138 offset:1024
	ds_read_b128 v[168:171], v138 offset:2048
	ds_read_b128 v[172:175], v138 offset:3072
	v_lshl_add_u64 v[138:139], s[64:65], 0, v[134:135]
	s_add_i32 m0, s23, 0xc000
	ds_read_b128 v[182:185], v143
	ds_read_b128 v[186:189], v143 offset:1024
	ds_read_b128 v[190:193], v143 offset:2048
	ds_read_b128 v[194:197], v143 offset:3072
	ds_read_b128 v[198:201], v143 offset:4096
	ds_read_b128 v[202:205], v143 offset:5120
	ds_read_b128 v[206:209], v143 offset:6144
	ds_read_b128 v[210:213], v143 offset:7168
	global_load_lds_dwordx4 v[138:139], off
	v_lshl_add_u64 v[138:139], s[64:65], 0, v[136:137]
	s_add_i32 m0, s23, 0xe000
	s_nop 0
	global_load_lds_dwordx4 v[138:139], off
	s_waitcnt vmcnt(24)
	s_waitcnt lgkmcnt(0)
	s_barrier
	s_setprio 1
	s_waitcnt lgkmcnt(0)
	v_mfma_f32_16x16x32_bf16 v[124:127], v[144:147], v[182:185], 0
	v_mfma_f32_16x16x32_bf16 v[120:123], v[152:155], v[182:185], 0
	v_mfma_f32_16x16x32_bf16 v[116:119], v[144:147], v[190:193], 0
	v_mfma_f32_16x16x32_bf16 v[108:111], v[152:155], v[190:193], 0
	v_mfma_f32_16x16x32_bf16 v[100:103], v[144:147], v[198:201], 0
	v_mfma_f32_16x16x32_bf16 v[92:95], v[152:155], v[198:201], 0
	v_mfma_f32_16x16x32_bf16 v[84:87], v[144:147], v[206:209], 0
	v_mfma_f32_16x16x32_bf16 v[76:79], v[152:155], v[206:209], 0
	v_mfma_f32_16x16x32_bf16 v[124:127], v[148:151], v[186:189], v[124:127]
	v_mfma_f32_16x16x32_bf16 v[120:123], v[156:159], v[186:189], v[120:123]
	v_mfma_f32_16x16x32_bf16 v[116:119], v[148:151], v[194:197], v[116:119]
	v_mfma_f32_16x16x32_bf16 v[108:111], v[156:159], v[194:197], v[108:111]
	v_mfma_f32_16x16x32_bf16 v[100:103], v[148:151], v[202:205], v[100:103]
	v_mfma_f32_16x16x32_bf16 v[92:95], v[156:159], v[202:205], v[92:95]
	v_mfma_f32_16x16x32_bf16 v[84:87], v[148:151], v[210:213], v[84:87]
	v_mfma_f32_16x16x32_bf16 v[76:79], v[156:159], v[210:213], v[76:79]
	s_setprio 0
	s_setprio 1
	v_mfma_f32_16x16x32_bf16 v[112:115], v[160:163], v[182:185], 0
	v_mfma_f32_16x16x32_bf16 v[104:107], v[168:171], v[182:185], 0
	v_mfma_f32_16x16x32_bf16 v[96:99], v[160:163], v[190:193], 0
	v_mfma_f32_16x16x32_bf16 v[88:91], v[168:171], v[190:193], 0
	v_mfma_f32_16x16x32_bf16 v[80:83], v[160:163], v[198:201], 0
	v_mfma_f32_16x16x32_bf16 v[72:75], v[168:171], v[198:201], 0
	v_mfma_f32_16x16x32_bf16 v[68:71], v[160:163], v[206:209], 0
	v_mfma_f32_16x16x32_bf16 v[64:67], v[168:171], v[206:209], 0
	v_mfma_f32_16x16x32_bf16 v[112:115], v[164:167], v[186:189], v[112:115]
	v_mfma_f32_16x16x32_bf16 v[104:107], v[172:175], v[186:189], v[104:107]
	v_mfma_f32_16x16x32_bf16 v[96:99], v[164:167], v[194:197], v[96:99]
	v_mfma_f32_16x16x32_bf16 v[88:91], v[172:175], v[194:197], v[88:91]
	v_mfma_f32_16x16x32_bf16 v[80:83], v[164:167], v[202:205], v[80:83]
	v_mfma_f32_16x16x32_bf16 v[72:75], v[172:175], v[202:205], v[72:75]
	v_mfma_f32_16x16x32_bf16 v[68:71], v[164:167], v[210:213], v[68:71]
	v_mfma_f32_16x16x32_bf16 v[64:67], v[172:175], v[210:213], v[64:67]
	s_setprio 0
	s_barrier
	s_add_i32 s28, s28, s22
	v_lshl_add_u64 v[138:139], s[4:5], 0, v[176:177]
	s_mov_b32 m0, s28
	ds_read_b128 v[182:185], v143 offset:16384
	ds_read_b128 v[186:189], v143 offset:17408
	ds_read_b128 v[190:193], v143 offset:18432
	ds_read_b128 v[194:197], v143 offset:19456
	ds_read_b128 v[198:201], v143 offset:20480
	ds_read_b128 v[202:205], v143 offset:21504
	ds_read_b128 v[206:209], v143 offset:22528
	ds_read_b128 v[210:213], v143 offset:23552
	global_load_lds_dwordx4 v[138:139], off
	s_add_i32 m0, s28, 0x2000
	s_add_u32 s38, s4, 0x100000
	v_lshl_add_u64 v[214:215], s[4:5], 0, v[128:129]
	s_addc_u32 s39, s5, 0
	s_add_i32 s28, s48, s22
	global_load_lds_dwordx4 v[214:215], off
	v_lshl_add_u64 v[216:217], s[38:39], 0, v[176:177]
	s_mov_b32 m0, s28
	v_lshl_add_u64 v[218:219], s[6:7], 0, v[130:131]
	global_load_lds_dwordx4 v[216:217], off
	v_lshl_add_u64 v[216:217], s[38:39], 0, v[128:129]
	s_add_i32 m0, s28, 0x2000
	s_nop 0
	global_load_lds_dwordx4 v[216:217], off
	v_lshl_add_u64 v[216:217], s[6:7], 0, v[132:133]
	s_mov_b32 m0, s23
	s_nop 0
	global_load_lds_dwordx4 v[216:217], off
	s_mov_b32 m0, s24
	s_nop 0
	global_load_lds_dwordx4 v[218:219], off
	s_waitcnt vmcnt(24)
	s_waitcnt lgkmcnt(0)
	s_barrier
; #define PG8_STAGE(bufoff, gbase, voff) do { _Pragma("unroll") for (int _i = 0; _i < 2; ++_i) \
;         __builtin_amdgcn_global_load_lds((const unsigned*)((const char*)(gbase) + (voff)[_i]), (PG8_LAS unsigned*)(lds + (bufoff) + ldsw + _i * 8192), 16, 0, 0); } while (0)
; #define PG8_LDA(dst, b, h) do { _Pragma("unroll") for (int m = 0; m < 4; ++m) _Pragma("unroll") for (int k = 0; k < 2; ++k) dst[m][k] = *(const PG8_LAS bf16x8*)(lds + PG8_SA(b, h) + aoff + m * 2048 + k * 1024); } while (0)
; #define PG8_LDB(dst, b, h) do { _Pragma("unroll") for (int n = 0; n < 2; ++n) _Pragma("unroll") for (int k = 0; k < 2; ++k) dst[n][k] = *(const PG8_LAS bf16x8*)(lds + PG8_SB(b, h) + boff + n * 2048 + k * 1024); } while (0)
; #define PG8_MMA(ai, bj, At, Bt) do { __builtin_amdgcn_s_setprio(1); _Pragma("unroll") for (int m = 0; m < 4; ++m) _Pragma("unroll") for (int n = 0; n < 2; ++n) _Pragma("unroll") for (int k = 0; k < 2; ++k) \
;         acc[ai][bj][m][n] = __builtin_amdgcn_mfma_f32_16x16x32_bf16(Bt[n][k], At[m][k], acc[ai][bj][m][n], 0, 0, 0); __builtin_amdgcn_s_setprio(0); } while (0)
; #define PG8_WAIT_V(n) asm volatile("s_waitcnt vmcnt(" #n ")" ::: "memory")
; #define PG8_WAIT_L(n) asm volatile("s_waitcnt lgkmcnt(" #n ")" ::: "memory")
; #define PG8_BAR __builtin_amdgcn_s_barrier()
; #define PG8_SCHED __builtin_amdgcn_sched_barrier(0)
; template <class Epi, class Sched, bool ALIGN_EPI = false, bool SP2 = false>
; __device__ __forceinline__ void gemm_phase(PG8_LAS unsigned char* lds, const Gemm g, const Sched& S, const Epi& E) {
;     ...
;             PG8_WAIT_V(8); PG8_WAIT_L(0); PG8_BAR; PG8_MMA(1, 0, At, B0); PG8_MMA(1, 1, At, B1); PG8_BAR; PG8_SCHED;
;             PG8_LDB(B0, 1, 0); PG8_LDB(B1, 1, 1); PG8_SCHED; PG8_LDA(At, 1, 0); PG8_STAGE(PG8_SA(0, 1), a2 + hstep, voffA);
;             PG8_WAIT_V(8); PG8_WAIT_L(0); PG8_BAR; PG8_MMA(0, 0, At, B0); PG8_MMA(0, 1, At, B1); PG8_BAR; PG8_SCHED;
	s_setprio 1
	s_waitcnt lgkmcnt(0)
	v_mfma_f32_16x16x32_bf16 v[60:63], v[144:147], v[182:185], 0
	v_mfma_f32_16x16x32_bf16 v[56:59], v[152:155], v[182:185], 0
	v_mfma_f32_16x16x32_bf16 v[52:55], v[144:147], v[190:193], 0
	v_mfma_f32_16x16x32_bf16 v[44:47], v[152:155], v[190:193], 0
	v_mfma_f32_16x16x32_bf16 v[36:39], v[144:147], v[198:201], 0
	v_mfma_f32_16x16x32_bf16 v[28:31], v[152:155], v[198:201], 0
	v_mfma_f32_16x16x32_bf16 v[20:23], v[144:147], v[206:209], 0
	v_mfma_f32_16x16x32_bf16 v[12:15], v[152:155], v[206:209], 0
	v_mfma_f32_16x16x32_bf16 v[60:63], v[148:151], v[186:189], v[60:63]
	v_mfma_f32_16x16x32_bf16 v[56:59], v[156:159], v[186:189], v[56:59]
	v_mfma_f32_16x16x32_bf16 v[52:55], v[148:151], v[194:197], v[52:55]
	v_mfma_f32_16x16x32_bf16 v[44:47], v[156:159], v[194:197], v[44:47]
	v_mfma_f32_16x16x32_bf16 v[36:39], v[148:151], v[202:205], v[36:39]
	v_mfma_f32_16x16x32_bf16 v[28:31], v[156:159], v[202:205], v[28:31]
	v_mfma_f32_16x16x32_bf16 v[20:23], v[148:151], v[210:213], v[20:23]
	v_mfma_f32_16x16x32_bf16 v[12:15], v[156:159], v[210:213], v[12:15]
	s_setprio 0
	s_setprio 1
	v_mfma_f32_16x16x32_bf16 v[48:51], v[160:163], v[182:185], 0
	v_mfma_f32_16x16x32_bf16 v[40:43], v[168:171], v[182:185], 0
	v_mfma_f32_16x16x32_bf16 v[32:35], v[160:163], v[190:193], 0
	v_mfma_f32_16x16x32_bf16 v[24:27], v[168:171], v[190:193], 0
	v_mfma_f32_16x16x32_bf16 v[16:19], v[160:163], v[198:201], 0
	v_mfma_f32_16x16x32_bf16 v[8:11], v[168:171], v[198:201], 0
	v_mfma_f32_16x16x32_bf16 v[4:7], v[160:163], v[206:209], 0
	v_mfma_f32_16x16x32_bf16 v[0:3], v[168:171], v[206:209], 0
	v_mfma_f32_16x16x32_bf16 v[48:51], v[164:167], v[186:189], v[48:51]
	v_mfma_f32_16x16x32_bf16 v[40:43], v[172:175], v[186:189], v[40:43]
	v_mfma_f32_16x16x32_bf16 v[32:35], v[164:167], v[194:197], v[32:35]
	v_mfma_f32_16x16x32_bf16 v[24:27], v[172:175], v[194:197], v[24:27]
	v_mfma_f32_16x16x32_bf16 v[16:19], v[164:167], v[202:205], v[16:19]
	v_mfma_f32_16x16x32_bf16 v[8:11], v[172:175], v[202:205], v[8:11]
	v_mfma_f32_16x16x32_bf16 v[4:7], v[164:167], v[210:213], v[4:7]
	v_mfma_f32_16x16x32_bf16 v[0:3], v[172:175], v[210:213], v[0:3]
	s_setprio 0
	s_barrier
	s_add_i32 s28, 0, 0x18000
	s_add_i32 s38, 0, 0x1c000
	v_add_u32_e32 v156, s28, v142
	v_add_u32_e32 v172, s38, v142
	ds_read_b128 v[144:147], v156
	ds_read_b128 v[148:151], v156 offset:1024
	ds_read_b128 v[152:155], v156 offset:2048
	ds_read_b128 v[156:159], v156 offset:3072
	ds_read_b128 v[160:163], v172
	ds_read_b128 v[164:167], v172 offset:1024
	ds_read_b128 v[168:171], v172 offset:2048
	ds_read_b128 v[172:175], v172 offset:3072
	s_add_u32 s6, s6, 0x100000
	s_addc_u32 s7, s7, 0
	s_mov_b32 m0, s25
	v_lshl_add_u64 v[220:221], s[6:7], 0, v[132:133]
	ds_read_b128 v[182:185], v143 offset:32768
	ds_read_b128 v[186:189], v143 offset:33792
	ds_read_b128 v[190:193], v143 offset:34816
	ds_read_b128 v[194:197], v143 offset:35840
	ds_read_b128 v[198:201], v143 offset:36864
	ds_read_b128 v[202:205], v143 offset:37888
	ds_read_b128 v[206:209], v143 offset:38912
	ds_read_b128 v[210:213], v143 offset:39936
	global_load_lds_dwordx4 v[220:221], off
	v_lshl_add_u64 v[220:221], s[6:7], 0, v[130:131]
	s_mov_b32 m0, s30
	s_nop 0
	global_load_lds_dwordx4 v[220:221], off
	s_waitcnt vmcnt(8)
	s_waitcnt lgkmcnt(0)
	s_barrier
	s_setprio 1
	s_waitcnt lgkmcnt(0)
	v_mfma_f32_16x16x32_bf16 v[124:127], v[144:147], v[182:185], v[124:127]
	v_mfma_f32_16x16x32_bf16 v[120:123], v[152:155], v[182:185], v[120:123]
	v_mfma_f32_16x16x32_bf16 v[116:119], v[144:147], v[190:193], v[116:119]
	v_mfma_f32_16x16x32_bf16 v[108:111], v[152:155], v[190:193], v[108:111]
	v_mfma_f32_16x16x32_bf16 v[100:103], v[144:147], v[198:201], v[100:103]
	v_mfma_f32_16x16x32_bf16 v[92:95], v[152:155], v[198:201], v[92:95]
	v_mfma_f32_16x16x32_bf16 v[84:87], v[144:147], v[206:209], v[84:87]
	v_mfma_f32_16x16x32_bf16 v[76:79], v[152:155], v[206:209], v[76:79]
	v_mfma_f32_16x16x32_bf16 v[124:127], v[148:151], v[186:189], v[124:127]
	v_mfma_f32_16x16x32_bf16 v[120:123], v[156:159], v[186:189], v[120:123]
	v_mfma_f32_16x16x32_bf16 v[116:119], v[148:151], v[194:197], v[116:119]
	v_mfma_f32_16x16x32_bf16 v[108:111], v[156:159], v[194:197], v[108:111]
	v_mfma_f32_16x16x32_bf16 v[100:103], v[148:151], v[202:205], v[100:103]
	v_mfma_f32_16x16x32_bf16 v[92:95], v[156:159], v[202:205], v[92:95]
	v_mfma_f32_16x16x32_bf16 v[84:87], v[148:151], v[210:213], v[84:87]
	v_mfma_f32_16x16x32_bf16 v[76:79], v[156:159], v[210:213], v[76:79]
	s_setprio 0
	s_setprio 1
	v_mfma_f32_16x16x32_bf16 v[112:115], v[160:163], v[182:185], v[112:115]
	v_mfma_f32_16x16x32_bf16 v[104:107], v[168:171], v[182:185], v[104:107]
	v_mfma_f32_16x16x32_bf16 v[96:99], v[160:163], v[190:193], v[96:99]
	v_mfma_f32_16x16x32_bf16 v[88:91], v[168:171], v[190:193], v[88:91]
	v_mfma_f32_16x16x32_bf16 v[80:83], v[160:163], v[198:201], v[80:83]
	v_mfma_f32_16x16x32_bf16 v[72:75], v[168:171], v[198:201], v[72:75]
	v_mfma_f32_16x16x32_bf16 v[68:71], v[160:163], v[206:209], v[68:71]
	v_mfma_f32_16x16x32_bf16 v[64:67], v[168:171], v[206:209], v[64:67]
	v_mfma_f32_16x16x32_bf16 v[112:115], v[164:167], v[186:189], v[112:115]
	v_mfma_f32_16x16x32_bf16 v[104:107], v[172:175], v[186:189], v[104:107]
	v_mfma_f32_16x16x32_bf16 v[96:99], v[164:167], v[194:197], v[96:99]
	v_mfma_f32_16x16x32_bf16 v[88:91], v[172:175], v[194:197], v[88:91]
	v_mfma_f32_16x16x32_bf16 v[80:83], v[164:167], v[202:205], v[80:83]
	v_mfma_f32_16x16x32_bf16 v[72:75], v[172:175], v[202:205], v[72:75]
	v_mfma_f32_16x16x32_bf16 v[68:71], v[164:167], v[210:213], v[68:71]
	v_mfma_f32_16x16x32_bf16 v[64:67], v[172:175], v[210:213], v[64:67]
	s_setprio 0
	s_barrier
; #define PG8_STAGE(bufoff, gbase, voff) do { _Pragma("unroll") for (int _i = 0; _i < 2; ++_i) \
;         __builtin_amdgcn_global_load_lds((const unsigned*)((const char*)(gbase) + (voff)[_i]), (PG8_LAS unsigned*)(lds + (bufoff) + ldsw + _i * 8192), 16, 0, 0); } while (0)
; #define PG8_LDA(dst, b, h) do { _Pragma("unroll") for (int m = 0; m < 4; ++m) _Pragma("unroll") for (int k = 0; k < 2; ++k) dst[m][k] = *(const PG8_LAS bf16x8*)(lds + PG8_SA(b, h) + aoff + m * 2048 + k * 1024); } while (0)
; #define PG8_MMA(ai, bj, At, Bt) do { __builtin_amdgcn_s_setprio(1); _Pragma("unroll") for (int m = 0; m < 4; ++m) _Pragma("unroll") for (int n = 0; n < 2; ++n) _Pragma("unroll") for (int k = 0; k < 2; ++k) \
;         acc[ai][bj][m][n] = __builtin_amdgcn_mfma_f32_16x16x32_bf16(Bt[n][k], At[m][k], acc[ai][bj][m][n], 0, 0, 0); __builtin_amdgcn_s_setprio(0); } while (0)
; #define PG8_WAIT_V(n) asm volatile("s_waitcnt vmcnt(" #n ")" ::: "memory")
; #define PG8_WAIT_L(n) asm volatile("s_waitcnt lgkmcnt(" #n ")" ::: "memory")
; #define PG8_BAR __builtin_amdgcn_s_barrier()
; #define PG8_SCHED __builtin_amdgcn_sched_barrier(0)
; template <class Epi, class Sched, bool ALIGN_EPI = false, bool SP2 = false>
; __device__ __forceinline__ void gemm_phase(PG8_LAS unsigned char* lds, const Gemm g, const Sched& S, const Epi& E) {
;     ...
;         for (int t = 0; t < nt; t += 2) {
;             const bool last = (t == nt - 2);
;             const char* a1 = cA + (size_t)(t + 1) * kstep;
;             const char* a2 = last ? nA : cA + (size_t)(t + 2) * kstep; const char* b2 = last ? nB : cB + (size_t)(t + 2) * kstep;
;     ...
;             PG8_LDA(At, 1, 1); PG8_STAGE(PG8_SB(1, 0), b3, voffB); PG8_STAGE(PG8_SB(1, 1), b3 + hstep, voffB); PG8_STAGE(PG8_SA(1, 0), a3, voffA);
;             PG8_WAIT_V(8); PG8_WAIT_L(0); PG8_BAR; PG8_MMA(1, 0, At, B0); PG8_MMA(1, 1, At, B1); PG8_BAR; PG8_SCHED;
	s_add_i32 s6, s28, s22
	v_lshl_add_u64 v[138:139], v[138:139], 0, s[44:45]
	s_mov_b32 m0, s6
	ds_read_b128 v[182:185], v143 offset:49152
	ds_read_b128 v[186:189], v143 offset:50176
	ds_read_b128 v[190:193], v143 offset:51200
	ds_read_b128 v[194:197], v143 offset:52224
	ds_read_b128 v[198:201], v143 offset:53248
	ds_read_b128 v[202:205], v143 offset:54272
	ds_read_b128 v[206:209], v143 offset:55296
	ds_read_b128 v[210:213], v143 offset:56320
	global_load_lds_dwordx4 v[138:139], off
	s_add_i32 m0, s6, 0x2000
	s_add_u32 s4, s4, 0x100080
	v_lshl_add_u64 v[138:139], v[214:215], 0, s[44:45]
	s_addc_u32 s5, s5, 0
	s_add_i32 s6, s38, s22
	global_load_lds_dwordx4 v[138:139], off
	v_lshl_add_u64 v[138:139], s[4:5], 0, v[176:177]
	s_mov_b32 m0, s6
	s_nop 0
	global_load_lds_dwordx4 v[138:139], off
	v_lshl_add_u64 v[138:139], s[4:5], 0, v[128:129]
	s_add_i32 m0, s6, 0x2000
	s_nop 0
	global_load_lds_dwordx4 v[138:139], off
	v_lshl_add_u64 v[138:139], v[216:217], 0, s[44:45]
	s_mov_b32 m0, s63
	s_nop 0
	global_load_lds_dwordx4 v[138:139], off
	v_lshl_add_u64 v[138:139], v[218:219], 0, s[44:45]
	s_mov_b32 m0, s68
	s_nop 0
	global_load_lds_dwordx4 v[138:139], off
	s_waitcnt vmcnt(8)
	s_waitcnt lgkmcnt(0)
	s_barrier
	s_setprio 1
	s_waitcnt lgkmcnt(0)
	v_mfma_f32_16x16x32_bf16 v[60:63], v[144:147], v[182:185], v[60:63]
	v_mfma_f32_16x16x32_bf16 v[56:59], v[152:155], v[182:185], v[56:59]
	v_mfma_f32_16x16x32_bf16 v[52:55], v[144:147], v[190:193], v[52:55]
	v_mfma_f32_16x16x32_bf16 v[44:47], v[152:155], v[190:193], v[44:47]
	v_mfma_f32_16x16x32_bf16 v[36:39], v[144:147], v[198:201], v[36:39]
	v_mfma_f32_16x16x32_bf16 v[28:31], v[152:155], v[198:201], v[28:31]
	v_mfma_f32_16x16x32_bf16 v[20:23], v[144:147], v[206:209], v[20:23]
	v_mfma_f32_16x16x32_bf16 v[12:15], v[152:155], v[206:209], v[12:15]
	v_mfma_f32_16x16x32_bf16 v[60:63], v[148:151], v[186:189], v[60:63]
	v_mfma_f32_16x16x32_bf16 v[56:59], v[156:159], v[186:189], v[56:59]
	v_mfma_f32_16x16x32_bf16 v[52:55], v[148:151], v[194:197], v[52:55]
	v_mfma_f32_16x16x32_bf16 v[44:47], v[156:159], v[194:197], v[44:47]
	v_mfma_f32_16x16x32_bf16 v[36:39], v[148:151], v[202:205], v[36:39]
	v_mfma_f32_16x16x32_bf16 v[28:31], v[156:159], v[202:205], v[28:31]
	v_mfma_f32_16x16x32_bf16 v[20:23], v[148:151], v[210:213], v[20:23]
	v_mfma_f32_16x16x32_bf16 v[12:15], v[156:159], v[210:213], v[12:15]
	s_setprio 0
	s_setprio 1
	v_mfma_f32_16x16x32_bf16 v[48:51], v[160:163], v[182:185], v[48:51]
	v_mfma_f32_16x16x32_bf16 v[40:43], v[168:171], v[182:185], v[40:43]
	v_mfma_f32_16x16x32_bf16 v[32:35], v[160:163], v[190:193], v[32:35]
	v_mfma_f32_16x16x32_bf16 v[24:27], v[168:171], v[190:193], v[24:27]
	v_mfma_f32_16x16x32_bf16 v[16:19], v[160:163], v[198:201], v[16:19]
	v_mfma_f32_16x16x32_bf16 v[8:11], v[168:171], v[198:201], v[8:11]
	v_mfma_f32_16x16x32_bf16 v[4:7], v[160:163], v[206:209], v[4:7]
	v_mfma_f32_16x16x32_bf16 v[0:3], v[168:171], v[206:209], v[0:3]
	v_mfma_f32_16x16x32_bf16 v[48:51], v[164:167], v[186:189], v[48:51]
	v_mfma_f32_16x16x32_bf16 v[40:43], v[172:175], v[186:189], v[40:43]
	v_mfma_f32_16x16x32_bf16 v[32:35], v[164:167], v[194:197], v[32:35]
	v_mfma_f32_16x16x32_bf16 v[24:27], v[172:175], v[194:197], v[24:27]
	v_mfma_f32_16x16x32_bf16 v[16:19], v[164:167], v[202:205], v[16:19]
	v_mfma_f32_16x16x32_bf16 v[8:11], v[172:175], v[202:205], v[8:11]
	v_mfma_f32_16x16x32_bf16 v[4:7], v[164:167], v[210:213], v[4:7]
	v_mfma_f32_16x16x32_bf16 v[0:3], v[172:175], v[210:213], v[0:3]
	s_setprio 0
	s_barrier
	s_add_i32 s74, s74, 2
	s_add_u32 s64, s64, 0x100
	s_addc_u32 s65, s65, 0
	s_add_u32 s66, s66, 0x100
	s_addc_u32 s67, s67, 0
	s_cmp_gt_u32 s74, 61
	s_cbranch_scc0 .LBB0_790
	s_branch .Lg4_post
